# GEMM k-loops: per-load address adds folded into immediate offsets on per-tile base registers (553 VALU ops and their pads removed)
# speedup vs baseline: 1.0126x; 1.0102x over previous
; template <int MODE>
; __device__ __forceinline__ void gemm_tile(const Params& P, int tm, int tn, unsigned char* smem) {
;     ...
;     uint4 ra0, ra1, ra2, ra3, rb0, rb1, rb2, rb3;
;     ...
;     unsigned char* sA0 = smem; unsigned char* sB0 = smem + 16384; unsigned char* sA1 = smem + 32768; unsigned char* sB1 = smem + 49152;
;     G_LOAD(0)
;     G_WRITE(sA0, sB0)
;     __syncthreads();
;     const int arow_off = (wr * 64 + lr) * 128, brow_off = (wc * 64 + lr) * 128, sw = lr & 7;
;     G_LOAD(1)
;     for (int kt = 0; kt < 16; ++kt) {
;         unsigned char* sA = (kt & 1) ? sA1 : sA0; unsigned char* sB = (kt & 1) ? sB1 : sB0;
;         unsigned char* nA = (kt & 1) ? sA0 : sA1; unsigned char* nB = (kt & 1) ? sB0 : sB1;
;         bf16x8 fa[4], fb[4], ga[4], gb[4];
;         const int ch0 = ((g ^ sw) << 4), ch1 = (((4 + g) ^ sw) << 4);
;         const unsigned ko = (unsigned)(kt + 2) * 128u;
;         const unsigned koa = ko + ((MODE == 2 && kt + 2 >= 8) ? (unsigned)(ZC_FQ - 512) * 2u : 0u);
;         const bool wr_ok = kt < 15, ld_ok = kt < 14;
; #pragma unroll
;         for (int i = 0; i < 4; ++i) { fa[i] = *(const bf16x8*)(sA + arow_off + i * 2048 + ch0); fb[i] = *(const bf16x8*)(sB + brow_off + i * 2048 + ch0); }
;         __builtin_amdgcn_sched_barrier(0);
;         __builtin_amdgcn_s_setprio(2);
;         if (wr_ok) *(uint4*)(nA + soff0) = ra0;
;         if (ld_ok) ra0 = *(const uint4*)(Ab + (aoff + 0u * LDA + koa));
;         ga[0] = *(const bf16x8*)(sA + arow_off + 0 * 2048 + ch1); gb[0] = *(const bf16x8*)(sB + brow_off + 0 * 2048 + ch1);
;         __builtin_amdgcn_sched_barrier(0);
; #pragma unroll
;         for (int j = 0; j < 4; ++j) acc[0][j] = __builtin_amdgcn_mfma_f32_16x16x32_bf16(fb[j], fa[0], acc[0][j], 0, 0, 0);
;         __builtin_amdgcn_sched_barrier(0);
;         if (wr_ok) *(uint4*)(nA + soff0 + 4096) = ra1;
;         if (ld_ok) ra1 = *(const uint4*)(Ab + (aoff + 32u * LDA + koa));
;         ga[1] = *(const bf16x8*)(sA + arow_off + 1 * 2048 + ch1); gb[1] = *(const bf16x8*)(sB + brow_off + 1 * 2048 + ch1);
;         __builtin_amdgcn_sched_barrier(0);
; #pragma unroll
;         for (int j = 0; j < 4; ++j) acc[1][j] = __builtin_amdgcn_mfma_f32_16x16x32_bf16(fb[j], fa[1], acc[1][j], 0, 0, 0);
;         __builtin_amdgcn_sched_barrier(0);
;         if (wr_ok) *(uint4*)(nA + soff0 + 8192) = ra2;
.LBB0_182:
	s_mul_hi_i32 s0, s35, 0x92492493
	s_add_i32 s0, s0, s35
	s_lshr_b32 s1, s0, 31
	s_ashr_i32 s0, s0, 7
	s_add_i32 s1, s0, s1
	s_mul_i32 s0, s1, 0xffffff20
	s_lshl_b32 s10, s1, 3
	s_add_i32 s0, s35, s0
	s_sub_i32 s10, 0x81, s10
	s_cmpk_gt_i32 s35, 0xdff
	s_cselect_b32 s10, s10, 8
	s_abs_i32 s11, s10
	v_cvt_f32_u32_e32 v2, s11
	s_ashr_i32 s0, s0, 31
	s_mul_i32 s13, s1, 0xe0
	s_sub_i32 s13, s0, s13
	v_rcp_iflag_f32_e32 v2, v2
	s_ashr_i32 s12, s10, 31
	s_add_i32 s13, s35, s13
	s_xor_b32 s12, s0, s12
	v_mul_f32_e32 v2, 0x4f7ffffe, v2
	v_cvt_u32_f32_e32 v2, v2
	s_xor_b32 s0, s13, s0
	s_sub_i32 s13, 0, s11
	s_mulk_i32 s1, 0xd8
	v_readfirstlane_b32 s42, v2
	s_mul_i32 s13, s13, s42
	s_mul_hi_u32 s13, s42, s13
	s_add_i32 s42, s42, s13
	s_mul_hi_u32 s13, s0, s42
	s_mul_i32 s42, s13, s11
	s_sub_i32 s0, s0, s42
	s_add_i32 s42, s13, 1
	s_sub_i32 s43, s0, s11
	s_cmp_ge_u32 s0, s11
	s_cselect_b32 s13, s42, s13
	s_cselect_b32 s0, s43, s0
	s_add_i32 s42, s13, 1
	s_cmp_ge_u32 s0, s11
	s_cselect_b32 s0, s42, s13
	s_xor_b32 s0, s0, s12
	s_sub_i32 s0, s0, s12
	s_mul_i32 s10, s10, s0
	s_add_i32 s10, s10, s1
	s_sub_i32 s1, s35, s10
	v_mov_b32_e32 v79, v0
	s_lshl_b32 s42, s1, 7
	v_ashrrev_i32_e32 v2, 3, v79
	v_lshlrev_b32_e32 v4, 4, v79
	s_lshl_b32 s10, s0, 7
	v_add_u32_e32 v3, s42, v2
	v_and_b32_e32 v4, 0x70, v4
	v_add_u32_e32 v5, s10, v2
	v_lshl_or_b32 v8, v3, 11, v4
	v_lshl_or_b32 v5, v5, 11, v4
	v_add_u32_e32 v3, 0x10000, v8
	v_add_u32_e32 v4, 0x20000, v8
	global_load_dwordx4 v[10:13], v3, s[36:37]
	global_load_dwordx4 v[14:17], v4, s[36:37]
	v_add_u32_e32 v3, 0x20000, v5
	v_add_u32_e32 v4, 0x30000, v5
	global_load_dwordx4 v[18:21], v3, s[4:5]
	global_load_dwordx4 v[22:25], v4, s[4:5]
	global_load_dwordx4 v[26:29], v8, s[36:37]
	global_load_dwordx4 v[30:33], v5, s[4:5]
	v_add_u32_e32 v3, 0x30000, v8
	v_add_u32_e32 v4, 0x10000, v5
	global_load_dwordx4 v[34:37], v3, s[36:37]
	global_load_dwordx4 v[38:41], v4, s[4:5]
	v_xor_b32_e32 v3, v2, v79
	v_lshlrev_b32_e32 v2, 7, v2
	v_lshlrev_b32_e32 v3, 4, v3
	v_and_or_b32 v2, v3, s20, v2
	v_add_u32_e32 v2, 0, v2
	v_or_b32_e32 v9, 0x80, v8
	v_or_b32_e32 v3, 0x80, v5
	v_add_u32_e32 v4, 0x10080, v5
	v_add_u32_e32 v6, 0x20080, v5
	v_add_u32_e32 v7, 0x30080, v5
	v_add_u32_e32 v42, 0x10080, v8
	v_add_u32_e32 v43, 0x20080, v8
	v_add_u32_e32 v44, 0x30080, v8
	v_and_b32_e32 v80, 15, v79
	v_ashrrev_i32_e32 v81, 7, v79
	v_bfe_u32 v82, v79, 6, 1
	v_bfe_u32 v83, v79, 4, 2
	s_waitcnt vmcnt(5)
	ds_write_b128 v2, v[18:21] offset:24576
	s_waitcnt vmcnt(4)
	ds_write_b128 v2, v[22:25] offset:28672
	s_waitcnt vmcnt(3)
	ds_write_b128 v2, v[26:29]
	s_waitcnt vmcnt(2)
	ds_write_b128 v2, v[30:33] offset:16384
	ds_write_b128 v2, v[10:13] offset:4096
	ds_write_b128 v2, v[14:17] offset:8192
	s_waitcnt vmcnt(1)
	ds_write_b128 v2, v[34:37] offset:12288
	s_waitcnt vmcnt(0)
	ds_write_b128 v2, v[38:41] offset:20480
	s_waitcnt lgkmcnt(0)
	s_barrier
	global_load_dwordx4 v[10:13], v9, s[36:37]
	global_load_dwordx4 v[14:17], v42, s[36:37]
	global_load_dwordx4 v[18:21], v43, s[36:37]
	global_load_dwordx4 v[22:25], v44, s[36:37]
	global_load_dwordx4 v[26:29], v3, s[4:5]
	global_load_dwordx4 v[30:33], v4, s[4:5]
	global_load_dwordx4 v[34:37], v6, s[4:5]
	global_load_dwordx4 v[38:41], v7, s[4:5]
	v_lshrrev_b32_e32 v3, 4, v79
	v_lshlrev_b32_e32 v4, 7, v80
	v_and_b32_e32 v9, 7, v79
	v_lshl_or_b32 v6, v81, 13, v4
	v_bitop3_b32 v3, v3, v9, 3 bitop3:0x6c
	v_lshl_or_b32 v4, v82, 13, v4
	v_lshlrev_b32_e32 v3, 4, v3
	v_add_u32_e32 v66, 0, v6
	v_add_u32_e32 v6, v66, v3
	v_add_u32_e32 v4, 0, v4
	v_add_u32_e32 v7, v4, v3
	ds_read_b128 v[42:45], v6
	ds_read_b128 v[46:49], v6 offset:2048
	ds_read_b128 v[50:53], v7 offset:16384
	ds_read_b128 v[54:57], v7 offset:18432
	ds_read_b128 v[58:61], v6 offset:4096
	ds_read_b128 v[62:65], v6 offset:6144
	ds_read_b128 v[84:87], v7 offset:20480
	ds_read_b128 v[88:91], v7 offset:22528
	v_bitop3_b32 v3, v83, v9, 4 bitop3:0x36
	v_lshlrev_b32_e32 v9, 4, v3
	s_setprio 2
	global_load_dwordx4 v[92:95], v8, s[36:37] offset:256
	s_waitcnt vmcnt(8)
	ds_write_b128 v2, v[10:13] offset:32768
	v_add_u32_e32 v3, v66, v9
	v_add_u32_e32 v4, v4, v9
	ds_read_b128 v[10:13], v3
	ds_read_b128 v[96:99], v4 offset:16384
	s_waitcnt lgkmcnt(8)
	v_mfma_f32_16x16x32_bf16 v[100:103], v[50:53], v[42:45], 0
	s_waitcnt lgkmcnt(7)
	v_mfma_f32_16x16x32_bf16 v[104:107], v[54:57], v[42:45], 0
	s_waitcnt lgkmcnt(4)
	v_mfma_f32_16x16x32_bf16 v[108:111], v[84:87], v[42:45], 0
	s_waitcnt lgkmcnt(3)
	v_mfma_f32_16x16x32_bf16 v[42:45], v[88:91], v[42:45], 0
	v_add_u32_e32 v216, 0x10000, v8
	global_load_dwordx4 v[112:115], v216, s[36:37] offset:256
	s_waitcnt vmcnt(8)
	ds_write_b128 v2, v[14:17] offset:36864
	ds_read_b128 v[14:17], v3 offset:2048
	ds_read_b128 v[116:119], v4 offset:18432
	v_mfma_f32_16x16x32_bf16 v[120:123], v[50:53], v[46:49], 0
	v_mfma_f32_16x16x32_bf16 v[124:127], v[54:57], v[46:49], 0
	v_mfma_f32_16x16x32_bf16 v[132:135], v[84:87], v[46:49], 0
	v_mfma_f32_16x16x32_bf16 v[46:49], v[88:91], v[46:49], 0
	v_add_u32_e32 v217, 0x20000, v8
	global_load_dwordx4 v[146:149], v217, s[36:37] offset:256
	s_waitcnt vmcnt(8)
	ds_write_b128 v2, v[18:21] offset:40960
	ds_read_b128 v[18:21], v3 offset:4096
	ds_read_b128 v[150:153], v4 offset:20480
	v_mfma_f32_16x16x32_bf16 v[154:157], v[50:53], v[58:61], 0
	v_mfma_f32_16x16x32_bf16 v[158:161], v[54:57], v[58:61], 0
	v_mfma_f32_16x16x32_bf16 v[162:165], v[84:87], v[58:61], 0
	v_mfma_f32_16x16x32_bf16 v[58:61], v[88:91], v[58:61], 0
	v_add_u32_e32 v218, 0x30000, v8
	global_load_dwordx4 v[166:169], v218, s[36:37] offset:256
	s_waitcnt vmcnt(8)
; template <int MODE>
; __device__ __forceinline__ void gemm_tile(const Params& P, int tm, int tn, unsigned char* smem) {
;     ...
; #pragma unroll
;         for (int i = 0; i < 4; ++i) { fa[i] = *(const bf16x8*)(sA + arow_off + i * 2048 + ch0); fb[i] = *(const bf16x8*)(sB + brow_off + i * 2048 + ch0); }
;         __builtin_amdgcn_sched_barrier(0);
;         __builtin_amdgcn_s_setprio(2);
;         if (wr_ok) *(uint4*)(nA + soff0) = ra0;
;         if (ld_ok) ra0 = *(const uint4*)(Ab + (aoff + 0u * LDA + koa));
;         ga[0] = *(const bf16x8*)(sA + arow_off + 0 * 2048 + ch1); gb[0] = *(const bf16x8*)(sB + brow_off + 0 * 2048 + ch1);
;         __builtin_amdgcn_sched_barrier(0);
; #pragma unroll
;         for (int j = 0; j < 4; ++j) acc[0][j] = __builtin_amdgcn_mfma_f32_16x16x32_bf16(fb[j], fa[0], acc[0][j], 0, 0, 0);
;         __builtin_amdgcn_sched_barrier(0);
;         if (wr_ok) *(uint4*)(nA + soff0 + 4096) = ra1;
;         if (ld_ok) ra1 = *(const uint4*)(Ab + (aoff + 32u * LDA + koa));
;         ga[1] = *(const bf16x8*)(sA + arow_off + 1 * 2048 + ch1); gb[1] = *(const bf16x8*)(sB + brow_off + 1 * 2048 + ch1);
;         __builtin_amdgcn_sched_barrier(0);
; #pragma unroll
;         for (int j = 0; j < 4; ++j) acc[1][j] = __builtin_amdgcn_mfma_f32_16x16x32_bf16(fb[j], fa[1], acc[1][j], 0, 0, 0);
;         __builtin_amdgcn_sched_barrier(0);
;         if (wr_ok) *(uint4*)(nA + soff0 + 8192) = ra2;
;         if (ld_ok) ra2 = *(const uint4*)(Ab + (aoff + 64u * LDA + koa));
;         ga[2] = *(const bf16x8*)(sA + arow_off + 2 * 2048 + ch1); gb[2] = *(const bf16x8*)(sB + brow_off + 2 * 2048 + ch1);
;         __builtin_amdgcn_sched_barrier(0);
; #pragma unroll
;         for (int j = 0; j < 4; ++j) acc[2][j] = __builtin_amdgcn_mfma_f32_16x16x32_bf16(fb[j], fa[2], acc[2][j], 0, 0, 0);
;         __builtin_amdgcn_sched_barrier(0);
;         if (wr_ok) *(uint4*)(nA + soff0 + 12288) = ra3;
;         if (ld_ok) ra3 = *(const uint4*)(Ab + (aoff + 96u * LDA + koa));
;         ga[3] = *(const bf16x8*)(sA + arow_off + 3 * 2048 + ch1); gb[3] = *(const bf16x8*)(sB + brow_off + 3 * 2048 + ch1);
;         __builtin_amdgcn_sched_barrier(0);
; #pragma unroll
;         for (int j = 0; j < 4; ++j) acc[3][j] = __builtin_amdgcn_mfma_f32_16x16x32_bf16(fb[j], fa[3], acc[3][j], 0, 0, 0);
;         __builtin_amdgcn_sched_barrier(0);
;         if (wr_ok) *(uint4*)(nB + soff0) = rb0;
	ds_write_b128 v2, v[22:25] offset:45056
	ds_read_b128 v[22:25], v3 offset:6144
	ds_read_b128 v[170:173], v4 offset:22528
	v_mfma_f32_16x16x32_bf16 v[50:53], v[50:53], v[62:65], 0
	v_mfma_f32_16x16x32_bf16 v[54:57], v[54:57], v[62:65], 0
	v_mfma_f32_16x16x32_bf16 v[84:87], v[84:87], v[62:65], 0
	v_mfma_f32_16x16x32_bf16 v[62:65], v[88:91], v[62:65], 0
	global_load_dwordx4 v[88:91], v5, s[4:5] offset:256
	s_waitcnt vmcnt(8)
	ds_write_b128 v2, v[26:29] offset:49152
	s_waitcnt lgkmcnt(10)
	v_mfma_f32_16x16x32_bf16 v[26:29], v[96:99], v[10:13], v[100:103]
	s_waitcnt lgkmcnt(7)
	v_mfma_f32_16x16x32_bf16 v[100:103], v[116:119], v[10:13], v[104:107]
	s_waitcnt lgkmcnt(4)
	v_mfma_f32_16x16x32_bf16 v[104:107], v[150:153], v[10:13], v[108:111]
	s_waitcnt lgkmcnt(1)
	v_mfma_f32_16x16x32_bf16 v[10:13], v[170:173], v[10:13], v[42:45]
	v_add_u32_e32 v219, 0x10000, v5
	global_load_dwordx4 v[42:45], v219, s[4:5] offset:256
	s_waitcnt vmcnt(8)
	ds_write_b128 v2, v[30:33] offset:53248
	v_mfma_f32_16x16x32_bf16 v[30:33], v[96:99], v[14:17], v[120:123]
	v_mfma_f32_16x16x32_bf16 v[108:111], v[116:119], v[14:17], v[124:127]
	v_mfma_f32_16x16x32_bf16 v[120:123], v[150:153], v[14:17], v[132:135]
	v_mfma_f32_16x16x32_bf16 v[14:17], v[170:173], v[14:17], v[46:49]
	v_add_u32_e32 v220, 0x20000, v5
	global_load_dwordx4 v[46:49], v220, s[4:5] offset:256
	s_waitcnt vmcnt(8)
	ds_write_b128 v2, v[34:37] offset:57344
	v_mfma_f32_16x16x32_bf16 v[34:37], v[96:99], v[18:21], v[154:157]
	v_mfma_f32_16x16x32_bf16 v[124:127], v[116:119], v[18:21], v[158:161]
	v_mfma_f32_16x16x32_bf16 v[132:135], v[150:153], v[18:21], v[162:165]
	v_mfma_f32_16x16x32_bf16 v[18:21], v[170:173], v[18:21], v[58:61]
	v_add_u32_e32 v221, 0x30000, v5
	global_load_dwordx4 v[58:61], v221, s[4:5] offset:256
	s_waitcnt vmcnt(8)
	ds_write_b128 v2, v[38:41] offset:61440
	v_mfma_f32_16x16x32_bf16 v[38:41], v[96:99], v[22:25], v[50:53]
	v_mfma_f32_16x16x32_bf16 v[50:53], v[116:119], v[22:25], v[54:57]
	v_mfma_f32_16x16x32_bf16 v[54:57], v[150:153], v[22:25], v[84:87]
	v_mfma_f32_16x16x32_bf16 v[22:25], v[170:173], v[22:25], v[62:65]
	s_setprio 0
	s_waitcnt lgkmcnt(0)
	s_barrier
	ds_read_b128 v[62:65], v6 offset:32768
	ds_read_b128 v[84:87], v6 offset:34816
	ds_read_b128 v[96:99], v7 offset:49152
	ds_read_b128 v[116:119], v7 offset:51200
	ds_read_b128 v[150:153], v6 offset:36864
	ds_read_b128 v[154:157], v6 offset:38912
	ds_read_b128 v[158:161], v7 offset:53248
	ds_read_b128 v[162:165], v7 offset:55296
	s_setprio 2
	global_load_dwordx4 v[170:173], v8, s[36:37] offset:384
	s_waitcnt vmcnt(8)
	ds_write_b128 v2, v[92:95]
	ds_read_b128 v[92:95], v3 offset:32768
	ds_read_b128 v[174:177], v4 offset:49152
	s_waitcnt lgkmcnt(8)
	v_mfma_f32_16x16x32_bf16 v[26:29], v[96:99], v[62:65], v[26:29]
	s_waitcnt lgkmcnt(3)
	v_mfma_f32_16x16x32_bf16 v[10:13], v[162:165], v[62:65], v[10:13]
	v_mfma_f32_16x16x32_bf16 v[100:103], v[116:119], v[62:65], v[100:103]
	v_mfma_f32_16x16x32_bf16 v[104:107], v[158:161], v[62:65], v[104:107]
	global_load_dwordx4 v[62:65], v216, s[36:37] offset:384
	s_waitcnt vmcnt(8)
	ds_write_b128 v2, v[112:115] offset:4096
	ds_read_b128 v[112:115], v3 offset:34816
	ds_read_b128 v[178:181], v4 offset:51200
	v_mfma_f32_16x16x32_bf16 v[30:33], v[96:99], v[84:87], v[30:33]
	v_mfma_f32_16x16x32_bf16 v[14:17], v[162:165], v[84:87], v[14:17]
	v_mfma_f32_16x16x32_bf16 v[108:111], v[116:119], v[84:87], v[108:111]
	v_mfma_f32_16x16x32_bf16 v[120:123], v[158:161], v[84:87], v[120:123]
	global_load_dwordx4 v[84:87], v217, s[36:37] offset:384
	s_waitcnt vmcnt(8)
	ds_write_b128 v2, v[146:149] offset:8192
	ds_read_b128 v[146:149], v3 offset:36864
	ds_read_b128 v[182:185], v4 offset:53248
	v_mfma_f32_16x16x32_bf16 v[34:37], v[96:99], v[150:153], v[34:37]
	v_mfma_f32_16x16x32_bf16 v[18:21], v[162:165], v[150:153], v[18:21]
	v_mfma_f32_16x16x32_bf16 v[124:127], v[116:119], v[150:153], v[124:127]
	v_mfma_f32_16x16x32_bf16 v[132:135], v[158:161], v[150:153], v[132:135]
	global_load_dwordx4 v[150:153], v218, s[36:37] offset:384
	s_waitcnt vmcnt(8)
	ds_write_b128 v2, v[166:169] offset:12288
	ds_read_b128 v[166:169], v3 offset:38912
	ds_read_b128 v[186:189], v4 offset:55296
	v_mfma_f32_16x16x32_bf16 v[38:41], v[96:99], v[154:157], v[38:41]
	v_mfma_f32_16x16x32_bf16 v[50:53], v[116:119], v[154:157], v[50:53]
	v_mfma_f32_16x16x32_bf16 v[54:57], v[158:161], v[154:157], v[54:57]
	v_mfma_f32_16x16x32_bf16 v[22:25], v[162:165], v[154:157], v[22:25]
	global_load_dwordx4 v[96:99], v5, s[4:5] offset:384
	s_waitcnt vmcnt(8)
	ds_write_b128 v2, v[88:91] offset:16384
	s_waitcnt lgkmcnt(10)
	v_mfma_f32_16x16x32_bf16 v[26:29], v[174:177], v[92:95], v[26:29]
	s_waitcnt lgkmcnt(1)
	v_mfma_f32_16x16x32_bf16 v[10:13], v[186:189], v[92:95], v[10:13]
	v_mfma_f32_16x16x32_bf16 v[88:91], v[178:181], v[92:95], v[100:103]
	v_mfma_f32_16x16x32_bf16 v[100:103], v[182:185], v[92:95], v[104:107]
	global_load_dwordx4 v[92:95], v219, s[4:5] offset:384
	s_waitcnt vmcnt(8)
	ds_write_b128 v2, v[42:45] offset:20480
	v_mfma_f32_16x16x32_bf16 v[30:33], v[174:177], v[112:115], v[30:33]
	v_mfma_f32_16x16x32_bf16 v[42:45], v[178:181], v[112:115], v[108:111]
	v_mfma_f32_16x16x32_bf16 v[14:17], v[186:189], v[112:115], v[14:17]
	v_mfma_f32_16x16x32_bf16 v[104:107], v[182:185], v[112:115], v[120:123]
	global_load_dwordx4 v[108:111], v220, s[4:5] offset:384
	s_waitcnt vmcnt(8)
	ds_write_b128 v2, v[46:49] offset:24576
	v_mfma_f32_16x16x32_bf16 v[34:37], v[174:177], v[146:149], v[34:37]
	v_mfma_f32_16x16x32_bf16 v[46:49], v[178:181], v[146:149], v[124:127]
	v_mfma_f32_16x16x32_bf16 v[18:21], v[186:189], v[146:149], v[18:21]
	v_mfma_f32_16x16x32_bf16 v[112:115], v[182:185], v[146:149], v[132:135]
	global_load_dwordx4 v[116:119], v221, s[4:5] offset:384
	s_waitcnt vmcnt(8)
	ds_write_b128 v2, v[58:61] offset:28672
	v_mfma_f32_16x16x32_bf16 v[38:41], v[174:177], v[166:169], v[38:41]
	v_mfma_f32_16x16x32_bf16 v[50:53], v[178:181], v[166:169], v[50:53]
	v_mfma_f32_16x16x32_bf16 v[54:57], v[182:185], v[166:169], v[54:57]
	v_mfma_f32_16x16x32_bf16 v[22:25], v[186:189], v[166:169], v[22:25]
	s_setprio 0
	s_waitcnt lgkmcnt(0)
	s_barrier
; template <int MODE>
; __device__ __forceinline__ void gemm_tile(const Params& P, int tm, int tn, unsigned char* smem) {
;     ...
; #pragma unroll
;         for (int i = 0; i < 4; ++i) { fa[i] = *(const bf16x8*)(sA + arow_off + i * 2048 + ch0); fb[i] = *(const bf16x8*)(sB + brow_off + i * 2048 + ch0); }
;         __builtin_amdgcn_sched_barrier(0);
;         __builtin_amdgcn_s_setprio(2);
;         if (wr_ok) *(uint4*)(nA + soff0) = ra0;
;         if (ld_ok) ra0 = *(const uint4*)(Ab + (aoff + 0u * LDA + koa));
;         ga[0] = *(const bf16x8*)(sA + arow_off + 0 * 2048 + ch1); gb[0] = *(const bf16x8*)(sB + brow_off + 0 * 2048 + ch1);
;         __builtin_amdgcn_sched_barrier(0);
; #pragma unroll
;         for (int j = 0; j < 4; ++j) acc[0][j] = __builtin_amdgcn_mfma_f32_16x16x32_bf16(fb[j], fa[0], acc[0][j], 0, 0, 0);
;         __builtin_amdgcn_sched_barrier(0);
;         if (wr_ok) *(uint4*)(nA + soff0 + 4096) = ra1;
;         if (ld_ok) ra1 = *(const uint4*)(Ab + (aoff + 32u * LDA + koa));
;         ga[1] = *(const bf16x8*)(sA + arow_off + 1 * 2048 + ch1); gb[1] = *(const bf16x8*)(sB + brow_off + 1 * 2048 + ch1);
;         __builtin_amdgcn_sched_barrier(0);
; #pragma unroll
;         for (int j = 0; j < 4; ++j) acc[1][j] = __builtin_amdgcn_mfma_f32_16x16x32_bf16(fb[j], fa[1], acc[1][j], 0, 0, 0);
;         __builtin_amdgcn_sched_barrier(0);
;         if (wr_ok) *(uint4*)(nA + soff0 + 8192) = ra2;
;         if (ld_ok) ra2 = *(const uint4*)(Ab + (aoff + 64u * LDA + koa));
;         ga[2] = *(const bf16x8*)(sA + arow_off + 2 * 2048 + ch1); gb[2] = *(const bf16x8*)(sB + brow_off + 2 * 2048 + ch1);
;         __builtin_amdgcn_sched_barrier(0);
; #pragma unroll
;         for (int j = 0; j < 4; ++j) acc[2][j] = __builtin_amdgcn_mfma_f32_16x16x32_bf16(fb[j], fa[2], acc[2][j], 0, 0, 0);
;         __builtin_amdgcn_sched_barrier(0);
;         if (wr_ok) *(uint4*)(nA + soff0 + 12288) = ra3;
;         if (ld_ok) ra3 = *(const uint4*)(Ab + (aoff + 96u * LDA + koa));
;         ga[3] = *(const bf16x8*)(sA + arow_off + 3 * 2048 + ch1); gb[3] = *(const bf16x8*)(sB + brow_off + 3 * 2048 + ch1);
;         __builtin_amdgcn_sched_barrier(0);
; #pragma unroll
;         for (int j = 0; j < 4; ++j) acc[3][j] = __builtin_amdgcn_mfma_f32_16x16x32_bf16(fb[j], fa[3], acc[3][j], 0, 0, 0);
;         __builtin_amdgcn_sched_barrier(0);
;         if (wr_ok) *(uint4*)(nB + soff0) = rb0;
	ds_read_b128 v[58:61], v6
	ds_read_b128 v[120:123], v6 offset:2048
	ds_read_b128 v[124:127], v7 offset:16384
	ds_read_b128 v[132:135], v7 offset:18432
	ds_read_b128 v[146:149], v6 offset:4096
	ds_read_b128 v[154:157], v6 offset:6144
	ds_read_b128 v[158:161], v7 offset:20480
	ds_read_b128 v[162:165], v7 offset:22528
	s_setprio 2
	global_load_dwordx4 v[166:169], v8, s[36:37] offset:512
	s_waitcnt vmcnt(8)
	ds_write_b128 v2, v[170:173] offset:32768
	ds_read_b128 v[170:173], v3
	ds_read_b128 v[174:177], v4 offset:16384
	s_waitcnt lgkmcnt(8)
	v_mfma_f32_16x16x32_bf16 v[26:29], v[124:127], v[58:61], v[26:29]
	s_waitcnt lgkmcnt(3)
	v_mfma_f32_16x16x32_bf16 v[10:13], v[162:165], v[58:61], v[10:13]
	v_mfma_f32_16x16x32_bf16 v[88:91], v[132:135], v[58:61], v[88:91]
	v_mfma_f32_16x16x32_bf16 v[100:103], v[158:161], v[58:61], v[100:103]
	global_load_dwordx4 v[58:61], v216, s[36:37] offset:512
	s_waitcnt vmcnt(8)
	ds_write_b128 v2, v[62:65] offset:36864
	ds_read_b128 v[62:65], v3 offset:2048
	ds_read_b128 v[178:181], v4 offset:18432
	v_mfma_f32_16x16x32_bf16 v[30:33], v[124:127], v[120:123], v[30:33]
	v_mfma_f32_16x16x32_bf16 v[42:45], v[132:135], v[120:123], v[42:45]
	v_mfma_f32_16x16x32_bf16 v[14:17], v[162:165], v[120:123], v[14:17]
	v_mfma_f32_16x16x32_bf16 v[104:107], v[158:161], v[120:123], v[104:107]
	global_load_dwordx4 v[120:123], v217, s[36:37] offset:512
	s_waitcnt vmcnt(8)
	ds_write_b128 v2, v[84:87] offset:40960
	ds_read_b128 v[84:87], v3 offset:4096
	ds_read_b128 v[182:185], v4 offset:20480
	v_mfma_f32_16x16x32_bf16 v[34:37], v[124:127], v[146:149], v[34:37]
	v_mfma_f32_16x16x32_bf16 v[46:49], v[132:135], v[146:149], v[46:49]
	v_mfma_f32_16x16x32_bf16 v[18:21], v[162:165], v[146:149], v[18:21]
	v_mfma_f32_16x16x32_bf16 v[112:115], v[158:161], v[146:149], v[112:115]
	global_load_dwordx4 v[146:149], v218, s[36:37] offset:512
	s_waitcnt vmcnt(8)
	ds_write_b128 v2, v[150:153] offset:45056
	ds_read_b128 v[150:153], v3 offset:6144
	ds_read_b128 v[186:189], v4 offset:22528
	v_mfma_f32_16x16x32_bf16 v[38:41], v[124:127], v[154:157], v[38:41]
	v_mfma_f32_16x16x32_bf16 v[50:53], v[132:135], v[154:157], v[50:53]
	v_mfma_f32_16x16x32_bf16 v[54:57], v[158:161], v[154:157], v[54:57]
	v_mfma_f32_16x16x32_bf16 v[22:25], v[162:165], v[154:157], v[22:25]
	global_load_dwordx4 v[124:127], v5, s[4:5] offset:512
	s_waitcnt vmcnt(8)
	ds_write_b128 v2, v[96:99] offset:49152
	s_waitcnt lgkmcnt(10)
	v_mfma_f32_16x16x32_bf16 v[26:29], v[174:177], v[170:173], v[26:29]
	s_waitcnt lgkmcnt(1)
	v_mfma_f32_16x16x32_bf16 v[10:13], v[186:189], v[170:173], v[10:13]
	v_mfma_f32_16x16x32_bf16 v[88:91], v[178:181], v[170:173], v[88:91]
	v_mfma_f32_16x16x32_bf16 v[96:99], v[182:185], v[170:173], v[100:103]
	global_load_dwordx4 v[100:103], v219, s[4:5] offset:512
	s_waitcnt vmcnt(8)
	ds_write_b128 v2, v[92:95] offset:53248
	v_mfma_f32_16x16x32_bf16 v[30:33], v[174:177], v[62:65], v[30:33]
	v_mfma_f32_16x16x32_bf16 v[42:45], v[178:181], v[62:65], v[42:45]
	v_mfma_f32_16x16x32_bf16 v[14:17], v[186:189], v[62:65], v[14:17]
	v_mfma_f32_16x16x32_bf16 v[92:95], v[182:185], v[62:65], v[104:107]
	global_load_dwordx4 v[62:65], v220, s[4:5] offset:512
	s_waitcnt vmcnt(8)
	ds_write_b128 v2, v[108:111] offset:57344
	v_mfma_f32_16x16x32_bf16 v[34:37], v[174:177], v[84:87], v[34:37]
	v_mfma_f32_16x16x32_bf16 v[46:49], v[178:181], v[84:87], v[46:49]
	v_mfma_f32_16x16x32_bf16 v[18:21], v[186:189], v[84:87], v[18:21]
	v_mfma_f32_16x16x32_bf16 v[104:107], v[182:185], v[84:87], v[112:115]
	global_load_dwordx4 v[84:87], v221, s[4:5] offset:512
	s_waitcnt vmcnt(8)
	ds_write_b128 v2, v[116:119] offset:61440
	v_mfma_f32_16x16x32_bf16 v[38:41], v[174:177], v[150:153], v[38:41]
	v_mfma_f32_16x16x32_bf16 v[50:53], v[178:181], v[150:153], v[50:53]
	v_mfma_f32_16x16x32_bf16 v[54:57], v[182:185], v[150:153], v[54:57]
	v_mfma_f32_16x16x32_bf16 v[22:25], v[186:189], v[150:153], v[22:25]
	s_setprio 0
	s_waitcnt lgkmcnt(0)
	s_barrier
	ds_read_b128 v[108:111], v6 offset:32768
	ds_read_b128 v[112:115], v6 offset:34816
	ds_read_b128 v[116:119], v7 offset:49152
	ds_read_b128 v[132:135], v7 offset:51200
	ds_read_b128 v[150:153], v6 offset:36864
	ds_read_b128 v[154:157], v6 offset:38912
	ds_read_b128 v[158:161], v7 offset:53248
	ds_read_b128 v[162:165], v7 offset:55296
	s_setprio 2
	global_load_dwordx4 v[170:173], v8, s[36:37] offset:640
	s_waitcnt vmcnt(8)
	ds_write_b128 v2, v[166:169]
	ds_read_b128 v[166:169], v3 offset:32768
	ds_read_b128 v[174:177], v4 offset:49152
	s_waitcnt lgkmcnt(8)
	v_mfma_f32_16x16x32_bf16 v[26:29], v[116:119], v[108:111], v[26:29]
	s_waitcnt lgkmcnt(3)
	v_mfma_f32_16x16x32_bf16 v[10:13], v[162:165], v[108:111], v[10:13]
	v_mfma_f32_16x16x32_bf16 v[88:91], v[132:135], v[108:111], v[88:91]
	v_mfma_f32_16x16x32_bf16 v[96:99], v[158:161], v[108:111], v[96:99]
	global_load_dwordx4 v[108:111], v216, s[36:37] offset:640
	s_waitcnt vmcnt(8)
	ds_write_b128 v2, v[58:61] offset:4096
	ds_read_b128 v[58:61], v3 offset:34816
	ds_read_b128 v[178:181], v4 offset:51200
	v_mfma_f32_16x16x32_bf16 v[30:33], v[116:119], v[112:115], v[30:33]
	v_mfma_f32_16x16x32_bf16 v[42:45], v[132:135], v[112:115], v[42:45]
	v_mfma_f32_16x16x32_bf16 v[14:17], v[162:165], v[112:115], v[14:17]
	v_mfma_f32_16x16x32_bf16 v[92:95], v[158:161], v[112:115], v[92:95]
	global_load_dwordx4 v[112:115], v217, s[36:37] offset:640
	s_waitcnt vmcnt(8)
	ds_write_b128 v2, v[120:123] offset:8192
	ds_read_b128 v[120:123], v3 offset:36864
	ds_read_b128 v[182:185], v4 offset:53248
	v_mfma_f32_16x16x32_bf16 v[34:37], v[116:119], v[150:153], v[34:37]
	v_mfma_f32_16x16x32_bf16 v[46:49], v[132:135], v[150:153], v[46:49]
	v_mfma_f32_16x16x32_bf16 v[18:21], v[162:165], v[150:153], v[18:21]
	v_mfma_f32_16x16x32_bf16 v[104:107], v[158:161], v[150:153], v[104:107]
	global_load_dwordx4 v[150:153], v218, s[36:37] offset:640
	s_waitcnt vmcnt(8)
; template <int MODE>
; __device__ __forceinline__ void gemm_tile(const Params& P, int tm, int tn, unsigned char* smem) {
;     ...
; #pragma unroll
;         for (int i = 0; i < 4; ++i) { fa[i] = *(const bf16x8*)(sA + arow_off + i * 2048 + ch0); fb[i] = *(const bf16x8*)(sB + brow_off + i * 2048 + ch0); }
;         __builtin_amdgcn_sched_barrier(0);
;         __builtin_amdgcn_s_setprio(2);
;         if (wr_ok) *(uint4*)(nA + soff0) = ra0;
;         if (ld_ok) ra0 = *(const uint4*)(Ab + (aoff + 0u * LDA + koa));
;         ga[0] = *(const bf16x8*)(sA + arow_off + 0 * 2048 + ch1); gb[0] = *(const bf16x8*)(sB + brow_off + 0 * 2048 + ch1);
;         __builtin_amdgcn_sched_barrier(0);
; #pragma unroll
;         for (int j = 0; j < 4; ++j) acc[0][j] = __builtin_amdgcn_mfma_f32_16x16x32_bf16(fb[j], fa[0], acc[0][j], 0, 0, 0);
;         __builtin_amdgcn_sched_barrier(0);
;         if (wr_ok) *(uint4*)(nA + soff0 + 4096) = ra1;
;         if (ld_ok) ra1 = *(const uint4*)(Ab + (aoff + 32u * LDA + koa));
;         ga[1] = *(const bf16x8*)(sA + arow_off + 1 * 2048 + ch1); gb[1] = *(const bf16x8*)(sB + brow_off + 1 * 2048 + ch1);
;         __builtin_amdgcn_sched_barrier(0);
; #pragma unroll
;         for (int j = 0; j < 4; ++j) acc[1][j] = __builtin_amdgcn_mfma_f32_16x16x32_bf16(fb[j], fa[1], acc[1][j], 0, 0, 0);
;         __builtin_amdgcn_sched_barrier(0);
;         if (wr_ok) *(uint4*)(nA + soff0 + 8192) = ra2;
;         if (ld_ok) ra2 = *(const uint4*)(Ab + (aoff + 64u * LDA + koa));
;         ga[2] = *(const bf16x8*)(sA + arow_off + 2 * 2048 + ch1); gb[2] = *(const bf16x8*)(sB + brow_off + 2 * 2048 + ch1);
;         __builtin_amdgcn_sched_barrier(0);
; #pragma unroll
;         for (int j = 0; j < 4; ++j) acc[2][j] = __builtin_amdgcn_mfma_f32_16x16x32_bf16(fb[j], fa[2], acc[2][j], 0, 0, 0);
;         __builtin_amdgcn_sched_barrier(0);
;         if (wr_ok) *(uint4*)(nA + soff0 + 12288) = ra3;
;         if (ld_ok) ra3 = *(const uint4*)(Ab + (aoff + 96u * LDA + koa));
;         ga[3] = *(const bf16x8*)(sA + arow_off + 3 * 2048 + ch1); gb[3] = *(const bf16x8*)(sB + brow_off + 3 * 2048 + ch1);
;         __builtin_amdgcn_sched_barrier(0);
; #pragma unroll
;         for (int j = 0; j < 4; ++j) acc[3][j] = __builtin_amdgcn_mfma_f32_16x16x32_bf16(fb[j], fa[3], acc[3][j], 0, 0, 0);
;         __builtin_amdgcn_sched_barrier(0);
;         if (wr_ok) *(uint4*)(nB + soff0) = rb0;
	ds_write_b128 v2, v[146:149] offset:12288
	ds_read_b128 v[146:149], v3 offset:38912
	ds_read_b128 v[186:189], v4 offset:55296
	v_mfma_f32_16x16x32_bf16 v[38:41], v[116:119], v[154:157], v[38:41]
	v_mfma_f32_16x16x32_bf16 v[50:53], v[132:135], v[154:157], v[50:53]
	v_mfma_f32_16x16x32_bf16 v[54:57], v[158:161], v[154:157], v[54:57]
	v_mfma_f32_16x16x32_bf16 v[22:25], v[162:165], v[154:157], v[22:25]
	global_load_dwordx4 v[116:119], v5, s[4:5] offset:640
	s_waitcnt vmcnt(8)
	ds_write_b128 v2, v[124:127] offset:16384
	s_waitcnt lgkmcnt(10)
	v_mfma_f32_16x16x32_bf16 v[26:29], v[174:177], v[166:169], v[26:29]
	s_waitcnt lgkmcnt(1)
	v_mfma_f32_16x16x32_bf16 v[10:13], v[186:189], v[166:169], v[10:13]
	v_mfma_f32_16x16x32_bf16 v[88:91], v[178:181], v[166:169], v[88:91]
	v_mfma_f32_16x16x32_bf16 v[96:99], v[182:185], v[166:169], v[96:99]
	global_load_dwordx4 v[124:127], v219, s[4:5] offset:640
	s_waitcnt vmcnt(8)
	ds_write_b128 v2, v[100:103] offset:20480
	v_mfma_f32_16x16x32_bf16 v[30:33], v[174:177], v[58:61], v[30:33]
	v_mfma_f32_16x16x32_bf16 v[42:45], v[178:181], v[58:61], v[42:45]
	v_mfma_f32_16x16x32_bf16 v[14:17], v[186:189], v[58:61], v[14:17]
	v_mfma_f32_16x16x32_bf16 v[92:95], v[182:185], v[58:61], v[92:95]
	global_load_dwordx4 v[58:61], v220, s[4:5] offset:640
	s_waitcnt vmcnt(8)
	ds_write_b128 v2, v[62:65] offset:24576
	v_mfma_f32_16x16x32_bf16 v[34:37], v[174:177], v[120:123], v[34:37]
	v_mfma_f32_16x16x32_bf16 v[46:49], v[178:181], v[120:123], v[46:49]
	v_mfma_f32_16x16x32_bf16 v[62:65], v[182:185], v[120:123], v[104:107]
	v_mfma_f32_16x16x32_bf16 v[18:21], v[186:189], v[120:123], v[18:21]
	global_load_dwordx4 v[100:103], v221, s[4:5] offset:640
	s_waitcnt vmcnt(8)
	ds_write_b128 v2, v[84:87] offset:28672
	v_mfma_f32_16x16x32_bf16 v[38:41], v[174:177], v[146:149], v[38:41]
	v_mfma_f32_16x16x32_bf16 v[50:53], v[178:181], v[146:149], v[50:53]
	v_mfma_f32_16x16x32_bf16 v[54:57], v[182:185], v[146:149], v[54:57]
	v_mfma_f32_16x16x32_bf16 v[22:25], v[186:189], v[146:149], v[22:25]
	s_setprio 0
	s_waitcnt lgkmcnt(0)
	s_barrier
	ds_read_b128 v[84:87], v6
	ds_read_b128 v[104:107], v6 offset:2048
	ds_read_b128 v[120:123], v7 offset:16384
	ds_read_b128 v[132:135], v7 offset:18432
	ds_read_b128 v[146:149], v6 offset:4096
	ds_read_b128 v[154:157], v6 offset:6144
	ds_read_b128 v[158:161], v7 offset:20480
	ds_read_b128 v[162:165], v7 offset:22528
	s_setprio 2
	global_load_dwordx4 v[166:169], v8, s[36:37] offset:768
	s_waitcnt vmcnt(8)
	ds_write_b128 v2, v[170:173] offset:32768
	ds_read_b128 v[170:173], v3
	ds_read_b128 v[174:177], v4 offset:16384
	s_waitcnt lgkmcnt(8)
	v_mfma_f32_16x16x32_bf16 v[26:29], v[120:123], v[84:87], v[26:29]
	s_waitcnt lgkmcnt(3)
	v_mfma_f32_16x16x32_bf16 v[10:13], v[162:165], v[84:87], v[10:13]
	v_mfma_f32_16x16x32_bf16 v[88:91], v[132:135], v[84:87], v[88:91]
	v_mfma_f32_16x16x32_bf16 v[96:99], v[158:161], v[84:87], v[96:99]
	global_load_dwordx4 v[84:87], v216, s[36:37] offset:768
	s_waitcnt vmcnt(8)
	ds_write_b128 v2, v[108:111] offset:36864
	ds_read_b128 v[108:111], v3 offset:2048
	ds_read_b128 v[178:181], v4 offset:18432
	v_mfma_f32_16x16x32_bf16 v[30:33], v[120:123], v[104:107], v[30:33]
	v_mfma_f32_16x16x32_bf16 v[42:45], v[132:135], v[104:107], v[42:45]
	v_mfma_f32_16x16x32_bf16 v[14:17], v[162:165], v[104:107], v[14:17]
	v_mfma_f32_16x16x32_bf16 v[92:95], v[158:161], v[104:107], v[92:95]
	global_load_dwordx4 v[104:107], v217, s[36:37] offset:768
	s_waitcnt vmcnt(8)
	ds_write_b128 v2, v[112:115] offset:40960
	ds_read_b128 v[112:115], v3 offset:4096
	ds_read_b128 v[182:185], v4 offset:20480
	v_mfma_f32_16x16x32_bf16 v[34:37], v[120:123], v[146:149], v[34:37]
	v_mfma_f32_16x16x32_bf16 v[46:49], v[132:135], v[146:149], v[46:49]
	v_mfma_f32_16x16x32_bf16 v[62:65], v[158:161], v[146:149], v[62:65]
	v_mfma_f32_16x16x32_bf16 v[18:21], v[162:165], v[146:149], v[18:21]
	global_load_dwordx4 v[146:149], v218, s[36:37] offset:768
	s_waitcnt vmcnt(8)
	ds_write_b128 v2, v[150:153] offset:45056
	ds_read_b128 v[150:153], v3 offset:6144
	ds_read_b128 v[186:189], v4 offset:22528
	v_mfma_f32_16x16x32_bf16 v[38:41], v[120:123], v[154:157], v[38:41]
	v_mfma_f32_16x16x32_bf16 v[50:53], v[132:135], v[154:157], v[50:53]
	v_mfma_f32_16x16x32_bf16 v[54:57], v[158:161], v[154:157], v[54:57]
	v_mfma_f32_16x16x32_bf16 v[22:25], v[162:165], v[154:157], v[22:25]
	global_load_dwordx4 v[120:123], v5, s[4:5] offset:768
	s_waitcnt vmcnt(8)
	ds_write_b128 v2, v[116:119] offset:49152
	s_waitcnt lgkmcnt(10)
	v_mfma_f32_16x16x32_bf16 v[26:29], v[174:177], v[170:173], v[26:29]
	s_waitcnt lgkmcnt(1)
	v_mfma_f32_16x16x32_bf16 v[10:13], v[186:189], v[170:173], v[10:13]
	v_mfma_f32_16x16x32_bf16 v[88:91], v[178:181], v[170:173], v[88:91]
	v_mfma_f32_16x16x32_bf16 v[96:99], v[182:185], v[170:173], v[96:99]
	global_load_dwordx4 v[116:119], v219, s[4:5] offset:768
	s_waitcnt vmcnt(8)
	ds_write_b128 v2, v[124:127] offset:53248
	v_mfma_f32_16x16x32_bf16 v[30:33], v[174:177], v[108:111], v[30:33]
	v_mfma_f32_16x16x32_bf16 v[42:45], v[178:181], v[108:111], v[42:45]
	v_mfma_f32_16x16x32_bf16 v[14:17], v[186:189], v[108:111], v[14:17]
	v_mfma_f32_16x16x32_bf16 v[92:95], v[182:185], v[108:111], v[92:95]
	global_load_dwordx4 v[108:111], v220, s[4:5] offset:768
	s_waitcnt vmcnt(8)
	ds_write_b128 v2, v[58:61] offset:57344
	v_mfma_f32_16x16x32_bf16 v[34:37], v[174:177], v[112:115], v[34:37]
	v_mfma_f32_16x16x32_bf16 v[46:49], v[178:181], v[112:115], v[46:49]
	v_mfma_f32_16x16x32_bf16 v[58:61], v[182:185], v[112:115], v[62:65]
	v_mfma_f32_16x16x32_bf16 v[18:21], v[186:189], v[112:115], v[18:21]
	global_load_dwordx4 v[62:65], v221, s[4:5] offset:768
	s_waitcnt vmcnt(8)
	ds_write_b128 v2, v[100:103] offset:61440
	v_mfma_f32_16x16x32_bf16 v[38:41], v[174:177], v[150:153], v[38:41]
	v_mfma_f32_16x16x32_bf16 v[50:53], v[178:181], v[150:153], v[50:53]
	v_mfma_f32_16x16x32_bf16 v[54:57], v[182:185], v[150:153], v[54:57]
	v_mfma_f32_16x16x32_bf16 v[22:25], v[186:189], v[150:153], v[22:25]
	s_setprio 0
	s_waitcnt lgkmcnt(0)
	s_barrier
; template <int MODE>
; __device__ __forceinline__ void gemm_tile(const Params& P, int tm, int tn, unsigned char* smem) {
;     ...
; #pragma unroll
;         for (int i = 0; i < 4; ++i) { fa[i] = *(const bf16x8*)(sA + arow_off + i * 2048 + ch0); fb[i] = *(const bf16x8*)(sB + brow_off + i * 2048 + ch0); }
;         __builtin_amdgcn_sched_barrier(0);
;         __builtin_amdgcn_s_setprio(2);
;         if (wr_ok) *(uint4*)(nA + soff0) = ra0;
;         if (ld_ok) ra0 = *(const uint4*)(Ab + (aoff + 0u * LDA + koa));
;         ga[0] = *(const bf16x8*)(sA + arow_off + 0 * 2048 + ch1); gb[0] = *(const bf16x8*)(sB + brow_off + 0 * 2048 + ch1);
;         __builtin_amdgcn_sched_barrier(0);
; #pragma unroll
;         for (int j = 0; j < 4; ++j) acc[0][j] = __builtin_amdgcn_mfma_f32_16x16x32_bf16(fb[j], fa[0], acc[0][j], 0, 0, 0);
;         __builtin_amdgcn_sched_barrier(0);
;         if (wr_ok) *(uint4*)(nA + soff0 + 4096) = ra1;
;         if (ld_ok) ra1 = *(const uint4*)(Ab + (aoff + 32u * LDA + koa));
;         ga[1] = *(const bf16x8*)(sA + arow_off + 1 * 2048 + ch1); gb[1] = *(const bf16x8*)(sB + brow_off + 1 * 2048 + ch1);
;         __builtin_amdgcn_sched_barrier(0);
; #pragma unroll
;         for (int j = 0; j < 4; ++j) acc[1][j] = __builtin_amdgcn_mfma_f32_16x16x32_bf16(fb[j], fa[1], acc[1][j], 0, 0, 0);
;         __builtin_amdgcn_sched_barrier(0);
;         if (wr_ok) *(uint4*)(nA + soff0 + 8192) = ra2;
;         if (ld_ok) ra2 = *(const uint4*)(Ab + (aoff + 64u * LDA + koa));
;         ga[2] = *(const bf16x8*)(sA + arow_off + 2 * 2048 + ch1); gb[2] = *(const bf16x8*)(sB + brow_off + 2 * 2048 + ch1);
;         __builtin_amdgcn_sched_barrier(0);
; #pragma unroll
;         for (int j = 0; j < 4; ++j) acc[2][j] = __builtin_amdgcn_mfma_f32_16x16x32_bf16(fb[j], fa[2], acc[2][j], 0, 0, 0);
;         __builtin_amdgcn_sched_barrier(0);
;         if (wr_ok) *(uint4*)(nA + soff0 + 12288) = ra3;
;         if (ld_ok) ra3 = *(const uint4*)(Ab + (aoff + 96u * LDA + koa));
;         ga[3] = *(const bf16x8*)(sA + arow_off + 3 * 2048 + ch1); gb[3] = *(const bf16x8*)(sB + brow_off + 3 * 2048 + ch1);
;         __builtin_amdgcn_sched_barrier(0);
; #pragma unroll
;         for (int j = 0; j < 4; ++j) acc[3][j] = __builtin_amdgcn_mfma_f32_16x16x32_bf16(fb[j], fa[3], acc[3][j], 0, 0, 0);
;         __builtin_amdgcn_sched_barrier(0);
;         if (wr_ok) *(uint4*)(nB + soff0) = rb0;
	ds_read_b128 v[100:103], v6 offset:32768
	ds_read_b128 v[112:115], v6 offset:34816
	ds_read_b128 v[124:127], v7 offset:49152
	ds_read_b128 v[132:135], v7 offset:51200
	ds_read_b128 v[150:153], v6 offset:36864
	ds_read_b128 v[154:157], v6 offset:38912
	ds_read_b128 v[158:161], v7 offset:53248
	ds_read_b128 v[162:165], v7 offset:55296
	s_setprio 2
	global_load_dwordx4 v[170:173], v8, s[36:37] offset:896
	s_waitcnt vmcnt(8)
	ds_write_b128 v2, v[166:169]
	ds_read_b128 v[166:169], v3 offset:32768
	ds_read_b128 v[174:177], v4 offset:49152
	s_waitcnt lgkmcnt(8)
	v_mfma_f32_16x16x32_bf16 v[26:29], v[124:127], v[100:103], v[26:29]
	s_waitcnt lgkmcnt(3)
	v_mfma_f32_16x16x32_bf16 v[10:13], v[162:165], v[100:103], v[10:13]
	v_mfma_f32_16x16x32_bf16 v[88:91], v[132:135], v[100:103], v[88:91]
	v_mfma_f32_16x16x32_bf16 v[96:99], v[158:161], v[100:103], v[96:99]
	global_load_dwordx4 v[100:103], v216, s[36:37] offset:896
	s_waitcnt vmcnt(8)
	ds_write_b128 v2, v[84:87] offset:4096
	ds_read_b128 v[84:87], v3 offset:34816
	ds_read_b128 v[178:181], v4 offset:51200
	v_mfma_f32_16x16x32_bf16 v[30:33], v[124:127], v[112:115], v[30:33]
	v_mfma_f32_16x16x32_bf16 v[42:45], v[132:135], v[112:115], v[42:45]
	v_mfma_f32_16x16x32_bf16 v[14:17], v[162:165], v[112:115], v[14:17]
	v_mfma_f32_16x16x32_bf16 v[92:95], v[158:161], v[112:115], v[92:95]
	global_load_dwordx4 v[112:115], v217, s[36:37] offset:896
	s_waitcnt vmcnt(8)
	ds_write_b128 v2, v[104:107] offset:8192
	ds_read_b128 v[104:107], v3 offset:36864
	ds_read_b128 v[182:185], v4 offset:53248
	v_mfma_f32_16x16x32_bf16 v[34:37], v[124:127], v[150:153], v[34:37]
	v_mfma_f32_16x16x32_bf16 v[46:49], v[132:135], v[150:153], v[46:49]
	v_mfma_f32_16x16x32_bf16 v[58:61], v[158:161], v[150:153], v[58:61]
	v_mfma_f32_16x16x32_bf16 v[18:21], v[162:165], v[150:153], v[18:21]
	global_load_dwordx4 v[150:153], v218, s[36:37] offset:896
	s_waitcnt vmcnt(8)
	ds_write_b128 v2, v[146:149] offset:12288
	ds_read_b128 v[146:149], v3 offset:38912
	ds_read_b128 v[186:189], v4 offset:55296
	v_mfma_f32_16x16x32_bf16 v[38:41], v[124:127], v[154:157], v[38:41]
	v_mfma_f32_16x16x32_bf16 v[50:53], v[132:135], v[154:157], v[50:53]
	v_mfma_f32_16x16x32_bf16 v[54:57], v[158:161], v[154:157], v[54:57]
	v_mfma_f32_16x16x32_bf16 v[22:25], v[162:165], v[154:157], v[22:25]
	global_load_dwordx4 v[124:127], v5, s[4:5] offset:896
	s_waitcnt vmcnt(8)
	ds_write_b128 v2, v[120:123] offset:16384
	s_waitcnt lgkmcnt(10)
	v_mfma_f32_16x16x32_bf16 v[26:29], v[174:177], v[166:169], v[26:29]
	s_waitcnt lgkmcnt(1)
	v_mfma_f32_16x16x32_bf16 v[10:13], v[186:189], v[166:169], v[10:13]
	v_mfma_f32_16x16x32_bf16 v[88:91], v[178:181], v[166:169], v[88:91]
	v_mfma_f32_16x16x32_bf16 v[96:99], v[182:185], v[166:169], v[96:99]
	global_load_dwordx4 v[120:123], v219, s[4:5] offset:896
	s_waitcnt vmcnt(8)
	ds_write_b128 v2, v[116:119] offset:20480
	v_mfma_f32_16x16x32_bf16 v[30:33], v[174:177], v[84:87], v[30:33]
	v_mfma_f32_16x16x32_bf16 v[42:45], v[178:181], v[84:87], v[42:45]
	v_mfma_f32_16x16x32_bf16 v[14:17], v[186:189], v[84:87], v[14:17]
	v_mfma_f32_16x16x32_bf16 v[92:95], v[182:185], v[84:87], v[92:95]
	global_load_dwordx4 v[84:87], v220, s[4:5] offset:896
	s_waitcnt vmcnt(8)
	ds_write_b128 v2, v[108:111] offset:24576
	v_mfma_f32_16x16x32_bf16 v[34:37], v[174:177], v[104:107], v[34:37]
	v_mfma_f32_16x16x32_bf16 v[46:49], v[178:181], v[104:107], v[46:49]
	v_mfma_f32_16x16x32_bf16 v[58:61], v[182:185], v[104:107], v[58:61]
	v_mfma_f32_16x16x32_bf16 v[18:21], v[186:189], v[104:107], v[18:21]
	global_load_dwordx4 v[104:107], v221, s[4:5] offset:896
	s_waitcnt vmcnt(8)
	ds_write_b128 v2, v[62:65] offset:28672
	v_mfma_f32_16x16x32_bf16 v[38:41], v[174:177], v[146:149], v[38:41]
	v_mfma_f32_16x16x32_bf16 v[50:53], v[178:181], v[146:149], v[50:53]
	v_mfma_f32_16x16x32_bf16 v[54:57], v[182:185], v[146:149], v[54:57]
	v_mfma_f32_16x16x32_bf16 v[22:25], v[186:189], v[146:149], v[22:25]
	s_setprio 0
	s_waitcnt lgkmcnt(0)
	s_barrier
	ds_read_b128 v[62:65], v6
	ds_read_b128 v[108:111], v6 offset:2048
	ds_read_b128 v[116:119], v7 offset:16384
	ds_read_b128 v[132:135], v7 offset:18432
	ds_read_b128 v[146:149], v6 offset:4096
	ds_read_b128 v[154:157], v6 offset:6144
	ds_read_b128 v[158:161], v7 offset:20480
	ds_read_b128 v[162:165], v7 offset:22528
	s_setprio 2
	global_load_dwordx4 v[166:169], v8, s[36:37] offset:1024
	s_waitcnt vmcnt(8)
	ds_write_b128 v2, v[170:173] offset:32768
	ds_read_b128 v[170:173], v3
	ds_read_b128 v[174:177], v4 offset:16384
	s_waitcnt lgkmcnt(8)
	v_mfma_f32_16x16x32_bf16 v[26:29], v[116:119], v[62:65], v[26:29]
	s_waitcnt lgkmcnt(3)
	v_mfma_f32_16x16x32_bf16 v[10:13], v[162:165], v[62:65], v[10:13]
	v_mfma_f32_16x16x32_bf16 v[88:91], v[132:135], v[62:65], v[88:91]
	v_mfma_f32_16x16x32_bf16 v[96:99], v[158:161], v[62:65], v[96:99]
	global_load_dwordx4 v[62:65], v216, s[36:37] offset:1024
	s_waitcnt vmcnt(8)
	ds_write_b128 v2, v[100:103] offset:36864
	ds_read_b128 v[100:103], v3 offset:2048
	ds_read_b128 v[178:181], v4 offset:18432
	v_mfma_f32_16x16x32_bf16 v[30:33], v[116:119], v[108:111], v[30:33]
	v_mfma_f32_16x16x32_bf16 v[42:45], v[132:135], v[108:111], v[42:45]
	v_mfma_f32_16x16x32_bf16 v[14:17], v[162:165], v[108:111], v[14:17]
	v_mfma_f32_16x16x32_bf16 v[92:95], v[158:161], v[108:111], v[92:95]
	global_load_dwordx4 v[108:111], v217, s[36:37] offset:1024
	s_waitcnt vmcnt(8)
	ds_write_b128 v2, v[112:115] offset:40960
	ds_read_b128 v[112:115], v3 offset:4096
	ds_read_b128 v[182:185], v4 offset:20480
	v_mfma_f32_16x16x32_bf16 v[34:37], v[116:119], v[146:149], v[34:37]
	v_mfma_f32_16x16x32_bf16 v[46:49], v[132:135], v[146:149], v[46:49]
	v_mfma_f32_16x16x32_bf16 v[58:61], v[158:161], v[146:149], v[58:61]
	v_mfma_f32_16x16x32_bf16 v[18:21], v[162:165], v[146:149], v[18:21]
	global_load_dwordx4 v[146:149], v218, s[36:37] offset:1024
	s_waitcnt vmcnt(8)
; template <int MODE>
; __device__ __forceinline__ void gemm_tile(const Params& P, int tm, int tn, unsigned char* smem) {
;     ...
; #pragma unroll
;         for (int i = 0; i < 4; ++i) { fa[i] = *(const bf16x8*)(sA + arow_off + i * 2048 + ch0); fb[i] = *(const bf16x8*)(sB + brow_off + i * 2048 + ch0); }
;         __builtin_amdgcn_sched_barrier(0);
;         __builtin_amdgcn_s_setprio(2);
;         if (wr_ok) *(uint4*)(nA + soff0) = ra0;
;         if (ld_ok) ra0 = *(const uint4*)(Ab + (aoff + 0u * LDA + koa));
;         ga[0] = *(const bf16x8*)(sA + arow_off + 0 * 2048 + ch1); gb[0] = *(const bf16x8*)(sB + brow_off + 0 * 2048 + ch1);
;         __builtin_amdgcn_sched_barrier(0);
; #pragma unroll
;         for (int j = 0; j < 4; ++j) acc[0][j] = __builtin_amdgcn_mfma_f32_16x16x32_bf16(fb[j], fa[0], acc[0][j], 0, 0, 0);
;         __builtin_amdgcn_sched_barrier(0);
;         if (wr_ok) *(uint4*)(nA + soff0 + 4096) = ra1;
;         if (ld_ok) ra1 = *(const uint4*)(Ab + (aoff + 32u * LDA + koa));
;         ga[1] = *(const bf16x8*)(sA + arow_off + 1 * 2048 + ch1); gb[1] = *(const bf16x8*)(sB + brow_off + 1 * 2048 + ch1);
;         __builtin_amdgcn_sched_barrier(0);
; #pragma unroll
;         for (int j = 0; j < 4; ++j) acc[1][j] = __builtin_amdgcn_mfma_f32_16x16x32_bf16(fb[j], fa[1], acc[1][j], 0, 0, 0);
;         __builtin_amdgcn_sched_barrier(0);
;         if (wr_ok) *(uint4*)(nA + soff0 + 8192) = ra2;
;         if (ld_ok) ra2 = *(const uint4*)(Ab + (aoff + 64u * LDA + koa));
;         ga[2] = *(const bf16x8*)(sA + arow_off + 2 * 2048 + ch1); gb[2] = *(const bf16x8*)(sB + brow_off + 2 * 2048 + ch1);
;         __builtin_amdgcn_sched_barrier(0);
; #pragma unroll
;         for (int j = 0; j < 4; ++j) acc[2][j] = __builtin_amdgcn_mfma_f32_16x16x32_bf16(fb[j], fa[2], acc[2][j], 0, 0, 0);
;         __builtin_amdgcn_sched_barrier(0);
;         if (wr_ok) *(uint4*)(nA + soff0 + 12288) = ra3;
;         if (ld_ok) ra3 = *(const uint4*)(Ab + (aoff + 96u * LDA + koa));
;         ga[3] = *(const bf16x8*)(sA + arow_off + 3 * 2048 + ch1); gb[3] = *(const bf16x8*)(sB + brow_off + 3 * 2048 + ch1);
;         __builtin_amdgcn_sched_barrier(0);
; #pragma unroll
;         for (int j = 0; j < 4; ++j) acc[3][j] = __builtin_amdgcn_mfma_f32_16x16x32_bf16(fb[j], fa[3], acc[3][j], 0, 0, 0);
;         __builtin_amdgcn_sched_barrier(0);
;         if (wr_ok) *(uint4*)(nB + soff0) = rb0;
	ds_write_b128 v2, v[150:153] offset:45056
	ds_read_b128 v[150:153], v3 offset:6144
	ds_read_b128 v[186:189], v4 offset:22528
	v_mfma_f32_16x16x32_bf16 v[38:41], v[116:119], v[154:157], v[38:41]
	v_mfma_f32_16x16x32_bf16 v[50:53], v[132:135], v[154:157], v[50:53]
	v_mfma_f32_16x16x32_bf16 v[54:57], v[158:161], v[154:157], v[54:57]
	v_mfma_f32_16x16x32_bf16 v[22:25], v[162:165], v[154:157], v[22:25]
	global_load_dwordx4 v[116:119], v5, s[4:5] offset:1024
	s_waitcnt vmcnt(8)
	ds_write_b128 v2, v[124:127] offset:49152
	s_waitcnt lgkmcnt(10)
	v_mfma_f32_16x16x32_bf16 v[26:29], v[174:177], v[170:173], v[26:29]
	s_waitcnt lgkmcnt(1)
	v_mfma_f32_16x16x32_bf16 v[10:13], v[186:189], v[170:173], v[10:13]
	v_mfma_f32_16x16x32_bf16 v[88:91], v[178:181], v[170:173], v[88:91]
	v_mfma_f32_16x16x32_bf16 v[96:99], v[182:185], v[170:173], v[96:99]
	global_load_dwordx4 v[124:127], v219, s[4:5] offset:1024
	s_waitcnt vmcnt(8)
	ds_write_b128 v2, v[120:123] offset:53248
	v_mfma_f32_16x16x32_bf16 v[30:33], v[174:177], v[100:103], v[30:33]
	v_mfma_f32_16x16x32_bf16 v[42:45], v[178:181], v[100:103], v[42:45]
	v_mfma_f32_16x16x32_bf16 v[14:17], v[186:189], v[100:103], v[14:17]
	v_mfma_f32_16x16x32_bf16 v[92:95], v[182:185], v[100:103], v[92:95]
	global_load_dwordx4 v[100:103], v220, s[4:5] offset:1024
	s_waitcnt vmcnt(8)
	ds_write_b128 v2, v[84:87] offset:57344
	v_mfma_f32_16x16x32_bf16 v[34:37], v[174:177], v[112:115], v[34:37]
	v_mfma_f32_16x16x32_bf16 v[46:49], v[178:181], v[112:115], v[46:49]
	v_mfma_f32_16x16x32_bf16 v[58:61], v[182:185], v[112:115], v[58:61]
	v_mfma_f32_16x16x32_bf16 v[18:21], v[186:189], v[112:115], v[18:21]
	global_load_dwordx4 v[84:87], v221, s[4:5] offset:1024
	s_waitcnt vmcnt(8)
	ds_write_b128 v2, v[104:107] offset:61440
	v_mfma_f32_16x16x32_bf16 v[38:41], v[174:177], v[150:153], v[38:41]
	v_mfma_f32_16x16x32_bf16 v[50:53], v[178:181], v[150:153], v[50:53]
	v_mfma_f32_16x16x32_bf16 v[54:57], v[182:185], v[150:153], v[54:57]
	v_mfma_f32_16x16x32_bf16 v[22:25], v[186:189], v[150:153], v[22:25]
	s_setprio 0
	s_waitcnt lgkmcnt(0)
	s_barrier
	ds_read_b128 v[104:107], v6 offset:32768
	ds_read_b128 v[112:115], v6 offset:34816
	ds_read_b128 v[120:123], v7 offset:49152
	ds_read_b128 v[132:135], v7 offset:51200
	ds_read_b128 v[150:153], v6 offset:36864
	ds_read_b128 v[154:157], v6 offset:38912
	ds_read_b128 v[158:161], v7 offset:53248
	ds_read_b128 v[162:165], v7 offset:55296
	s_setprio 2
	global_load_dwordx4 v[170:173], v8, s[36:37] offset:1152
	s_waitcnt vmcnt(8)
	ds_write_b128 v2, v[166:169]
	ds_read_b128 v[166:169], v3 offset:32768
	ds_read_b128 v[174:177], v4 offset:49152
	s_waitcnt lgkmcnt(8)
	v_mfma_f32_16x16x32_bf16 v[26:29], v[120:123], v[104:107], v[26:29]
	s_waitcnt lgkmcnt(3)
	v_mfma_f32_16x16x32_bf16 v[10:13], v[162:165], v[104:107], v[10:13]
	v_mfma_f32_16x16x32_bf16 v[88:91], v[132:135], v[104:107], v[88:91]
	v_mfma_f32_16x16x32_bf16 v[96:99], v[158:161], v[104:107], v[96:99]
	global_load_dwordx4 v[104:107], v216, s[36:37] offset:1152
	s_waitcnt vmcnt(8)
	ds_write_b128 v2, v[62:65] offset:4096
	ds_read_b128 v[62:65], v3 offset:34816
	ds_read_b128 v[178:181], v4 offset:51200
	v_mfma_f32_16x16x32_bf16 v[30:33], v[120:123], v[112:115], v[30:33]
	v_mfma_f32_16x16x32_bf16 v[42:45], v[132:135], v[112:115], v[42:45]
	v_mfma_f32_16x16x32_bf16 v[14:17], v[162:165], v[112:115], v[14:17]
	v_mfma_f32_16x16x32_bf16 v[92:95], v[158:161], v[112:115], v[92:95]
	global_load_dwordx4 v[112:115], v217, s[36:37] offset:1152
	s_waitcnt vmcnt(8)
	ds_write_b128 v2, v[108:111] offset:8192
	ds_read_b128 v[108:111], v3 offset:36864
	ds_read_b128 v[182:185], v4 offset:53248
	v_mfma_f32_16x16x32_bf16 v[34:37], v[120:123], v[150:153], v[34:37]
	v_mfma_f32_16x16x32_bf16 v[46:49], v[132:135], v[150:153], v[46:49]
	v_mfma_f32_16x16x32_bf16 v[58:61], v[158:161], v[150:153], v[58:61]
	v_mfma_f32_16x16x32_bf16 v[18:21], v[162:165], v[150:153], v[18:21]
	global_load_dwordx4 v[150:153], v218, s[36:37] offset:1152
	s_waitcnt vmcnt(8)
	ds_write_b128 v2, v[146:149] offset:12288
	ds_read_b128 v[146:149], v3 offset:38912
	ds_read_b128 v[186:189], v4 offset:55296
	v_mfma_f32_16x16x32_bf16 v[38:41], v[120:123], v[154:157], v[38:41]
	v_mfma_f32_16x16x32_bf16 v[50:53], v[132:135], v[154:157], v[50:53]
	v_mfma_f32_16x16x32_bf16 v[54:57], v[158:161], v[154:157], v[54:57]
	v_mfma_f32_16x16x32_bf16 v[22:25], v[162:165], v[154:157], v[22:25]
	global_load_dwordx4 v[120:123], v5, s[4:5] offset:1152
	s_waitcnt vmcnt(8)
	ds_write_b128 v2, v[116:119] offset:16384
	s_waitcnt lgkmcnt(10)
	v_mfma_f32_16x16x32_bf16 v[26:29], v[174:177], v[166:169], v[26:29]
	s_waitcnt lgkmcnt(1)
	v_mfma_f32_16x16x32_bf16 v[10:13], v[186:189], v[166:169], v[10:13]
	v_mfma_f32_16x16x32_bf16 v[88:91], v[178:181], v[166:169], v[88:91]
	v_mfma_f32_16x16x32_bf16 v[96:99], v[182:185], v[166:169], v[96:99]
	global_load_dwordx4 v[116:119], v219, s[4:5] offset:1152
	s_waitcnt vmcnt(8)
	ds_write_b128 v2, v[124:127] offset:20480
	v_mfma_f32_16x16x32_bf16 v[30:33], v[174:177], v[62:65], v[30:33]
	v_mfma_f32_16x16x32_bf16 v[42:45], v[178:181], v[62:65], v[42:45]
	v_mfma_f32_16x16x32_bf16 v[14:17], v[186:189], v[62:65], v[14:17]
	v_mfma_f32_16x16x32_bf16 v[92:95], v[182:185], v[62:65], v[92:95]
	global_load_dwordx4 v[62:65], v220, s[4:5] offset:1152
	s_waitcnt vmcnt(8)
	ds_write_b128 v2, v[100:103] offset:24576
	v_mfma_f32_16x16x32_bf16 v[34:37], v[174:177], v[108:111], v[34:37]
	v_mfma_f32_16x16x32_bf16 v[46:49], v[178:181], v[108:111], v[46:49]
	v_mfma_f32_16x16x32_bf16 v[58:61], v[182:185], v[108:111], v[58:61]
	v_mfma_f32_16x16x32_bf16 v[18:21], v[186:189], v[108:111], v[18:21]
	global_load_dwordx4 v[100:103], v221, s[4:5] offset:1152
	s_waitcnt vmcnt(8)
	ds_write_b128 v2, v[84:87] offset:28672
	v_mfma_f32_16x16x32_bf16 v[38:41], v[174:177], v[146:149], v[38:41]
	v_mfma_f32_16x16x32_bf16 v[50:53], v[178:181], v[146:149], v[50:53]
	v_mfma_f32_16x16x32_bf16 v[54:57], v[182:185], v[146:149], v[54:57]
	v_mfma_f32_16x16x32_bf16 v[22:25], v[186:189], v[146:149], v[22:25]
	s_setprio 0
	s_waitcnt lgkmcnt(0)
	s_barrier
; template <int MODE>
; __device__ __forceinline__ void gemm_tile(const Params& P, int tm, int tn, unsigned char* smem) {
;     ...
; #pragma unroll
;         for (int i = 0; i < 4; ++i) { fa[i] = *(const bf16x8*)(sA + arow_off + i * 2048 + ch0); fb[i] = *(const bf16x8*)(sB + brow_off + i * 2048 + ch0); }
;         __builtin_amdgcn_sched_barrier(0);
;         __builtin_amdgcn_s_setprio(2);
;         if (wr_ok) *(uint4*)(nA + soff0) = ra0;
;         if (ld_ok) ra0 = *(const uint4*)(Ab + (aoff + 0u * LDA + koa));
;         ga[0] = *(const bf16x8*)(sA + arow_off + 0 * 2048 + ch1); gb[0] = *(const bf16x8*)(sB + brow_off + 0 * 2048 + ch1);
;         __builtin_amdgcn_sched_barrier(0);
; #pragma unroll
;         for (int j = 0; j < 4; ++j) acc[0][j] = __builtin_amdgcn_mfma_f32_16x16x32_bf16(fb[j], fa[0], acc[0][j], 0, 0, 0);
;         __builtin_amdgcn_sched_barrier(0);
;         if (wr_ok) *(uint4*)(nA + soff0 + 4096) = ra1;
;         if (ld_ok) ra1 = *(const uint4*)(Ab + (aoff + 32u * LDA + koa));
;         ga[1] = *(const bf16x8*)(sA + arow_off + 1 * 2048 + ch1); gb[1] = *(const bf16x8*)(sB + brow_off + 1 * 2048 + ch1);
;         __builtin_amdgcn_sched_barrier(0);
; #pragma unroll
;         for (int j = 0; j < 4; ++j) acc[1][j] = __builtin_amdgcn_mfma_f32_16x16x32_bf16(fb[j], fa[1], acc[1][j], 0, 0, 0);
;         __builtin_amdgcn_sched_barrier(0);
;         if (wr_ok) *(uint4*)(nA + soff0 + 8192) = ra2;
;         if (ld_ok) ra2 = *(const uint4*)(Ab + (aoff + 64u * LDA + koa));
;         ga[2] = *(const bf16x8*)(sA + arow_off + 2 * 2048 + ch1); gb[2] = *(const bf16x8*)(sB + brow_off + 2 * 2048 + ch1);
;         __builtin_amdgcn_sched_barrier(0);
; #pragma unroll
;         for (int j = 0; j < 4; ++j) acc[2][j] = __builtin_amdgcn_mfma_f32_16x16x32_bf16(fb[j], fa[2], acc[2][j], 0, 0, 0);
;         __builtin_amdgcn_sched_barrier(0);
;         if (wr_ok) *(uint4*)(nA + soff0 + 12288) = ra3;
;         if (ld_ok) ra3 = *(const uint4*)(Ab + (aoff + 96u * LDA + koa));
;         ga[3] = *(const bf16x8*)(sA + arow_off + 3 * 2048 + ch1); gb[3] = *(const bf16x8*)(sB + brow_off + 3 * 2048 + ch1);
;         __builtin_amdgcn_sched_barrier(0);
; #pragma unroll
;         for (int j = 0; j < 4; ++j) acc[3][j] = __builtin_amdgcn_mfma_f32_16x16x32_bf16(fb[j], fa[3], acc[3][j], 0, 0, 0);
;         __builtin_amdgcn_sched_barrier(0);
;         if (wr_ok) *(uint4*)(nB + soff0) = rb0;
	ds_read_b128 v[84:87], v6
	ds_read_b128 v[108:111], v6 offset:2048
	ds_read_b128 v[124:127], v7 offset:16384
	ds_read_b128 v[132:135], v7 offset:18432
	ds_read_b128 v[146:149], v6 offset:4096
	ds_read_b128 v[154:157], v6 offset:6144
	ds_read_b128 v[158:161], v7 offset:20480
	ds_read_b128 v[162:165], v7 offset:22528
	s_setprio 2
	global_load_dwordx4 v[166:169], v8, s[36:37] offset:1280
	s_waitcnt vmcnt(8)
	ds_write_b128 v2, v[170:173] offset:32768
	ds_read_b128 v[170:173], v3
	ds_read_b128 v[174:177], v4 offset:16384
	s_waitcnt lgkmcnt(8)
	v_mfma_f32_16x16x32_bf16 v[26:29], v[124:127], v[84:87], v[26:29]
	s_waitcnt lgkmcnt(3)
	v_mfma_f32_16x16x32_bf16 v[10:13], v[162:165], v[84:87], v[10:13]
	v_mfma_f32_16x16x32_bf16 v[88:91], v[132:135], v[84:87], v[88:91]
	v_mfma_f32_16x16x32_bf16 v[96:99], v[158:161], v[84:87], v[96:99]
	global_load_dwordx4 v[84:87], v216, s[36:37] offset:1280
	s_waitcnt vmcnt(8)
	ds_write_b128 v2, v[104:107] offset:36864
	ds_read_b128 v[104:107], v3 offset:2048
	ds_read_b128 v[178:181], v4 offset:18432
	v_mfma_f32_16x16x32_bf16 v[30:33], v[124:127], v[108:111], v[30:33]
	v_mfma_f32_16x16x32_bf16 v[42:45], v[132:135], v[108:111], v[42:45]
	v_mfma_f32_16x16x32_bf16 v[14:17], v[162:165], v[108:111], v[14:17]
	v_mfma_f32_16x16x32_bf16 v[92:95], v[158:161], v[108:111], v[92:95]
	global_load_dwordx4 v[108:111], v217, s[36:37] offset:1280
	s_waitcnt vmcnt(8)
	ds_write_b128 v2, v[112:115] offset:40960
	ds_read_b128 v[112:115], v3 offset:4096
	ds_read_b128 v[182:185], v4 offset:20480
	v_mfma_f32_16x16x32_bf16 v[34:37], v[124:127], v[146:149], v[34:37]
	v_mfma_f32_16x16x32_bf16 v[46:49], v[132:135], v[146:149], v[46:49]
	v_mfma_f32_16x16x32_bf16 v[58:61], v[158:161], v[146:149], v[58:61]
	v_mfma_f32_16x16x32_bf16 v[18:21], v[162:165], v[146:149], v[18:21]
	global_load_dwordx4 v[146:149], v218, s[36:37] offset:1280
	s_waitcnt vmcnt(8)
	ds_write_b128 v2, v[150:153] offset:45056
	ds_read_b128 v[150:153], v3 offset:6144
	ds_read_b128 v[186:189], v4 offset:22528
	v_mfma_f32_16x16x32_bf16 v[38:41], v[124:127], v[154:157], v[38:41]
	v_mfma_f32_16x16x32_bf16 v[50:53], v[132:135], v[154:157], v[50:53]
	v_mfma_f32_16x16x32_bf16 v[54:57], v[158:161], v[154:157], v[54:57]
	v_mfma_f32_16x16x32_bf16 v[22:25], v[162:165], v[154:157], v[22:25]
	global_load_dwordx4 v[124:127], v5, s[4:5] offset:1280
	s_waitcnt vmcnt(8)
	ds_write_b128 v2, v[120:123] offset:49152
	s_waitcnt lgkmcnt(10)
	v_mfma_f32_16x16x32_bf16 v[26:29], v[174:177], v[170:173], v[26:29]
	s_waitcnt lgkmcnt(1)
	v_mfma_f32_16x16x32_bf16 v[10:13], v[186:189], v[170:173], v[10:13]
	v_mfma_f32_16x16x32_bf16 v[88:91], v[178:181], v[170:173], v[88:91]
	v_mfma_f32_16x16x32_bf16 v[96:99], v[182:185], v[170:173], v[96:99]
	global_load_dwordx4 v[120:123], v219, s[4:5] offset:1280
	s_waitcnt vmcnt(8)
	ds_write_b128 v2, v[116:119] offset:53248
	v_mfma_f32_16x16x32_bf16 v[30:33], v[174:177], v[104:107], v[30:33]
	v_mfma_f32_16x16x32_bf16 v[42:45], v[178:181], v[104:107], v[42:45]
	v_mfma_f32_16x16x32_bf16 v[14:17], v[186:189], v[104:107], v[14:17]
	v_mfma_f32_16x16x32_bf16 v[92:95], v[182:185], v[104:107], v[92:95]
	global_load_dwordx4 v[104:107], v220, s[4:5] offset:1280
	s_waitcnt vmcnt(8)
	ds_write_b128 v2, v[62:65] offset:57344
	v_mfma_f32_16x16x32_bf16 v[34:37], v[174:177], v[112:115], v[34:37]
	v_mfma_f32_16x16x32_bf16 v[46:49], v[178:181], v[112:115], v[46:49]
	v_mfma_f32_16x16x32_bf16 v[58:61], v[182:185], v[112:115], v[58:61]
	v_mfma_f32_16x16x32_bf16 v[18:21], v[186:189], v[112:115], v[18:21]
	global_load_dwordx4 v[62:65], v221, s[4:5] offset:1280
	s_waitcnt vmcnt(8)
	ds_write_b128 v2, v[100:103] offset:61440
	v_mfma_f32_16x16x32_bf16 v[38:41], v[174:177], v[150:153], v[38:41]
	v_mfma_f32_16x16x32_bf16 v[50:53], v[178:181], v[150:153], v[50:53]
	v_mfma_f32_16x16x32_bf16 v[54:57], v[182:185], v[150:153], v[54:57]
	v_mfma_f32_16x16x32_bf16 v[22:25], v[186:189], v[150:153], v[22:25]
	s_setprio 0
	s_waitcnt lgkmcnt(0)
	s_barrier
	ds_read_b128 v[100:103], v6 offset:32768
	ds_read_b128 v[112:115], v6 offset:34816
	ds_read_b128 v[116:119], v7 offset:49152
	ds_read_b128 v[132:135], v7 offset:51200
	ds_read_b128 v[150:153], v6 offset:36864
	ds_read_b128 v[154:157], v6 offset:38912
	ds_read_b128 v[158:161], v7 offset:53248
	ds_read_b128 v[162:165], v7 offset:55296
	s_setprio 2
	global_load_dwordx4 v[170:173], v8, s[36:37] offset:1408
	s_waitcnt vmcnt(8)
	ds_write_b128 v2, v[166:169]
	ds_read_b128 v[166:169], v3 offset:32768
	ds_read_b128 v[174:177], v4 offset:49152
	s_waitcnt lgkmcnt(8)
	v_mfma_f32_16x16x32_bf16 v[26:29], v[116:119], v[100:103], v[26:29]
	s_waitcnt lgkmcnt(3)
	v_mfma_f32_16x16x32_bf16 v[10:13], v[162:165], v[100:103], v[10:13]
	v_mfma_f32_16x16x32_bf16 v[88:91], v[132:135], v[100:103], v[88:91]
	v_mfma_f32_16x16x32_bf16 v[96:99], v[158:161], v[100:103], v[96:99]
	global_load_dwordx4 v[100:103], v216, s[36:37] offset:1408
	s_waitcnt vmcnt(8)
	ds_write_b128 v2, v[84:87] offset:4096
	ds_read_b128 v[84:87], v3 offset:34816
	ds_read_b128 v[178:181], v4 offset:51200
	v_mfma_f32_16x16x32_bf16 v[30:33], v[116:119], v[112:115], v[30:33]
	v_mfma_f32_16x16x32_bf16 v[42:45], v[132:135], v[112:115], v[42:45]
	v_mfma_f32_16x16x32_bf16 v[14:17], v[162:165], v[112:115], v[14:17]
	v_mfma_f32_16x16x32_bf16 v[92:95], v[158:161], v[112:115], v[92:95]
	global_load_dwordx4 v[112:115], v217, s[36:37] offset:1408
	s_waitcnt vmcnt(8)
	ds_write_b128 v2, v[108:111] offset:8192
	ds_read_b128 v[108:111], v3 offset:36864
	ds_read_b128 v[182:185], v4 offset:53248
	v_mfma_f32_16x16x32_bf16 v[34:37], v[116:119], v[150:153], v[34:37]
	v_mfma_f32_16x16x32_bf16 v[46:49], v[132:135], v[150:153], v[46:49]
	v_mfma_f32_16x16x32_bf16 v[58:61], v[158:161], v[150:153], v[58:61]
	v_mfma_f32_16x16x32_bf16 v[18:21], v[162:165], v[150:153], v[18:21]
	global_load_dwordx4 v[150:153], v218, s[36:37] offset:1408
	s_waitcnt vmcnt(8)
; template <int MODE>
; __device__ __forceinline__ void gemm_tile(const Params& P, int tm, int tn, unsigned char* smem) {
;     ...
; #pragma unroll
;         for (int i = 0; i < 4; ++i) { fa[i] = *(const bf16x8*)(sA + arow_off + i * 2048 + ch0); fb[i] = *(const bf16x8*)(sB + brow_off + i * 2048 + ch0); }
;         __builtin_amdgcn_sched_barrier(0);
;         __builtin_amdgcn_s_setprio(2);
;         if (wr_ok) *(uint4*)(nA + soff0) = ra0;
;         if (ld_ok) ra0 = *(const uint4*)(Ab + (aoff + 0u * LDA + koa));
;         ga[0] = *(const bf16x8*)(sA + arow_off + 0 * 2048 + ch1); gb[0] = *(const bf16x8*)(sB + brow_off + 0 * 2048 + ch1);
;         __builtin_amdgcn_sched_barrier(0);
; #pragma unroll
;         for (int j = 0; j < 4; ++j) acc[0][j] = __builtin_amdgcn_mfma_f32_16x16x32_bf16(fb[j], fa[0], acc[0][j], 0, 0, 0);
;         __builtin_amdgcn_sched_barrier(0);
;         if (wr_ok) *(uint4*)(nA + soff0 + 4096) = ra1;
;         if (ld_ok) ra1 = *(const uint4*)(Ab + (aoff + 32u * LDA + koa));
;         ga[1] = *(const bf16x8*)(sA + arow_off + 1 * 2048 + ch1); gb[1] = *(const bf16x8*)(sB + brow_off + 1 * 2048 + ch1);
;         __builtin_amdgcn_sched_barrier(0);
; #pragma unroll
;         for (int j = 0; j < 4; ++j) acc[1][j] = __builtin_amdgcn_mfma_f32_16x16x32_bf16(fb[j], fa[1], acc[1][j], 0, 0, 0);
;         __builtin_amdgcn_sched_barrier(0);
;         if (wr_ok) *(uint4*)(nA + soff0 + 8192) = ra2;
;         if (ld_ok) ra2 = *(const uint4*)(Ab + (aoff + 64u * LDA + koa));
;         ga[2] = *(const bf16x8*)(sA + arow_off + 2 * 2048 + ch1); gb[2] = *(const bf16x8*)(sB + brow_off + 2 * 2048 + ch1);
;         __builtin_amdgcn_sched_barrier(0);
; #pragma unroll
;         for (int j = 0; j < 4; ++j) acc[2][j] = __builtin_amdgcn_mfma_f32_16x16x32_bf16(fb[j], fa[2], acc[2][j], 0, 0, 0);
;         __builtin_amdgcn_sched_barrier(0);
;         if (wr_ok) *(uint4*)(nA + soff0 + 12288) = ra3;
;         if (ld_ok) ra3 = *(const uint4*)(Ab + (aoff + 96u * LDA + koa));
;         ga[3] = *(const bf16x8*)(sA + arow_off + 3 * 2048 + ch1); gb[3] = *(const bf16x8*)(sB + brow_off + 3 * 2048 + ch1);
;         __builtin_amdgcn_sched_barrier(0);
; #pragma unroll
;         for (int j = 0; j < 4; ++j) acc[3][j] = __builtin_amdgcn_mfma_f32_16x16x32_bf16(fb[j], fa[3], acc[3][j], 0, 0, 0);
;         __builtin_amdgcn_sched_barrier(0);
;         if (wr_ok) *(uint4*)(nB + soff0) = rb0;
	ds_write_b128 v2, v[146:149] offset:12288
	ds_read_b128 v[146:149], v3 offset:38912
	ds_read_b128 v[186:189], v4 offset:55296
	v_mfma_f32_16x16x32_bf16 v[38:41], v[116:119], v[154:157], v[38:41]
	v_mfma_f32_16x16x32_bf16 v[50:53], v[132:135], v[154:157], v[50:53]
	v_mfma_f32_16x16x32_bf16 v[54:57], v[158:161], v[154:157], v[54:57]
	v_mfma_f32_16x16x32_bf16 v[22:25], v[162:165], v[154:157], v[22:25]
	global_load_dwordx4 v[116:119], v5, s[4:5] offset:1408
	s_waitcnt vmcnt(8)
	ds_write_b128 v2, v[124:127] offset:16384
	s_waitcnt lgkmcnt(10)
	v_mfma_f32_16x16x32_bf16 v[26:29], v[174:177], v[166:169], v[26:29]
	s_waitcnt lgkmcnt(1)
	v_mfma_f32_16x16x32_bf16 v[10:13], v[186:189], v[166:169], v[10:13]
	v_mfma_f32_16x16x32_bf16 v[88:91], v[178:181], v[166:169], v[88:91]
	v_mfma_f32_16x16x32_bf16 v[96:99], v[182:185], v[166:169], v[96:99]
	global_load_dwordx4 v[124:127], v219, s[4:5] offset:1408
	s_waitcnt vmcnt(8)
	ds_write_b128 v2, v[120:123] offset:20480
	v_mfma_f32_16x16x32_bf16 v[30:33], v[174:177], v[84:87], v[30:33]
	v_mfma_f32_16x16x32_bf16 v[42:45], v[178:181], v[84:87], v[42:45]
	v_mfma_f32_16x16x32_bf16 v[14:17], v[186:189], v[84:87], v[14:17]
	v_mfma_f32_16x16x32_bf16 v[92:95], v[182:185], v[84:87], v[92:95]
	global_load_dwordx4 v[84:87], v220, s[4:5] offset:1408
	s_waitcnt vmcnt(8)
	ds_write_b128 v2, v[104:107] offset:24576
	v_mfma_f32_16x16x32_bf16 v[34:37], v[174:177], v[108:111], v[34:37]
	v_mfma_f32_16x16x32_bf16 v[46:49], v[178:181], v[108:111], v[46:49]
	v_mfma_f32_16x16x32_bf16 v[58:61], v[182:185], v[108:111], v[58:61]
	v_mfma_f32_16x16x32_bf16 v[18:21], v[186:189], v[108:111], v[18:21]
	global_load_dwordx4 v[104:107], v221, s[4:5] offset:1408
	s_waitcnt vmcnt(8)
	ds_write_b128 v2, v[62:65] offset:28672
	v_mfma_f32_16x16x32_bf16 v[38:41], v[174:177], v[146:149], v[38:41]
	v_mfma_f32_16x16x32_bf16 v[50:53], v[178:181], v[146:149], v[50:53]
	v_mfma_f32_16x16x32_bf16 v[54:57], v[182:185], v[146:149], v[54:57]
	v_mfma_f32_16x16x32_bf16 v[22:25], v[186:189], v[146:149], v[22:25]
	s_setprio 0
	s_waitcnt lgkmcnt(0)
	s_barrier
	ds_read_b128 v[62:65], v6
	ds_read_b128 v[108:111], v6 offset:2048
	ds_read_b128 v[120:123], v7 offset:16384
	ds_read_b128 v[132:135], v7 offset:18432
	ds_read_b128 v[146:149], v6 offset:4096
	ds_read_b128 v[154:157], v6 offset:6144
	ds_read_b128 v[158:161], v7 offset:20480
	ds_read_b128 v[162:165], v7 offset:22528
	s_setprio 2
	global_load_dwordx4 v[166:169], v8, s[36:37] offset:1536
	s_waitcnt vmcnt(8)
	ds_write_b128 v2, v[170:173] offset:32768
	ds_read_b128 v[170:173], v3
	ds_read_b128 v[174:177], v4 offset:16384
	s_waitcnt lgkmcnt(8)
	v_mfma_f32_16x16x32_bf16 v[26:29], v[120:123], v[62:65], v[26:29]
	s_waitcnt lgkmcnt(3)
	v_mfma_f32_16x16x32_bf16 v[10:13], v[162:165], v[62:65], v[10:13]
	v_mfma_f32_16x16x32_bf16 v[88:91], v[132:135], v[62:65], v[88:91]
	v_mfma_f32_16x16x32_bf16 v[96:99], v[158:161], v[62:65], v[96:99]
	global_load_dwordx4 v[62:65], v216, s[36:37] offset:1536
	s_waitcnt vmcnt(8)
	ds_write_b128 v2, v[100:103] offset:36864
	ds_read_b128 v[100:103], v3 offset:2048
	ds_read_b128 v[178:181], v4 offset:18432
	v_mfma_f32_16x16x32_bf16 v[30:33], v[120:123], v[108:111], v[30:33]
	v_mfma_f32_16x16x32_bf16 v[42:45], v[132:135], v[108:111], v[42:45]
	v_mfma_f32_16x16x32_bf16 v[14:17], v[162:165], v[108:111], v[14:17]
	v_mfma_f32_16x16x32_bf16 v[92:95], v[158:161], v[108:111], v[92:95]
	global_load_dwordx4 v[108:111], v217, s[36:37] offset:1536
	s_waitcnt vmcnt(8)
	ds_write_b128 v2, v[112:115] offset:40960
	ds_read_b128 v[112:115], v3 offset:4096
	ds_read_b128 v[182:185], v4 offset:20480
	v_mfma_f32_16x16x32_bf16 v[34:37], v[120:123], v[146:149], v[34:37]
	v_mfma_f32_16x16x32_bf16 v[46:49], v[132:135], v[146:149], v[46:49]
	v_mfma_f32_16x16x32_bf16 v[58:61], v[158:161], v[146:149], v[58:61]
	v_mfma_f32_16x16x32_bf16 v[18:21], v[162:165], v[146:149], v[18:21]
	global_load_dwordx4 v[146:149], v218, s[36:37] offset:1536
	s_waitcnt vmcnt(8)
	ds_write_b128 v2, v[150:153] offset:45056
	ds_read_b128 v[150:153], v3 offset:6144
	ds_read_b128 v[186:189], v4 offset:22528
	v_mfma_f32_16x16x32_bf16 v[38:41], v[120:123], v[154:157], v[38:41]
	v_mfma_f32_16x16x32_bf16 v[50:53], v[132:135], v[154:157], v[50:53]
	v_mfma_f32_16x16x32_bf16 v[54:57], v[158:161], v[154:157], v[54:57]
	v_mfma_f32_16x16x32_bf16 v[22:25], v[162:165], v[154:157], v[22:25]
	global_load_dwordx4 v[120:123], v5, s[4:5] offset:1536
	s_waitcnt vmcnt(8)
	ds_write_b128 v2, v[116:119] offset:49152
	s_waitcnt lgkmcnt(10)
	v_mfma_f32_16x16x32_bf16 v[26:29], v[174:177], v[170:173], v[26:29]
	s_waitcnt lgkmcnt(1)
	v_mfma_f32_16x16x32_bf16 v[10:13], v[186:189], v[170:173], v[10:13]
	v_mfma_f32_16x16x32_bf16 v[88:91], v[178:181], v[170:173], v[88:91]
	v_mfma_f32_16x16x32_bf16 v[96:99], v[182:185], v[170:173], v[96:99]
	global_load_dwordx4 v[116:119], v219, s[4:5] offset:1536
	s_waitcnt vmcnt(8)
	ds_write_b128 v2, v[124:127] offset:53248
	v_mfma_f32_16x16x32_bf16 v[30:33], v[174:177], v[100:103], v[30:33]
	v_mfma_f32_16x16x32_bf16 v[42:45], v[178:181], v[100:103], v[42:45]
	v_mfma_f32_16x16x32_bf16 v[14:17], v[186:189], v[100:103], v[14:17]
	v_mfma_f32_16x16x32_bf16 v[92:95], v[182:185], v[100:103], v[92:95]
	global_load_dwordx4 v[100:103], v220, s[4:5] offset:1536
	s_waitcnt vmcnt(8)
	ds_write_b128 v2, v[84:87] offset:57344
	v_mfma_f32_16x16x32_bf16 v[34:37], v[174:177], v[112:115], v[34:37]
	v_mfma_f32_16x16x32_bf16 v[46:49], v[178:181], v[112:115], v[46:49]
	v_mfma_f32_16x16x32_bf16 v[58:61], v[182:185], v[112:115], v[58:61]
	v_mfma_f32_16x16x32_bf16 v[18:21], v[186:189], v[112:115], v[18:21]
	global_load_dwordx4 v[84:87], v221, s[4:5] offset:1536
	s_waitcnt vmcnt(8)
	ds_write_b128 v2, v[104:107] offset:61440
	v_mfma_f32_16x16x32_bf16 v[38:41], v[174:177], v[150:153], v[38:41]
	v_mfma_f32_16x16x32_bf16 v[50:53], v[178:181], v[150:153], v[50:53]
	v_mfma_f32_16x16x32_bf16 v[54:57], v[182:185], v[150:153], v[54:57]
	v_mfma_f32_16x16x32_bf16 v[22:25], v[186:189], v[150:153], v[22:25]
	s_setprio 0
	s_waitcnt lgkmcnt(0)
	s_barrier
; template <int MODE>
; __device__ __forceinline__ void gemm_tile(const Params& P, int tm, int tn, unsigned char* smem) {
;     ...
; #pragma unroll
;         for (int i = 0; i < 4; ++i) { fa[i] = *(const bf16x8*)(sA + arow_off + i * 2048 + ch0); fb[i] = *(const bf16x8*)(sB + brow_off + i * 2048 + ch0); }
;         __builtin_amdgcn_sched_barrier(0);
;         __builtin_amdgcn_s_setprio(2);
;         if (wr_ok) *(uint4*)(nA + soff0) = ra0;
;         if (ld_ok) ra0 = *(const uint4*)(Ab + (aoff + 0u * LDA + koa));
;         ga[0] = *(const bf16x8*)(sA + arow_off + 0 * 2048 + ch1); gb[0] = *(const bf16x8*)(sB + brow_off + 0 * 2048 + ch1);
;         __builtin_amdgcn_sched_barrier(0);
; #pragma unroll
;         for (int j = 0; j < 4; ++j) acc[0][j] = __builtin_amdgcn_mfma_f32_16x16x32_bf16(fb[j], fa[0], acc[0][j], 0, 0, 0);
;         __builtin_amdgcn_sched_barrier(0);
;         if (wr_ok) *(uint4*)(nA + soff0 + 4096) = ra1;
;         if (ld_ok) ra1 = *(const uint4*)(Ab + (aoff + 32u * LDA + koa));
;         ga[1] = *(const bf16x8*)(sA + arow_off + 1 * 2048 + ch1); gb[1] = *(const bf16x8*)(sB + brow_off + 1 * 2048 + ch1);
;         __builtin_amdgcn_sched_barrier(0);
; #pragma unroll
;         for (int j = 0; j < 4; ++j) acc[1][j] = __builtin_amdgcn_mfma_f32_16x16x32_bf16(fb[j], fa[1], acc[1][j], 0, 0, 0);
;         __builtin_amdgcn_sched_barrier(0);
;         if (wr_ok) *(uint4*)(nA + soff0 + 8192) = ra2;
;         if (ld_ok) ra2 = *(const uint4*)(Ab + (aoff + 64u * LDA + koa));
;         ga[2] = *(const bf16x8*)(sA + arow_off + 2 * 2048 + ch1); gb[2] = *(const bf16x8*)(sB + brow_off + 2 * 2048 + ch1);
;         __builtin_amdgcn_sched_barrier(0);
; #pragma unroll
;         for (int j = 0; j < 4; ++j) acc[2][j] = __builtin_amdgcn_mfma_f32_16x16x32_bf16(fb[j], fa[2], acc[2][j], 0, 0, 0);
;         __builtin_amdgcn_sched_barrier(0);
;         if (wr_ok) *(uint4*)(nA + soff0 + 12288) = ra3;
;         if (ld_ok) ra3 = *(const uint4*)(Ab + (aoff + 96u * LDA + koa));
;         ga[3] = *(const bf16x8*)(sA + arow_off + 3 * 2048 + ch1); gb[3] = *(const bf16x8*)(sB + brow_off + 3 * 2048 + ch1);
;         __builtin_amdgcn_sched_barrier(0);
; #pragma unroll
;         for (int j = 0; j < 4; ++j) acc[3][j] = __builtin_amdgcn_mfma_f32_16x16x32_bf16(fb[j], fa[3], acc[3][j], 0, 0, 0);
;         __builtin_amdgcn_sched_barrier(0);
;         if (wr_ok) *(uint4*)(nB + soff0) = rb0;
	ds_read_b128 v[104:107], v6 offset:32768
	ds_read_b128 v[112:115], v6 offset:34816
	ds_read_b128 v[124:127], v7 offset:49152
	ds_read_b128 v[132:135], v7 offset:51200
	ds_read_b128 v[150:153], v6 offset:36864
	ds_read_b128 v[154:157], v6 offset:38912
	ds_read_b128 v[158:161], v7 offset:53248
	ds_read_b128 v[162:165], v7 offset:55296
	s_setprio 2
	global_load_dwordx4 v[170:173], v8, s[36:37] offset:1664
	s_waitcnt vmcnt(8)
	ds_write_b128 v2, v[166:169]
	ds_read_b128 v[166:169], v3 offset:32768
	ds_read_b128 v[174:177], v4 offset:49152
	s_waitcnt lgkmcnt(8)
	v_mfma_f32_16x16x32_bf16 v[26:29], v[124:127], v[104:107], v[26:29]
	s_waitcnt lgkmcnt(3)
	v_mfma_f32_16x16x32_bf16 v[10:13], v[162:165], v[104:107], v[10:13]
	v_mfma_f32_16x16x32_bf16 v[88:91], v[132:135], v[104:107], v[88:91]
	v_mfma_f32_16x16x32_bf16 v[96:99], v[158:161], v[104:107], v[96:99]
	global_load_dwordx4 v[104:107], v216, s[36:37] offset:1664
	s_waitcnt vmcnt(8)
	ds_write_b128 v2, v[62:65] offset:4096
	ds_read_b128 v[62:65], v3 offset:34816
	ds_read_b128 v[178:181], v4 offset:51200
	v_mfma_f32_16x16x32_bf16 v[30:33], v[124:127], v[112:115], v[30:33]
	v_mfma_f32_16x16x32_bf16 v[42:45], v[132:135], v[112:115], v[42:45]
	v_mfma_f32_16x16x32_bf16 v[14:17], v[162:165], v[112:115], v[14:17]
	v_mfma_f32_16x16x32_bf16 v[92:95], v[158:161], v[112:115], v[92:95]
	global_load_dwordx4 v[112:115], v217, s[36:37] offset:1664
	s_waitcnt vmcnt(8)
	ds_write_b128 v2, v[108:111] offset:8192
	ds_read_b128 v[108:111], v3 offset:36864
	ds_read_b128 v[182:185], v4 offset:53248
	v_mfma_f32_16x16x32_bf16 v[34:37], v[124:127], v[150:153], v[34:37]
	v_mfma_f32_16x16x32_bf16 v[46:49], v[132:135], v[150:153], v[46:49]
	v_mfma_f32_16x16x32_bf16 v[58:61], v[158:161], v[150:153], v[58:61]
	v_mfma_f32_16x16x32_bf16 v[18:21], v[162:165], v[150:153], v[18:21]
	global_load_dwordx4 v[150:153], v218, s[36:37] offset:1664
	s_waitcnt vmcnt(8)
	ds_write_b128 v2, v[146:149] offset:12288
	ds_read_b128 v[146:149], v3 offset:38912
	ds_read_b128 v[186:189], v4 offset:55296
	v_mfma_f32_16x16x32_bf16 v[38:41], v[124:127], v[154:157], v[38:41]
	v_mfma_f32_16x16x32_bf16 v[50:53], v[132:135], v[154:157], v[50:53]
	v_mfma_f32_16x16x32_bf16 v[54:57], v[158:161], v[154:157], v[54:57]
	v_mfma_f32_16x16x32_bf16 v[22:25], v[162:165], v[154:157], v[22:25]
	global_load_dwordx4 v[124:127], v5, s[4:5] offset:1664
	s_waitcnt vmcnt(8)
	ds_write_b128 v2, v[120:123] offset:16384
	s_waitcnt lgkmcnt(10)
	v_mfma_f32_16x16x32_bf16 v[26:29], v[174:177], v[166:169], v[26:29]
	s_waitcnt lgkmcnt(1)
	v_mfma_f32_16x16x32_bf16 v[10:13], v[186:189], v[166:169], v[10:13]
	v_mfma_f32_16x16x32_bf16 v[88:91], v[178:181], v[166:169], v[88:91]
	v_mfma_f32_16x16x32_bf16 v[96:99], v[182:185], v[166:169], v[96:99]
	global_load_dwordx4 v[120:123], v219, s[4:5] offset:1664
	s_waitcnt vmcnt(8)
	ds_write_b128 v2, v[116:119] offset:20480
	v_mfma_f32_16x16x32_bf16 v[30:33], v[174:177], v[62:65], v[30:33]
	v_mfma_f32_16x16x32_bf16 v[42:45], v[178:181], v[62:65], v[42:45]
	v_mfma_f32_16x16x32_bf16 v[14:17], v[186:189], v[62:65], v[14:17]
	v_mfma_f32_16x16x32_bf16 v[92:95], v[182:185], v[62:65], v[92:95]
	global_load_dwordx4 v[62:65], v220, s[4:5] offset:1664
	s_waitcnt vmcnt(8)
	ds_write_b128 v2, v[100:103] offset:24576
	v_mfma_f32_16x16x32_bf16 v[34:37], v[174:177], v[108:111], v[34:37]
	v_mfma_f32_16x16x32_bf16 v[46:49], v[178:181], v[108:111], v[46:49]
	v_mfma_f32_16x16x32_bf16 v[58:61], v[182:185], v[108:111], v[58:61]
	v_mfma_f32_16x16x32_bf16 v[18:21], v[186:189], v[108:111], v[18:21]
	global_load_dwordx4 v[100:103], v221, s[4:5] offset:1664
	s_waitcnt vmcnt(8)
	ds_write_b128 v2, v[84:87] offset:28672
	v_mfma_f32_16x16x32_bf16 v[38:41], v[174:177], v[146:149], v[38:41]
	v_mfma_f32_16x16x32_bf16 v[50:53], v[178:181], v[146:149], v[50:53]
	v_mfma_f32_16x16x32_bf16 v[54:57], v[182:185], v[146:149], v[54:57]
	v_mfma_f32_16x16x32_bf16 v[22:25], v[186:189], v[146:149], v[22:25]
	s_setprio 0
	s_waitcnt lgkmcnt(0)
	s_barrier
	ds_read_b128 v[84:87], v6
	ds_read_b128 v[108:111], v6 offset:2048
	ds_read_b128 v[116:119], v7 offset:16384
	ds_read_b128 v[132:135], v7 offset:18432
	ds_read_b128 v[146:149], v6 offset:4096
	ds_read_b128 v[154:157], v6 offset:6144
	ds_read_b128 v[158:161], v7 offset:20480
	ds_read_b128 v[162:165], v7 offset:22528
	s_setprio 2
	global_load_dwordx4 v[166:169], v8, s[36:37] offset:1792
	s_waitcnt vmcnt(8)
	ds_write_b128 v2, v[170:173] offset:32768
	ds_read_b128 v[170:173], v3
	ds_read_b128 v[174:177], v4 offset:16384
	s_waitcnt lgkmcnt(8)
	v_mfma_f32_16x16x32_bf16 v[26:29], v[116:119], v[84:87], v[26:29]
	s_waitcnt lgkmcnt(3)
	v_mfma_f32_16x16x32_bf16 v[10:13], v[162:165], v[84:87], v[10:13]
	v_mfma_f32_16x16x32_bf16 v[88:91], v[132:135], v[84:87], v[88:91]
	v_mfma_f32_16x16x32_bf16 v[96:99], v[158:161], v[84:87], v[96:99]
	global_load_dwordx4 v[84:87], v216, s[36:37] offset:1792
	s_waitcnt vmcnt(8)
	ds_write_b128 v2, v[104:107] offset:36864
	ds_read_b128 v[104:107], v3 offset:2048
	ds_read_b128 v[178:181], v4 offset:18432
	v_mfma_f32_16x16x32_bf16 v[30:33], v[116:119], v[108:111], v[30:33]
	v_mfma_f32_16x16x32_bf16 v[42:45], v[132:135], v[108:111], v[42:45]
	v_mfma_f32_16x16x32_bf16 v[14:17], v[162:165], v[108:111], v[14:17]
	v_mfma_f32_16x16x32_bf16 v[92:95], v[158:161], v[108:111], v[92:95]
	global_load_dwordx4 v[108:111], v217, s[36:37] offset:1792
	s_waitcnt vmcnt(8)
	ds_write_b128 v2, v[112:115] offset:40960
	ds_read_b128 v[112:115], v3 offset:4096
	ds_read_b128 v[182:185], v4 offset:20480
	v_mfma_f32_16x16x32_bf16 v[34:37], v[116:119], v[146:149], v[34:37]
	v_mfma_f32_16x16x32_bf16 v[46:49], v[132:135], v[146:149], v[46:49]
	v_mfma_f32_16x16x32_bf16 v[58:61], v[158:161], v[146:149], v[58:61]
	v_mfma_f32_16x16x32_bf16 v[18:21], v[162:165], v[146:149], v[18:21]
	global_load_dwordx4 v[146:149], v218, s[36:37] offset:1792
	s_waitcnt vmcnt(8)
; template <int MODE>
; __device__ __forceinline__ void gemm_tile(const Params& P, int tm, int tn, unsigned char* smem) {
;     ...
; #pragma unroll
;         for (int i = 0; i < 4; ++i) { fa[i] = *(const bf16x8*)(sA + arow_off + i * 2048 + ch0); fb[i] = *(const bf16x8*)(sB + brow_off + i * 2048 + ch0); }
;         __builtin_amdgcn_sched_barrier(0);
;         __builtin_amdgcn_s_setprio(2);
;         if (wr_ok) *(uint4*)(nA + soff0) = ra0;
;         if (ld_ok) ra0 = *(const uint4*)(Ab + (aoff + 0u * LDA + koa));
;         ga[0] = *(const bf16x8*)(sA + arow_off + 0 * 2048 + ch1); gb[0] = *(const bf16x8*)(sB + brow_off + 0 * 2048 + ch1);
;         __builtin_amdgcn_sched_barrier(0);
; #pragma unroll
;         for (int j = 0; j < 4; ++j) acc[0][j] = __builtin_amdgcn_mfma_f32_16x16x32_bf16(fb[j], fa[0], acc[0][j], 0, 0, 0);
;         __builtin_amdgcn_sched_barrier(0);
;         if (wr_ok) *(uint4*)(nA + soff0 + 4096) = ra1;
;         if (ld_ok) ra1 = *(const uint4*)(Ab + (aoff + 32u * LDA + koa));
;         ga[1] = *(const bf16x8*)(sA + arow_off + 1 * 2048 + ch1); gb[1] = *(const bf16x8*)(sB + brow_off + 1 * 2048 + ch1);
;         __builtin_amdgcn_sched_barrier(0);
; #pragma unroll
;         for (int j = 0; j < 4; ++j) acc[1][j] = __builtin_amdgcn_mfma_f32_16x16x32_bf16(fb[j], fa[1], acc[1][j], 0, 0, 0);
;         __builtin_amdgcn_sched_barrier(0);
;         if (wr_ok) *(uint4*)(nA + soff0 + 8192) = ra2;
;         if (ld_ok) ra2 = *(const uint4*)(Ab + (aoff + 64u * LDA + koa));
;         ga[2] = *(const bf16x8*)(sA + arow_off + 2 * 2048 + ch1); gb[2] = *(const bf16x8*)(sB + brow_off + 2 * 2048 + ch1);
;         __builtin_amdgcn_sched_barrier(0);
; #pragma unroll
;         for (int j = 0; j < 4; ++j) acc[2][j] = __builtin_amdgcn_mfma_f32_16x16x32_bf16(fb[j], fa[2], acc[2][j], 0, 0, 0);
;         __builtin_amdgcn_sched_barrier(0);
;         if (wr_ok) *(uint4*)(nA + soff0 + 12288) = ra3;
;         if (ld_ok) ra3 = *(const uint4*)(Ab + (aoff + 96u * LDA + koa));
;         ga[3] = *(const bf16x8*)(sA + arow_off + 3 * 2048 + ch1); gb[3] = *(const bf16x8*)(sB + brow_off + 3 * 2048 + ch1);
;         __builtin_amdgcn_sched_barrier(0);
; #pragma unroll
;         for (int j = 0; j < 4; ++j) acc[3][j] = __builtin_amdgcn_mfma_f32_16x16x32_bf16(fb[j], fa[3], acc[3][j], 0, 0, 0);
;         __builtin_amdgcn_sched_barrier(0);
;         if (wr_ok) *(uint4*)(nB + soff0) = rb0;
	ds_write_b128 v2, v[150:153] offset:45056
	ds_read_b128 v[150:153], v3 offset:6144
	ds_read_b128 v[186:189], v4 offset:22528
	v_mfma_f32_16x16x32_bf16 v[38:41], v[116:119], v[154:157], v[38:41]
	v_mfma_f32_16x16x32_bf16 v[50:53], v[132:135], v[154:157], v[50:53]
	v_mfma_f32_16x16x32_bf16 v[54:57], v[158:161], v[154:157], v[54:57]
	v_mfma_f32_16x16x32_bf16 v[22:25], v[162:165], v[154:157], v[22:25]
	global_load_dwordx4 v[116:119], v5, s[4:5] offset:1792
	s_waitcnt vmcnt(8)
	ds_write_b128 v2, v[124:127] offset:49152
	s_waitcnt lgkmcnt(10)
	v_mfma_f32_16x16x32_bf16 v[26:29], v[174:177], v[170:173], v[26:29]
	s_waitcnt lgkmcnt(1)
	v_mfma_f32_16x16x32_bf16 v[10:13], v[186:189], v[170:173], v[10:13]
	v_mfma_f32_16x16x32_bf16 v[88:91], v[178:181], v[170:173], v[88:91]
	v_mfma_f32_16x16x32_bf16 v[96:99], v[182:185], v[170:173], v[96:99]
	global_load_dwordx4 v[124:127], v219, s[4:5] offset:1792
	s_waitcnt vmcnt(8)
	ds_write_b128 v2, v[120:123] offset:53248
	v_mfma_f32_16x16x32_bf16 v[30:33], v[174:177], v[104:107], v[30:33]
	v_mfma_f32_16x16x32_bf16 v[42:45], v[178:181], v[104:107], v[42:45]
	v_mfma_f32_16x16x32_bf16 v[14:17], v[186:189], v[104:107], v[14:17]
	v_mfma_f32_16x16x32_bf16 v[92:95], v[182:185], v[104:107], v[92:95]
	global_load_dwordx4 v[104:107], v220, s[4:5] offset:1792
	s_waitcnt vmcnt(8)
	ds_write_b128 v2, v[62:65] offset:57344
	v_mfma_f32_16x16x32_bf16 v[34:37], v[174:177], v[112:115], v[34:37]
	v_mfma_f32_16x16x32_bf16 v[46:49], v[178:181], v[112:115], v[46:49]
	v_mfma_f32_16x16x32_bf16 v[58:61], v[182:185], v[112:115], v[58:61]
	v_mfma_f32_16x16x32_bf16 v[18:21], v[186:189], v[112:115], v[18:21]
	global_load_dwordx4 v[62:65], v221, s[4:5] offset:1792
	s_waitcnt vmcnt(8)
	ds_write_b128 v2, v[100:103] offset:61440
	v_mfma_f32_16x16x32_bf16 v[38:41], v[174:177], v[150:153], v[38:41]
	v_mfma_f32_16x16x32_bf16 v[50:53], v[178:181], v[150:153], v[50:53]
	v_mfma_f32_16x16x32_bf16 v[54:57], v[182:185], v[150:153], v[54:57]
	v_mfma_f32_16x16x32_bf16 v[22:25], v[186:189], v[150:153], v[22:25]
	s_setprio 0
	s_waitcnt lgkmcnt(0)
	s_barrier
	ds_read_b128 v[100:103], v6 offset:32768
	ds_read_b128 v[112:115], v6 offset:34816
	ds_read_b128 v[120:123], v7 offset:49152
	ds_read_b128 v[132:135], v7 offset:51200
	ds_read_b128 v[150:153], v6 offset:36864
	ds_read_b128 v[154:157], v6 offset:38912
	ds_read_b128 v[158:161], v7 offset:53248
	ds_read_b128 v[162:165], v7 offset:55296
	s_setprio 2
	global_load_dwordx4 v[170:173], v8, s[36:37] offset:1920
	s_waitcnt vmcnt(8)
	ds_write_b128 v2, v[166:169]
	ds_read_b128 v[166:169], v3 offset:32768
	ds_read_b128 v[174:177], v4 offset:49152
	s_waitcnt lgkmcnt(8)
	v_mfma_f32_16x16x32_bf16 v[26:29], v[120:123], v[100:103], v[26:29]
	s_waitcnt lgkmcnt(3)
	v_mfma_f32_16x16x32_bf16 v[10:13], v[162:165], v[100:103], v[10:13]
	v_mfma_f32_16x16x32_bf16 v[88:91], v[132:135], v[100:103], v[88:91]
	v_mfma_f32_16x16x32_bf16 v[96:99], v[158:161], v[100:103], v[96:99]
	global_load_dwordx4 v[100:103], v216, s[36:37] offset:1920
	s_waitcnt vmcnt(8)
	ds_write_b128 v2, v[84:87] offset:4096
	ds_read_b128 v[84:87], v3 offset:34816
	ds_read_b128 v[178:181], v4 offset:51200
	v_mfma_f32_16x16x32_bf16 v[30:33], v[120:123], v[112:115], v[30:33]
	v_mfma_f32_16x16x32_bf16 v[42:45], v[132:135], v[112:115], v[42:45]
	v_mfma_f32_16x16x32_bf16 v[14:17], v[162:165], v[112:115], v[14:17]
	v_mfma_f32_16x16x32_bf16 v[92:95], v[158:161], v[112:115], v[92:95]
	global_load_dwordx4 v[112:115], v217, s[36:37] offset:1920
	s_waitcnt vmcnt(8)
	ds_write_b128 v2, v[108:111] offset:8192
	ds_read_b128 v[108:111], v3 offset:36864
	ds_read_b128 v[182:185], v4 offset:53248
	v_mfma_f32_16x16x32_bf16 v[34:37], v[120:123], v[150:153], v[34:37]
	v_mfma_f32_16x16x32_bf16 v[46:49], v[132:135], v[150:153], v[46:49]
	v_mfma_f32_16x16x32_bf16 v[58:61], v[158:161], v[150:153], v[58:61]
	v_mfma_f32_16x16x32_bf16 v[18:21], v[162:165], v[150:153], v[18:21]
	v_add_u32_e32 v8, 0x30780, v8
	global_load_dwordx4 v[150:153], v8, s[36:37]
	s_waitcnt vmcnt(8)
	ds_write_b128 v2, v[146:149] offset:12288
	ds_read_b128 v[146:149], v3 offset:38912
	ds_read_b128 v[186:189], v4 offset:55296
	v_mfma_f32_16x16x32_bf16 v[38:41], v[120:123], v[154:157], v[38:41]
	v_mfma_f32_16x16x32_bf16 v[50:53], v[132:135], v[154:157], v[50:53]
	v_mfma_f32_16x16x32_bf16 v[54:57], v[158:161], v[154:157], v[54:57]
	v_mfma_f32_16x16x32_bf16 v[22:25], v[162:165], v[154:157], v[22:25]
	global_load_dwordx4 v[120:123], v5, s[4:5] offset:1920
	s_waitcnt vmcnt(8)
	ds_write_b128 v2, v[116:119] offset:16384
	s_waitcnt lgkmcnt(10)
	v_mfma_f32_16x16x32_bf16 v[26:29], v[174:177], v[166:169], v[26:29]
	s_waitcnt lgkmcnt(1)
	v_mfma_f32_16x16x32_bf16 v[8:11], v[186:189], v[166:169], v[10:13]
	v_mfma_f32_16x16x32_bf16 v[88:91], v[178:181], v[166:169], v[88:91]
	v_mfma_f32_16x16x32_bf16 v[96:99], v[182:185], v[166:169], v[96:99]
	s_nop 0
	global_load_dwordx4 v[116:119], v219, s[4:5] offset:1920
	s_waitcnt vmcnt(8)
	ds_write_b128 v2, v[124:127] offset:20480
	v_mfma_f32_16x16x32_bf16 v[30:33], v[174:177], v[84:87], v[30:33]
	v_mfma_f32_16x16x32_bf16 v[42:45], v[178:181], v[84:87], v[42:45]
	v_mfma_f32_16x16x32_bf16 v[12:15], v[186:189], v[84:87], v[14:17]
	v_mfma_f32_16x16x32_bf16 v[92:95], v[182:185], v[84:87], v[92:95]
	s_nop 1
	global_load_dwordx4 v[84:87], v220, s[4:5] offset:1920
	s_waitcnt vmcnt(8)
	ds_write_b128 v2, v[104:107] offset:24576
	v_mfma_f32_16x16x32_bf16 v[34:37], v[174:177], v[108:111], v[34:37]
	v_mfma_f32_16x16x32_bf16 v[46:49], v[178:181], v[108:111], v[46:49]
	v_mfma_f32_16x16x32_bf16 v[58:61], v[182:185], v[108:111], v[58:61]
	v_mfma_f32_16x16x32_bf16 v[16:19], v[186:189], v[108:111], v[18:21]
	v_add_u32_e32 v5, 0x30780, v5
	global_load_dwordx4 v[104:107], v5, s[4:5]
	s_waitcnt vmcnt(8)
	ds_write_b128 v2, v[62:65] offset:28672
	v_mfma_f32_16x16x32_bf16 v[38:41], v[174:177], v[146:149], v[38:41]
	v_mfma_f32_16x16x32_bf16 v[50:53], v[178:181], v[146:149], v[50:53]
	v_mfma_f32_16x16x32_bf16 v[54:57], v[182:185], v[146:149], v[54:57]
	v_mfma_f32_16x16x32_bf16 v[20:23], v[186:189], v[146:149], v[22:25]
	s_setprio 0
	s_waitcnt lgkmcnt(0)
	s_barrier
; template <int MODE>
; __device__ __forceinline__ void gemm_tile(const Params& P, int tm, int tn, unsigned char* smem) {
;     ...
; #pragma unroll
;         for (int i = 0; i < 4; ++i) { fa[i] = *(const bf16x8*)(sA + arow_off + i * 2048 + ch0); fb[i] = *(const bf16x8*)(sB + brow_off + i * 2048 + ch0); }
;         __builtin_amdgcn_sched_barrier(0);
;         __builtin_amdgcn_s_setprio(2);
;         if (wr_ok) *(uint4*)(nA + soff0) = ra0;
;         if (ld_ok) ra0 = *(const uint4*)(Ab + (aoff + 0u * LDA + koa));
;         ga[0] = *(const bf16x8*)(sA + arow_off + 0 * 2048 + ch1); gb[0] = *(const bf16x8*)(sB + brow_off + 0 * 2048 + ch1);
;         __builtin_amdgcn_sched_barrier(0);
; #pragma unroll
;         for (int j = 0; j < 4; ++j) acc[0][j] = __builtin_amdgcn_mfma_f32_16x16x32_bf16(fb[j], fa[0], acc[0][j], 0, 0, 0);
;         __builtin_amdgcn_sched_barrier(0);
;         if (wr_ok) *(uint4*)(nA + soff0 + 4096) = ra1;
;         if (ld_ok) ra1 = *(const uint4*)(Ab + (aoff + 32u * LDA + koa));
;         ga[1] = *(const bf16x8*)(sA + arow_off + 1 * 2048 + ch1); gb[1] = *(const bf16x8*)(sB + brow_off + 1 * 2048 + ch1);
;         __builtin_amdgcn_sched_barrier(0);
; #pragma unroll
;         for (int j = 0; j < 4; ++j) acc[1][j] = __builtin_amdgcn_mfma_f32_16x16x32_bf16(fb[j], fa[1], acc[1][j], 0, 0, 0);
;         __builtin_amdgcn_sched_barrier(0);
;         if (wr_ok) *(uint4*)(nA + soff0 + 8192) = ra2;
;         if (ld_ok) ra2 = *(const uint4*)(Ab + (aoff + 64u * LDA + koa));
;         ga[2] = *(const bf16x8*)(sA + arow_off + 2 * 2048 + ch1); gb[2] = *(const bf16x8*)(sB + brow_off + 2 * 2048 + ch1);
;         __builtin_amdgcn_sched_barrier(0);
; #pragma unroll
;         for (int j = 0; j < 4; ++j) acc[2][j] = __builtin_amdgcn_mfma_f32_16x16x32_bf16(fb[j], fa[2], acc[2][j], 0, 0, 0);
;         __builtin_amdgcn_sched_barrier(0);
;         if (wr_ok) *(uint4*)(nA + soff0 + 12288) = ra3;
;         if (ld_ok) ra3 = *(const uint4*)(Ab + (aoff + 96u * LDA + koa));
;         ga[3] = *(const bf16x8*)(sA + arow_off + 3 * 2048 + ch1); gb[3] = *(const bf16x8*)(sB + brow_off + 3 * 2048 + ch1);
;         __builtin_amdgcn_sched_barrier(0);
; #pragma unroll
;         for (int j = 0; j < 4; ++j) acc[3][j] = __builtin_amdgcn_mfma_f32_16x16x32_bf16(fb[j], fa[3], acc[3][j], 0, 0, 0);
;         __builtin_amdgcn_sched_barrier(0);
;         if (wr_ok) *(uint4*)(nB + soff0) = rb0;
	ds_read_b128 v[62:65], v6
	ds_read_b128 v[108:111], v6 offset:2048
	ds_read_b128 v[124:127], v7 offset:16384
	ds_read_b128 v[132:135], v7 offset:18432
	ds_read_b128 v[146:149], v6 offset:4096
	ds_read_b128 v[154:157], v6 offset:6144
	ds_read_b128 v[158:161], v7 offset:20480
	ds_read_b128 v[162:165], v7 offset:22528
	s_setprio 2
	s_waitcnt vmcnt(7)
	ds_write_b128 v2, v[170:173] offset:32768
	ds_read_b128 v[166:169], v3
	ds_read_b128 v[170:173], v4 offset:16384
	s_waitcnt lgkmcnt(8)
	v_mfma_f32_16x16x32_bf16 v[24:27], v[124:127], v[62:65], v[26:29]
	s_waitcnt lgkmcnt(3)
	v_mfma_f32_16x16x32_bf16 v[8:11], v[162:165], v[62:65], v[8:11]
	v_mfma_f32_16x16x32_bf16 v[88:91], v[132:135], v[62:65], v[88:91]
	v_mfma_f32_16x16x32_bf16 v[96:99], v[158:161], v[62:65], v[96:99]
	s_waitcnt vmcnt(6)
	ds_write_b128 v2, v[100:103] offset:36864
	ds_read_b128 v[62:65], v3 offset:2048
	ds_read_b128 v[100:103], v4 offset:18432
	v_mfma_f32_16x16x32_bf16 v[28:31], v[124:127], v[108:111], v[30:33]
	v_mfma_f32_16x16x32_bf16 v[42:45], v[132:135], v[108:111], v[42:45]
	v_mfma_f32_16x16x32_bf16 v[12:15], v[162:165], v[108:111], v[12:15]
	v_mfma_f32_16x16x32_bf16 v[92:95], v[158:161], v[108:111], v[92:95]
	s_waitcnt vmcnt(5)
	ds_write_b128 v2, v[112:115] offset:40960
	ds_read_b128 v[108:111], v3 offset:4096
	ds_read_b128 v[112:115], v4 offset:20480
	v_mfma_f32_16x16x32_bf16 v[32:35], v[124:127], v[146:149], v[34:37]
	v_mfma_f32_16x16x32_bf16 v[46:49], v[132:135], v[146:149], v[46:49]
	v_mfma_f32_16x16x32_bf16 v[58:61], v[158:161], v[146:149], v[58:61]
	v_mfma_f32_16x16x32_bf16 v[16:19], v[162:165], v[146:149], v[16:19]
	s_waitcnt vmcnt(4)
	ds_write_b128 v2, v[150:153] offset:45056
	ds_read_b128 v[146:149], v3 offset:6144
	ds_read_b128 v[150:153], v4 offset:22528
	v_mfma_f32_16x16x32_bf16 v[36:39], v[124:127], v[154:157], v[38:41]
	v_mfma_f32_16x16x32_bf16 v[50:53], v[132:135], v[154:157], v[50:53]
	v_mfma_f32_16x16x32_bf16 v[54:57], v[158:161], v[154:157], v[54:57]
	v_mfma_f32_16x16x32_bf16 v[20:23], v[162:165], v[154:157], v[20:23]
	s_waitcnt vmcnt(3)
	ds_write_b128 v2, v[120:123] offset:49152
	s_waitcnt lgkmcnt(10)
	v_mfma_f32_16x16x32_bf16 v[24:27], v[170:173], v[166:169], v[24:27]
	s_waitcnt lgkmcnt(1)
	v_mfma_f32_16x16x32_bf16 v[8:11], v[150:153], v[166:169], v[8:11]
	v_mfma_f32_16x16x32_bf16 v[88:91], v[100:103], v[166:169], v[88:91]
	v_mfma_f32_16x16x32_bf16 v[96:99], v[112:115], v[166:169], v[96:99]
	s_waitcnt vmcnt(2)
	ds_write_b128 v2, v[116:119] offset:53248
	v_mfma_f32_16x16x32_bf16 v[28:31], v[170:173], v[62:65], v[28:31]
	v_mfma_f32_16x16x32_bf16 v[40:43], v[100:103], v[62:65], v[42:45]
	v_mfma_f32_16x16x32_bf16 v[12:15], v[150:153], v[62:65], v[12:15]
	v_mfma_f32_16x16x32_bf16 v[92:95], v[112:115], v[62:65], v[92:95]
	s_waitcnt vmcnt(1)
	ds_write_b128 v2, v[84:87] offset:57344
	v_mfma_f32_16x16x32_bf16 v[32:35], v[170:173], v[108:111], v[32:35]
	v_mfma_f32_16x16x32_bf16 v[44:47], v[100:103], v[108:111], v[46:49]
	v_mfma_f32_16x16x32_bf16 v[58:61], v[112:115], v[108:111], v[58:61]
	v_mfma_f32_16x16x32_bf16 v[16:19], v[150:153], v[108:111], v[16:19]
	s_waitcnt vmcnt(0)
	ds_write_b128 v2, v[104:107] offset:61440
	v_mfma_f32_16x16x32_bf16 v[36:39], v[170:173], v[146:149], v[36:39]
	v_mfma_f32_16x16x32_bf16 v[48:51], v[100:103], v[146:149], v[50:53]
	v_mfma_f32_16x16x32_bf16 v[52:55], v[112:115], v[146:149], v[54:57]
	v_mfma_f32_16x16x32_bf16 v[20:23], v[150:153], v[146:149], v[20:23]
	s_setprio 0
	s_waitcnt lgkmcnt(0)
	s_barrier
	ds_read_b128 v[62:65], v6 offset:32768
	ds_read_b128 v[84:87], v6 offset:34816
	ds_read_b128 v[100:103], v7 offset:49152
	ds_read_b128 v[104:107], v7 offset:51200
	ds_read_b128 v[108:111], v6 offset:36864
	ds_read_b128 v[112:115], v6 offset:38912
	ds_read_b128 v[116:119], v7 offset:53248
	ds_read_b128 v[120:123], v7 offset:55296
	s_setprio 2
	ds_read_b128 v[124:127], v3 offset:32768
	ds_read_b128 v[132:135], v4 offset:49152
	s_waitcnt lgkmcnt(7)
	v_mfma_f32_16x16x32_bf16 v[24:27], v[100:103], v[62:65], v[24:27]
	s_waitcnt lgkmcnt(2)
	v_mfma_f32_16x16x32_bf16 v[6:9], v[120:123], v[62:65], v[8:11]
	v_mfma_f32_16x16x32_bf16 v[88:91], v[104:107], v[62:65], v[88:91]
	v_mfma_f32_16x16x32_bf16 v[96:99], v[116:119], v[62:65], v[96:99]
	ds_read_b128 v[146:149], v3 offset:34816
	ds_read_b128 v[150:153], v4 offset:51200
	v_mfma_f32_16x16x32_bf16 v[28:31], v[100:103], v[84:87], v[28:31]
	v_mfma_f32_16x16x32_bf16 v[40:43], v[104:107], v[84:87], v[40:43]
	v_mfma_f32_16x16x32_bf16 v[10:13], v[120:123], v[84:87], v[12:15]
	v_mfma_f32_16x16x32_bf16 v[92:95], v[116:119], v[84:87], v[92:95]
	ds_read_b128 v[84:87], v3 offset:36864
	ds_read_b128 v[154:157], v4 offset:53248
	v_mfma_f32_16x16x32_bf16 v[14:17], v[120:123], v[108:111], v[16:19]
	v_mfma_f32_16x16x32_bf16 v[158:161], v[100:103], v[108:111], v[32:35]
	v_mfma_f32_16x16x32_bf16 v[162:165], v[104:107], v[108:111], v[44:47]
	v_mfma_f32_16x16x32_bf16 v[166:169], v[116:119], v[108:111], v[58:61]
	ds_read_b128 v[108:111], v3 offset:38912
	ds_read_b128 v[2:5], v4 offset:55296
	v_mfma_f32_16x16x32_bf16 v[100:103], v[100:103], v[112:115], v[36:39]
	v_mfma_f32_16x16x32_bf16 v[104:107], v[104:107], v[112:115], v[48:51]
	v_mfma_f32_16x16x32_bf16 v[116:119], v[116:119], v[112:115], v[52:55]
	v_mfma_f32_16x16x32_bf16 v[112:115], v[120:123], v[112:115], v[20:23]
	s_waitcnt lgkmcnt(6)
	v_mfma_f32_16x16x32_bf16 v[62:65], v[132:135], v[124:127], v[24:27]
	s_waitcnt lgkmcnt(4)
	v_mfma_f32_16x16x32_bf16 v[58:61], v[150:153], v[124:127], v[88:91]
	s_waitcnt lgkmcnt(2)
	v_mfma_f32_16x16x32_bf16 v[54:57], v[154:157], v[124:127], v[96:99]
	s_waitcnt lgkmcnt(0)
	v_mfma_f32_16x16x32_bf16 v[50:53], v[2:5], v[124:127], v[6:9]
	v_mfma_f32_16x16x32_bf16 v[46:49], v[132:135], v[146:149], v[28:31]
	v_mfma_f32_16x16x32_bf16 v[42:45], v[150:153], v[146:149], v[40:43]
	v_mfma_f32_16x16x32_bf16 v[38:41], v[154:157], v[146:149], v[92:95]
	v_mfma_f32_16x16x32_bf16 v[34:37], v[2:5], v[146:149], v[10:13]
	v_mfma_f32_16x16x32_bf16 v[30:33], v[132:135], v[84:87], v[158:161]
	v_mfma_f32_16x16x32_bf16 v[26:29], v[150:153], v[84:87], v[162:165]
	v_mfma_f32_16x16x32_bf16 v[22:25], v[154:157], v[84:87], v[166:169]
	v_mfma_f32_16x16x32_bf16 v[18:21], v[2:5], v[84:87], v[14:17]
	v_mfma_f32_16x16x32_bf16 v[14:17], v[132:135], v[108:111], v[100:103]
	v_mfma_f32_16x16x32_bf16 v[10:13], v[150:153], v[108:111], v[104:107]
	v_mfma_f32_16x16x32_bf16 v[6:9], v[154:157], v[108:111], v[116:119]
	v_mfma_f32_16x16x32_bf16 v[2:5], v[2:5], v[108:111], v[112:115]
	s_setprio 0
	s_and_b32 s1, s0, -8
	s_cmp_lg_u32 s1, 16
	s_barrier
; template <int MODE>
; __device__ __forceinline__ void gemm_tile(const Params& P, int tm, int tn, unsigned char* smem) {
;     ...
;         if (n0 >= ZC_FQ && n0 < ZC_FV) {
;             const bool isk = n0 >= ZC_FK;
;             const float* gain = isk ? P.f_k_norm : P.f_q_norm;
;             const float scl = isk ? 1.0f : 0.125f * LOG2E;
;             float gn[4][4];
; #pragma unroll
;             for (int j = 0; j < 4; ++j)
; #pragma unroll
;                 for (int r = 0; r < 4; ++r) gn[j][r] = gain[16 * j + 4 * g + r];
; #pragma unroll
;             for (int i = 0; i < 4; ++i) {
;                 float ss = 0.f;
; #pragma unroll
;                 for (int j = 0; j < 4; ++j)
; #pragma unroll
;                     for (int r = 0; r < 4; ++r) ss += acc[i][j][r] * acc[i][j][r];
;                 ss = x4_sum(ss);
;                 const float rstd = rsqrtf(ss * (1.0f / 64.0f) + EPS) * scl;
	s_cbranch_scc1 .LBB0_181
	v_mul_f32_e32 v66, v63, v63
	v_fmac_f32_e32 v66, v62, v62
	v_fmac_f32_e32 v66, v64, v64
	v_fmac_f32_e32 v66, v65, v65
	v_fmac_f32_e32 v66, v58, v58
	v_fmac_f32_e32 v66, v59, v59
	v_fmac_f32_e32 v66, v60, v60
	v_fmac_f32_e32 v66, v61, v61
	v_fmac_f32_e32 v66, v54, v54
	v_fmac_f32_e32 v66, v55, v55
	v_fmac_f32_e32 v66, v56, v56
	v_fmac_f32_e32 v66, v57, v57
	v_pk_mul_f32 v[84:85], v[50:51], v[50:51]
	v_pk_mul_f32 v[68:69], v[52:53], v[52:53]
	v_add_f32_e32 v66, v84, v66
	v_add_f32_e32 v66, v85, v66
	v_add_f32_e32 v66, v68, v66
	v_add_f32_e32 v66, v69, v66
	v_mov_b32_e32 v68, v66
	s_nop 1
	v_permlane32_swap_b32_e32 v66, v68
	v_add_f32_e32 v69, v66, v68
	v_mul_f32_e32 v66, v47, v47
	v_fmac_f32_e32 v66, v46, v46
	v_fmac_f32_e32 v66, v48, v48
	v_fmac_f32_e32 v66, v49, v49
	v_fmac_f32_e32 v66, v42, v42
	v_fmac_f32_e32 v66, v43, v43
	v_fmac_f32_e32 v66, v44, v44
	v_fmac_f32_e32 v66, v45, v45
	v_fmac_f32_e32 v66, v38, v38
	v_fmac_f32_e32 v66, v39, v39
	v_fmac_f32_e32 v66, v40, v40
	v_fmac_f32_e32 v66, v41, v41
	v_pk_mul_f32 v[88:89], v[34:35], v[34:35]
	v_pk_mul_f32 v[86:87], v[36:37], v[36:37]
	v_add_f32_e32 v66, v88, v66
	v_add_f32_e32 v66, v89, v66
	v_add_f32_e32 v66, v86, v66
	v_add_f32_e32 v66, v87, v66
	v_mov_b32_e32 v68, v66
	s_nop 1
	v_permlane32_swap_b32_e32 v66, v68
	v_add_f32_e32 v68, v66, v68
	v_mov_b32_e32 v85, v69
	v_mov_b32_e32 v84, v68
	s_nop 0
	v_permlane16_swap_b32_e32 v69, v85
	v_permlane16_swap_b32_e32 v68, v84
	v_pk_add_f32 v[84:85], v[68:69], v[84:85]
	v_mov_b64_e32 v[68:69], s[8:9]
	v_mul_f32_e32 v97, v31, v31
	s_cmp_gt_u32 s0, 19
	v_pk_fma_f32 v[88:89], v[84:85], s[6:7], v[68:69] op_sel_hi:[1,0,0]
	v_fmac_f32_e32 v97, v30, v30
	s_cselect_b64 s[0:1], -1, 0
	v_mul_f32_e32 v66, 0x4b800000, v89
	v_cmp_gt_f32_e32 vcc, s21, v89
	v_fmac_f32_e32 v97, v32, v32
	v_cndmask_b32_e64 v108, v78, 1.0, s[0:1]
	s_and_b64 s[0:1], s[0:1], exec
	v_cndmask_b32_e32 v66, v89, v66, vcc
	v_fmac_f32_e32 v97, v33, v33
	v_rsq_f32_e32 v66, v66
	v_mul_f32_e32 v70, 0x4b800000, v88
	v_cmp_gt_f32_e64 s[0:1], s21, v88
	v_fmac_f32_e32 v97, v26, v26
	v_fmac_f32_e32 v97, v27, v27
	v_cndmask_b32_e64 v70, v88, v70, s[0:1]
	v_rsq_f32_e32 v88, v70
	v_fmac_f32_e32 v97, v28, v28
	s_cselect_b32 s13, s41, s39
	s_cselect_b32 s12, s40, s38
	v_lshlrev_b32_e32 v96, 4, v83
	v_fmac_f32_e32 v97, v29, v29
	global_load_dwordx4 v[84:87], v96, s[12:13]
	v_mul_f32_e32 v70, 0x45800000, v66
	v_fmac_f32_e32 v97, v22, v22
	v_cndmask_b32_e32 v66, v66, v70, vcc
	v_fmac_f32_e32 v97, v23, v23
	v_mul_f32_e32 v70, v108, v66
	v_mul_f32_e32 v66, 0x45800000, v88
	v_fmac_f32_e32 v97, v24, v24
	v_cndmask_b32_e64 v66, v88, v66, s[0:1]
	global_load_dwordx4 v[88:91], v96, s[12:13] offset:64
	v_fmac_f32_e32 v97, v25, v25
	v_pk_mul_f32 v[94:95], v[18:19], v[18:19]
	v_pk_mul_f32 v[92:93], v[20:21], v[20:21]
	v_add_f32_e32 v94, v94, v97
	v_add_f32_e32 v94, v95, v94
	v_add_f32_e32 v92, v92, v94
	v_add_f32_e32 v97, v93, v92
	global_load_dwordx4 v[92:95], v96, s[12:13] offset:128
	v_mov_b32_e32 v98, v97
	s_nop 1
	v_permlane32_swap_b32_e32 v97, v98
	v_add_f32_e32 v101, v97, v98
	global_load_dwordx4 v[96:99], v96, s[12:13] offset:192
	v_mul_f32_e32 v100, v15, v15
	v_fmac_f32_e32 v100, v14, v14
	v_fmac_f32_e32 v100, v16, v16
	v_fmac_f32_e32 v100, v17, v17
	v_fmac_f32_e32 v100, v10, v10
	v_fmac_f32_e32 v100, v11, v11
	v_fmac_f32_e32 v100, v12, v12
	v_fmac_f32_e32 v100, v13, v13
	v_fmac_f32_e32 v100, v6, v6
	v_fmac_f32_e32 v100, v7, v7
	v_fmac_f32_e32 v100, v8, v8
	v_fmac_f32_e32 v100, v9, v9
	v_pk_mul_f32 v[106:107], v[2:3], v[2:3]
	v_pk_mul_f32 v[104:105], v[4:5], v[4:5]
	v_add_f32_e32 v100, v106, v100
	v_add_f32_e32 v100, v107, v100
	v_add_f32_e32 v100, v104, v100
	v_add_f32_e32 v100, v105, v100
	v_mov_b32_e32 v102, v100
	s_nop 1
	v_permlane32_swap_b32_e32 v100, v102
	v_add_f32_e32 v100, v100, v102
	v_mov_b32_e32 v103, v101
	v_mov_b32_e32 v102, v100
	s_nop 0
	v_permlane16_swap_b32_e32 v101, v103
	v_permlane16_swap_b32_e32 v100, v102
	v_pk_add_f32 v[100:101], v[100:101], v[102:103]
	v_mul_f32_e32 v66, v108, v66
	v_pk_fma_f32 v[68:69], v[100:101], s[6:7], v[68:69] op_sel_hi:[1,0,0]
	s_waitcnt vmcnt(3)
; template <int MODE>
; __device__ __forceinline__ void gemm_tile(const Params& P, int tm, int tn, unsigned char* smem) {
;     ...
; #pragma unroll
;                 for (int j = 0; j < 4; ++j)
; #pragma unroll
;                     for (int r = 0; r < 4; ++r) acc[i][j][r] *= rstd * gn[j][r];
;             }
	v_pk_mul_f32 v[102:103], v[84:85], v[70:71] op_sel_hi:[1,0]
	v_mul_f32_e32 v100, 0x4b800000, v69
	v_cmp_gt_f32_e32 vcc, s21, v69
	v_cmp_gt_f32_e64 s[0:1], s21, v68
	v_pk_mul_f32 v[62:63], v[62:63], v[102:103]
	v_cndmask_b32_e32 v69, v69, v100, vcc
	v_mul_f32_e32 v100, 0x4b800000, v68
	v_rsq_f32_e32 v69, v69
	v_cndmask_b32_e64 v68, v68, v100, s[0:1]
	v_rsq_f32_e32 v100, v68
	v_pk_mul_f32 v[102:103], v[84:85], v[66:67] op_sel_hi:[1,0]
	v_mul_f32_e32 v68, 0x45800000, v69
	v_cndmask_b32_e32 v68, v69, v68, vcc
	v_mul_f32_e32 v69, 0x45800000, v100
	v_cndmask_b32_e64 v69, v100, v69, s[0:1]
	v_mul_f32_e32 v68, v108, v68
	v_mul_f32_e32 v100, v108, v69
	v_pk_mul_f32 v[104:105], v[86:87], v[70:71] op_sel_hi:[1,0]
	v_pk_mul_f32 v[46:47], v[46:47], v[102:103]
	v_pk_mul_f32 v[102:103], v[84:85], v[68:69] op_sel_hi:[1,0]
	v_pk_mul_f32 v[84:85], v[84:85], v[100:101] op_sel_hi:[1,0]
	v_pk_mul_f32 v[64:65], v[64:65], v[104:105]
	v_pk_mul_f32 v[104:105], v[86:87], v[66:67] op_sel_hi:[1,0]
	v_pk_mul_f32 v[14:15], v[14:15], v[84:85]
	s_waitcnt vmcnt(2)
	v_pk_mul_f32 v[84:85], v[88:89], v[70:71] op_sel_hi:[1,0]
	v_pk_mul_f32 v[48:49], v[48:49], v[104:105]
	v_pk_mul_f32 v[104:105], v[86:87], v[68:69] op_sel_hi:[1,0]
	v_pk_mul_f32 v[86:87], v[86:87], v[100:101] op_sel_hi:[1,0]
	v_pk_mul_f32 v[58:59], v[58:59], v[84:85]
	v_pk_mul_f32 v[84:85], v[88:89], v[66:67] op_sel_hi:[1,0]
	v_pk_mul_f32 v[16:17], v[16:17], v[86:87]
	v_pk_mul_f32 v[86:87], v[90:91], v[70:71] op_sel_hi:[1,0]
	v_pk_mul_f32 v[42:43], v[42:43], v[84:85]
	v_pk_mul_f32 v[84:85], v[88:89], v[68:69] op_sel_hi:[1,0]
	v_pk_mul_f32 v[60:61], v[60:61], v[86:87]
	v_pk_mul_f32 v[86:87], v[90:91], v[66:67] op_sel_hi:[1,0]
	v_pk_mul_f32 v[26:27], v[26:27], v[84:85]
	v_pk_mul_f32 v[84:85], v[88:89], v[100:101] op_sel_hi:[1,0]
	v_pk_mul_f32 v[44:45], v[44:45], v[86:87]
	v_pk_mul_f32 v[86:87], v[90:91], v[68:69] op_sel_hi:[1,0]
	v_pk_mul_f32 v[10:11], v[10:11], v[84:85]
	s_waitcnt vmcnt(1)
	v_pk_mul_f32 v[84:85], v[92:93], v[70:71] op_sel_hi:[1,0]
	v_pk_mul_f32 v[28:29], v[28:29], v[86:87]
	v_pk_mul_f32 v[86:87], v[90:91], v[100:101] op_sel_hi:[1,0]
	v_pk_mul_f32 v[54:55], v[54:55], v[84:85]
	v_pk_mul_f32 v[84:85], v[92:93], v[66:67] op_sel_hi:[1,0]
	v_pk_mul_f32 v[12:13], v[12:13], v[86:87]
	v_pk_mul_f32 v[86:87], v[94:95], v[70:71] op_sel_hi:[1,0]
	v_pk_mul_f32 v[38:39], v[38:39], v[84:85]
	v_pk_mul_f32 v[84:85], v[92:93], v[68:69] op_sel_hi:[1,0]
	v_pk_mul_f32 v[56:57], v[56:57], v[86:87]
	v_pk_mul_f32 v[86:87], v[94:95], v[66:67] op_sel_hi:[1,0]
	v_pk_mul_f32 v[22:23], v[22:23], v[84:85]
	v_pk_mul_f32 v[84:85], v[92:93], v[100:101] op_sel_hi:[1,0]
	v_pk_mul_f32 v[40:41], v[40:41], v[86:87]
	v_pk_mul_f32 v[86:87], v[94:95], v[68:69] op_sel_hi:[1,0]
	v_pk_mul_f32 v[6:7], v[6:7], v[84:85]
	s_waitcnt vmcnt(0)
	v_pk_mul_f32 v[84:85], v[96:97], v[70:71] op_sel_hi:[1,0]
	v_pk_mul_f32 v[24:25], v[24:25], v[86:87]
	v_pk_mul_f32 v[86:87], v[94:95], v[100:101] op_sel_hi:[1,0]
	v_pk_mul_f32 v[50:51], v[50:51], v[84:85]
	v_pk_mul_f32 v[84:85], v[96:97], v[66:67] op_sel_hi:[1,0]
	v_pk_mul_f32 v[8:9], v[8:9], v[86:87]
	v_pk_mul_f32 v[86:87], v[98:99], v[70:71] op_sel_hi:[1,0]
	v_pk_mul_f32 v[34:35], v[34:35], v[84:85]
	v_pk_mul_f32 v[84:85], v[96:97], v[68:69] op_sel_hi:[1,0]
	v_pk_mul_f32 v[68:69], v[98:99], v[68:69] op_sel_hi:[1,0]
	v_pk_mul_f32 v[52:53], v[52:53], v[86:87]
	v_pk_mul_f32 v[86:87], v[98:99], v[66:67] op_sel_hi:[1,0]
	v_pk_mul_f32 v[20:21], v[20:21], v[68:69]
	v_pk_mul_f32 v[18:19], v[18:19], v[84:85]
	v_pk_mul_f32 v[68:69], v[96:97], v[100:101] op_sel_hi:[1,0]
	v_pk_mul_f32 v[84:85], v[98:99], v[100:101] op_sel_hi:[1,0]
	v_pk_mul_f32 v[32:33], v[32:33], v[104:105]
	v_pk_mul_f32 v[30:31], v[30:31], v[102:103]
	v_pk_mul_f32 v[36:37], v[36:37], v[86:87]
	v_pk_mul_f32 v[4:5], v[4:5], v[84:85]
	v_pk_mul_f32 v[2:3], v[2:3], v[68:69]
	s_branch .LBB0_181

; template <int MODE>
; __device__ __forceinline__ void gemm_tile(const Params& P, int tm, int tn, unsigned char* smem) {
;     ...
;     const int tid = opaque_tid(), lane = tid & 63, wave = tid >> 6, wr = wave >> 1, wc = wave & 1, g = lane >> 4, lr = lane & 15;
;     const int m0 = tm * 128, n0 = tn * 128;
;     const int srow = tid >> 3, sc = tid & 7;
;     constexpr unsigned LDA = (MODE == 2 ? NZ : 1024) * 2u;
;     unsigned aoff, boff; int soff0;
;     {
;         int ar = m0 + srow;
;         if (MODE == 2) { const int b = ar >> 11, t = ar & 2047; ar = b * L + NMETA + t; }
;         aoff = (unsigned)ar * LDA + (unsigned)sc * 16u;
;         boff = (unsigned)(n0 + srow) * 2048u + (unsigned)sc * 16u;
;         soff0 = srow * 128 + ((sc ^ (srow & 7)) << 4);
;     }
;     const unsigned char* Ab = (const unsigned char*)A; const unsigned char* Bb = (const unsigned char*)Bt;
;     float4 ssp0, ssp1, ssp2, ssp3;
;     if (MODE == 3) {
;         const float* ssq = (const float*)(P.ws + WS_SSQ) + (size_t)(m0 + wr * 64 + lr) * 16 + 4 * g;
;         ssp0 = *(const float4*)(ssq); ssp1 = *(const float4*)(ssq + 16 * 16); ssp2 = *(const float4*)(ssq + 32 * 16); ssp3 = *(const float4*)(ssq + 48 * 16);
;     }
;     f32x4 acc[4][4];
; #pragma unroll
;     for (int i = 0; i < 4; ++i)
; #pragma unroll
;         for (int j = 0; j < 4; ++j) acc[i][j] = (f32x4){0.f, 0.f, 0.f, 0.f};
;     uint4 ra0, ra1, ra2, ra3, rb0, rb1, rb2, rb3;
;     ...
;     unsigned char* sA0 = smem; unsigned char* sB0 = smem + 16384; unsigned char* sA1 = smem + 32768; unsigned char* sB1 = smem + 49152;
;     G_LOAD(0)
;     G_WRITE(sA0, sB0)
;     __syncthreads();
;     const int arow_off = (wr * 64 + lr) * 128, brow_off = (wc * 64 + lr) * 128, sw = lr & 7;
;     G_LOAD(1)
;     for (int kt = 0; kt < 16; ++kt) {
;         unsigned char* sA = (kt & 1) ? sA1 : sA0; unsigned char* sB = (kt & 1) ? sB1 : sB0;
;         unsigned char* nA = (kt & 1) ? sA0 : sA1; unsigned char* nB = (kt & 1) ? sB0 : sB1;
;         bf16x8 fa[4], fb[4], ga[4], gb[4];
;         const int ch0 = ((g ^ sw) << 4), ch1 = (((4 + g) ^ sw) << 4);
;         const unsigned ko = (unsigned)(kt + 2) * 128u;
;         const unsigned koa = ko + ((MODE == 2 && kt + 2 >= 8) ? (unsigned)(ZC_FQ - 512) * 2u : 0u);
;         const bool wr_ok = kt < 15, ld_ok = kt < 14;
; #pragma unroll
.LBB0_221:
	s_add_i32 s0, s14, s3
	s_mul_hi_i32 s1, s0, 0x92492493
	s_add_i32 s1, s1, s0
	s_lshr_b32 s6, s1, 31
	s_ashr_i32 s1, s1, 7
	s_add_i32 s1, s1, s6
	s_mul_i32 s6, s1, 0xffffff20
	s_lshl_b32 s1, s1, 3
	s_add_i32 s6, s6, s0
	s_sub_i32 s7, 0x81, s1
	s_cmpk_gt_i32 s0, 0xdff
	s_cselect_b32 s0, s7, 8
	s_abs_i32 s7, s0
	v_cvt_f32_u32_e32 v2, s7
	s_sub_i32 s10, 0, s7
	s_abs_i32 s8, s6
	s_xor_b32 s9, s6, s0
	v_rcp_iflag_f32_e32 v2, v2
	s_ashr_i32 s9, s9, 31
	v_mov_b32_e32 v69, v0
	v_mul_f32_e32 v2, 0x4f7ffffe, v2
	v_cvt_u32_f32_e32 v2, v2
	v_lshlrev_b32_e32 v3, 4, v69
	v_and_b32_e32 v5, 0x70, v3
	v_and_b32_e32 v78, 15, v69
	v_readfirstlane_b32 s11, v2
	s_mul_i32 s10, s10, s11
	s_mul_hi_u32 s10, s11, s10
	s_add_i32 s11, s11, s10
	s_mul_hi_u32 s10, s8, s11
	s_mul_i32 s11, s10, s7
	s_sub_i32 s8, s8, s11
	s_add_i32 s12, s10, 1
	s_sub_i32 s11, s8, s7
	s_cmp_ge_u32 s8, s7
	s_cselect_b32 s10, s12, s10
	s_cselect_b32 s8, s11, s8
	s_add_i32 s11, s10, 1
	s_cmp_ge_u32 s8, s7
	s_cselect_b32 s7, s11, s10
	s_xor_b32 s7, s7, s9
	s_sub_i32 s7, s7, s9
	s_mul_i32 s0, s7, s0
	s_add_i32 s6, s6, s1
	s_sub_i32 s0, s6, s0
	s_lshl_b32 s11, s0, 7
	v_ashrrev_i32_e32 v2, 3, v69
	s_lshl_b32 s6, s7, 7
	v_add_u32_e32 v4, s11, v2
	v_add_u32_e32 v3, s6, v2
	v_lshl_or_b32 v8, v4, 11, v5
	v_lshl_or_b32 v3, v3, 11, v5
	s_add_u32 s0, s28, 0xc075800
	v_add_u32_e32 v9, 0x10000, v8
	s_addc_u32 s1, s29, 0
	v_add_u32_e32 v22, 0x20000, v8
	global_load_dwordx4 v[4:7], v9, s[36:37]
	global_load_dwordx4 v[10:13], v22, s[36:37]
	global_load_dwordx4 v[14:17], v8, s[36:37]
	global_load_dwordx4 v[18:21], v3, s[0:1]
	v_add_u32_e32 v9, 0x20000, v3
	v_add_u32_e32 v30, 0x30000, v3
	global_load_dwordx4 v[22:25], v9, s[0:1]
	global_load_dwordx4 v[26:29], v30, s[0:1]
	v_add_u32_e32 v9, 0x30000, v8
	v_add_u32_e32 v38, 0x10000, v3
	global_load_dwordx4 v[30:33], v9, s[36:37]
	global_load_dwordx4 v[34:37], v38, s[0:1]
	v_xor_b32_e32 v9, v2, v69
	s_movk_i32 s8, 0x70
	v_lshlrev_b32_e32 v2, 7, v2
	v_lshlrev_b32_e32 v9, 4, v9
	v_and_or_b32 v2, v9, s8, v2
	v_add_u32_e32 v2, 0, v2
	v_or_b32_e32 v45, 0x80, v8
	v_or_b32_e32 v9, 0x80, v3
	v_add_u32_e32 v42, 0x10080, v3
	v_add_u32_e32 v43, 0x20080, v3
	v_add_u32_e32 v44, 0x30080, v3
	v_add_u32_e32 v46, 0x10080, v8
	v_add_u32_e32 v47, 0x20080, v8
	v_add_u32_e32 v48, 0x30080, v8
	v_ashrrev_i32_e32 v79, 7, v69
	v_bfe_u32 v80, v69, 6, 1
	v_bfe_u32 v81, v69, 4, 2
	s_waitcnt vmcnt(5)
	ds_write_b128 v2, v[14:17]
	s_waitcnt vmcnt(4)
	ds_write_b128 v2, v[18:21] offset:16384
	s_waitcnt vmcnt(3)
	ds_write_b128 v2, v[22:25] offset:24576
	s_waitcnt vmcnt(2)
	ds_write_b128 v2, v[26:29] offset:28672
	ds_write_b128 v2, v[4:7] offset:4096
	ds_write_b128 v2, v[10:13] offset:8192
	s_waitcnt vmcnt(1)
	ds_write_b128 v2, v[30:33] offset:12288
	s_waitcnt vmcnt(0)
	ds_write_b128 v2, v[34:37] offset:20480
	s_waitcnt lgkmcnt(0)
	s_barrier
	global_load_dwordx4 v[10:13], v45, s[36:37]
	global_load_dwordx4 v[14:17], v46, s[36:37]
	global_load_dwordx4 v[18:21], v47, s[36:37]
	global_load_dwordx4 v[22:25], v48, s[36:37]
	global_load_dwordx4 v[26:29], v9, s[0:1]
	global_load_dwordx4 v[30:33], v42, s[0:1]
	global_load_dwordx4 v[34:37], v43, s[0:1]
	global_load_dwordx4 v[38:41], v44, s[0:1]
	v_lshrrev_b32_e32 v4, 4, v69
	v_lshlrev_b32_e32 v5, 7, v78
	v_and_b32_e32 v9, 7, v69
	v_lshl_or_b32 v6, v79, 13, v5
	v_bitop3_b32 v4, v4, v9, 3 bitop3:0x6c
	v_lshl_or_b32 v5, v80, 13, v5
	v_lshlrev_b32_e32 v4, 4, v4
	v_add_u32_e32 v66, 0, v6
	v_add_u32_e32 v6, v66, v4
	v_add_u32_e32 v5, 0, v5
	v_add_u32_e32 v7, v5, v4
	ds_read_b128 v[42:45], v6
	ds_read_b128 v[46:49], v6 offset:2048
	ds_read_b128 v[50:53], v7 offset:16384
	ds_read_b128 v[54:57], v7 offset:18432
	ds_read_b128 v[58:61], v6 offset:4096
	ds_read_b128 v[62:65], v6 offset:6144
	ds_read_b128 v[82:85], v7 offset:20480
	ds_read_b128 v[86:89], v7 offset:22528
	v_bitop3_b32 v4, v81, v9, 4 bitop3:0x36
	v_lshlrev_b32_e32 v9, 4, v4
	s_setprio 2
	global_load_dwordx4 v[90:93], v8, s[36:37] offset:256
	s_waitcnt vmcnt(8)
	ds_write_b128 v2, v[10:13] offset:32768
	v_add_u32_e32 v4, v66, v9
	v_add_u32_e32 v5, v5, v9
	ds_read_b128 v[10:13], v4
	ds_read_b128 v[94:97], v5 offset:16384
	s_waitcnt lgkmcnt(8)
	v_mfma_f32_16x16x32_bf16 v[98:101], v[50:53], v[42:45], 0
	s_waitcnt lgkmcnt(7)
	v_mfma_f32_16x16x32_bf16 v[102:105], v[54:57], v[42:45], 0
	s_waitcnt lgkmcnt(4)
	v_mfma_f32_16x16x32_bf16 v[106:109], v[82:85], v[42:45], 0
	s_waitcnt lgkmcnt(3)
	v_mfma_f32_16x16x32_bf16 v[42:45], v[86:89], v[42:45], 0
	v_add_u32_e32 v222, 0x10000, v8
	global_load_dwordx4 v[110:113], v222, s[36:37] offset:256
	s_waitcnt vmcnt(8)
	ds_write_b128 v2, v[14:17] offset:36864
	ds_read_b128 v[14:17], v4 offset:2048
	ds_read_b128 v[114:117], v5 offset:18432
	v_mfma_f32_16x16x32_bf16 v[118:121], v[50:53], v[46:49], 0
	v_mfma_f32_16x16x32_bf16 v[122:125], v[54:57], v[46:49], 0
	v_mfma_f32_16x16x32_bf16 v[126:129], v[82:85], v[46:49], 0
	v_mfma_f32_16x16x32_bf16 v[46:49], v[86:89], v[46:49], 0
	v_add_u32_e32 v223, 0x20000, v8
	global_load_dwordx4 v[132:135], v223, s[36:37] offset:256
	s_waitcnt vmcnt(8)
	ds_write_b128 v2, v[18:21] offset:40960
	ds_read_b128 v[18:21], v4 offset:4096
	ds_read_b128 v[146:149], v5 offset:20480
	v_mfma_f32_16x16x32_bf16 v[150:153], v[50:53], v[58:61], 0
	v_mfma_f32_16x16x32_bf16 v[154:157], v[54:57], v[58:61], 0
	v_mfma_f32_16x16x32_bf16 v[158:161], v[82:85], v[58:61], 0
	v_mfma_f32_16x16x32_bf16 v[58:61], v[86:89], v[58:61], 0
	v_add_u32_e32 v224, 0x30000, v8
	global_load_dwordx4 v[162:165], v224, s[36:37] offset:256
	s_waitcnt vmcnt(8)
; template <int MODE>
; __device__ __forceinline__ void gemm_tile(const Params& P, int tm, int tn, unsigned char* smem) {
;     ...
; #pragma unroll
;         for (int i = 0; i < 4; ++i) { fa[i] = *(const bf16x8*)(sA + arow_off + i * 2048 + ch0); fb[i] = *(const bf16x8*)(sB + brow_off + i * 2048 + ch0); }
;         __builtin_amdgcn_sched_barrier(0);
;         __builtin_amdgcn_s_setprio(2);
;         if (wr_ok) *(uint4*)(nA + soff0) = ra0;
;         if (ld_ok) ra0 = *(const uint4*)(Ab + (aoff + 0u * LDA + koa));
;         ga[0] = *(const bf16x8*)(sA + arow_off + 0 * 2048 + ch1); gb[0] = *(const bf16x8*)(sB + brow_off + 0 * 2048 + ch1);
;         __builtin_amdgcn_sched_barrier(0);
; #pragma unroll
;         for (int j = 0; j < 4; ++j) acc[0][j] = __builtin_amdgcn_mfma_f32_16x16x32_bf16(fb[j], fa[0], acc[0][j], 0, 0, 0);
;         __builtin_amdgcn_sched_barrier(0);
;         if (wr_ok) *(uint4*)(nA + soff0 + 4096) = ra1;
;         if (ld_ok) ra1 = *(const uint4*)(Ab + (aoff + 32u * LDA + koa));
;         ga[1] = *(const bf16x8*)(sA + arow_off + 1 * 2048 + ch1); gb[1] = *(const bf16x8*)(sB + brow_off + 1 * 2048 + ch1);
;         __builtin_amdgcn_sched_barrier(0);
; #pragma unroll
;         for (int j = 0; j < 4; ++j) acc[1][j] = __builtin_amdgcn_mfma_f32_16x16x32_bf16(fb[j], fa[1], acc[1][j], 0, 0, 0);
;         __builtin_amdgcn_sched_barrier(0);
;         if (wr_ok) *(uint4*)(nA + soff0 + 8192) = ra2;
;         if (ld_ok) ra2 = *(const uint4*)(Ab + (aoff + 64u * LDA + koa));
;         ga[2] = *(const bf16x8*)(sA + arow_off + 2 * 2048 + ch1); gb[2] = *(const bf16x8*)(sB + brow_off + 2 * 2048 + ch1);
;         __builtin_amdgcn_sched_barrier(0);
; #pragma unroll
;         for (int j = 0; j < 4; ++j) acc[2][j] = __builtin_amdgcn_mfma_f32_16x16x32_bf16(fb[j], fa[2], acc[2][j], 0, 0, 0);
;         __builtin_amdgcn_sched_barrier(0);
;         if (wr_ok) *(uint4*)(nA + soff0 + 12288) = ra3;
;         if (ld_ok) ra3 = *(const uint4*)(Ab + (aoff + 96u * LDA + koa));
;         ga[3] = *(const bf16x8*)(sA + arow_off + 3 * 2048 + ch1); gb[3] = *(const bf16x8*)(sB + brow_off + 3 * 2048 + ch1);
;         __builtin_amdgcn_sched_barrier(0);
; #pragma unroll
;         for (int j = 0; j < 4; ++j) acc[3][j] = __builtin_amdgcn_mfma_f32_16x16x32_bf16(fb[j], fa[3], acc[3][j], 0, 0, 0);
;         __builtin_amdgcn_sched_barrier(0);
;         if (wr_ok) *(uint4*)(nB + soff0) = rb0;
	ds_write_b128 v2, v[22:25] offset:45056
	ds_read_b128 v[22:25], v4 offset:6144
	ds_read_b128 v[166:169], v5 offset:22528
	v_mfma_f32_16x16x32_bf16 v[50:53], v[50:53], v[62:65], 0
	v_mfma_f32_16x16x32_bf16 v[54:57], v[54:57], v[62:65], 0
	v_mfma_f32_16x16x32_bf16 v[82:85], v[82:85], v[62:65], 0
	v_mfma_f32_16x16x32_bf16 v[62:65], v[86:89], v[62:65], 0
	global_load_dwordx4 v[86:89], v3, s[0:1] offset:256
	s_waitcnt vmcnt(8)
	ds_write_b128 v2, v[26:29] offset:49152
	s_waitcnt lgkmcnt(10)
	v_mfma_f32_16x16x32_bf16 v[26:29], v[94:97], v[10:13], v[98:101]
	s_waitcnt lgkmcnt(7)
	v_mfma_f32_16x16x32_bf16 v[98:101], v[114:117], v[10:13], v[102:105]
	s_waitcnt lgkmcnt(4)
	v_mfma_f32_16x16x32_bf16 v[102:105], v[146:149], v[10:13], v[106:109]
	s_waitcnt lgkmcnt(1)
	v_mfma_f32_16x16x32_bf16 v[10:13], v[166:169], v[10:13], v[42:45]
	v_add_u32_e32 v225, 0x10000, v3
	global_load_dwordx4 v[42:45], v225, s[0:1] offset:256
	s_waitcnt vmcnt(8)
	ds_write_b128 v2, v[30:33] offset:53248
	v_mfma_f32_16x16x32_bf16 v[30:33], v[94:97], v[14:17], v[118:121]
	v_mfma_f32_16x16x32_bf16 v[106:109], v[114:117], v[14:17], v[122:125]
	v_mfma_f32_16x16x32_bf16 v[118:121], v[146:149], v[14:17], v[126:129]
	v_mfma_f32_16x16x32_bf16 v[14:17], v[166:169], v[14:17], v[46:49]
	v_add_u32_e32 v226, 0x20000, v3
	global_load_dwordx4 v[46:49], v226, s[0:1] offset:256
	s_waitcnt vmcnt(8)
	ds_write_b128 v2, v[34:37] offset:57344
	v_mfma_f32_16x16x32_bf16 v[34:37], v[94:97], v[18:21], v[150:153]
	v_mfma_f32_16x16x32_bf16 v[122:125], v[114:117], v[18:21], v[154:157]
	v_mfma_f32_16x16x32_bf16 v[126:129], v[146:149], v[18:21], v[158:161]
	v_mfma_f32_16x16x32_bf16 v[18:21], v[166:169], v[18:21], v[58:61]
	v_add_u32_e32 v227, 0x30000, v3
	global_load_dwordx4 v[58:61], v227, s[0:1] offset:256
	s_waitcnt vmcnt(8)
	ds_write_b128 v2, v[38:41] offset:61440
	v_mfma_f32_16x16x32_bf16 v[38:41], v[94:97], v[22:25], v[50:53]
	v_mfma_f32_16x16x32_bf16 v[50:53], v[114:117], v[22:25], v[54:57]
	v_mfma_f32_16x16x32_bf16 v[54:57], v[146:149], v[22:25], v[82:85]
	v_mfma_f32_16x16x32_bf16 v[22:25], v[166:169], v[22:25], v[62:65]
	s_setprio 0
	s_waitcnt lgkmcnt(0)
	s_barrier
	ds_read_b128 v[62:65], v6 offset:32768
	ds_read_b128 v[82:85], v6 offset:34816
	ds_read_b128 v[94:97], v7 offset:49152
	ds_read_b128 v[114:117], v7 offset:51200
	ds_read_b128 v[146:149], v6 offset:36864
	ds_read_b128 v[150:153], v6 offset:38912
	ds_read_b128 v[154:157], v7 offset:53248
	ds_read_b128 v[158:161], v7 offset:55296
	s_setprio 2
	global_load_dwordx4 v[166:169], v8, s[36:37] offset:384
	s_waitcnt vmcnt(8)
	ds_write_b128 v2, v[90:93]
	ds_read_b128 v[90:93], v4 offset:32768
	ds_read_b128 v[170:173], v5 offset:49152
	s_waitcnt lgkmcnt(8)
	v_mfma_f32_16x16x32_bf16 v[26:29], v[94:97], v[62:65], v[26:29]
	s_waitcnt lgkmcnt(3)
	v_mfma_f32_16x16x32_bf16 v[10:13], v[158:161], v[62:65], v[10:13]
	v_mfma_f32_16x16x32_bf16 v[98:101], v[114:117], v[62:65], v[98:101]
	v_mfma_f32_16x16x32_bf16 v[102:105], v[154:157], v[62:65], v[102:105]
	global_load_dwordx4 v[62:65], v222, s[36:37] offset:384
	s_waitcnt vmcnt(8)
	ds_write_b128 v2, v[110:113] offset:4096
	ds_read_b128 v[110:113], v4 offset:34816
	ds_read_b128 v[174:177], v5 offset:51200
	v_mfma_f32_16x16x32_bf16 v[30:33], v[94:97], v[82:85], v[30:33]
	v_mfma_f32_16x16x32_bf16 v[14:17], v[158:161], v[82:85], v[14:17]
	v_mfma_f32_16x16x32_bf16 v[106:109], v[114:117], v[82:85], v[106:109]
	v_mfma_f32_16x16x32_bf16 v[118:121], v[154:157], v[82:85], v[118:121]
	global_load_dwordx4 v[82:85], v223, s[36:37] offset:384
	s_waitcnt vmcnt(8)
	ds_write_b128 v2, v[132:135] offset:8192
	ds_read_b128 v[132:135], v4 offset:36864
	ds_read_b128 v[178:181], v5 offset:53248
	v_mfma_f32_16x16x32_bf16 v[34:37], v[94:97], v[146:149], v[34:37]
	v_mfma_f32_16x16x32_bf16 v[18:21], v[158:161], v[146:149], v[18:21]
	v_mfma_f32_16x16x32_bf16 v[122:125], v[114:117], v[146:149], v[122:125]
	v_mfma_f32_16x16x32_bf16 v[126:129], v[154:157], v[146:149], v[126:129]
	global_load_dwordx4 v[146:149], v224, s[36:37] offset:384
	s_waitcnt vmcnt(8)
	ds_write_b128 v2, v[162:165] offset:12288
	ds_read_b128 v[162:165], v4 offset:38912
	ds_read_b128 v[182:185], v5 offset:55296
	v_mfma_f32_16x16x32_bf16 v[38:41], v[94:97], v[150:153], v[38:41]
	v_mfma_f32_16x16x32_bf16 v[50:53], v[114:117], v[150:153], v[50:53]
	v_mfma_f32_16x16x32_bf16 v[54:57], v[154:157], v[150:153], v[54:57]
	v_mfma_f32_16x16x32_bf16 v[22:25], v[158:161], v[150:153], v[22:25]
	global_load_dwordx4 v[94:97], v3, s[0:1] offset:384
	s_waitcnt vmcnt(8)
	ds_write_b128 v2, v[86:89] offset:16384
	s_waitcnt lgkmcnt(10)
	v_mfma_f32_16x16x32_bf16 v[26:29], v[170:173], v[90:93], v[26:29]
	s_waitcnt lgkmcnt(1)
	v_mfma_f32_16x16x32_bf16 v[10:13], v[182:185], v[90:93], v[10:13]
	v_mfma_f32_16x16x32_bf16 v[86:89], v[174:177], v[90:93], v[98:101]
	v_mfma_f32_16x16x32_bf16 v[98:101], v[178:181], v[90:93], v[102:105]
	global_load_dwordx4 v[90:93], v225, s[0:1] offset:384
	s_waitcnt vmcnt(8)
	ds_write_b128 v2, v[42:45] offset:20480
	v_mfma_f32_16x16x32_bf16 v[30:33], v[170:173], v[110:113], v[30:33]
	v_mfma_f32_16x16x32_bf16 v[42:45], v[174:177], v[110:113], v[106:109]
	v_mfma_f32_16x16x32_bf16 v[14:17], v[182:185], v[110:113], v[14:17]
	v_mfma_f32_16x16x32_bf16 v[102:105], v[178:181], v[110:113], v[118:121]
	global_load_dwordx4 v[106:109], v226, s[0:1] offset:384
	s_waitcnt vmcnt(8)
	ds_write_b128 v2, v[46:49] offset:24576
	v_mfma_f32_16x16x32_bf16 v[34:37], v[170:173], v[132:135], v[34:37]
	v_mfma_f32_16x16x32_bf16 v[46:49], v[174:177], v[132:135], v[122:125]
	v_mfma_f32_16x16x32_bf16 v[18:21], v[182:185], v[132:135], v[18:21]
	v_mfma_f32_16x16x32_bf16 v[110:113], v[178:181], v[132:135], v[126:129]
	global_load_dwordx4 v[114:117], v227, s[0:1] offset:384
	s_waitcnt vmcnt(8)
	ds_write_b128 v2, v[58:61] offset:28672
	v_mfma_f32_16x16x32_bf16 v[38:41], v[170:173], v[162:165], v[38:41]
	v_mfma_f32_16x16x32_bf16 v[50:53], v[174:177], v[162:165], v[50:53]
	v_mfma_f32_16x16x32_bf16 v[54:57], v[178:181], v[162:165], v[54:57]
	v_mfma_f32_16x16x32_bf16 v[22:25], v[182:185], v[162:165], v[22:25]
	s_setprio 0
	s_waitcnt lgkmcnt(0)
	s_barrier
; template <int MODE>
; __device__ __forceinline__ void gemm_tile(const Params& P, int tm, int tn, unsigned char* smem) {
;     ...
; #pragma unroll
;         for (int i = 0; i < 4; ++i) { fa[i] = *(const bf16x8*)(sA + arow_off + i * 2048 + ch0); fb[i] = *(const bf16x8*)(sB + brow_off + i * 2048 + ch0); }
;         __builtin_amdgcn_sched_barrier(0);
;         __builtin_amdgcn_s_setprio(2);
;         if (wr_ok) *(uint4*)(nA + soff0) = ra0;
;         if (ld_ok) ra0 = *(const uint4*)(Ab + (aoff + 0u * LDA + koa));
;         ga[0] = *(const bf16x8*)(sA + arow_off + 0 * 2048 + ch1); gb[0] = *(const bf16x8*)(sB + brow_off + 0 * 2048 + ch1);
;         __builtin_amdgcn_sched_barrier(0);
; #pragma unroll
;         for (int j = 0; j < 4; ++j) acc[0][j] = __builtin_amdgcn_mfma_f32_16x16x32_bf16(fb[j], fa[0], acc[0][j], 0, 0, 0);
;         __builtin_amdgcn_sched_barrier(0);
;         if (wr_ok) *(uint4*)(nA + soff0 + 4096) = ra1;
;         if (ld_ok) ra1 = *(const uint4*)(Ab + (aoff + 32u * LDA + koa));
;         ga[1] = *(const bf16x8*)(sA + arow_off + 1 * 2048 + ch1); gb[1] = *(const bf16x8*)(sB + brow_off + 1 * 2048 + ch1);
;         __builtin_amdgcn_sched_barrier(0);
; #pragma unroll
;         for (int j = 0; j < 4; ++j) acc[1][j] = __builtin_amdgcn_mfma_f32_16x16x32_bf16(fb[j], fa[1], acc[1][j], 0, 0, 0);
;         __builtin_amdgcn_sched_barrier(0);
;         if (wr_ok) *(uint4*)(nA + soff0 + 8192) = ra2;
;         if (ld_ok) ra2 = *(const uint4*)(Ab + (aoff + 64u * LDA + koa));
;         ga[2] = *(const bf16x8*)(sA + arow_off + 2 * 2048 + ch1); gb[2] = *(const bf16x8*)(sB + brow_off + 2 * 2048 + ch1);
;         __builtin_amdgcn_sched_barrier(0);
; #pragma unroll
;         for (int j = 0; j < 4; ++j) acc[2][j] = __builtin_amdgcn_mfma_f32_16x16x32_bf16(fb[j], fa[2], acc[2][j], 0, 0, 0);
;         __builtin_amdgcn_sched_barrier(0);
;         if (wr_ok) *(uint4*)(nA + soff0 + 12288) = ra3;
;         if (ld_ok) ra3 = *(const uint4*)(Ab + (aoff + 96u * LDA + koa));
;         ga[3] = *(const bf16x8*)(sA + arow_off + 3 * 2048 + ch1); gb[3] = *(const bf16x8*)(sB + brow_off + 3 * 2048 + ch1);
;         __builtin_amdgcn_sched_barrier(0);
; #pragma unroll
;         for (int j = 0; j < 4; ++j) acc[3][j] = __builtin_amdgcn_mfma_f32_16x16x32_bf16(fb[j], fa[3], acc[3][j], 0, 0, 0);
;         __builtin_amdgcn_sched_barrier(0);
;         if (wr_ok) *(uint4*)(nB + soff0) = rb0;
	ds_read_b128 v[58:61], v6
	ds_read_b128 v[118:121], v6 offset:2048
	ds_read_b128 v[122:125], v7 offset:16384
	ds_read_b128 v[126:129], v7 offset:18432
	ds_read_b128 v[132:135], v6 offset:4096
	ds_read_b128 v[150:153], v6 offset:6144
	ds_read_b128 v[154:157], v7 offset:20480
	ds_read_b128 v[158:161], v7 offset:22528
	s_setprio 2
	global_load_dwordx4 v[162:165], v8, s[36:37] offset:512
	s_waitcnt vmcnt(8)
	ds_write_b128 v2, v[166:169] offset:32768
	ds_read_b128 v[166:169], v4
	ds_read_b128 v[170:173], v5 offset:16384
	s_waitcnt lgkmcnt(8)
	v_mfma_f32_16x16x32_bf16 v[26:29], v[122:125], v[58:61], v[26:29]
	s_waitcnt lgkmcnt(3)
	v_mfma_f32_16x16x32_bf16 v[10:13], v[158:161], v[58:61], v[10:13]
	v_mfma_f32_16x16x32_bf16 v[86:89], v[126:129], v[58:61], v[86:89]
	v_mfma_f32_16x16x32_bf16 v[98:101], v[154:157], v[58:61], v[98:101]
	global_load_dwordx4 v[58:61], v222, s[36:37] offset:512
	s_waitcnt vmcnt(8)
	ds_write_b128 v2, v[62:65] offset:36864
	ds_read_b128 v[62:65], v4 offset:2048
	ds_read_b128 v[174:177], v5 offset:18432
	v_mfma_f32_16x16x32_bf16 v[30:33], v[122:125], v[118:121], v[30:33]
	v_mfma_f32_16x16x32_bf16 v[42:45], v[126:129], v[118:121], v[42:45]
	v_mfma_f32_16x16x32_bf16 v[14:17], v[158:161], v[118:121], v[14:17]
	v_mfma_f32_16x16x32_bf16 v[102:105], v[154:157], v[118:121], v[102:105]
	global_load_dwordx4 v[118:121], v223, s[36:37] offset:512
	s_waitcnt vmcnt(8)
	ds_write_b128 v2, v[82:85] offset:40960
	ds_read_b128 v[82:85], v4 offset:4096
	ds_read_b128 v[178:181], v5 offset:20480
	v_mfma_f32_16x16x32_bf16 v[34:37], v[122:125], v[132:135], v[34:37]
	v_mfma_f32_16x16x32_bf16 v[46:49], v[126:129], v[132:135], v[46:49]
	v_mfma_f32_16x16x32_bf16 v[18:21], v[158:161], v[132:135], v[18:21]
	v_mfma_f32_16x16x32_bf16 v[110:113], v[154:157], v[132:135], v[110:113]
	global_load_dwordx4 v[132:135], v224, s[36:37] offset:512
	s_waitcnt vmcnt(8)
	ds_write_b128 v2, v[146:149] offset:45056
	ds_read_b128 v[146:149], v4 offset:6144
	ds_read_b128 v[182:185], v5 offset:22528
	v_mfma_f32_16x16x32_bf16 v[38:41], v[122:125], v[150:153], v[38:41]
	v_mfma_f32_16x16x32_bf16 v[50:53], v[126:129], v[150:153], v[50:53]
	v_mfma_f32_16x16x32_bf16 v[54:57], v[154:157], v[150:153], v[54:57]
	v_mfma_f32_16x16x32_bf16 v[22:25], v[158:161], v[150:153], v[22:25]
	global_load_dwordx4 v[122:125], v3, s[0:1] offset:512
	s_waitcnt vmcnt(8)
	ds_write_b128 v2, v[94:97] offset:49152
	s_waitcnt lgkmcnt(10)
	v_mfma_f32_16x16x32_bf16 v[26:29], v[170:173], v[166:169], v[26:29]
	s_waitcnt lgkmcnt(1)
	v_mfma_f32_16x16x32_bf16 v[10:13], v[182:185], v[166:169], v[10:13]
	v_mfma_f32_16x16x32_bf16 v[86:89], v[174:177], v[166:169], v[86:89]
	v_mfma_f32_16x16x32_bf16 v[94:97], v[178:181], v[166:169], v[98:101]
	global_load_dwordx4 v[98:101], v225, s[0:1] offset:512
	s_waitcnt vmcnt(8)
	ds_write_b128 v2, v[90:93] offset:53248
	v_mfma_f32_16x16x32_bf16 v[30:33], v[170:173], v[62:65], v[30:33]
	v_mfma_f32_16x16x32_bf16 v[42:45], v[174:177], v[62:65], v[42:45]
	v_mfma_f32_16x16x32_bf16 v[14:17], v[182:185], v[62:65], v[14:17]
	v_mfma_f32_16x16x32_bf16 v[90:93], v[178:181], v[62:65], v[102:105]
	global_load_dwordx4 v[62:65], v226, s[0:1] offset:512
	s_waitcnt vmcnt(8)
	ds_write_b128 v2, v[106:109] offset:57344
	v_mfma_f32_16x16x32_bf16 v[34:37], v[170:173], v[82:85], v[34:37]
	v_mfma_f32_16x16x32_bf16 v[46:49], v[174:177], v[82:85], v[46:49]
	v_mfma_f32_16x16x32_bf16 v[18:21], v[182:185], v[82:85], v[18:21]
	v_mfma_f32_16x16x32_bf16 v[102:105], v[178:181], v[82:85], v[110:113]
	global_load_dwordx4 v[82:85], v227, s[0:1] offset:512
	s_waitcnt vmcnt(8)
	ds_write_b128 v2, v[114:117] offset:61440
	v_mfma_f32_16x16x32_bf16 v[38:41], v[170:173], v[146:149], v[38:41]
	v_mfma_f32_16x16x32_bf16 v[50:53], v[174:177], v[146:149], v[50:53]
	v_mfma_f32_16x16x32_bf16 v[54:57], v[178:181], v[146:149], v[54:57]
	v_mfma_f32_16x16x32_bf16 v[22:25], v[182:185], v[146:149], v[22:25]
	s_setprio 0
	s_waitcnt lgkmcnt(0)
	s_barrier
	ds_read_b128 v[106:109], v6 offset:32768
	ds_read_b128 v[110:113], v6 offset:34816
	ds_read_b128 v[114:117], v7 offset:49152
	ds_read_b128 v[126:129], v7 offset:51200
	ds_read_b128 v[146:149], v6 offset:36864
	ds_read_b128 v[150:153], v6 offset:38912
	ds_read_b128 v[154:157], v7 offset:53248
	ds_read_b128 v[158:161], v7 offset:55296
	s_setprio 2
	global_load_dwordx4 v[166:169], v8, s[36:37] offset:640
	s_waitcnt vmcnt(8)
	ds_write_b128 v2, v[162:165]
	ds_read_b128 v[162:165], v4 offset:32768
	ds_read_b128 v[170:173], v5 offset:49152
	s_waitcnt lgkmcnt(8)
	v_mfma_f32_16x16x32_bf16 v[26:29], v[114:117], v[106:109], v[26:29]
	s_waitcnt lgkmcnt(3)
	v_mfma_f32_16x16x32_bf16 v[10:13], v[158:161], v[106:109], v[10:13]
	v_mfma_f32_16x16x32_bf16 v[86:89], v[126:129], v[106:109], v[86:89]
	v_mfma_f32_16x16x32_bf16 v[94:97], v[154:157], v[106:109], v[94:97]
	global_load_dwordx4 v[106:109], v222, s[36:37] offset:640
	s_waitcnt vmcnt(8)
	ds_write_b128 v2, v[58:61] offset:4096
	ds_read_b128 v[58:61], v4 offset:34816
	ds_read_b128 v[174:177], v5 offset:51200
	v_mfma_f32_16x16x32_bf16 v[30:33], v[114:117], v[110:113], v[30:33]
	v_mfma_f32_16x16x32_bf16 v[42:45], v[126:129], v[110:113], v[42:45]
	v_mfma_f32_16x16x32_bf16 v[14:17], v[158:161], v[110:113], v[14:17]
	v_mfma_f32_16x16x32_bf16 v[90:93], v[154:157], v[110:113], v[90:93]
	global_load_dwordx4 v[110:113], v223, s[36:37] offset:640
	s_waitcnt vmcnt(8)
	ds_write_b128 v2, v[118:121] offset:8192
	ds_read_b128 v[118:121], v4 offset:36864
	ds_read_b128 v[178:181], v5 offset:53248
	v_mfma_f32_16x16x32_bf16 v[34:37], v[114:117], v[146:149], v[34:37]
	v_mfma_f32_16x16x32_bf16 v[46:49], v[126:129], v[146:149], v[46:49]
	v_mfma_f32_16x16x32_bf16 v[18:21], v[158:161], v[146:149], v[18:21]
	v_mfma_f32_16x16x32_bf16 v[102:105], v[154:157], v[146:149], v[102:105]
	global_load_dwordx4 v[146:149], v224, s[36:37] offset:640
	s_waitcnt vmcnt(8)
; template <int MODE>
; __device__ __forceinline__ void gemm_tile(const Params& P, int tm, int tn, unsigned char* smem) {
;     ...
; #pragma unroll
;         for (int i = 0; i < 4; ++i) { fa[i] = *(const bf16x8*)(sA + arow_off + i * 2048 + ch0); fb[i] = *(const bf16x8*)(sB + brow_off + i * 2048 + ch0); }
;         __builtin_amdgcn_sched_barrier(0);
;         __builtin_amdgcn_s_setprio(2);
;         if (wr_ok) *(uint4*)(nA + soff0) = ra0;
;         if (ld_ok) ra0 = *(const uint4*)(Ab + (aoff + 0u * LDA + koa));
;         ga[0] = *(const bf16x8*)(sA + arow_off + 0 * 2048 + ch1); gb[0] = *(const bf16x8*)(sB + brow_off + 0 * 2048 + ch1);
;         __builtin_amdgcn_sched_barrier(0);
; #pragma unroll
;         for (int j = 0; j < 4; ++j) acc[0][j] = __builtin_amdgcn_mfma_f32_16x16x32_bf16(fb[j], fa[0], acc[0][j], 0, 0, 0);
;         __builtin_amdgcn_sched_barrier(0);
;         if (wr_ok) *(uint4*)(nA + soff0 + 4096) = ra1;
;         if (ld_ok) ra1 = *(const uint4*)(Ab + (aoff + 32u * LDA + koa));
;         ga[1] = *(const bf16x8*)(sA + arow_off + 1 * 2048 + ch1); gb[1] = *(const bf16x8*)(sB + brow_off + 1 * 2048 + ch1);
;         __builtin_amdgcn_sched_barrier(0);
; #pragma unroll
;         for (int j = 0; j < 4; ++j) acc[1][j] = __builtin_amdgcn_mfma_f32_16x16x32_bf16(fb[j], fa[1], acc[1][j], 0, 0, 0);
;         __builtin_amdgcn_sched_barrier(0);
;         if (wr_ok) *(uint4*)(nA + soff0 + 8192) = ra2;
;         if (ld_ok) ra2 = *(const uint4*)(Ab + (aoff + 64u * LDA + koa));
;         ga[2] = *(const bf16x8*)(sA + arow_off + 2 * 2048 + ch1); gb[2] = *(const bf16x8*)(sB + brow_off + 2 * 2048 + ch1);
;         __builtin_amdgcn_sched_barrier(0);
; #pragma unroll
;         for (int j = 0; j < 4; ++j) acc[2][j] = __builtin_amdgcn_mfma_f32_16x16x32_bf16(fb[j], fa[2], acc[2][j], 0, 0, 0);
;         __builtin_amdgcn_sched_barrier(0);
;         if (wr_ok) *(uint4*)(nA + soff0 + 12288) = ra3;
;         if (ld_ok) ra3 = *(const uint4*)(Ab + (aoff + 96u * LDA + koa));
;         ga[3] = *(const bf16x8*)(sA + arow_off + 3 * 2048 + ch1); gb[3] = *(const bf16x8*)(sB + brow_off + 3 * 2048 + ch1);
;         __builtin_amdgcn_sched_barrier(0);
; #pragma unroll
;         for (int j = 0; j < 4; ++j) acc[3][j] = __builtin_amdgcn_mfma_f32_16x16x32_bf16(fb[j], fa[3], acc[3][j], 0, 0, 0);
;         __builtin_amdgcn_sched_barrier(0);
;         if (wr_ok) *(uint4*)(nB + soff0) = rb0;
	ds_write_b128 v2, v[132:135] offset:12288
	ds_read_b128 v[132:135], v4 offset:38912
	ds_read_b128 v[182:185], v5 offset:55296
	v_mfma_f32_16x16x32_bf16 v[38:41], v[114:117], v[150:153], v[38:41]
	v_mfma_f32_16x16x32_bf16 v[50:53], v[126:129], v[150:153], v[50:53]
	v_mfma_f32_16x16x32_bf16 v[54:57], v[154:157], v[150:153], v[54:57]
	v_mfma_f32_16x16x32_bf16 v[22:25], v[158:161], v[150:153], v[22:25]
	global_load_dwordx4 v[114:117], v3, s[0:1] offset:640
	s_waitcnt vmcnt(8)
	ds_write_b128 v2, v[122:125] offset:16384
	s_waitcnt lgkmcnt(10)
	v_mfma_f32_16x16x32_bf16 v[26:29], v[170:173], v[162:165], v[26:29]
	s_waitcnt lgkmcnt(1)
	v_mfma_f32_16x16x32_bf16 v[10:13], v[182:185], v[162:165], v[10:13]
	v_mfma_f32_16x16x32_bf16 v[86:89], v[174:177], v[162:165], v[86:89]
	v_mfma_f32_16x16x32_bf16 v[94:97], v[178:181], v[162:165], v[94:97]
	global_load_dwordx4 v[122:125], v225, s[0:1] offset:640
	s_waitcnt vmcnt(8)
	ds_write_b128 v2, v[98:101] offset:20480
	v_mfma_f32_16x16x32_bf16 v[30:33], v[170:173], v[58:61], v[30:33]
	v_mfma_f32_16x16x32_bf16 v[42:45], v[174:177], v[58:61], v[42:45]
	v_mfma_f32_16x16x32_bf16 v[14:17], v[182:185], v[58:61], v[14:17]
	v_mfma_f32_16x16x32_bf16 v[90:93], v[178:181], v[58:61], v[90:93]
	global_load_dwordx4 v[58:61], v226, s[0:1] offset:640
	s_waitcnt vmcnt(8)
	ds_write_b128 v2, v[62:65] offset:24576
	v_mfma_f32_16x16x32_bf16 v[34:37], v[170:173], v[118:121], v[34:37]
	v_mfma_f32_16x16x32_bf16 v[46:49], v[174:177], v[118:121], v[46:49]
	v_mfma_f32_16x16x32_bf16 v[62:65], v[178:181], v[118:121], v[102:105]
	v_mfma_f32_16x16x32_bf16 v[18:21], v[182:185], v[118:121], v[18:21]
	global_load_dwordx4 v[98:101], v227, s[0:1] offset:640
	s_waitcnt vmcnt(8)
	ds_write_b128 v2, v[82:85] offset:28672
	v_mfma_f32_16x16x32_bf16 v[38:41], v[170:173], v[132:135], v[38:41]
	v_mfma_f32_16x16x32_bf16 v[50:53], v[174:177], v[132:135], v[50:53]
	v_mfma_f32_16x16x32_bf16 v[54:57], v[178:181], v[132:135], v[54:57]
	v_mfma_f32_16x16x32_bf16 v[22:25], v[182:185], v[132:135], v[22:25]
	s_setprio 0
	s_waitcnt lgkmcnt(0)
	s_barrier
	ds_read_b128 v[82:85], v6
	ds_read_b128 v[102:105], v6 offset:2048
	ds_read_b128 v[118:121], v7 offset:16384
	ds_read_b128 v[126:129], v7 offset:18432
	ds_read_b128 v[132:135], v6 offset:4096
	ds_read_b128 v[150:153], v6 offset:6144
	ds_read_b128 v[154:157], v7 offset:20480
	ds_read_b128 v[158:161], v7 offset:22528
	s_setprio 2
	global_load_dwordx4 v[162:165], v8, s[36:37] offset:768
	s_waitcnt vmcnt(8)
	ds_write_b128 v2, v[166:169] offset:32768
	ds_read_b128 v[166:169], v4
	ds_read_b128 v[170:173], v5 offset:16384
	s_waitcnt lgkmcnt(8)
	v_mfma_f32_16x16x32_bf16 v[26:29], v[118:121], v[82:85], v[26:29]
	s_waitcnt lgkmcnt(3)
	v_mfma_f32_16x16x32_bf16 v[10:13], v[158:161], v[82:85], v[10:13]
	v_mfma_f32_16x16x32_bf16 v[86:89], v[126:129], v[82:85], v[86:89]
	v_mfma_f32_16x16x32_bf16 v[94:97], v[154:157], v[82:85], v[94:97]
	global_load_dwordx4 v[82:85], v222, s[36:37] offset:768
	s_waitcnt vmcnt(8)
	ds_write_b128 v2, v[106:109] offset:36864
	ds_read_b128 v[106:109], v4 offset:2048
	ds_read_b128 v[174:177], v5 offset:18432
	v_mfma_f32_16x16x32_bf16 v[30:33], v[118:121], v[102:105], v[30:33]
	v_mfma_f32_16x16x32_bf16 v[42:45], v[126:129], v[102:105], v[42:45]
	v_mfma_f32_16x16x32_bf16 v[14:17], v[158:161], v[102:105], v[14:17]
	v_mfma_f32_16x16x32_bf16 v[90:93], v[154:157], v[102:105], v[90:93]
	global_load_dwordx4 v[102:105], v223, s[36:37] offset:768
	s_waitcnt vmcnt(8)
	ds_write_b128 v2, v[110:113] offset:40960
	ds_read_b128 v[110:113], v4 offset:4096
	ds_read_b128 v[178:181], v5 offset:20480
	v_mfma_f32_16x16x32_bf16 v[34:37], v[118:121], v[132:135], v[34:37]
	v_mfma_f32_16x16x32_bf16 v[46:49], v[126:129], v[132:135], v[46:49]
	v_mfma_f32_16x16x32_bf16 v[62:65], v[154:157], v[132:135], v[62:65]
	v_mfma_f32_16x16x32_bf16 v[18:21], v[158:161], v[132:135], v[18:21]
	global_load_dwordx4 v[132:135], v224, s[36:37] offset:768
	s_waitcnt vmcnt(8)
	ds_write_b128 v2, v[146:149] offset:45056
	ds_read_b128 v[146:149], v4 offset:6144
	ds_read_b128 v[182:185], v5 offset:22528
	v_mfma_f32_16x16x32_bf16 v[38:41], v[118:121], v[150:153], v[38:41]
	v_mfma_f32_16x16x32_bf16 v[50:53], v[126:129], v[150:153], v[50:53]
	v_mfma_f32_16x16x32_bf16 v[54:57], v[154:157], v[150:153], v[54:57]
	v_mfma_f32_16x16x32_bf16 v[22:25], v[158:161], v[150:153], v[22:25]
	global_load_dwordx4 v[118:121], v3, s[0:1] offset:768
	s_waitcnt vmcnt(8)
	ds_write_b128 v2, v[114:117] offset:49152
	s_waitcnt lgkmcnt(10)
	v_mfma_f32_16x16x32_bf16 v[26:29], v[170:173], v[166:169], v[26:29]
	s_waitcnt lgkmcnt(1)
	v_mfma_f32_16x16x32_bf16 v[10:13], v[182:185], v[166:169], v[10:13]
	v_mfma_f32_16x16x32_bf16 v[86:89], v[174:177], v[166:169], v[86:89]
	v_mfma_f32_16x16x32_bf16 v[94:97], v[178:181], v[166:169], v[94:97]
	global_load_dwordx4 v[114:117], v225, s[0:1] offset:768
	s_waitcnt vmcnt(8)
	ds_write_b128 v2, v[122:125] offset:53248
	v_mfma_f32_16x16x32_bf16 v[30:33], v[170:173], v[106:109], v[30:33]
	v_mfma_f32_16x16x32_bf16 v[42:45], v[174:177], v[106:109], v[42:45]
	v_mfma_f32_16x16x32_bf16 v[14:17], v[182:185], v[106:109], v[14:17]
	v_mfma_f32_16x16x32_bf16 v[90:93], v[178:181], v[106:109], v[90:93]
	global_load_dwordx4 v[106:109], v226, s[0:1] offset:768
	s_waitcnt vmcnt(8)
	ds_write_b128 v2, v[58:61] offset:57344
	v_mfma_f32_16x16x32_bf16 v[34:37], v[170:173], v[110:113], v[34:37]
	v_mfma_f32_16x16x32_bf16 v[46:49], v[174:177], v[110:113], v[46:49]
	v_mfma_f32_16x16x32_bf16 v[58:61], v[178:181], v[110:113], v[62:65]
	v_mfma_f32_16x16x32_bf16 v[18:21], v[182:185], v[110:113], v[18:21]
	global_load_dwordx4 v[62:65], v227, s[0:1] offset:768
	s_waitcnt vmcnt(8)
	ds_write_b128 v2, v[98:101] offset:61440
	v_mfma_f32_16x16x32_bf16 v[38:41], v[170:173], v[146:149], v[38:41]
	v_mfma_f32_16x16x32_bf16 v[50:53], v[174:177], v[146:149], v[50:53]
	v_mfma_f32_16x16x32_bf16 v[54:57], v[178:181], v[146:149], v[54:57]
	v_mfma_f32_16x16x32_bf16 v[22:25], v[182:185], v[146:149], v[22:25]
	s_setprio 0
	s_waitcnt lgkmcnt(0)
	s_barrier
; template <int MODE>
; __device__ __forceinline__ void gemm_tile(const Params& P, int tm, int tn, unsigned char* smem) {
;     ...
; #pragma unroll
;         for (int i = 0; i < 4; ++i) { fa[i] = *(const bf16x8*)(sA + arow_off + i * 2048 + ch0); fb[i] = *(const bf16x8*)(sB + brow_off + i * 2048 + ch0); }
;         __builtin_amdgcn_sched_barrier(0);
;         __builtin_amdgcn_s_setprio(2);
;         if (wr_ok) *(uint4*)(nA + soff0) = ra0;
;         if (ld_ok) ra0 = *(const uint4*)(Ab + (aoff + 0u * LDA + koa));
;         ga[0] = *(const bf16x8*)(sA + arow_off + 0 * 2048 + ch1); gb[0] = *(const bf16x8*)(sB + brow_off + 0 * 2048 + ch1);
;         __builtin_amdgcn_sched_barrier(0);
; #pragma unroll
;         for (int j = 0; j < 4; ++j) acc[0][j] = __builtin_amdgcn_mfma_f32_16x16x32_bf16(fb[j], fa[0], acc[0][j], 0, 0, 0);
;         __builtin_amdgcn_sched_barrier(0);
;         if (wr_ok) *(uint4*)(nA + soff0 + 4096) = ra1;
;         if (ld_ok) ra1 = *(const uint4*)(Ab + (aoff + 32u * LDA + koa));
;         ga[1] = *(const bf16x8*)(sA + arow_off + 1 * 2048 + ch1); gb[1] = *(const bf16x8*)(sB + brow_off + 1 * 2048 + ch1);
;         __builtin_amdgcn_sched_barrier(0);
; #pragma unroll
;         for (int j = 0; j < 4; ++j) acc[1][j] = __builtin_amdgcn_mfma_f32_16x16x32_bf16(fb[j], fa[1], acc[1][j], 0, 0, 0);
;         __builtin_amdgcn_sched_barrier(0);
;         if (wr_ok) *(uint4*)(nA + soff0 + 8192) = ra2;
;         if (ld_ok) ra2 = *(const uint4*)(Ab + (aoff + 64u * LDA + koa));
;         ga[2] = *(const bf16x8*)(sA + arow_off + 2 * 2048 + ch1); gb[2] = *(const bf16x8*)(sB + brow_off + 2 * 2048 + ch1);
;         __builtin_amdgcn_sched_barrier(0);
; #pragma unroll
;         for (int j = 0; j < 4; ++j) acc[2][j] = __builtin_amdgcn_mfma_f32_16x16x32_bf16(fb[j], fa[2], acc[2][j], 0, 0, 0);
;         __builtin_amdgcn_sched_barrier(0);
;         if (wr_ok) *(uint4*)(nA + soff0 + 12288) = ra3;
;         if (ld_ok) ra3 = *(const uint4*)(Ab + (aoff + 96u * LDA + koa));
;         ga[3] = *(const bf16x8*)(sA + arow_off + 3 * 2048 + ch1); gb[3] = *(const bf16x8*)(sB + brow_off + 3 * 2048 + ch1);
;         __builtin_amdgcn_sched_barrier(0);
; #pragma unroll
;         for (int j = 0; j < 4; ++j) acc[3][j] = __builtin_amdgcn_mfma_f32_16x16x32_bf16(fb[j], fa[3], acc[3][j], 0, 0, 0);
;         __builtin_amdgcn_sched_barrier(0);
;         if (wr_ok) *(uint4*)(nB + soff0) = rb0;
	ds_read_b128 v[98:101], v6 offset:32768
	ds_read_b128 v[110:113], v6 offset:34816
	ds_read_b128 v[122:125], v7 offset:49152
	ds_read_b128 v[126:129], v7 offset:51200
	ds_read_b128 v[146:149], v6 offset:36864
	ds_read_b128 v[150:153], v6 offset:38912
	ds_read_b128 v[154:157], v7 offset:53248
	ds_read_b128 v[158:161], v7 offset:55296
	s_setprio 2
	global_load_dwordx4 v[166:169], v8, s[36:37] offset:896
	s_waitcnt vmcnt(8)
	ds_write_b128 v2, v[162:165]
	ds_read_b128 v[162:165], v4 offset:32768
	ds_read_b128 v[170:173], v5 offset:49152
	s_waitcnt lgkmcnt(8)
	v_mfma_f32_16x16x32_bf16 v[26:29], v[122:125], v[98:101], v[26:29]
	s_waitcnt lgkmcnt(3)
	v_mfma_f32_16x16x32_bf16 v[10:13], v[158:161], v[98:101], v[10:13]
	v_mfma_f32_16x16x32_bf16 v[86:89], v[126:129], v[98:101], v[86:89]
	v_mfma_f32_16x16x32_bf16 v[94:97], v[154:157], v[98:101], v[94:97]
	global_load_dwordx4 v[98:101], v222, s[36:37] offset:896
	s_waitcnt vmcnt(8)
	ds_write_b128 v2, v[82:85] offset:4096
	ds_read_b128 v[82:85], v4 offset:34816
	ds_read_b128 v[174:177], v5 offset:51200
	v_mfma_f32_16x16x32_bf16 v[30:33], v[122:125], v[110:113], v[30:33]
	v_mfma_f32_16x16x32_bf16 v[42:45], v[126:129], v[110:113], v[42:45]
	v_mfma_f32_16x16x32_bf16 v[14:17], v[158:161], v[110:113], v[14:17]
	v_mfma_f32_16x16x32_bf16 v[90:93], v[154:157], v[110:113], v[90:93]
	global_load_dwordx4 v[110:113], v223, s[36:37] offset:896
	s_waitcnt vmcnt(8)
	ds_write_b128 v2, v[102:105] offset:8192
	ds_read_b128 v[102:105], v4 offset:36864
	ds_read_b128 v[178:181], v5 offset:53248
	v_mfma_f32_16x16x32_bf16 v[34:37], v[122:125], v[146:149], v[34:37]
	v_mfma_f32_16x16x32_bf16 v[46:49], v[126:129], v[146:149], v[46:49]
	v_mfma_f32_16x16x32_bf16 v[58:61], v[154:157], v[146:149], v[58:61]
	v_mfma_f32_16x16x32_bf16 v[18:21], v[158:161], v[146:149], v[18:21]
	global_load_dwordx4 v[146:149], v224, s[36:37] offset:896
	s_waitcnt vmcnt(8)
	ds_write_b128 v2, v[132:135] offset:12288
	ds_read_b128 v[132:135], v4 offset:38912
	ds_read_b128 v[182:185], v5 offset:55296
	v_mfma_f32_16x16x32_bf16 v[38:41], v[122:125], v[150:153], v[38:41]
	v_mfma_f32_16x16x32_bf16 v[50:53], v[126:129], v[150:153], v[50:53]
	v_mfma_f32_16x16x32_bf16 v[54:57], v[154:157], v[150:153], v[54:57]
	v_mfma_f32_16x16x32_bf16 v[22:25], v[158:161], v[150:153], v[22:25]
	global_load_dwordx4 v[122:125], v3, s[0:1] offset:896
	s_waitcnt vmcnt(8)
	ds_write_b128 v2, v[118:121] offset:16384
	s_waitcnt lgkmcnt(10)
	v_mfma_f32_16x16x32_bf16 v[26:29], v[170:173], v[162:165], v[26:29]
	s_waitcnt lgkmcnt(1)
	v_mfma_f32_16x16x32_bf16 v[10:13], v[182:185], v[162:165], v[10:13]
	v_mfma_f32_16x16x32_bf16 v[86:89], v[174:177], v[162:165], v[86:89]
	v_mfma_f32_16x16x32_bf16 v[94:97], v[178:181], v[162:165], v[94:97]
	global_load_dwordx4 v[118:121], v225, s[0:1] offset:896
	s_waitcnt vmcnt(8)
	ds_write_b128 v2, v[114:117] offset:20480
	v_mfma_f32_16x16x32_bf16 v[30:33], v[170:173], v[82:85], v[30:33]
	v_mfma_f32_16x16x32_bf16 v[42:45], v[174:177], v[82:85], v[42:45]
	v_mfma_f32_16x16x32_bf16 v[14:17], v[182:185], v[82:85], v[14:17]
	v_mfma_f32_16x16x32_bf16 v[90:93], v[178:181], v[82:85], v[90:93]
	global_load_dwordx4 v[82:85], v226, s[0:1] offset:896
	s_waitcnt vmcnt(8)
	ds_write_b128 v2, v[106:109] offset:24576
	v_mfma_f32_16x16x32_bf16 v[34:37], v[170:173], v[102:105], v[34:37]
	v_mfma_f32_16x16x32_bf16 v[46:49], v[174:177], v[102:105], v[46:49]
	v_mfma_f32_16x16x32_bf16 v[58:61], v[178:181], v[102:105], v[58:61]
	v_mfma_f32_16x16x32_bf16 v[18:21], v[182:185], v[102:105], v[18:21]
	global_load_dwordx4 v[102:105], v227, s[0:1] offset:896
	s_waitcnt vmcnt(8)
	ds_write_b128 v2, v[62:65] offset:28672
	v_mfma_f32_16x16x32_bf16 v[38:41], v[170:173], v[132:135], v[38:41]
	v_mfma_f32_16x16x32_bf16 v[50:53], v[174:177], v[132:135], v[50:53]
	v_mfma_f32_16x16x32_bf16 v[54:57], v[178:181], v[132:135], v[54:57]
	v_mfma_f32_16x16x32_bf16 v[22:25], v[182:185], v[132:135], v[22:25]
	s_setprio 0
	s_waitcnt lgkmcnt(0)
	s_barrier
	ds_read_b128 v[62:65], v6
	ds_read_b128 v[106:109], v6 offset:2048
	ds_read_b128 v[114:117], v7 offset:16384
	ds_read_b128 v[126:129], v7 offset:18432
	ds_read_b128 v[132:135], v6 offset:4096
	ds_read_b128 v[150:153], v6 offset:6144
	ds_read_b128 v[154:157], v7 offset:20480
	ds_read_b128 v[158:161], v7 offset:22528
	s_setprio 2
	global_load_dwordx4 v[162:165], v8, s[36:37] offset:1024
	s_waitcnt vmcnt(8)
	ds_write_b128 v2, v[166:169] offset:32768
	ds_read_b128 v[166:169], v4
	ds_read_b128 v[170:173], v5 offset:16384
	s_waitcnt lgkmcnt(8)
	v_mfma_f32_16x16x32_bf16 v[26:29], v[114:117], v[62:65], v[26:29]
	s_waitcnt lgkmcnt(3)
	v_mfma_f32_16x16x32_bf16 v[10:13], v[158:161], v[62:65], v[10:13]
	v_mfma_f32_16x16x32_bf16 v[86:89], v[126:129], v[62:65], v[86:89]
	v_mfma_f32_16x16x32_bf16 v[94:97], v[154:157], v[62:65], v[94:97]
	global_load_dwordx4 v[62:65], v222, s[36:37] offset:1024
	s_waitcnt vmcnt(8)
	ds_write_b128 v2, v[98:101] offset:36864
	ds_read_b128 v[98:101], v4 offset:2048
	ds_read_b128 v[174:177], v5 offset:18432
	v_mfma_f32_16x16x32_bf16 v[30:33], v[114:117], v[106:109], v[30:33]
	v_mfma_f32_16x16x32_bf16 v[42:45], v[126:129], v[106:109], v[42:45]
	v_mfma_f32_16x16x32_bf16 v[14:17], v[158:161], v[106:109], v[14:17]
	v_mfma_f32_16x16x32_bf16 v[90:93], v[154:157], v[106:109], v[90:93]
	global_load_dwordx4 v[106:109], v223, s[36:37] offset:1024
	s_waitcnt vmcnt(8)
	ds_write_b128 v2, v[110:113] offset:40960
	ds_read_b128 v[110:113], v4 offset:4096
	ds_read_b128 v[178:181], v5 offset:20480
	v_mfma_f32_16x16x32_bf16 v[34:37], v[114:117], v[132:135], v[34:37]
	v_mfma_f32_16x16x32_bf16 v[46:49], v[126:129], v[132:135], v[46:49]
	v_mfma_f32_16x16x32_bf16 v[58:61], v[154:157], v[132:135], v[58:61]
	v_mfma_f32_16x16x32_bf16 v[18:21], v[158:161], v[132:135], v[18:21]
	global_load_dwordx4 v[132:135], v224, s[36:37] offset:1024
	s_waitcnt vmcnt(8)
; template <int MODE>
; __device__ __forceinline__ void gemm_tile(const Params& P, int tm, int tn, unsigned char* smem) {
;     ...
; #pragma unroll
;         for (int i = 0; i < 4; ++i) { fa[i] = *(const bf16x8*)(sA + arow_off + i * 2048 + ch0); fb[i] = *(const bf16x8*)(sB + brow_off + i * 2048 + ch0); }
;         __builtin_amdgcn_sched_barrier(0);
;         __builtin_amdgcn_s_setprio(2);
;         if (wr_ok) *(uint4*)(nA + soff0) = ra0;
;         if (ld_ok) ra0 = *(const uint4*)(Ab + (aoff + 0u * LDA + koa));
;         ga[0] = *(const bf16x8*)(sA + arow_off + 0 * 2048 + ch1); gb[0] = *(const bf16x8*)(sB + brow_off + 0 * 2048 + ch1);
;         __builtin_amdgcn_sched_barrier(0);
; #pragma unroll
;         for (int j = 0; j < 4; ++j) acc[0][j] = __builtin_amdgcn_mfma_f32_16x16x32_bf16(fb[j], fa[0], acc[0][j], 0, 0, 0);
;         __builtin_amdgcn_sched_barrier(0);
;         if (wr_ok) *(uint4*)(nA + soff0 + 4096) = ra1;
;         if (ld_ok) ra1 = *(const uint4*)(Ab + (aoff + 32u * LDA + koa));
;         ga[1] = *(const bf16x8*)(sA + arow_off + 1 * 2048 + ch1); gb[1] = *(const bf16x8*)(sB + brow_off + 1 * 2048 + ch1);
;         __builtin_amdgcn_sched_barrier(0);
; #pragma unroll
;         for (int j = 0; j < 4; ++j) acc[1][j] = __builtin_amdgcn_mfma_f32_16x16x32_bf16(fb[j], fa[1], acc[1][j], 0, 0, 0);
;         __builtin_amdgcn_sched_barrier(0);
;         if (wr_ok) *(uint4*)(nA + soff0 + 8192) = ra2;
;         if (ld_ok) ra2 = *(const uint4*)(Ab + (aoff + 64u * LDA + koa));
;         ga[2] = *(const bf16x8*)(sA + arow_off + 2 * 2048 + ch1); gb[2] = *(const bf16x8*)(sB + brow_off + 2 * 2048 + ch1);
;         __builtin_amdgcn_sched_barrier(0);
; #pragma unroll
;         for (int j = 0; j < 4; ++j) acc[2][j] = __builtin_amdgcn_mfma_f32_16x16x32_bf16(fb[j], fa[2], acc[2][j], 0, 0, 0);
;         __builtin_amdgcn_sched_barrier(0);
;         if (wr_ok) *(uint4*)(nA + soff0 + 12288) = ra3;
;         if (ld_ok) ra3 = *(const uint4*)(Ab + (aoff + 96u * LDA + koa));
;         ga[3] = *(const bf16x8*)(sA + arow_off + 3 * 2048 + ch1); gb[3] = *(const bf16x8*)(sB + brow_off + 3 * 2048 + ch1);
;         __builtin_amdgcn_sched_barrier(0);
; #pragma unroll
;         for (int j = 0; j < 4; ++j) acc[3][j] = __builtin_amdgcn_mfma_f32_16x16x32_bf16(fb[j], fa[3], acc[3][j], 0, 0, 0);
;         __builtin_amdgcn_sched_barrier(0);
;         if (wr_ok) *(uint4*)(nB + soff0) = rb0;
	ds_write_b128 v2, v[146:149] offset:45056
	ds_read_b128 v[146:149], v4 offset:6144
	ds_read_b128 v[182:185], v5 offset:22528
	v_mfma_f32_16x16x32_bf16 v[38:41], v[114:117], v[150:153], v[38:41]
	v_mfma_f32_16x16x32_bf16 v[50:53], v[126:129], v[150:153], v[50:53]
	v_mfma_f32_16x16x32_bf16 v[54:57], v[154:157], v[150:153], v[54:57]
	v_mfma_f32_16x16x32_bf16 v[22:25], v[158:161], v[150:153], v[22:25]
	global_load_dwordx4 v[114:117], v3, s[0:1] offset:1024
	s_waitcnt vmcnt(8)
	ds_write_b128 v2, v[122:125] offset:49152
	s_waitcnt lgkmcnt(10)
	v_mfma_f32_16x16x32_bf16 v[26:29], v[170:173], v[166:169], v[26:29]
	s_waitcnt lgkmcnt(1)
	v_mfma_f32_16x16x32_bf16 v[10:13], v[182:185], v[166:169], v[10:13]
	v_mfma_f32_16x16x32_bf16 v[86:89], v[174:177], v[166:169], v[86:89]
	v_mfma_f32_16x16x32_bf16 v[94:97], v[178:181], v[166:169], v[94:97]
	global_load_dwordx4 v[122:125], v225, s[0:1] offset:1024
	s_waitcnt vmcnt(8)
	ds_write_b128 v2, v[118:121] offset:53248
	v_mfma_f32_16x16x32_bf16 v[30:33], v[170:173], v[98:101], v[30:33]
	v_mfma_f32_16x16x32_bf16 v[42:45], v[174:177], v[98:101], v[42:45]
	v_mfma_f32_16x16x32_bf16 v[14:17], v[182:185], v[98:101], v[14:17]
	v_mfma_f32_16x16x32_bf16 v[90:93], v[178:181], v[98:101], v[90:93]
	global_load_dwordx4 v[98:101], v226, s[0:1] offset:1024
	s_waitcnt vmcnt(8)
	ds_write_b128 v2, v[82:85] offset:57344
	v_mfma_f32_16x16x32_bf16 v[34:37], v[170:173], v[110:113], v[34:37]
	v_mfma_f32_16x16x32_bf16 v[46:49], v[174:177], v[110:113], v[46:49]
	v_mfma_f32_16x16x32_bf16 v[58:61], v[178:181], v[110:113], v[58:61]
	v_mfma_f32_16x16x32_bf16 v[18:21], v[182:185], v[110:113], v[18:21]
	global_load_dwordx4 v[82:85], v227, s[0:1] offset:1024
	s_waitcnt vmcnt(8)
	ds_write_b128 v2, v[102:105] offset:61440
	v_mfma_f32_16x16x32_bf16 v[38:41], v[170:173], v[146:149], v[38:41]
	v_mfma_f32_16x16x32_bf16 v[50:53], v[174:177], v[146:149], v[50:53]
	v_mfma_f32_16x16x32_bf16 v[54:57], v[178:181], v[146:149], v[54:57]
	v_mfma_f32_16x16x32_bf16 v[22:25], v[182:185], v[146:149], v[22:25]
	s_setprio 0
	s_waitcnt lgkmcnt(0)
	s_barrier
	ds_read_b128 v[102:105], v6 offset:32768
	ds_read_b128 v[110:113], v6 offset:34816
	ds_read_b128 v[118:121], v7 offset:49152
	ds_read_b128 v[126:129], v7 offset:51200
	ds_read_b128 v[146:149], v6 offset:36864
	ds_read_b128 v[150:153], v6 offset:38912
	ds_read_b128 v[154:157], v7 offset:53248
	ds_read_b128 v[158:161], v7 offset:55296
	s_setprio 2
	global_load_dwordx4 v[166:169], v8, s[36:37] offset:1152
	s_waitcnt vmcnt(8)
	ds_write_b128 v2, v[162:165]
	ds_read_b128 v[162:165], v4 offset:32768
	ds_read_b128 v[170:173], v5 offset:49152
	s_waitcnt lgkmcnt(8)
	v_mfma_f32_16x16x32_bf16 v[26:29], v[118:121], v[102:105], v[26:29]
	s_waitcnt lgkmcnt(3)
	v_mfma_f32_16x16x32_bf16 v[10:13], v[158:161], v[102:105], v[10:13]
	v_mfma_f32_16x16x32_bf16 v[86:89], v[126:129], v[102:105], v[86:89]
	v_mfma_f32_16x16x32_bf16 v[94:97], v[154:157], v[102:105], v[94:97]
	global_load_dwordx4 v[102:105], v222, s[36:37] offset:1152
	s_waitcnt vmcnt(8)
	ds_write_b128 v2, v[62:65] offset:4096
	ds_read_b128 v[62:65], v4 offset:34816
	ds_read_b128 v[174:177], v5 offset:51200
	v_mfma_f32_16x16x32_bf16 v[30:33], v[118:121], v[110:113], v[30:33]
	v_mfma_f32_16x16x32_bf16 v[42:45], v[126:129], v[110:113], v[42:45]
	v_mfma_f32_16x16x32_bf16 v[14:17], v[158:161], v[110:113], v[14:17]
	v_mfma_f32_16x16x32_bf16 v[90:93], v[154:157], v[110:113], v[90:93]
	global_load_dwordx4 v[110:113], v223, s[36:37] offset:1152
	s_waitcnt vmcnt(8)
	ds_write_b128 v2, v[106:109] offset:8192
	ds_read_b128 v[106:109], v4 offset:36864
	ds_read_b128 v[178:181], v5 offset:53248
	v_mfma_f32_16x16x32_bf16 v[34:37], v[118:121], v[146:149], v[34:37]
	v_mfma_f32_16x16x32_bf16 v[46:49], v[126:129], v[146:149], v[46:49]
	v_mfma_f32_16x16x32_bf16 v[58:61], v[154:157], v[146:149], v[58:61]
	v_mfma_f32_16x16x32_bf16 v[18:21], v[158:161], v[146:149], v[18:21]
	global_load_dwordx4 v[146:149], v224, s[36:37] offset:1152
	s_waitcnt vmcnt(8)
	ds_write_b128 v2, v[132:135] offset:12288
	ds_read_b128 v[132:135], v4 offset:38912
	ds_read_b128 v[182:185], v5 offset:55296
	v_mfma_f32_16x16x32_bf16 v[38:41], v[118:121], v[150:153], v[38:41]
	v_mfma_f32_16x16x32_bf16 v[50:53], v[126:129], v[150:153], v[50:53]
	v_mfma_f32_16x16x32_bf16 v[54:57], v[154:157], v[150:153], v[54:57]
	v_mfma_f32_16x16x32_bf16 v[22:25], v[158:161], v[150:153], v[22:25]
	global_load_dwordx4 v[118:121], v3, s[0:1] offset:1152
	s_waitcnt vmcnt(8)
	ds_write_b128 v2, v[114:117] offset:16384
	s_waitcnt lgkmcnt(10)
	v_mfma_f32_16x16x32_bf16 v[26:29], v[170:173], v[162:165], v[26:29]
	s_waitcnt lgkmcnt(1)
	v_mfma_f32_16x16x32_bf16 v[10:13], v[182:185], v[162:165], v[10:13]
	v_mfma_f32_16x16x32_bf16 v[86:89], v[174:177], v[162:165], v[86:89]
	v_mfma_f32_16x16x32_bf16 v[94:97], v[178:181], v[162:165], v[94:97]
	global_load_dwordx4 v[114:117], v225, s[0:1] offset:1152
	s_waitcnt vmcnt(8)
	ds_write_b128 v2, v[122:125] offset:20480
	v_mfma_f32_16x16x32_bf16 v[30:33], v[170:173], v[62:65], v[30:33]
	v_mfma_f32_16x16x32_bf16 v[42:45], v[174:177], v[62:65], v[42:45]
	v_mfma_f32_16x16x32_bf16 v[14:17], v[182:185], v[62:65], v[14:17]
	v_mfma_f32_16x16x32_bf16 v[90:93], v[178:181], v[62:65], v[90:93]
	global_load_dwordx4 v[62:65], v226, s[0:1] offset:1152
	s_waitcnt vmcnt(8)
	ds_write_b128 v2, v[98:101] offset:24576
	v_mfma_f32_16x16x32_bf16 v[34:37], v[170:173], v[106:109], v[34:37]
	v_mfma_f32_16x16x32_bf16 v[46:49], v[174:177], v[106:109], v[46:49]
	v_mfma_f32_16x16x32_bf16 v[58:61], v[178:181], v[106:109], v[58:61]
	v_mfma_f32_16x16x32_bf16 v[18:21], v[182:185], v[106:109], v[18:21]
	global_load_dwordx4 v[98:101], v227, s[0:1] offset:1152
	s_waitcnt vmcnt(8)
	ds_write_b128 v2, v[82:85] offset:28672
	v_mfma_f32_16x16x32_bf16 v[38:41], v[170:173], v[132:135], v[38:41]
	v_mfma_f32_16x16x32_bf16 v[50:53], v[174:177], v[132:135], v[50:53]
	v_mfma_f32_16x16x32_bf16 v[54:57], v[178:181], v[132:135], v[54:57]
	v_mfma_f32_16x16x32_bf16 v[22:25], v[182:185], v[132:135], v[22:25]
	s_setprio 0
	s_waitcnt lgkmcnt(0)
	s_barrier
; template <int MODE>
; __device__ __forceinline__ void gemm_tile(const Params& P, int tm, int tn, unsigned char* smem) {
;     ...
; #pragma unroll
;         for (int i = 0; i < 4; ++i) { fa[i] = *(const bf16x8*)(sA + arow_off + i * 2048 + ch0); fb[i] = *(const bf16x8*)(sB + brow_off + i * 2048 + ch0); }
;         __builtin_amdgcn_sched_barrier(0);
;         __builtin_amdgcn_s_setprio(2);
;         if (wr_ok) *(uint4*)(nA + soff0) = ra0;
;         if (ld_ok) ra0 = *(const uint4*)(Ab + (aoff + 0u * LDA + koa));
;         ga[0] = *(const bf16x8*)(sA + arow_off + 0 * 2048 + ch1); gb[0] = *(const bf16x8*)(sB + brow_off + 0 * 2048 + ch1);
;         __builtin_amdgcn_sched_barrier(0);
; #pragma unroll
;         for (int j = 0; j < 4; ++j) acc[0][j] = __builtin_amdgcn_mfma_f32_16x16x32_bf16(fb[j], fa[0], acc[0][j], 0, 0, 0);
;         __builtin_amdgcn_sched_barrier(0);
;         if (wr_ok) *(uint4*)(nA + soff0 + 4096) = ra1;
;         if (ld_ok) ra1 = *(const uint4*)(Ab + (aoff + 32u * LDA + koa));
;         ga[1] = *(const bf16x8*)(sA + arow_off + 1 * 2048 + ch1); gb[1] = *(const bf16x8*)(sB + brow_off + 1 * 2048 + ch1);
;         __builtin_amdgcn_sched_barrier(0);
; #pragma unroll
;         for (int j = 0; j < 4; ++j) acc[1][j] = __builtin_amdgcn_mfma_f32_16x16x32_bf16(fb[j], fa[1], acc[1][j], 0, 0, 0);
;         __builtin_amdgcn_sched_barrier(0);
;         if (wr_ok) *(uint4*)(nA + soff0 + 8192) = ra2;
;         if (ld_ok) ra2 = *(const uint4*)(Ab + (aoff + 64u * LDA + koa));
;         ga[2] = *(const bf16x8*)(sA + arow_off + 2 * 2048 + ch1); gb[2] = *(const bf16x8*)(sB + brow_off + 2 * 2048 + ch1);
;         __builtin_amdgcn_sched_barrier(0);
; #pragma unroll
;         for (int j = 0; j < 4; ++j) acc[2][j] = __builtin_amdgcn_mfma_f32_16x16x32_bf16(fb[j], fa[2], acc[2][j], 0, 0, 0);
;         __builtin_amdgcn_sched_barrier(0);
;         if (wr_ok) *(uint4*)(nA + soff0 + 12288) = ra3;
;         if (ld_ok) ra3 = *(const uint4*)(Ab + (aoff + 96u * LDA + koa));
;         ga[3] = *(const bf16x8*)(sA + arow_off + 3 * 2048 + ch1); gb[3] = *(const bf16x8*)(sB + brow_off + 3 * 2048 + ch1);
;         __builtin_amdgcn_sched_barrier(0);
; #pragma unroll
;         for (int j = 0; j < 4; ++j) acc[3][j] = __builtin_amdgcn_mfma_f32_16x16x32_bf16(fb[j], fa[3], acc[3][j], 0, 0, 0);
;         __builtin_amdgcn_sched_barrier(0);
;         if (wr_ok) *(uint4*)(nB + soff0) = rb0;
	ds_read_b128 v[82:85], v6
	ds_read_b128 v[106:109], v6 offset:2048
	ds_read_b128 v[122:125], v7 offset:16384
	ds_read_b128 v[126:129], v7 offset:18432
	ds_read_b128 v[132:135], v6 offset:4096
	ds_read_b128 v[150:153], v6 offset:6144
	ds_read_b128 v[154:157], v7 offset:20480
	ds_read_b128 v[158:161], v7 offset:22528
	s_setprio 2
	global_load_dwordx4 v[162:165], v8, s[36:37] offset:1280
	s_waitcnt vmcnt(8)
	ds_write_b128 v2, v[166:169] offset:32768
	ds_read_b128 v[166:169], v4
	ds_read_b128 v[170:173], v5 offset:16384
	s_waitcnt lgkmcnt(8)
	v_mfma_f32_16x16x32_bf16 v[26:29], v[122:125], v[82:85], v[26:29]
	s_waitcnt lgkmcnt(3)
	v_mfma_f32_16x16x32_bf16 v[10:13], v[158:161], v[82:85], v[10:13]
	v_mfma_f32_16x16x32_bf16 v[86:89], v[126:129], v[82:85], v[86:89]
	v_mfma_f32_16x16x32_bf16 v[94:97], v[154:157], v[82:85], v[94:97]
	global_load_dwordx4 v[82:85], v222, s[36:37] offset:1280
	s_waitcnt vmcnt(8)
	ds_write_b128 v2, v[102:105] offset:36864
	ds_read_b128 v[102:105], v4 offset:2048
	ds_read_b128 v[174:177], v5 offset:18432
	v_mfma_f32_16x16x32_bf16 v[30:33], v[122:125], v[106:109], v[30:33]
	v_mfma_f32_16x16x32_bf16 v[42:45], v[126:129], v[106:109], v[42:45]
	v_mfma_f32_16x16x32_bf16 v[14:17], v[158:161], v[106:109], v[14:17]
	v_mfma_f32_16x16x32_bf16 v[90:93], v[154:157], v[106:109], v[90:93]
	global_load_dwordx4 v[106:109], v223, s[36:37] offset:1280
	s_waitcnt vmcnt(8)
	ds_write_b128 v2, v[110:113] offset:40960
	ds_read_b128 v[110:113], v4 offset:4096
	ds_read_b128 v[178:181], v5 offset:20480
	v_mfma_f32_16x16x32_bf16 v[34:37], v[122:125], v[132:135], v[34:37]
	v_mfma_f32_16x16x32_bf16 v[46:49], v[126:129], v[132:135], v[46:49]
	v_mfma_f32_16x16x32_bf16 v[58:61], v[154:157], v[132:135], v[58:61]
	v_mfma_f32_16x16x32_bf16 v[18:21], v[158:161], v[132:135], v[18:21]
	global_load_dwordx4 v[132:135], v224, s[36:37] offset:1280
	s_waitcnt vmcnt(8)
	ds_write_b128 v2, v[146:149] offset:45056
	ds_read_b128 v[146:149], v4 offset:6144
	ds_read_b128 v[182:185], v5 offset:22528
	v_mfma_f32_16x16x32_bf16 v[38:41], v[122:125], v[150:153], v[38:41]
	v_mfma_f32_16x16x32_bf16 v[50:53], v[126:129], v[150:153], v[50:53]
	v_mfma_f32_16x16x32_bf16 v[54:57], v[154:157], v[150:153], v[54:57]
	v_mfma_f32_16x16x32_bf16 v[22:25], v[158:161], v[150:153], v[22:25]
	global_load_dwordx4 v[122:125], v3, s[0:1] offset:1280
	s_waitcnt vmcnt(8)
	ds_write_b128 v2, v[118:121] offset:49152
	s_waitcnt lgkmcnt(10)
	v_mfma_f32_16x16x32_bf16 v[26:29], v[170:173], v[166:169], v[26:29]
	s_waitcnt lgkmcnt(1)
	v_mfma_f32_16x16x32_bf16 v[10:13], v[182:185], v[166:169], v[10:13]
	v_mfma_f32_16x16x32_bf16 v[86:89], v[174:177], v[166:169], v[86:89]
	v_mfma_f32_16x16x32_bf16 v[94:97], v[178:181], v[166:169], v[94:97]
	global_load_dwordx4 v[118:121], v225, s[0:1] offset:1280
	s_waitcnt vmcnt(8)
	ds_write_b128 v2, v[114:117] offset:53248
	v_mfma_f32_16x16x32_bf16 v[30:33], v[170:173], v[102:105], v[30:33]
	v_mfma_f32_16x16x32_bf16 v[42:45], v[174:177], v[102:105], v[42:45]
	v_mfma_f32_16x16x32_bf16 v[14:17], v[182:185], v[102:105], v[14:17]
	v_mfma_f32_16x16x32_bf16 v[90:93], v[178:181], v[102:105], v[90:93]
	global_load_dwordx4 v[102:105], v226, s[0:1] offset:1280
	s_waitcnt vmcnt(8)
	ds_write_b128 v2, v[62:65] offset:57344
	v_mfma_f32_16x16x32_bf16 v[34:37], v[170:173], v[110:113], v[34:37]
	v_mfma_f32_16x16x32_bf16 v[46:49], v[174:177], v[110:113], v[46:49]
	v_mfma_f32_16x16x32_bf16 v[58:61], v[178:181], v[110:113], v[58:61]
	v_mfma_f32_16x16x32_bf16 v[18:21], v[182:185], v[110:113], v[18:21]
	global_load_dwordx4 v[62:65], v227, s[0:1] offset:1280
	s_waitcnt vmcnt(8)
	ds_write_b128 v2, v[98:101] offset:61440
	v_mfma_f32_16x16x32_bf16 v[38:41], v[170:173], v[146:149], v[38:41]
	v_mfma_f32_16x16x32_bf16 v[50:53], v[174:177], v[146:149], v[50:53]
	v_mfma_f32_16x16x32_bf16 v[54:57], v[178:181], v[146:149], v[54:57]
	v_mfma_f32_16x16x32_bf16 v[22:25], v[182:185], v[146:149], v[22:25]
	s_setprio 0
	s_waitcnt lgkmcnt(0)
	s_barrier
	ds_read_b128 v[98:101], v6 offset:32768
	ds_read_b128 v[110:113], v6 offset:34816
	ds_read_b128 v[114:117], v7 offset:49152
	ds_read_b128 v[126:129], v7 offset:51200
	ds_read_b128 v[146:149], v6 offset:36864
	ds_read_b128 v[150:153], v6 offset:38912
	ds_read_b128 v[154:157], v7 offset:53248
	ds_read_b128 v[158:161], v7 offset:55296
	s_setprio 2
	global_load_dwordx4 v[166:169], v8, s[36:37] offset:1408
	s_waitcnt vmcnt(8)
	ds_write_b128 v2, v[162:165]
	ds_read_b128 v[162:165], v4 offset:32768
	ds_read_b128 v[170:173], v5 offset:49152
	s_waitcnt lgkmcnt(8)
	v_mfma_f32_16x16x32_bf16 v[26:29], v[114:117], v[98:101], v[26:29]
	s_waitcnt lgkmcnt(3)
	v_mfma_f32_16x16x32_bf16 v[10:13], v[158:161], v[98:101], v[10:13]
	v_mfma_f32_16x16x32_bf16 v[86:89], v[126:129], v[98:101], v[86:89]
	v_mfma_f32_16x16x32_bf16 v[94:97], v[154:157], v[98:101], v[94:97]
	global_load_dwordx4 v[98:101], v222, s[36:37] offset:1408
	s_waitcnt vmcnt(8)
	ds_write_b128 v2, v[82:85] offset:4096
	ds_read_b128 v[82:85], v4 offset:34816
	ds_read_b128 v[174:177], v5 offset:51200
	v_mfma_f32_16x16x32_bf16 v[30:33], v[114:117], v[110:113], v[30:33]
	v_mfma_f32_16x16x32_bf16 v[42:45], v[126:129], v[110:113], v[42:45]
	v_mfma_f32_16x16x32_bf16 v[14:17], v[158:161], v[110:113], v[14:17]
	v_mfma_f32_16x16x32_bf16 v[90:93], v[154:157], v[110:113], v[90:93]
	global_load_dwordx4 v[110:113], v223, s[36:37] offset:1408
	s_waitcnt vmcnt(8)
	ds_write_b128 v2, v[106:109] offset:8192
	ds_read_b128 v[106:109], v4 offset:36864
	ds_read_b128 v[178:181], v5 offset:53248
	v_mfma_f32_16x16x32_bf16 v[34:37], v[114:117], v[146:149], v[34:37]
	v_mfma_f32_16x16x32_bf16 v[46:49], v[126:129], v[146:149], v[46:49]
	v_mfma_f32_16x16x32_bf16 v[58:61], v[154:157], v[146:149], v[58:61]
	v_mfma_f32_16x16x32_bf16 v[18:21], v[158:161], v[146:149], v[18:21]
	global_load_dwordx4 v[146:149], v224, s[36:37] offset:1408
	s_waitcnt vmcnt(8)
; template <int MODE>
; __device__ __forceinline__ void gemm_tile(const Params& P, int tm, int tn, unsigned char* smem) {
;     ...
; #pragma unroll
;         for (int i = 0; i < 4; ++i) { fa[i] = *(const bf16x8*)(sA + arow_off + i * 2048 + ch0); fb[i] = *(const bf16x8*)(sB + brow_off + i * 2048 + ch0); }
;         __builtin_amdgcn_sched_barrier(0);
;         __builtin_amdgcn_s_setprio(2);
;         if (wr_ok) *(uint4*)(nA + soff0) = ra0;
;         if (ld_ok) ra0 = *(const uint4*)(Ab + (aoff + 0u * LDA + koa));
;         ga[0] = *(const bf16x8*)(sA + arow_off + 0 * 2048 + ch1); gb[0] = *(const bf16x8*)(sB + brow_off + 0 * 2048 + ch1);
;         __builtin_amdgcn_sched_barrier(0);
; #pragma unroll
;         for (int j = 0; j < 4; ++j) acc[0][j] = __builtin_amdgcn_mfma_f32_16x16x32_bf16(fb[j], fa[0], acc[0][j], 0, 0, 0);
;         __builtin_amdgcn_sched_barrier(0);
;         if (wr_ok) *(uint4*)(nA + soff0 + 4096) = ra1;
;         if (ld_ok) ra1 = *(const uint4*)(Ab + (aoff + 32u * LDA + koa));
;         ga[1] = *(const bf16x8*)(sA + arow_off + 1 * 2048 + ch1); gb[1] = *(const bf16x8*)(sB + brow_off + 1 * 2048 + ch1);
;         __builtin_amdgcn_sched_barrier(0);
; #pragma unroll
;         for (int j = 0; j < 4; ++j) acc[1][j] = __builtin_amdgcn_mfma_f32_16x16x32_bf16(fb[j], fa[1], acc[1][j], 0, 0, 0);
;         __builtin_amdgcn_sched_barrier(0);
;         if (wr_ok) *(uint4*)(nA + soff0 + 8192) = ra2;
;         if (ld_ok) ra2 = *(const uint4*)(Ab + (aoff + 64u * LDA + koa));
;         ga[2] = *(const bf16x8*)(sA + arow_off + 2 * 2048 + ch1); gb[2] = *(const bf16x8*)(sB + brow_off + 2 * 2048 + ch1);
;         __builtin_amdgcn_sched_barrier(0);
; #pragma unroll
;         for (int j = 0; j < 4; ++j) acc[2][j] = __builtin_amdgcn_mfma_f32_16x16x32_bf16(fb[j], fa[2], acc[2][j], 0, 0, 0);
;         __builtin_amdgcn_sched_barrier(0);
;         if (wr_ok) *(uint4*)(nA + soff0 + 12288) = ra3;
;         if (ld_ok) ra3 = *(const uint4*)(Ab + (aoff + 96u * LDA + koa));
;         ga[3] = *(const bf16x8*)(sA + arow_off + 3 * 2048 + ch1); gb[3] = *(const bf16x8*)(sB + brow_off + 3 * 2048 + ch1);
;         __builtin_amdgcn_sched_barrier(0);
; #pragma unroll
;         for (int j = 0; j < 4; ++j) acc[3][j] = __builtin_amdgcn_mfma_f32_16x16x32_bf16(fb[j], fa[3], acc[3][j], 0, 0, 0);
;         __builtin_amdgcn_sched_barrier(0);
;         if (wr_ok) *(uint4*)(nB + soff0) = rb0;
	ds_write_b128 v2, v[132:135] offset:12288
	ds_read_b128 v[132:135], v4 offset:38912
	ds_read_b128 v[182:185], v5 offset:55296
	v_mfma_f32_16x16x32_bf16 v[38:41], v[114:117], v[150:153], v[38:41]
	v_mfma_f32_16x16x32_bf16 v[50:53], v[126:129], v[150:153], v[50:53]
	v_mfma_f32_16x16x32_bf16 v[54:57], v[154:157], v[150:153], v[54:57]
	v_mfma_f32_16x16x32_bf16 v[22:25], v[158:161], v[150:153], v[22:25]
	global_load_dwordx4 v[114:117], v3, s[0:1] offset:1408
	s_waitcnt vmcnt(8)
	ds_write_b128 v2, v[122:125] offset:16384
	s_waitcnt lgkmcnt(10)
	v_mfma_f32_16x16x32_bf16 v[26:29], v[170:173], v[162:165], v[26:29]
	s_waitcnt lgkmcnt(1)
	v_mfma_f32_16x16x32_bf16 v[10:13], v[182:185], v[162:165], v[10:13]
	v_mfma_f32_16x16x32_bf16 v[86:89], v[174:177], v[162:165], v[86:89]
	v_mfma_f32_16x16x32_bf16 v[94:97], v[178:181], v[162:165], v[94:97]
	global_load_dwordx4 v[122:125], v225, s[0:1] offset:1408
	s_waitcnt vmcnt(8)
	ds_write_b128 v2, v[118:121] offset:20480
	v_mfma_f32_16x16x32_bf16 v[30:33], v[170:173], v[82:85], v[30:33]
	v_mfma_f32_16x16x32_bf16 v[42:45], v[174:177], v[82:85], v[42:45]
	v_mfma_f32_16x16x32_bf16 v[14:17], v[182:185], v[82:85], v[14:17]
	v_mfma_f32_16x16x32_bf16 v[90:93], v[178:181], v[82:85], v[90:93]
	global_load_dwordx4 v[82:85], v226, s[0:1] offset:1408
	s_waitcnt vmcnt(8)
	ds_write_b128 v2, v[102:105] offset:24576
	v_mfma_f32_16x16x32_bf16 v[34:37], v[170:173], v[106:109], v[34:37]
	v_mfma_f32_16x16x32_bf16 v[46:49], v[174:177], v[106:109], v[46:49]
	v_mfma_f32_16x16x32_bf16 v[58:61], v[178:181], v[106:109], v[58:61]
	v_mfma_f32_16x16x32_bf16 v[18:21], v[182:185], v[106:109], v[18:21]
	global_load_dwordx4 v[102:105], v227, s[0:1] offset:1408
	s_waitcnt vmcnt(8)
	ds_write_b128 v2, v[62:65] offset:28672
	v_mfma_f32_16x16x32_bf16 v[38:41], v[170:173], v[132:135], v[38:41]
	v_mfma_f32_16x16x32_bf16 v[50:53], v[174:177], v[132:135], v[50:53]
	v_mfma_f32_16x16x32_bf16 v[54:57], v[178:181], v[132:135], v[54:57]
	v_mfma_f32_16x16x32_bf16 v[22:25], v[182:185], v[132:135], v[22:25]
	s_setprio 0
	s_waitcnt lgkmcnt(0)
	s_barrier
	ds_read_b128 v[62:65], v6
	ds_read_b128 v[106:109], v6 offset:2048
	ds_read_b128 v[118:121], v7 offset:16384
	ds_read_b128 v[126:129], v7 offset:18432
	ds_read_b128 v[132:135], v6 offset:4096
	ds_read_b128 v[150:153], v6 offset:6144
	ds_read_b128 v[154:157], v7 offset:20480
	ds_read_b128 v[158:161], v7 offset:22528
	s_setprio 2
	global_load_dwordx4 v[162:165], v8, s[36:37] offset:1536
	s_waitcnt vmcnt(8)
	ds_write_b128 v2, v[166:169] offset:32768
	ds_read_b128 v[166:169], v4
	ds_read_b128 v[170:173], v5 offset:16384
	s_waitcnt lgkmcnt(8)
	v_mfma_f32_16x16x32_bf16 v[26:29], v[118:121], v[62:65], v[26:29]
	s_waitcnt lgkmcnt(3)
	v_mfma_f32_16x16x32_bf16 v[10:13], v[158:161], v[62:65], v[10:13]
	v_mfma_f32_16x16x32_bf16 v[86:89], v[126:129], v[62:65], v[86:89]
	v_mfma_f32_16x16x32_bf16 v[94:97], v[154:157], v[62:65], v[94:97]
	global_load_dwordx4 v[62:65], v222, s[36:37] offset:1536
	s_waitcnt vmcnt(8)
	ds_write_b128 v2, v[98:101] offset:36864
	ds_read_b128 v[98:101], v4 offset:2048
	ds_read_b128 v[174:177], v5 offset:18432
	v_mfma_f32_16x16x32_bf16 v[30:33], v[118:121], v[106:109], v[30:33]
	v_mfma_f32_16x16x32_bf16 v[42:45], v[126:129], v[106:109], v[42:45]
	v_mfma_f32_16x16x32_bf16 v[14:17], v[158:161], v[106:109], v[14:17]
	v_mfma_f32_16x16x32_bf16 v[90:93], v[154:157], v[106:109], v[90:93]
	global_load_dwordx4 v[106:109], v223, s[36:37] offset:1536
	s_waitcnt vmcnt(8)
	ds_write_b128 v2, v[110:113] offset:40960
	ds_read_b128 v[110:113], v4 offset:4096
	ds_read_b128 v[178:181], v5 offset:20480
	v_mfma_f32_16x16x32_bf16 v[34:37], v[118:121], v[132:135], v[34:37]
	v_mfma_f32_16x16x32_bf16 v[46:49], v[126:129], v[132:135], v[46:49]
	v_mfma_f32_16x16x32_bf16 v[58:61], v[154:157], v[132:135], v[58:61]
	v_mfma_f32_16x16x32_bf16 v[18:21], v[158:161], v[132:135], v[18:21]
	global_load_dwordx4 v[132:135], v224, s[36:37] offset:1536
	s_waitcnt vmcnt(8)
	ds_write_b128 v2, v[146:149] offset:45056
	ds_read_b128 v[146:149], v4 offset:6144
	ds_read_b128 v[182:185], v5 offset:22528
	v_mfma_f32_16x16x32_bf16 v[38:41], v[118:121], v[150:153], v[38:41]
	v_mfma_f32_16x16x32_bf16 v[50:53], v[126:129], v[150:153], v[50:53]
	v_mfma_f32_16x16x32_bf16 v[54:57], v[154:157], v[150:153], v[54:57]
	v_mfma_f32_16x16x32_bf16 v[22:25], v[158:161], v[150:153], v[22:25]
	global_load_dwordx4 v[118:121], v3, s[0:1] offset:1536
	s_waitcnt vmcnt(8)
	ds_write_b128 v2, v[114:117] offset:49152
	s_waitcnt lgkmcnt(10)
	v_mfma_f32_16x16x32_bf16 v[26:29], v[170:173], v[166:169], v[26:29]
	s_waitcnt lgkmcnt(1)
	v_mfma_f32_16x16x32_bf16 v[10:13], v[182:185], v[166:169], v[10:13]
	v_mfma_f32_16x16x32_bf16 v[86:89], v[174:177], v[166:169], v[86:89]
	v_mfma_f32_16x16x32_bf16 v[94:97], v[178:181], v[166:169], v[94:97]
	global_load_dwordx4 v[114:117], v225, s[0:1] offset:1536
	s_waitcnt vmcnt(8)
	ds_write_b128 v2, v[122:125] offset:53248
	v_mfma_f32_16x16x32_bf16 v[30:33], v[170:173], v[98:101], v[30:33]
	v_mfma_f32_16x16x32_bf16 v[42:45], v[174:177], v[98:101], v[42:45]
	v_mfma_f32_16x16x32_bf16 v[14:17], v[182:185], v[98:101], v[14:17]
	v_mfma_f32_16x16x32_bf16 v[90:93], v[178:181], v[98:101], v[90:93]
	global_load_dwordx4 v[98:101], v226, s[0:1] offset:1536
	s_waitcnt vmcnt(8)
	ds_write_b128 v2, v[82:85] offset:57344
	v_mfma_f32_16x16x32_bf16 v[34:37], v[170:173], v[110:113], v[34:37]
	v_mfma_f32_16x16x32_bf16 v[46:49], v[174:177], v[110:113], v[46:49]
	v_mfma_f32_16x16x32_bf16 v[58:61], v[178:181], v[110:113], v[58:61]
	v_mfma_f32_16x16x32_bf16 v[18:21], v[182:185], v[110:113], v[18:21]
	global_load_dwordx4 v[82:85], v227, s[0:1] offset:1536
	s_waitcnt vmcnt(8)
	ds_write_b128 v2, v[102:105] offset:61440
	v_mfma_f32_16x16x32_bf16 v[38:41], v[170:173], v[146:149], v[38:41]
	v_mfma_f32_16x16x32_bf16 v[50:53], v[174:177], v[146:149], v[50:53]
	v_mfma_f32_16x16x32_bf16 v[54:57], v[178:181], v[146:149], v[54:57]
	v_mfma_f32_16x16x32_bf16 v[22:25], v[182:185], v[146:149], v[22:25]
	s_setprio 0
	s_waitcnt lgkmcnt(0)
	s_barrier
; template <int MODE>
; __device__ __forceinline__ void gemm_tile(const Params& P, int tm, int tn, unsigned char* smem) {
;     ...
; #pragma unroll
;         for (int i = 0; i < 4; ++i) { fa[i] = *(const bf16x8*)(sA + arow_off + i * 2048 + ch0); fb[i] = *(const bf16x8*)(sB + brow_off + i * 2048 + ch0); }
;         __builtin_amdgcn_sched_barrier(0);
;         __builtin_amdgcn_s_setprio(2);
;         if (wr_ok) *(uint4*)(nA + soff0) = ra0;
;         if (ld_ok) ra0 = *(const uint4*)(Ab + (aoff + 0u * LDA + koa));
;         ga[0] = *(const bf16x8*)(sA + arow_off + 0 * 2048 + ch1); gb[0] = *(const bf16x8*)(sB + brow_off + 0 * 2048 + ch1);
;         __builtin_amdgcn_sched_barrier(0);
; #pragma unroll
;         for (int j = 0; j < 4; ++j) acc[0][j] = __builtin_amdgcn_mfma_f32_16x16x32_bf16(fb[j], fa[0], acc[0][j], 0, 0, 0);
;         __builtin_amdgcn_sched_barrier(0);
;         if (wr_ok) *(uint4*)(nA + soff0 + 4096) = ra1;
;         if (ld_ok) ra1 = *(const uint4*)(Ab + (aoff + 32u * LDA + koa));
;         ga[1] = *(const bf16x8*)(sA + arow_off + 1 * 2048 + ch1); gb[1] = *(const bf16x8*)(sB + brow_off + 1 * 2048 + ch1);
;         __builtin_amdgcn_sched_barrier(0);
; #pragma unroll
;         for (int j = 0; j < 4; ++j) acc[1][j] = __builtin_amdgcn_mfma_f32_16x16x32_bf16(fb[j], fa[1], acc[1][j], 0, 0, 0);
;         __builtin_amdgcn_sched_barrier(0);
;         if (wr_ok) *(uint4*)(nA + soff0 + 8192) = ra2;
;         if (ld_ok) ra2 = *(const uint4*)(Ab + (aoff + 64u * LDA + koa));
;         ga[2] = *(const bf16x8*)(sA + arow_off + 2 * 2048 + ch1); gb[2] = *(const bf16x8*)(sB + brow_off + 2 * 2048 + ch1);
;         __builtin_amdgcn_sched_barrier(0);
; #pragma unroll
;         for (int j = 0; j < 4; ++j) acc[2][j] = __builtin_amdgcn_mfma_f32_16x16x32_bf16(fb[j], fa[2], acc[2][j], 0, 0, 0);
;         __builtin_amdgcn_sched_barrier(0);
;         if (wr_ok) *(uint4*)(nA + soff0 + 12288) = ra3;
;         if (ld_ok) ra3 = *(const uint4*)(Ab + (aoff + 96u * LDA + koa));
;         ga[3] = *(const bf16x8*)(sA + arow_off + 3 * 2048 + ch1); gb[3] = *(const bf16x8*)(sB + brow_off + 3 * 2048 + ch1);
;         __builtin_amdgcn_sched_barrier(0);
; #pragma unroll
;         for (int j = 0; j < 4; ++j) acc[3][j] = __builtin_amdgcn_mfma_f32_16x16x32_bf16(fb[j], fa[3], acc[3][j], 0, 0, 0);
;         __builtin_amdgcn_sched_barrier(0);
;         if (wr_ok) *(uint4*)(nB + soff0) = rb0;
	ds_read_b128 v[102:105], v6 offset:32768
	ds_read_b128 v[110:113], v6 offset:34816
	ds_read_b128 v[122:125], v7 offset:49152
	ds_read_b128 v[126:129], v7 offset:51200
	ds_read_b128 v[146:149], v6 offset:36864
	ds_read_b128 v[150:153], v6 offset:38912
	ds_read_b128 v[154:157], v7 offset:53248
	ds_read_b128 v[158:161], v7 offset:55296
	s_setprio 2
	global_load_dwordx4 v[166:169], v8, s[36:37] offset:1664
	s_waitcnt vmcnt(8)
	ds_write_b128 v2, v[162:165]
	ds_read_b128 v[162:165], v4 offset:32768
	ds_read_b128 v[170:173], v5 offset:49152
	s_waitcnt lgkmcnt(8)
	v_mfma_f32_16x16x32_bf16 v[26:29], v[122:125], v[102:105], v[26:29]
	s_waitcnt lgkmcnt(3)
	v_mfma_f32_16x16x32_bf16 v[10:13], v[158:161], v[102:105], v[10:13]
	v_mfma_f32_16x16x32_bf16 v[86:89], v[126:129], v[102:105], v[86:89]
	v_mfma_f32_16x16x32_bf16 v[94:97], v[154:157], v[102:105], v[94:97]
	global_load_dwordx4 v[102:105], v222, s[36:37] offset:1664
	s_waitcnt vmcnt(8)
	ds_write_b128 v2, v[62:65] offset:4096
	ds_read_b128 v[62:65], v4 offset:34816
	ds_read_b128 v[174:177], v5 offset:51200
	v_mfma_f32_16x16x32_bf16 v[30:33], v[122:125], v[110:113], v[30:33]
	v_mfma_f32_16x16x32_bf16 v[42:45], v[126:129], v[110:113], v[42:45]
	v_mfma_f32_16x16x32_bf16 v[14:17], v[158:161], v[110:113], v[14:17]
	v_mfma_f32_16x16x32_bf16 v[90:93], v[154:157], v[110:113], v[90:93]
	global_load_dwordx4 v[110:113], v223, s[36:37] offset:1664
	s_waitcnt vmcnt(8)
	ds_write_b128 v2, v[106:109] offset:8192
	ds_read_b128 v[106:109], v4 offset:36864
	ds_read_b128 v[178:181], v5 offset:53248
	v_mfma_f32_16x16x32_bf16 v[34:37], v[122:125], v[146:149], v[34:37]
	v_mfma_f32_16x16x32_bf16 v[46:49], v[126:129], v[146:149], v[46:49]
	v_mfma_f32_16x16x32_bf16 v[58:61], v[154:157], v[146:149], v[58:61]
	v_mfma_f32_16x16x32_bf16 v[18:21], v[158:161], v[146:149], v[18:21]
	global_load_dwordx4 v[146:149], v224, s[36:37] offset:1664
	s_waitcnt vmcnt(8)
	ds_write_b128 v2, v[132:135] offset:12288
	ds_read_b128 v[132:135], v4 offset:38912
	ds_read_b128 v[182:185], v5 offset:55296
	v_mfma_f32_16x16x32_bf16 v[38:41], v[122:125], v[150:153], v[38:41]
	v_mfma_f32_16x16x32_bf16 v[50:53], v[126:129], v[150:153], v[50:53]
	v_mfma_f32_16x16x32_bf16 v[54:57], v[154:157], v[150:153], v[54:57]
	v_mfma_f32_16x16x32_bf16 v[22:25], v[158:161], v[150:153], v[22:25]
	global_load_dwordx4 v[122:125], v3, s[0:1] offset:1664
	s_waitcnt vmcnt(8)
	ds_write_b128 v2, v[118:121] offset:16384
	s_waitcnt lgkmcnt(10)
	v_mfma_f32_16x16x32_bf16 v[26:29], v[170:173], v[162:165], v[26:29]
	s_waitcnt lgkmcnt(1)
	v_mfma_f32_16x16x32_bf16 v[10:13], v[182:185], v[162:165], v[10:13]
	v_mfma_f32_16x16x32_bf16 v[86:89], v[174:177], v[162:165], v[86:89]
	v_mfma_f32_16x16x32_bf16 v[94:97], v[178:181], v[162:165], v[94:97]
	global_load_dwordx4 v[118:121], v225, s[0:1] offset:1664
	s_waitcnt vmcnt(8)
	ds_write_b128 v2, v[114:117] offset:20480
	v_mfma_f32_16x16x32_bf16 v[30:33], v[170:173], v[62:65], v[30:33]
	v_mfma_f32_16x16x32_bf16 v[42:45], v[174:177], v[62:65], v[42:45]
	v_mfma_f32_16x16x32_bf16 v[14:17], v[182:185], v[62:65], v[14:17]
	v_mfma_f32_16x16x32_bf16 v[90:93], v[178:181], v[62:65], v[90:93]
	global_load_dwordx4 v[62:65], v226, s[0:1] offset:1664
	s_waitcnt vmcnt(8)
	ds_write_b128 v2, v[98:101] offset:24576
	v_mfma_f32_16x16x32_bf16 v[34:37], v[170:173], v[106:109], v[34:37]
	v_mfma_f32_16x16x32_bf16 v[46:49], v[174:177], v[106:109], v[46:49]
	v_mfma_f32_16x16x32_bf16 v[58:61], v[178:181], v[106:109], v[58:61]
	v_mfma_f32_16x16x32_bf16 v[18:21], v[182:185], v[106:109], v[18:21]
	global_load_dwordx4 v[98:101], v227, s[0:1] offset:1664
	s_waitcnt vmcnt(8)
	ds_write_b128 v2, v[82:85] offset:28672
	v_mfma_f32_16x16x32_bf16 v[38:41], v[170:173], v[132:135], v[38:41]
	v_mfma_f32_16x16x32_bf16 v[50:53], v[174:177], v[132:135], v[50:53]
	v_mfma_f32_16x16x32_bf16 v[54:57], v[178:181], v[132:135], v[54:57]
	v_mfma_f32_16x16x32_bf16 v[22:25], v[182:185], v[132:135], v[22:25]
	s_setprio 0
	s_waitcnt lgkmcnt(0)
	s_barrier
	ds_read_b128 v[82:85], v6
	ds_read_b128 v[106:109], v6 offset:2048
	ds_read_b128 v[114:117], v7 offset:16384
	ds_read_b128 v[126:129], v7 offset:18432
	ds_read_b128 v[132:135], v6 offset:4096
	ds_read_b128 v[150:153], v6 offset:6144
	ds_read_b128 v[154:157], v7 offset:20480
	ds_read_b128 v[158:161], v7 offset:22528
	s_setprio 2
	global_load_dwordx4 v[162:165], v8, s[36:37] offset:1792
	s_waitcnt vmcnt(8)
	ds_write_b128 v2, v[166:169] offset:32768
	ds_read_b128 v[166:169], v4
	ds_read_b128 v[170:173], v5 offset:16384
	s_waitcnt lgkmcnt(8)
	v_mfma_f32_16x16x32_bf16 v[26:29], v[114:117], v[82:85], v[26:29]
	s_waitcnt lgkmcnt(3)
	v_mfma_f32_16x16x32_bf16 v[10:13], v[158:161], v[82:85], v[10:13]
	v_mfma_f32_16x16x32_bf16 v[86:89], v[126:129], v[82:85], v[86:89]
	v_mfma_f32_16x16x32_bf16 v[94:97], v[154:157], v[82:85], v[94:97]
	global_load_dwordx4 v[82:85], v222, s[36:37] offset:1792
	s_waitcnt vmcnt(8)
	ds_write_b128 v2, v[102:105] offset:36864
	ds_read_b128 v[102:105], v4 offset:2048
	ds_read_b128 v[174:177], v5 offset:18432
	v_mfma_f32_16x16x32_bf16 v[30:33], v[114:117], v[106:109], v[30:33]
	v_mfma_f32_16x16x32_bf16 v[42:45], v[126:129], v[106:109], v[42:45]
	v_mfma_f32_16x16x32_bf16 v[14:17], v[158:161], v[106:109], v[14:17]
	v_mfma_f32_16x16x32_bf16 v[90:93], v[154:157], v[106:109], v[90:93]
	global_load_dwordx4 v[106:109], v223, s[36:37] offset:1792
	s_waitcnt vmcnt(8)
	ds_write_b128 v2, v[110:113] offset:40960
	ds_read_b128 v[110:113], v4 offset:4096
	ds_read_b128 v[178:181], v5 offset:20480
	v_mfma_f32_16x16x32_bf16 v[34:37], v[114:117], v[132:135], v[34:37]
	v_mfma_f32_16x16x32_bf16 v[46:49], v[126:129], v[132:135], v[46:49]
	v_mfma_f32_16x16x32_bf16 v[58:61], v[154:157], v[132:135], v[58:61]
	v_mfma_f32_16x16x32_bf16 v[18:21], v[158:161], v[132:135], v[18:21]
	global_load_dwordx4 v[132:135], v224, s[36:37] offset:1792
	s_waitcnt vmcnt(8)
; template <int MODE>
; __device__ __forceinline__ void gemm_tile(const Params& P, int tm, int tn, unsigned char* smem) {
;     ...
; #pragma unroll
;         for (int i = 0; i < 4; ++i) { fa[i] = *(const bf16x8*)(sA + arow_off + i * 2048 + ch0); fb[i] = *(const bf16x8*)(sB + brow_off + i * 2048 + ch0); }
;         __builtin_amdgcn_sched_barrier(0);
;         __builtin_amdgcn_s_setprio(2);
;         if (wr_ok) *(uint4*)(nA + soff0) = ra0;
;         if (ld_ok) ra0 = *(const uint4*)(Ab + (aoff + 0u * LDA + koa));
;         ga[0] = *(const bf16x8*)(sA + arow_off + 0 * 2048 + ch1); gb[0] = *(const bf16x8*)(sB + brow_off + 0 * 2048 + ch1);
;         __builtin_amdgcn_sched_barrier(0);
; #pragma unroll
;         for (int j = 0; j < 4; ++j) acc[0][j] = __builtin_amdgcn_mfma_f32_16x16x32_bf16(fb[j], fa[0], acc[0][j], 0, 0, 0);
;         __builtin_amdgcn_sched_barrier(0);
;         if (wr_ok) *(uint4*)(nA + soff0 + 4096) = ra1;
;         if (ld_ok) ra1 = *(const uint4*)(Ab + (aoff + 32u * LDA + koa));
;         ga[1] = *(const bf16x8*)(sA + arow_off + 1 * 2048 + ch1); gb[1] = *(const bf16x8*)(sB + brow_off + 1 * 2048 + ch1);
;         __builtin_amdgcn_sched_barrier(0);
; #pragma unroll
;         for (int j = 0; j < 4; ++j) acc[1][j] = __builtin_amdgcn_mfma_f32_16x16x32_bf16(fb[j], fa[1], acc[1][j], 0, 0, 0);
;         __builtin_amdgcn_sched_barrier(0);
;         if (wr_ok) *(uint4*)(nA + soff0 + 8192) = ra2;
;         if (ld_ok) ra2 = *(const uint4*)(Ab + (aoff + 64u * LDA + koa));
;         ga[2] = *(const bf16x8*)(sA + arow_off + 2 * 2048 + ch1); gb[2] = *(const bf16x8*)(sB + brow_off + 2 * 2048 + ch1);
;         __builtin_amdgcn_sched_barrier(0);
; #pragma unroll
;         for (int j = 0; j < 4; ++j) acc[2][j] = __builtin_amdgcn_mfma_f32_16x16x32_bf16(fb[j], fa[2], acc[2][j], 0, 0, 0);
;         __builtin_amdgcn_sched_barrier(0);
;         if (wr_ok) *(uint4*)(nA + soff0 + 12288) = ra3;
;         if (ld_ok) ra3 = *(const uint4*)(Ab + (aoff + 96u * LDA + koa));
;         ga[3] = *(const bf16x8*)(sA + arow_off + 3 * 2048 + ch1); gb[3] = *(const bf16x8*)(sB + brow_off + 3 * 2048 + ch1);
;         __builtin_amdgcn_sched_barrier(0);
; #pragma unroll
;         for (int j = 0; j < 4; ++j) acc[3][j] = __builtin_amdgcn_mfma_f32_16x16x32_bf16(fb[j], fa[3], acc[3][j], 0, 0, 0);
;         __builtin_amdgcn_sched_barrier(0);
;         if (wr_ok) *(uint4*)(nB + soff0) = rb0;
	ds_write_b128 v2, v[146:149] offset:45056
	ds_read_b128 v[146:149], v4 offset:6144
	ds_read_b128 v[182:185], v5 offset:22528
	v_mfma_f32_16x16x32_bf16 v[38:41], v[114:117], v[150:153], v[38:41]
	v_mfma_f32_16x16x32_bf16 v[50:53], v[126:129], v[150:153], v[50:53]
	v_mfma_f32_16x16x32_bf16 v[54:57], v[154:157], v[150:153], v[54:57]
	v_mfma_f32_16x16x32_bf16 v[22:25], v[158:161], v[150:153], v[22:25]
	global_load_dwordx4 v[114:117], v3, s[0:1] offset:1792
	s_waitcnt vmcnt(8)
	ds_write_b128 v2, v[122:125] offset:49152
	s_waitcnt lgkmcnt(10)
	v_mfma_f32_16x16x32_bf16 v[26:29], v[170:173], v[166:169], v[26:29]
	s_waitcnt lgkmcnt(1)
	v_mfma_f32_16x16x32_bf16 v[10:13], v[182:185], v[166:169], v[10:13]
	v_mfma_f32_16x16x32_bf16 v[86:89], v[174:177], v[166:169], v[86:89]
	v_mfma_f32_16x16x32_bf16 v[94:97], v[178:181], v[166:169], v[94:97]
	global_load_dwordx4 v[122:125], v225, s[0:1] offset:1792
	s_waitcnt vmcnt(8)
	ds_write_b128 v2, v[118:121] offset:53248
	v_mfma_f32_16x16x32_bf16 v[30:33], v[170:173], v[102:105], v[30:33]
	v_mfma_f32_16x16x32_bf16 v[42:45], v[174:177], v[102:105], v[42:45]
	v_mfma_f32_16x16x32_bf16 v[14:17], v[182:185], v[102:105], v[14:17]
	v_mfma_f32_16x16x32_bf16 v[90:93], v[178:181], v[102:105], v[90:93]
	global_load_dwordx4 v[102:105], v226, s[0:1] offset:1792
	s_waitcnt vmcnt(8)
	ds_write_b128 v2, v[62:65] offset:57344
	v_mfma_f32_16x16x32_bf16 v[34:37], v[170:173], v[110:113], v[34:37]
	v_mfma_f32_16x16x32_bf16 v[46:49], v[174:177], v[110:113], v[46:49]
	v_mfma_f32_16x16x32_bf16 v[58:61], v[178:181], v[110:113], v[58:61]
	v_mfma_f32_16x16x32_bf16 v[18:21], v[182:185], v[110:113], v[18:21]
	global_load_dwordx4 v[62:65], v227, s[0:1] offset:1792
	s_waitcnt vmcnt(8)
	ds_write_b128 v2, v[98:101] offset:61440
	v_mfma_f32_16x16x32_bf16 v[38:41], v[170:173], v[146:149], v[38:41]
	v_mfma_f32_16x16x32_bf16 v[50:53], v[174:177], v[146:149], v[50:53]
	v_mfma_f32_16x16x32_bf16 v[54:57], v[178:181], v[146:149], v[54:57]
	v_mfma_f32_16x16x32_bf16 v[22:25], v[182:185], v[146:149], v[22:25]
	s_setprio 0
	s_waitcnt lgkmcnt(0)
	s_barrier
	ds_read_b128 v[98:101], v6 offset:32768
	ds_read_b128 v[110:113], v6 offset:34816
	ds_read_b128 v[118:121], v7 offset:49152
	ds_read_b128 v[126:129], v7 offset:51200
	ds_read_b128 v[146:149], v6 offset:36864
	ds_read_b128 v[150:153], v6 offset:38912
	ds_read_b128 v[154:157], v7 offset:53248
	ds_read_b128 v[158:161], v7 offset:55296
	s_setprio 2
	global_load_dwordx4 v[166:169], v8, s[36:37] offset:1920
	s_waitcnt vmcnt(8)
	ds_write_b128 v2, v[162:165]
	ds_read_b128 v[162:165], v4 offset:32768
	ds_read_b128 v[170:173], v5 offset:49152
	s_waitcnt lgkmcnt(8)
	v_mfma_f32_16x16x32_bf16 v[26:29], v[118:121], v[98:101], v[26:29]
	s_waitcnt lgkmcnt(3)
	v_mfma_f32_16x16x32_bf16 v[10:13], v[158:161], v[98:101], v[10:13]
	v_mfma_f32_16x16x32_bf16 v[86:89], v[126:129], v[98:101], v[86:89]
	v_mfma_f32_16x16x32_bf16 v[94:97], v[154:157], v[98:101], v[94:97]
	global_load_dwordx4 v[98:101], v222, s[36:37] offset:1920
	s_waitcnt vmcnt(8)
	ds_write_b128 v2, v[82:85] offset:4096
	ds_read_b128 v[82:85], v4 offset:34816
	ds_read_b128 v[174:177], v5 offset:51200
	v_mfma_f32_16x16x32_bf16 v[30:33], v[118:121], v[110:113], v[30:33]
	v_mfma_f32_16x16x32_bf16 v[42:45], v[126:129], v[110:113], v[42:45]
	v_mfma_f32_16x16x32_bf16 v[14:17], v[158:161], v[110:113], v[14:17]
	v_mfma_f32_16x16x32_bf16 v[90:93], v[154:157], v[110:113], v[90:93]
	global_load_dwordx4 v[110:113], v223, s[36:37] offset:1920
	s_waitcnt vmcnt(8)
	ds_write_b128 v2, v[106:109] offset:8192
	ds_read_b128 v[106:109], v4 offset:36864
	ds_read_b128 v[178:181], v5 offset:53248
	v_mfma_f32_16x16x32_bf16 v[34:37], v[118:121], v[146:149], v[34:37]
	v_mfma_f32_16x16x32_bf16 v[46:49], v[126:129], v[146:149], v[46:49]
	v_mfma_f32_16x16x32_bf16 v[58:61], v[154:157], v[146:149], v[58:61]
	v_mfma_f32_16x16x32_bf16 v[18:21], v[158:161], v[146:149], v[18:21]
	v_add_u32_e32 v8, 0x30780, v8
	global_load_dwordx4 v[146:149], v8, s[36:37]
	s_waitcnt vmcnt(8)
	ds_write_b128 v2, v[132:135] offset:12288
	ds_read_b128 v[132:135], v4 offset:38912
	ds_read_b128 v[182:185], v5 offset:55296
	v_mfma_f32_16x16x32_bf16 v[38:41], v[118:121], v[150:153], v[38:41]
	v_mfma_f32_16x16x32_bf16 v[50:53], v[126:129], v[150:153], v[50:53]
	v_mfma_f32_16x16x32_bf16 v[54:57], v[154:157], v[150:153], v[54:57]
	v_mfma_f32_16x16x32_bf16 v[22:25], v[158:161], v[150:153], v[22:25]
	global_load_dwordx4 v[118:121], v3, s[0:1] offset:1920
	s_waitcnt vmcnt(8)
	ds_write_b128 v2, v[114:117] offset:16384
	s_waitcnt lgkmcnt(10)
	v_mfma_f32_16x16x32_bf16 v[26:29], v[170:173], v[162:165], v[26:29]
	s_waitcnt lgkmcnt(1)
	v_mfma_f32_16x16x32_bf16 v[8:11], v[182:185], v[162:165], v[10:13]
	v_mfma_f32_16x16x32_bf16 v[86:89], v[174:177], v[162:165], v[86:89]
	v_mfma_f32_16x16x32_bf16 v[94:97], v[178:181], v[162:165], v[94:97]
	s_nop 0
	global_load_dwordx4 v[114:117], v225, s[0:1] offset:1920
	s_waitcnt vmcnt(8)
	ds_write_b128 v2, v[122:125] offset:20480
	v_mfma_f32_16x16x32_bf16 v[30:33], v[170:173], v[82:85], v[30:33]
	v_mfma_f32_16x16x32_bf16 v[42:45], v[174:177], v[82:85], v[42:45]
	v_mfma_f32_16x16x32_bf16 v[12:15], v[182:185], v[82:85], v[14:17]
	v_mfma_f32_16x16x32_bf16 v[90:93], v[178:181], v[82:85], v[90:93]
	s_nop 1
	global_load_dwordx4 v[82:85], v226, s[0:1] offset:1920
	s_waitcnt vmcnt(8)
	ds_write_b128 v2, v[102:105] offset:24576
	v_mfma_f32_16x16x32_bf16 v[34:37], v[170:173], v[106:109], v[34:37]
	v_mfma_f32_16x16x32_bf16 v[46:49], v[174:177], v[106:109], v[46:49]
	v_mfma_f32_16x16x32_bf16 v[58:61], v[178:181], v[106:109], v[58:61]
	v_mfma_f32_16x16x32_bf16 v[16:19], v[182:185], v[106:109], v[18:21]
	v_add_u32_e32 v3, 0x30780, v3
	global_load_dwordx4 v[102:105], v3, s[0:1]
	s_waitcnt vmcnt(8)
	ds_write_b128 v2, v[62:65] offset:28672
	v_mfma_f32_16x16x32_bf16 v[38:41], v[170:173], v[132:135], v[38:41]
	v_mfma_f32_16x16x32_bf16 v[50:53], v[174:177], v[132:135], v[50:53]
	v_mfma_f32_16x16x32_bf16 v[54:57], v[178:181], v[132:135], v[54:57]
	v_mfma_f32_16x16x32_bf16 v[20:23], v[182:185], v[132:135], v[22:25]
	s_setprio 0
	s_waitcnt lgkmcnt(0)
	s_barrier
; template <int MODE>
; __device__ __forceinline__ void gemm_tile(const Params& P, int tm, int tn, unsigned char* smem) {
;     ...
; #pragma unroll
;         for (int i = 0; i < 4; ++i) { fa[i] = *(const bf16x8*)(sA + arow_off + i * 2048 + ch0); fb[i] = *(const bf16x8*)(sB + brow_off + i * 2048 + ch0); }
;         __builtin_amdgcn_sched_barrier(0);
;         __builtin_amdgcn_s_setprio(2);
;         if (wr_ok) *(uint4*)(nA + soff0) = ra0;
;         if (ld_ok) ra0 = *(const uint4*)(Ab + (aoff + 0u * LDA + koa));
;         ga[0] = *(const bf16x8*)(sA + arow_off + 0 * 2048 + ch1); gb[0] = *(const bf16x8*)(sB + brow_off + 0 * 2048 + ch1);
;         __builtin_amdgcn_sched_barrier(0);
; #pragma unroll
;         for (int j = 0; j < 4; ++j) acc[0][j] = __builtin_amdgcn_mfma_f32_16x16x32_bf16(fb[j], fa[0], acc[0][j], 0, 0, 0);
;         __builtin_amdgcn_sched_barrier(0);
;         if (wr_ok) *(uint4*)(nA + soff0 + 4096) = ra1;
;         if (ld_ok) ra1 = *(const uint4*)(Ab + (aoff + 32u * LDA + koa));
;         ga[1] = *(const bf16x8*)(sA + arow_off + 1 * 2048 + ch1); gb[1] = *(const bf16x8*)(sB + brow_off + 1 * 2048 + ch1);
;         __builtin_amdgcn_sched_barrier(0);
; #pragma unroll
;         for (int j = 0; j < 4; ++j) acc[1][j] = __builtin_amdgcn_mfma_f32_16x16x32_bf16(fb[j], fa[1], acc[1][j], 0, 0, 0);
;         __builtin_amdgcn_sched_barrier(0);
;         if (wr_ok) *(uint4*)(nA + soff0 + 8192) = ra2;
;         if (ld_ok) ra2 = *(const uint4*)(Ab + (aoff + 64u * LDA + koa));
;         ga[2] = *(const bf16x8*)(sA + arow_off + 2 * 2048 + ch1); gb[2] = *(const bf16x8*)(sB + brow_off + 2 * 2048 + ch1);
;         __builtin_amdgcn_sched_barrier(0);
; #pragma unroll
;         for (int j = 0; j < 4; ++j) acc[2][j] = __builtin_amdgcn_mfma_f32_16x16x32_bf16(fb[j], fa[2], acc[2][j], 0, 0, 0);
;         __builtin_amdgcn_sched_barrier(0);
;         if (wr_ok) *(uint4*)(nA + soff0 + 12288) = ra3;
;         if (ld_ok) ra3 = *(const uint4*)(Ab + (aoff + 96u * LDA + koa));
;         ga[3] = *(const bf16x8*)(sA + arow_off + 3 * 2048 + ch1); gb[3] = *(const bf16x8*)(sB + brow_off + 3 * 2048 + ch1);
;         __builtin_amdgcn_sched_barrier(0);
; #pragma unroll
;         for (int j = 0; j < 4; ++j) acc[3][j] = __builtin_amdgcn_mfma_f32_16x16x32_bf16(fb[j], fa[3], acc[3][j], 0, 0, 0);
;         __builtin_amdgcn_sched_barrier(0);
;         if (wr_ok) *(uint4*)(nB + soff0) = rb0;
	ds_read_b128 v[62:65], v6
	ds_read_b128 v[106:109], v6 offset:2048
	ds_read_b128 v[122:125], v7 offset:16384
	ds_read_b128 v[126:129], v7 offset:18432
	ds_read_b128 v[132:135], v6 offset:4096
	ds_read_b128 v[150:153], v6 offset:6144
	ds_read_b128 v[154:157], v7 offset:20480
	ds_read_b128 v[158:161], v7 offset:22528
	s_setprio 2
	s_waitcnt vmcnt(7)
	ds_write_b128 v2, v[166:169] offset:32768
	ds_read_b128 v[162:165], v4
	ds_read_b128 v[166:169], v5 offset:16384
	s_waitcnt lgkmcnt(8)
	v_mfma_f32_16x16x32_bf16 v[24:27], v[122:125], v[62:65], v[26:29]
	s_waitcnt lgkmcnt(3)
	v_mfma_f32_16x16x32_bf16 v[8:11], v[158:161], v[62:65], v[8:11]
	v_mfma_f32_16x16x32_bf16 v[86:89], v[126:129], v[62:65], v[86:89]
	v_mfma_f32_16x16x32_bf16 v[94:97], v[154:157], v[62:65], v[94:97]
	s_waitcnt vmcnt(6)
	ds_write_b128 v2, v[98:101] offset:36864
	ds_read_b128 v[62:65], v4 offset:2048
	ds_read_b128 v[98:101], v5 offset:18432
	v_mfma_f32_16x16x32_bf16 v[28:31], v[122:125], v[106:109], v[30:33]
	v_mfma_f32_16x16x32_bf16 v[42:45], v[126:129], v[106:109], v[42:45]
	v_mfma_f32_16x16x32_bf16 v[12:15], v[158:161], v[106:109], v[12:15]
	v_mfma_f32_16x16x32_bf16 v[90:93], v[154:157], v[106:109], v[90:93]
	s_waitcnt vmcnt(5)
	ds_write_b128 v2, v[110:113] offset:40960
	ds_read_b128 v[106:109], v4 offset:4096
	ds_read_b128 v[110:113], v5 offset:20480
	v_mfma_f32_16x16x32_bf16 v[32:35], v[122:125], v[132:135], v[34:37]
	v_mfma_f32_16x16x32_bf16 v[46:49], v[126:129], v[132:135], v[46:49]
	v_mfma_f32_16x16x32_bf16 v[58:61], v[154:157], v[132:135], v[58:61]
	v_mfma_f32_16x16x32_bf16 v[16:19], v[158:161], v[132:135], v[16:19]
	s_waitcnt vmcnt(4)
	ds_write_b128 v2, v[146:149] offset:45056
	ds_read_b128 v[132:135], v4 offset:6144
	ds_read_b128 v[146:149], v5 offset:22528
	v_mfma_f32_16x16x32_bf16 v[36:39], v[122:125], v[150:153], v[38:41]
	v_mfma_f32_16x16x32_bf16 v[50:53], v[126:129], v[150:153], v[50:53]
	v_mfma_f32_16x16x32_bf16 v[54:57], v[154:157], v[150:153], v[54:57]
	v_mfma_f32_16x16x32_bf16 v[20:23], v[158:161], v[150:153], v[20:23]
	s_waitcnt vmcnt(3)
	ds_write_b128 v2, v[118:121] offset:49152
	s_waitcnt lgkmcnt(10)
	v_mfma_f32_16x16x32_bf16 v[24:27], v[166:169], v[162:165], v[24:27]
	s_waitcnt lgkmcnt(1)
	v_mfma_f32_16x16x32_bf16 v[8:11], v[146:149], v[162:165], v[8:11]
	v_mfma_f32_16x16x32_bf16 v[86:89], v[98:101], v[162:165], v[86:89]
	v_mfma_f32_16x16x32_bf16 v[94:97], v[110:113], v[162:165], v[94:97]
	s_waitcnt vmcnt(2)
	ds_write_b128 v2, v[114:117] offset:53248
	v_mfma_f32_16x16x32_bf16 v[28:31], v[166:169], v[62:65], v[28:31]
	v_mfma_f32_16x16x32_bf16 v[40:43], v[98:101], v[62:65], v[42:45]
	v_mfma_f32_16x16x32_bf16 v[12:15], v[146:149], v[62:65], v[12:15]
	v_mfma_f32_16x16x32_bf16 v[90:93], v[110:113], v[62:65], v[90:93]
	s_waitcnt vmcnt(1)
	ds_write_b128 v2, v[82:85] offset:57344
	v_mfma_f32_16x16x32_bf16 v[32:35], v[166:169], v[106:109], v[32:35]
	v_mfma_f32_16x16x32_bf16 v[44:47], v[98:101], v[106:109], v[46:49]
	v_mfma_f32_16x16x32_bf16 v[58:61], v[110:113], v[106:109], v[58:61]
	v_mfma_f32_16x16x32_bf16 v[16:19], v[146:149], v[106:109], v[16:19]
	s_waitcnt vmcnt(0)
	ds_write_b128 v2, v[102:105] offset:61440
	v_mfma_f32_16x16x32_bf16 v[36:39], v[166:169], v[132:135], v[36:39]
	v_mfma_f32_16x16x32_bf16 v[48:51], v[98:101], v[132:135], v[50:53]
	v_mfma_f32_16x16x32_bf16 v[52:55], v[110:113], v[132:135], v[54:57]
	v_mfma_f32_16x16x32_bf16 v[20:23], v[146:149], v[132:135], v[20:23]
	s_setprio 0
	s_waitcnt lgkmcnt(0)
	s_barrier
	ds_read_b128 v[62:65], v6 offset:32768
	ds_read_b128 v[82:85], v6 offset:34816
	ds_read_b128 v[98:101], v7 offset:49152
	ds_read_b128 v[102:105], v7 offset:51200
	ds_read_b128 v[106:109], v6 offset:36864
	ds_read_b128 v[110:113], v6 offset:38912
	ds_read_b128 v[114:117], v7 offset:53248
	ds_read_b128 v[118:121], v7 offset:55296
	s_setprio 2
	ds_read_b128 v[122:125], v4 offset:32768
	ds_read_b128 v[126:129], v5 offset:49152
	s_waitcnt lgkmcnt(7)
	v_mfma_f32_16x16x32_bf16 v[24:27], v[98:101], v[62:65], v[24:27]
	s_waitcnt lgkmcnt(2)
	v_mfma_f32_16x16x32_bf16 v[6:9], v[118:121], v[62:65], v[8:11]
	v_mfma_f32_16x16x32_bf16 v[86:89], v[102:105], v[62:65], v[86:89]
	v_mfma_f32_16x16x32_bf16 v[94:97], v[114:117], v[62:65], v[94:97]
	ds_read_b128 v[132:135], v4 offset:34816
	ds_read_b128 v[146:149], v5 offset:51200
	v_mfma_f32_16x16x32_bf16 v[28:31], v[98:101], v[82:85], v[28:31]
	v_mfma_f32_16x16x32_bf16 v[40:43], v[102:105], v[82:85], v[40:43]
	v_mfma_f32_16x16x32_bf16 v[10:13], v[118:121], v[82:85], v[12:15]
	v_mfma_f32_16x16x32_bf16 v[90:93], v[114:117], v[82:85], v[90:93]
	ds_read_b128 v[82:85], v4 offset:36864
	ds_read_b128 v[150:153], v5 offset:53248
	v_mfma_f32_16x16x32_bf16 v[14:17], v[118:121], v[106:109], v[16:19]
	v_mfma_f32_16x16x32_bf16 v[154:157], v[98:101], v[106:109], v[32:35]
	v_mfma_f32_16x16x32_bf16 v[158:161], v[102:105], v[106:109], v[44:47]
	v_mfma_f32_16x16x32_bf16 v[162:165], v[114:117], v[106:109], v[58:61]
	ds_read_b128 v[106:109], v4 offset:38912
	ds_read_b128 v[2:5], v5 offset:55296
	v_mfma_f32_16x16x32_bf16 v[98:101], v[98:101], v[110:113], v[36:39]
	v_mfma_f32_16x16x32_bf16 v[102:105], v[102:105], v[110:113], v[48:51]
	v_mfma_f32_16x16x32_bf16 v[114:117], v[114:117], v[110:113], v[52:55]
	v_mfma_f32_16x16x32_bf16 v[110:113], v[118:121], v[110:113], v[20:23]
	s_waitcnt lgkmcnt(6)
	v_mfma_f32_16x16x32_bf16 v[62:65], v[126:129], v[122:125], v[24:27]
	s_waitcnt lgkmcnt(4)
	v_mfma_f32_16x16x32_bf16 v[58:61], v[146:149], v[122:125], v[86:89]
	s_waitcnt lgkmcnt(2)
	v_mfma_f32_16x16x32_bf16 v[54:57], v[150:153], v[122:125], v[94:97]
	s_waitcnt lgkmcnt(0)
	v_mfma_f32_16x16x32_bf16 v[50:53], v[2:5], v[122:125], v[6:9]
	v_mfma_f32_16x16x32_bf16 v[46:49], v[126:129], v[132:135], v[28:31]
	v_mfma_f32_16x16x32_bf16 v[42:45], v[146:149], v[132:135], v[40:43]
	v_mfma_f32_16x16x32_bf16 v[38:41], v[150:153], v[132:135], v[90:93]
	v_mfma_f32_16x16x32_bf16 v[34:37], v[2:5], v[132:135], v[10:13]
	v_mfma_f32_16x16x32_bf16 v[30:33], v[126:129], v[82:85], v[154:157]
	v_mfma_f32_16x16x32_bf16 v[26:29], v[146:149], v[82:85], v[158:161]
	v_mfma_f32_16x16x32_bf16 v[22:25], v[150:153], v[82:85], v[162:165]
	v_mfma_f32_16x16x32_bf16 v[18:21], v[2:5], v[82:85], v[14:17]
	v_mfma_f32_16x16x32_bf16 v[14:17], v[126:129], v[106:109], v[98:101]
	v_mfma_f32_16x16x32_bf16 v[10:13], v[146:149], v[106:109], v[102:105]
	v_mfma_f32_16x16x32_bf16 v[6:9], v[150:153], v[106:109], v[114:117]
	v_mfma_f32_16x16x32_bf16 v[2:5], v[2:5], v[106:109], v[110:113]
	s_setprio 0
	s_and_b32 s0, s7, -8
	s_cmp_lg_u32 s0, 16
	s_barrier
; template <int MODE>
; __device__ __forceinline__ void gemm_tile(const Params& P, int tm, int tn, unsigned char* smem) {
;     ...
;         if (n0 >= ZC_FQ && n0 < ZC_FV) {
;             const bool isk = n0 >= ZC_FK;
;             const float* gain = isk ? P.f_k_norm : P.f_q_norm;
;             const float scl = isk ? 1.0f : 0.125f * LOG2E;
;             float gn[4][4];
; #pragma unroll
;             for (int j = 0; j < 4; ++j)
; #pragma unroll
;                 for (int r = 0; r < 4; ++r) gn[j][r] = gain[16 * j + 4 * g + r];
; #pragma unroll
;             for (int i = 0; i < 4; ++i) {
;                 float ss = 0.f;
; #pragma unroll
;                 for (int j = 0; j < 4; ++j)
; #pragma unroll
;                     for (int r = 0; r < 4; ++r) ss += acc[i][j][r] * acc[i][j][r];
;                 ss = x4_sum(ss);
;                 const float rstd = rsqrtf(ss * (1.0f / 64.0f) + EPS) * scl;
	s_cbranch_scc1 .LBB0_223
	v_mul_f32_e32 v68, v63, v63
	v_fmac_f32_e32 v68, v62, v62
	v_fmac_f32_e32 v68, v64, v64
	v_fmac_f32_e32 v68, v65, v65
	v_fmac_f32_e32 v68, v58, v58
	v_fmac_f32_e32 v68, v59, v59
	v_fmac_f32_e32 v68, v60, v60
	v_fmac_f32_e32 v68, v61, v61
	v_fmac_f32_e32 v68, v54, v54
	v_fmac_f32_e32 v68, v55, v55
	v_fmac_f32_e32 v68, v56, v56
	s_cmp_gt_u32 s7, 19
	v_fmac_f32_e32 v68, v57, v57
	v_pk_mul_f32 v[82:83], v[50:51], v[50:51]
	v_mov_b32_e32 v66, 0x3e38aa3b
	s_cselect_b64 s[0:1], -1, 0
	v_add_f32_e32 v68, v82, v68
	v_cndmask_b32_e64 v106, v66, 1.0, s[0:1]
	v_pk_mul_f32 v[66:67], v[52:53], v[52:53]
	v_add_f32_e32 v68, v83, v68
	v_add_f32_e32 v66, v66, v68
	v_add_f32_e32 v66, v67, v66
	v_mov_b32_e32 v67, v66
	s_nop 1
	v_permlane32_swap_b32_e32 v66, v67
	v_add_f32_e32 v67, v66, v67
	v_mul_f32_e32 v66, v47, v47
	v_fmac_f32_e32 v66, v46, v46
	v_fmac_f32_e32 v66, v48, v48
	v_fmac_f32_e32 v66, v49, v49
	v_fmac_f32_e32 v66, v42, v42
	v_fmac_f32_e32 v66, v43, v43
	v_fmac_f32_e32 v66, v44, v44
	v_fmac_f32_e32 v66, v45, v45
	v_fmac_f32_e32 v66, v38, v38
	v_fmac_f32_e32 v66, v39, v39
	v_fmac_f32_e32 v66, v40, v40
	v_fmac_f32_e32 v66, v41, v41
	v_pk_mul_f32 v[86:87], v[34:35], v[34:35]
	v_pk_mul_f32 v[84:85], v[36:37], v[36:37]
	v_add_f32_e32 v66, v86, v66
	v_add_f32_e32 v66, v87, v66
	v_add_f32_e32 v66, v84, v66
	v_add_f32_e32 v66, v85, v66
	v_mov_b32_e32 v68, v66
	s_nop 1
	v_permlane32_swap_b32_e32 v66, v68
	v_add_f32_e32 v66, v66, v68
	s_and_b64 s[0:1], s[0:1], exec
	v_mov_b32_e32 v83, v67
	v_mov_b32_e32 v82, v66
	s_nop 0
	v_permlane16_swap_b32_e32 v67, v83
	v_permlane16_swap_b32_e32 v66, v82
	s_mov_b32 s0, 0x358637bd
	v_pk_add_f32 v[82:83], v[66:67], v[82:83]
	s_mov_b32 s10, 0x3c800000
	v_mov_b64_e32 v[66:67], s[0:1]
	v_mul_f32_e32 v95, v31, v31
	v_pk_fma_f32 v[86:87], v[82:83], s[10:11], v[66:67] op_sel_hi:[1,0,0]
	s_mov_b32 s7, 0x800000
	v_fmac_f32_e32 v95, v30, v30
	v_mul_f32_e32 v68, 0x4b800000, v87
	v_cmp_gt_f32_e32 vcc, s7, v87
	v_fmac_f32_e32 v95, v32, v32
	v_fmac_f32_e32 v95, v33, v33
	v_cndmask_b32_e32 v68, v87, v68, vcc
	v_rsq_f32_e32 v68, v68
	v_mul_f32_e32 v70, 0x4b800000, v86
	v_cmp_gt_f32_e64 s[0:1], s7, v86
	v_fmac_f32_e32 v95, v26, v26
	v_fmac_f32_e32 v95, v27, v27
	v_cndmask_b32_e64 v70, v86, v70, s[0:1]
	v_rsq_f32_e32 v86, v70
	v_fmac_f32_e32 v95, v28, v28
	s_cselect_b32 s9, s41, s39
	s_cselect_b32 s8, s40, s38
	v_lshlrev_b32_e32 v94, 4, v81
	v_fmac_f32_e32 v95, v29, v29
	global_load_dwordx4 v[82:85], v94, s[8:9]
	v_mul_f32_e32 v70, 0x45800000, v68
	v_fmac_f32_e32 v95, v22, v22
	v_cndmask_b32_e32 v68, v68, v70, vcc
	v_fmac_f32_e32 v95, v23, v23
	v_mul_f32_e32 v70, v106, v68
	v_mul_f32_e32 v68, 0x45800000, v86
	v_fmac_f32_e32 v95, v24, v24
	v_cndmask_b32_e64 v68, v86, v68, s[0:1]
	global_load_dwordx4 v[86:89], v94, s[8:9] offset:64
	v_fmac_f32_e32 v95, v25, v25
	v_pk_mul_f32 v[92:93], v[18:19], v[18:19]
	v_pk_mul_f32 v[90:91], v[20:21], v[20:21]
	v_add_f32_e32 v92, v92, v95
	v_add_f32_e32 v92, v93, v92
	v_add_f32_e32 v90, v90, v92
	v_add_f32_e32 v95, v91, v90
	global_load_dwordx4 v[90:93], v94, s[8:9] offset:128
	v_mov_b32_e32 v96, v95
	s_nop 1
	v_permlane32_swap_b32_e32 v95, v96
	v_add_f32_e32 v99, v95, v96
	global_load_dwordx4 v[94:97], v94, s[8:9] offset:192
	v_mul_f32_e32 v98, v15, v15
	v_fmac_f32_e32 v98, v14, v14
	v_fmac_f32_e32 v98, v16, v16
	v_fmac_f32_e32 v98, v17, v17
	v_fmac_f32_e32 v98, v10, v10
	v_fmac_f32_e32 v98, v11, v11
	v_fmac_f32_e32 v98, v12, v12
	v_fmac_f32_e32 v98, v13, v13
	v_fmac_f32_e32 v98, v6, v6
	v_fmac_f32_e32 v98, v7, v7
	v_fmac_f32_e32 v98, v8, v8
	v_fmac_f32_e32 v98, v9, v9
	v_pk_mul_f32 v[104:105], v[2:3], v[2:3]
	v_pk_mul_f32 v[102:103], v[4:5], v[4:5]
	v_add_f32_e32 v98, v104, v98
	v_add_f32_e32 v98, v105, v98
	v_add_f32_e32 v98, v102, v98
	v_add_f32_e32 v98, v103, v98
	v_mov_b32_e32 v100, v98
	s_nop 1
	v_permlane32_swap_b32_e32 v98, v100
	v_add_f32_e32 v98, v98, v100
	v_mov_b32_e32 v101, v99
	v_mov_b32_e32 v100, v98
	s_nop 0
	v_permlane16_swap_b32_e32 v99, v101
	v_permlane16_swap_b32_e32 v98, v100
	v_pk_add_f32 v[98:99], v[98:99], v[100:101]
	v_mul_f32_e32 v68, v106, v68
	v_pk_fma_f32 v[66:67], v[98:99], s[10:11], v[66:67] op_sel_hi:[1,0,0]
	s_waitcnt vmcnt(3)
; template <int MODE>
; __device__ __forceinline__ void gemm_tile(const Params& P, int tm, int tn, unsigned char* smem) {
;     ...
; #pragma unroll
;                 for (int j = 0; j < 4; ++j)
; #pragma unroll
;                     for (int r = 0; r < 4; ++r) acc[i][j][r] *= rstd * gn[j][r];
;             }
	v_pk_mul_f32 v[100:101], v[82:83], v[70:71] op_sel_hi:[1,0]
	v_mul_f32_e32 v98, 0x4b800000, v67
	v_cmp_gt_f32_e32 vcc, s7, v67
	v_cmp_gt_f32_e64 s[0:1], s7, v66
	v_pk_mul_f32 v[62:63], v[62:63], v[100:101]
	v_cndmask_b32_e32 v67, v67, v98, vcc
	v_mul_f32_e32 v98, 0x4b800000, v66
	v_rsq_f32_e32 v67, v67
	v_cndmask_b32_e64 v66, v66, v98, s[0:1]
	v_rsq_f32_e32 v98, v66
	v_pk_mul_f32 v[100:101], v[82:83], v[68:69] op_sel_hi:[1,0]
	v_mul_f32_e32 v66, 0x45800000, v67
	v_cndmask_b32_e32 v66, v67, v66, vcc
	v_mul_f32_e32 v67, 0x45800000, v98
	v_cndmask_b32_e64 v67, v98, v67, s[0:1]
	v_mul_f32_e32 v66, v106, v66
	v_mul_f32_e32 v98, v106, v67
	v_pk_mul_f32 v[102:103], v[84:85], v[70:71] op_sel_hi:[1,0]
	v_pk_mul_f32 v[46:47], v[46:47], v[100:101]
	v_pk_mul_f32 v[100:101], v[82:83], v[66:67] op_sel_hi:[1,0]
	v_pk_mul_f32 v[82:83], v[82:83], v[98:99] op_sel_hi:[1,0]
	v_pk_mul_f32 v[64:65], v[64:65], v[102:103]
	v_pk_mul_f32 v[102:103], v[84:85], v[68:69] op_sel_hi:[1,0]
	v_pk_mul_f32 v[14:15], v[14:15], v[82:83]
	s_waitcnt vmcnt(2)
	v_pk_mul_f32 v[82:83], v[86:87], v[70:71] op_sel_hi:[1,0]
	v_pk_mul_f32 v[48:49], v[48:49], v[102:103]
	v_pk_mul_f32 v[102:103], v[84:85], v[66:67] op_sel_hi:[1,0]
	v_pk_mul_f32 v[84:85], v[84:85], v[98:99] op_sel_hi:[1,0]
	v_pk_mul_f32 v[58:59], v[58:59], v[82:83]
	v_pk_mul_f32 v[82:83], v[86:87], v[68:69] op_sel_hi:[1,0]
	v_pk_mul_f32 v[16:17], v[16:17], v[84:85]
	v_pk_mul_f32 v[84:85], v[88:89], v[70:71] op_sel_hi:[1,0]
	v_pk_mul_f32 v[42:43], v[42:43], v[82:83]
	v_pk_mul_f32 v[82:83], v[86:87], v[66:67] op_sel_hi:[1,0]
	v_pk_mul_f32 v[60:61], v[60:61], v[84:85]
	v_pk_mul_f32 v[84:85], v[88:89], v[68:69] op_sel_hi:[1,0]
	v_pk_mul_f32 v[26:27], v[26:27], v[82:83]
	v_pk_mul_f32 v[82:83], v[86:87], v[98:99] op_sel_hi:[1,0]
	v_pk_mul_f32 v[44:45], v[44:45], v[84:85]
	v_pk_mul_f32 v[84:85], v[88:89], v[66:67] op_sel_hi:[1,0]
	v_pk_mul_f32 v[10:11], v[10:11], v[82:83]
	s_waitcnt vmcnt(1)
	v_pk_mul_f32 v[82:83], v[90:91], v[70:71] op_sel_hi:[1,0]
	v_pk_mul_f32 v[28:29], v[28:29], v[84:85]
	v_pk_mul_f32 v[84:85], v[88:89], v[98:99] op_sel_hi:[1,0]
	v_pk_mul_f32 v[54:55], v[54:55], v[82:83]
	v_pk_mul_f32 v[82:83], v[90:91], v[68:69] op_sel_hi:[1,0]
	v_pk_mul_f32 v[12:13], v[12:13], v[84:85]
	v_pk_mul_f32 v[84:85], v[92:93], v[70:71] op_sel_hi:[1,0]
	v_pk_mul_f32 v[38:39], v[38:39], v[82:83]
	v_pk_mul_f32 v[82:83], v[90:91], v[66:67] op_sel_hi:[1,0]
	v_pk_mul_f32 v[56:57], v[56:57], v[84:85]
	v_pk_mul_f32 v[84:85], v[92:93], v[68:69] op_sel_hi:[1,0]
	v_pk_mul_f32 v[22:23], v[22:23], v[82:83]
	v_pk_mul_f32 v[82:83], v[90:91], v[98:99] op_sel_hi:[1,0]
	v_pk_mul_f32 v[40:41], v[40:41], v[84:85]
	v_pk_mul_f32 v[84:85], v[92:93], v[66:67] op_sel_hi:[1,0]
	v_pk_mul_f32 v[6:7], v[6:7], v[82:83]
	s_waitcnt vmcnt(0)
	v_pk_mul_f32 v[82:83], v[94:95], v[70:71] op_sel_hi:[1,0]
	v_pk_mul_f32 v[24:25], v[24:25], v[84:85]
	v_pk_mul_f32 v[84:85], v[92:93], v[98:99] op_sel_hi:[1,0]
	v_pk_mul_f32 v[50:51], v[50:51], v[82:83]
	v_pk_mul_f32 v[82:83], v[94:95], v[68:69] op_sel_hi:[1,0]
	v_pk_mul_f32 v[8:9], v[8:9], v[84:85]
	v_pk_mul_f32 v[84:85], v[96:97], v[70:71] op_sel_hi:[1,0]
	v_pk_mul_f32 v[34:35], v[34:35], v[82:83]
	v_pk_mul_f32 v[82:83], v[94:95], v[66:67] op_sel_hi:[1,0]
	v_pk_mul_f32 v[66:67], v[96:97], v[66:67] op_sel_hi:[1,0]
	v_pk_mul_f32 v[52:53], v[52:53], v[84:85]
	v_pk_mul_f32 v[84:85], v[96:97], v[68:69] op_sel_hi:[1,0]
	v_pk_mul_f32 v[20:21], v[20:21], v[66:67]
	v_pk_mul_f32 v[18:19], v[18:19], v[82:83]
	v_pk_mul_f32 v[66:67], v[94:95], v[98:99] op_sel_hi:[1,0]
	v_pk_mul_f32 v[82:83], v[96:97], v[98:99] op_sel_hi:[1,0]
	v_pk_mul_f32 v[32:33], v[32:33], v[102:103]
	v_pk_mul_f32 v[30:31], v[30:31], v[100:101]
	v_pk_mul_f32 v[36:37], v[36:37], v[84:85]
	v_pk_mul_f32 v[4:5], v[4:5], v[82:83]
	v_pk_mul_f32 v[2:3], v[2:3], v[66:67]

; template <int MODE>
; __device__ __forceinline__ void gemm_tile(const Params& P, int tm, int tn, unsigned char* smem) {
;     ...
;     const int tid = opaque_tid(), lane = tid & 63, wave = tid >> 6, wr = wave >> 1, wc = wave & 1, g = lane >> 4, lr = lane & 15;
;     const int m0 = tm * 128, n0 = tn * 128;
;     const int srow = tid >> 3, sc = tid & 7;
;     constexpr unsigned LDA = (MODE == 2 ? NZ : 1024) * 2u;
;     unsigned aoff, boff; int soff0;
;     {
;         int ar = m0 + srow;
;         if (MODE == 2) { const int b = ar >> 11, t = ar & 2047; ar = b * L + NMETA + t; }
;         aoff = (unsigned)ar * LDA + (unsigned)sc * 16u;
;         boff = (unsigned)(n0 + srow) * 2048u + (unsigned)sc * 16u;
;         soff0 = srow * 128 + ((sc ^ (srow & 7)) << 4);
;     }
;     const unsigned char* Ab = (const unsigned char*)A; const unsigned char* Bb = (const unsigned char*)Bt;
;     float4 ssp0, ssp1, ssp2, ssp3;
;     if (MODE == 3) {
;         const float* ssq = (const float*)(P.ws + WS_SSQ) + (size_t)(m0 + wr * 64 + lr) * 16 + 4 * g;
;         ssp0 = *(const float4*)(ssq); ssp1 = *(const float4*)(ssq + 16 * 16); ssp2 = *(const float4*)(ssq + 32 * 16); ssp3 = *(const float4*)(ssq + 48 * 16);
;     }
;     f32x4 acc[4][4];
; #pragma unroll
;     for (int i = 0; i < 4; ++i)
; #pragma unroll
;         for (int j = 0; j < 4; ++j) acc[i][j] = (f32x4){0.f, 0.f, 0.f, 0.f};
;     uint4 ra0, ra1, ra2, ra3, rb0, rb1, rb2, rb3;
;     ...
;     unsigned char* sA0 = smem; unsigned char* sB0 = smem + 16384; unsigned char* sA1 = smem + 32768; unsigned char* sB1 = smem + 49152;
;     G_LOAD(0)
;     G_WRITE(sA0, sB0)
;     __syncthreads();
;     const int arow_off = (wr * 64 + lr) * 128, brow_off = (wc * 64 + lr) * 128, sw = lr & 7;
;     G_LOAD(1)
;     for (int kt = 0; kt < 16; ++kt) {
;         unsigned char* sA = (kt & 1) ? sA1 : sA0; unsigned char* sB = (kt & 1) ? sB1 : sB0;
;         unsigned char* nA = (kt & 1) ? sA0 : sA1; unsigned char* nB = (kt & 1) ? sB0 : sB1;
;         bf16x8 fa[4], fb[4], ga[4], gb[4];
;         const int ch0 = ((g ^ sw) << 4), ch1 = (((4 + g) ^ sw) << 4);
;         const unsigned ko = (unsigned)(kt + 2) * 128u;
;         const unsigned koa = ko + ((MODE == 2 && kt + 2 >= 8) ? (unsigned)(ZC_FQ - 512) * 2u : 0u);
;         const bool wr_ok = kt < 15, ld_ok = kt < 14;
; #pragma unroll
.LBB0_241:
	s_andn2_b64 vcc, exec, s[4:5]
	s_cbranch_vccnz .LBB0_245
	s_add_i32 s14, s14, s10
	s_mul_hi_i32 s0, s14, 0x92492493
	s_add_i32 s0, s0, s14
	s_lshr_b32 s1, s0, 31
	s_ashr_i32 s0, s0, 7
	s_add_i32 s0, s0, s1
	s_mul_i32 s1, s0, 0xffffff20
	s_lshl_b32 s0, s0, 3
	s_add_i32 s1, s1, s14
	s_sub_i32 s3, 0x81, s0
	s_cmpk_gt_i32 s14, 0xdff
	s_cselect_b32 s3, s3, 8
	s_abs_i32 s4, s3
	v_cvt_f32_u32_e32 v2, s4
	s_sub_i32 s7, 0, s4
	s_abs_i32 s5, s1
	s_xor_b32 s6, s1, s3
	v_rcp_iflag_f32_e32 v2, v2
	s_ashr_i32 s6, s6, 31
	v_mov_b32_e32 v69, v0
	v_mul_f32_e32 v2, 0x4f7ffffe, v2
	v_cvt_u32_f32_e32 v2, v2
	v_lshlrev_b32_e32 v3, 4, v69
	v_and_b32_e32 v5, 0x70, v3
	v_and_b32_e32 v78, 15, v69
	v_readfirstlane_b32 s8, v2
	s_mul_i32 s7, s7, s8
	s_mul_hi_u32 s7, s8, s7
	s_add_i32 s8, s8, s7
	s_mul_hi_u32 s7, s5, s8
	s_mul_i32 s8, s7, s4
	s_sub_i32 s5, s5, s8
	s_add_i32 s9, s7, 1
	s_sub_i32 s8, s5, s4
	s_cmp_ge_u32 s5, s4
	s_cselect_b32 s7, s9, s7
	s_cselect_b32 s5, s8, s5
	s_add_i32 s8, s7, 1
	s_cmp_ge_u32 s5, s4
	s_cselect_b32 s4, s8, s7
	s_xor_b32 s4, s4, s6
	s_sub_i32 s5, s4, s6
	s_mul_i32 s3, s5, s3
	s_add_i32 s1, s1, s0
	s_sub_i32 s0, s1, s3
	s_lshl_b32 s3, s0, 7
	v_ashrrev_i32_e32 v2, 3, v69
	s_lshl_b32 s4, s5, 7
	v_add_u32_e32 v4, s3, v2
	v_add_u32_e32 v3, s4, v2
	v_lshl_or_b32 v8, v4, 11, v5
	v_lshl_or_b32 v3, v3, 11, v5
	s_add_u32 s0, s28, 0xc075800
	v_add_u32_e32 v9, 0x10000, v8
	s_addc_u32 s1, s29, 0
	v_add_u32_e32 v22, 0x20000, v8
	global_load_dwordx4 v[4:7], v9, s[36:37]
	global_load_dwordx4 v[10:13], v22, s[36:37]
	global_load_dwordx4 v[14:17], v8, s[36:37]
	global_load_dwordx4 v[18:21], v3, s[0:1]
	v_add_u32_e32 v9, 0x20000, v3
	v_add_u32_e32 v30, 0x30000, v3
	global_load_dwordx4 v[22:25], v9, s[0:1]
	global_load_dwordx4 v[26:29], v30, s[0:1]
	v_add_u32_e32 v9, 0x30000, v8
	v_add_u32_e32 v38, 0x10000, v3
	global_load_dwordx4 v[30:33], v9, s[36:37]
	global_load_dwordx4 v[34:37], v38, s[0:1]
	v_xor_b32_e32 v9, v2, v69
	s_movk_i32 s6, 0x70
	v_lshlrev_b32_e32 v2, 7, v2
	v_lshlrev_b32_e32 v9, 4, v9
	v_and_or_b32 v2, v9, s6, v2
	v_add_u32_e32 v2, 0, v2
	v_or_b32_e32 v45, 0x80, v8
	v_or_b32_e32 v9, 0x80, v3
	v_add_u32_e32 v42, 0x10080, v3
	v_add_u32_e32 v43, 0x20080, v3
	v_add_u32_e32 v44, 0x30080, v3
	v_add_u32_e32 v46, 0x10080, v8
	v_add_u32_e32 v47, 0x20080, v8
	v_add_u32_e32 v48, 0x30080, v8
	v_ashrrev_i32_e32 v79, 7, v69
	v_bfe_u32 v80, v69, 6, 1
	v_bfe_u32 v81, v69, 4, 2
	s_waitcnt vmcnt(5)
	ds_write_b128 v2, v[14:17]
	s_waitcnt vmcnt(4)
	ds_write_b128 v2, v[18:21] offset:16384
	s_waitcnt vmcnt(3)
	ds_write_b128 v2, v[22:25] offset:24576
	s_waitcnt vmcnt(2)
	ds_write_b128 v2, v[26:29] offset:28672
	ds_write_b128 v2, v[4:7] offset:4096
	ds_write_b128 v2, v[10:13] offset:8192
	s_waitcnt vmcnt(1)
	ds_write_b128 v2, v[30:33] offset:12288
	s_waitcnt vmcnt(0)
	ds_write_b128 v2, v[34:37] offset:20480
	s_waitcnt lgkmcnt(0)
	s_barrier
	global_load_dwordx4 v[10:13], v45, s[36:37]
	global_load_dwordx4 v[14:17], v46, s[36:37]
	global_load_dwordx4 v[18:21], v47, s[36:37]
	global_load_dwordx4 v[22:25], v48, s[36:37]
	global_load_dwordx4 v[26:29], v9, s[0:1]
	global_load_dwordx4 v[30:33], v42, s[0:1]
	global_load_dwordx4 v[34:37], v43, s[0:1]
	global_load_dwordx4 v[38:41], v44, s[0:1]
	v_lshrrev_b32_e32 v4, 4, v69
	v_lshlrev_b32_e32 v5, 7, v78
	v_and_b32_e32 v9, 7, v69
	v_lshl_or_b32 v6, v79, 13, v5
	v_bitop3_b32 v4, v4, v9, 3 bitop3:0x6c
	v_lshl_or_b32 v5, v80, 13, v5
	v_lshlrev_b32_e32 v4, 4, v4
	v_add_u32_e32 v66, 0, v6
	v_add_u32_e32 v6, v66, v4
	v_add_u32_e32 v5, 0, v5
	v_add_u32_e32 v7, v5, v4
	ds_read_b128 v[42:45], v6
	ds_read_b128 v[46:49], v6 offset:2048
	ds_read_b128 v[50:53], v7 offset:16384
	ds_read_b128 v[54:57], v7 offset:18432
	ds_read_b128 v[58:61], v6 offset:4096
	ds_read_b128 v[62:65], v6 offset:6144
	ds_read_b128 v[82:85], v7 offset:20480
	ds_read_b128 v[86:89], v7 offset:22528
	v_bitop3_b32 v4, v81, v9, 4 bitop3:0x36
	v_lshlrev_b32_e32 v9, 4, v4
	s_setprio 2
	global_load_dwordx4 v[90:93], v8, s[36:37] offset:256
	s_waitcnt vmcnt(8)
	ds_write_b128 v2, v[10:13] offset:32768
	v_add_u32_e32 v4, v66, v9
	v_add_u32_e32 v5, v5, v9
	ds_read_b128 v[10:13], v4
	ds_read_b128 v[94:97], v5 offset:16384
	s_waitcnt lgkmcnt(8)
	v_mfma_f32_16x16x32_bf16 v[98:101], v[50:53], v[42:45], 0
	s_waitcnt lgkmcnt(7)
	v_mfma_f32_16x16x32_bf16 v[102:105], v[54:57], v[42:45], 0
	s_waitcnt lgkmcnt(4)
	v_mfma_f32_16x16x32_bf16 v[106:109], v[82:85], v[42:45], 0
	s_waitcnt lgkmcnt(3)
	v_mfma_f32_16x16x32_bf16 v[42:45], v[86:89], v[42:45], 0
	v_add_u32_e32 v228, 0x10000, v8
	global_load_dwordx4 v[110:113], v228, s[36:37] offset:256
	s_waitcnt vmcnt(8)
	ds_write_b128 v2, v[14:17] offset:36864
	ds_read_b128 v[14:17], v4 offset:2048
	ds_read_b128 v[114:117], v5 offset:18432
	v_mfma_f32_16x16x32_bf16 v[118:121], v[50:53], v[46:49], 0
	v_mfma_f32_16x16x32_bf16 v[122:125], v[54:57], v[46:49], 0
	v_mfma_f32_16x16x32_bf16 v[126:129], v[82:85], v[46:49], 0
	v_mfma_f32_16x16x32_bf16 v[46:49], v[86:89], v[46:49], 0
	v_add_u32_e32 v229, 0x20000, v8
	global_load_dwordx4 v[132:135], v229, s[36:37] offset:256
	s_waitcnt vmcnt(8)
	ds_write_b128 v2, v[18:21] offset:40960
	ds_read_b128 v[18:21], v4 offset:4096
	ds_read_b128 v[146:149], v5 offset:20480
	v_mfma_f32_16x16x32_bf16 v[150:153], v[50:53], v[58:61], 0
	v_mfma_f32_16x16x32_bf16 v[154:157], v[54:57], v[58:61], 0
	v_mfma_f32_16x16x32_bf16 v[158:161], v[82:85], v[58:61], 0
	v_mfma_f32_16x16x32_bf16 v[58:61], v[86:89], v[58:61], 0
	v_add_u32_e32 v230, 0x30000, v8
	global_load_dwordx4 v[162:165], v230, s[36:37] offset:256
	s_waitcnt vmcnt(8)
; template <int MODE>
; __device__ __forceinline__ void gemm_tile(const Params& P, int tm, int tn, unsigned char* smem) {
;     ...
; #pragma unroll
;         for (int i = 0; i < 4; ++i) { fa[i] = *(const bf16x8*)(sA + arow_off + i * 2048 + ch0); fb[i] = *(const bf16x8*)(sB + brow_off + i * 2048 + ch0); }
;         __builtin_amdgcn_sched_barrier(0);
;         __builtin_amdgcn_s_setprio(2);
;         if (wr_ok) *(uint4*)(nA + soff0) = ra0;
;         if (ld_ok) ra0 = *(const uint4*)(Ab + (aoff + 0u * LDA + koa));
;         ga[0] = *(const bf16x8*)(sA + arow_off + 0 * 2048 + ch1); gb[0] = *(const bf16x8*)(sB + brow_off + 0 * 2048 + ch1);
;         __builtin_amdgcn_sched_barrier(0);
; #pragma unroll
;         for (int j = 0; j < 4; ++j) acc[0][j] = __builtin_amdgcn_mfma_f32_16x16x32_bf16(fb[j], fa[0], acc[0][j], 0, 0, 0);
;         __builtin_amdgcn_sched_barrier(0);
;         if (wr_ok) *(uint4*)(nA + soff0 + 4096) = ra1;
;         if (ld_ok) ra1 = *(const uint4*)(Ab + (aoff + 32u * LDA + koa));
;         ga[1] = *(const bf16x8*)(sA + arow_off + 1 * 2048 + ch1); gb[1] = *(const bf16x8*)(sB + brow_off + 1 * 2048 + ch1);
;         __builtin_amdgcn_sched_barrier(0);
; #pragma unroll
;         for (int j = 0; j < 4; ++j) acc[1][j] = __builtin_amdgcn_mfma_f32_16x16x32_bf16(fb[j], fa[1], acc[1][j], 0, 0, 0);
;         __builtin_amdgcn_sched_barrier(0);
;         if (wr_ok) *(uint4*)(nA + soff0 + 8192) = ra2;
;         if (ld_ok) ra2 = *(const uint4*)(Ab + (aoff + 64u * LDA + koa));
;         ga[2] = *(const bf16x8*)(sA + arow_off + 2 * 2048 + ch1); gb[2] = *(const bf16x8*)(sB + brow_off + 2 * 2048 + ch1);
;         __builtin_amdgcn_sched_barrier(0);
; #pragma unroll
;         for (int j = 0; j < 4; ++j) acc[2][j] = __builtin_amdgcn_mfma_f32_16x16x32_bf16(fb[j], fa[2], acc[2][j], 0, 0, 0);
;         __builtin_amdgcn_sched_barrier(0);
;         if (wr_ok) *(uint4*)(nA + soff0 + 12288) = ra3;
;         if (ld_ok) ra3 = *(const uint4*)(Ab + (aoff + 96u * LDA + koa));
;         ga[3] = *(const bf16x8*)(sA + arow_off + 3 * 2048 + ch1); gb[3] = *(const bf16x8*)(sB + brow_off + 3 * 2048 + ch1);
;         __builtin_amdgcn_sched_barrier(0);
; #pragma unroll
;         for (int j = 0; j < 4; ++j) acc[3][j] = __builtin_amdgcn_mfma_f32_16x16x32_bf16(fb[j], fa[3], acc[3][j], 0, 0, 0);
;         __builtin_amdgcn_sched_barrier(0);
;         if (wr_ok) *(uint4*)(nB + soff0) = rb0;
	ds_write_b128 v2, v[22:25] offset:45056
	ds_read_b128 v[22:25], v4 offset:6144
	ds_read_b128 v[166:169], v5 offset:22528
	v_mfma_f32_16x16x32_bf16 v[50:53], v[50:53], v[62:65], 0
	v_mfma_f32_16x16x32_bf16 v[54:57], v[54:57], v[62:65], 0
	v_mfma_f32_16x16x32_bf16 v[82:85], v[82:85], v[62:65], 0
	v_mfma_f32_16x16x32_bf16 v[62:65], v[86:89], v[62:65], 0
	global_load_dwordx4 v[86:89], v3, s[0:1] offset:256
	s_waitcnt vmcnt(8)
	ds_write_b128 v2, v[26:29] offset:49152
	s_waitcnt lgkmcnt(10)
	v_mfma_f32_16x16x32_bf16 v[26:29], v[94:97], v[10:13], v[98:101]
	s_waitcnt lgkmcnt(7)
	v_mfma_f32_16x16x32_bf16 v[98:101], v[114:117], v[10:13], v[102:105]
	s_waitcnt lgkmcnt(4)
	v_mfma_f32_16x16x32_bf16 v[102:105], v[146:149], v[10:13], v[106:109]
	s_waitcnt lgkmcnt(1)
	v_mfma_f32_16x16x32_bf16 v[10:13], v[166:169], v[10:13], v[42:45]
	v_add_u32_e32 v231, 0x10000, v3
	global_load_dwordx4 v[42:45], v231, s[0:1] offset:256
	s_waitcnt vmcnt(8)
	ds_write_b128 v2, v[30:33] offset:53248
	v_mfma_f32_16x16x32_bf16 v[30:33], v[94:97], v[14:17], v[118:121]
	v_mfma_f32_16x16x32_bf16 v[106:109], v[114:117], v[14:17], v[122:125]
	v_mfma_f32_16x16x32_bf16 v[118:121], v[146:149], v[14:17], v[126:129]
	v_mfma_f32_16x16x32_bf16 v[14:17], v[166:169], v[14:17], v[46:49]
	v_add_u32_e32 v232, 0x20000, v3
	global_load_dwordx4 v[46:49], v232, s[0:1] offset:256
	s_waitcnt vmcnt(8)
	ds_write_b128 v2, v[34:37] offset:57344
	v_mfma_f32_16x16x32_bf16 v[34:37], v[94:97], v[18:21], v[150:153]
	v_mfma_f32_16x16x32_bf16 v[122:125], v[114:117], v[18:21], v[154:157]
	v_mfma_f32_16x16x32_bf16 v[126:129], v[146:149], v[18:21], v[158:161]
	v_mfma_f32_16x16x32_bf16 v[18:21], v[166:169], v[18:21], v[58:61]
	v_add_u32_e32 v233, 0x30000, v3
	global_load_dwordx4 v[58:61], v233, s[0:1] offset:256
	s_waitcnt vmcnt(8)
	ds_write_b128 v2, v[38:41] offset:61440
	v_mfma_f32_16x16x32_bf16 v[38:41], v[94:97], v[22:25], v[50:53]
	v_mfma_f32_16x16x32_bf16 v[50:53], v[114:117], v[22:25], v[54:57]
	v_mfma_f32_16x16x32_bf16 v[54:57], v[146:149], v[22:25], v[82:85]
	v_mfma_f32_16x16x32_bf16 v[22:25], v[166:169], v[22:25], v[62:65]
	s_setprio 0
	s_waitcnt lgkmcnt(0)
	s_barrier
	ds_read_b128 v[62:65], v6 offset:32768
	ds_read_b128 v[82:85], v6 offset:34816
	ds_read_b128 v[94:97], v7 offset:49152
	ds_read_b128 v[114:117], v7 offset:51200
	ds_read_b128 v[146:149], v6 offset:36864
	ds_read_b128 v[150:153], v6 offset:38912
	ds_read_b128 v[154:157], v7 offset:53248
	ds_read_b128 v[158:161], v7 offset:55296
	s_setprio 2
	global_load_dwordx4 v[166:169], v8, s[36:37] offset:384
	s_waitcnt vmcnt(8)
	ds_write_b128 v2, v[90:93]
	ds_read_b128 v[90:93], v4 offset:32768
	ds_read_b128 v[170:173], v5 offset:49152
	s_waitcnt lgkmcnt(8)
	v_mfma_f32_16x16x32_bf16 v[26:29], v[94:97], v[62:65], v[26:29]
	s_waitcnt lgkmcnt(3)
	v_mfma_f32_16x16x32_bf16 v[10:13], v[158:161], v[62:65], v[10:13]
	v_mfma_f32_16x16x32_bf16 v[98:101], v[114:117], v[62:65], v[98:101]
	v_mfma_f32_16x16x32_bf16 v[102:105], v[154:157], v[62:65], v[102:105]
	global_load_dwordx4 v[62:65], v228, s[36:37] offset:384
	s_waitcnt vmcnt(8)
	ds_write_b128 v2, v[110:113] offset:4096
	ds_read_b128 v[110:113], v4 offset:34816
	ds_read_b128 v[174:177], v5 offset:51200
	v_mfma_f32_16x16x32_bf16 v[30:33], v[94:97], v[82:85], v[30:33]
	v_mfma_f32_16x16x32_bf16 v[14:17], v[158:161], v[82:85], v[14:17]
	v_mfma_f32_16x16x32_bf16 v[106:109], v[114:117], v[82:85], v[106:109]
	v_mfma_f32_16x16x32_bf16 v[118:121], v[154:157], v[82:85], v[118:121]
	global_load_dwordx4 v[82:85], v229, s[36:37] offset:384
	s_waitcnt vmcnt(8)
	ds_write_b128 v2, v[132:135] offset:8192
	ds_read_b128 v[132:135], v4 offset:36864
	ds_read_b128 v[178:181], v5 offset:53248
	v_mfma_f32_16x16x32_bf16 v[34:37], v[94:97], v[146:149], v[34:37]
	v_mfma_f32_16x16x32_bf16 v[18:21], v[158:161], v[146:149], v[18:21]
	v_mfma_f32_16x16x32_bf16 v[122:125], v[114:117], v[146:149], v[122:125]
	v_mfma_f32_16x16x32_bf16 v[126:129], v[154:157], v[146:149], v[126:129]
	global_load_dwordx4 v[146:149], v230, s[36:37] offset:384
	s_waitcnt vmcnt(8)
	ds_write_b128 v2, v[162:165] offset:12288
	ds_read_b128 v[162:165], v4 offset:38912
	ds_read_b128 v[182:185], v5 offset:55296
	v_mfma_f32_16x16x32_bf16 v[38:41], v[94:97], v[150:153], v[38:41]
	v_mfma_f32_16x16x32_bf16 v[50:53], v[114:117], v[150:153], v[50:53]
	v_mfma_f32_16x16x32_bf16 v[54:57], v[154:157], v[150:153], v[54:57]
	v_mfma_f32_16x16x32_bf16 v[22:25], v[158:161], v[150:153], v[22:25]
	global_load_dwordx4 v[94:97], v3, s[0:1] offset:384
	s_waitcnt vmcnt(8)
	ds_write_b128 v2, v[86:89] offset:16384
	s_waitcnt lgkmcnt(10)
	v_mfma_f32_16x16x32_bf16 v[26:29], v[170:173], v[90:93], v[26:29]
	s_waitcnt lgkmcnt(1)
	v_mfma_f32_16x16x32_bf16 v[10:13], v[182:185], v[90:93], v[10:13]
	v_mfma_f32_16x16x32_bf16 v[86:89], v[174:177], v[90:93], v[98:101]
	v_mfma_f32_16x16x32_bf16 v[98:101], v[178:181], v[90:93], v[102:105]
	global_load_dwordx4 v[90:93], v231, s[0:1] offset:384
	s_waitcnt vmcnt(8)
	ds_write_b128 v2, v[42:45] offset:20480
	v_mfma_f32_16x16x32_bf16 v[30:33], v[170:173], v[110:113], v[30:33]
	v_mfma_f32_16x16x32_bf16 v[42:45], v[174:177], v[110:113], v[106:109]
	v_mfma_f32_16x16x32_bf16 v[14:17], v[182:185], v[110:113], v[14:17]
	v_mfma_f32_16x16x32_bf16 v[102:105], v[178:181], v[110:113], v[118:121]
	global_load_dwordx4 v[106:109], v232, s[0:1] offset:384
	s_waitcnt vmcnt(8)
	ds_write_b128 v2, v[46:49] offset:24576
	v_mfma_f32_16x16x32_bf16 v[34:37], v[170:173], v[132:135], v[34:37]
	v_mfma_f32_16x16x32_bf16 v[46:49], v[174:177], v[132:135], v[122:125]
	v_mfma_f32_16x16x32_bf16 v[18:21], v[182:185], v[132:135], v[18:21]
	v_mfma_f32_16x16x32_bf16 v[110:113], v[178:181], v[132:135], v[126:129]
	global_load_dwordx4 v[114:117], v233, s[0:1] offset:384
	s_waitcnt vmcnt(8)
	ds_write_b128 v2, v[58:61] offset:28672
	v_mfma_f32_16x16x32_bf16 v[38:41], v[170:173], v[162:165], v[38:41]
	v_mfma_f32_16x16x32_bf16 v[50:53], v[174:177], v[162:165], v[50:53]
	v_mfma_f32_16x16x32_bf16 v[54:57], v[178:181], v[162:165], v[54:57]
	v_mfma_f32_16x16x32_bf16 v[22:25], v[182:185], v[162:165], v[22:25]
	s_setprio 0
	s_waitcnt lgkmcnt(0)
	s_barrier
; template <int MODE>
; __device__ __forceinline__ void gemm_tile(const Params& P, int tm, int tn, unsigned char* smem) {
;     ...
;     for (int kt = 0; kt < 16; ++kt) {
;         unsigned char* sA = (kt & 1) ? sA1 : sA0; unsigned char* sB = (kt & 1) ? sB1 : sB0;
;         unsigned char* nA = (kt & 1) ? sA0 : sA1; unsigned char* nB = (kt & 1) ? sB0 : sB1;
;         bf16x8 fa[4], fb[4], ga[4], gb[4];
;         const int ch0 = ((g ^ sw) << 4), ch1 = (((4 + g) ^ sw) << 4);
;         const unsigned ko = (unsigned)(kt + 2) * 128u;
;         const unsigned koa = ko + ((MODE == 2 && kt + 2 >= 8) ? (unsigned)(ZC_FQ - 512) * 2u : 0u);
;         const bool wr_ok = kt < 15, ld_ok = kt < 14;
; #pragma unroll
;         for (int i = 0; i < 4; ++i) { fa[i] = *(const bf16x8*)(sA + arow_off + i * 2048 + ch0); fb[i] = *(const bf16x8*)(sB + brow_off + i * 2048 + ch0); }
;         __builtin_amdgcn_sched_barrier(0);
;         __builtin_amdgcn_s_setprio(2);
;         if (wr_ok) *(uint4*)(nA + soff0) = ra0;
;         if (ld_ok) ra0 = *(const uint4*)(Ab + (aoff + 0u * LDA + koa));
;         ga[0] = *(const bf16x8*)(sA + arow_off + 0 * 2048 + ch1); gb[0] = *(const bf16x8*)(sB + brow_off + 0 * 2048 + ch1);
;         __builtin_amdgcn_sched_barrier(0);
; #pragma unroll
;         for (int j = 0; j < 4; ++j) acc[0][j] = __builtin_amdgcn_mfma_f32_16x16x32_bf16(fb[j], fa[0], acc[0][j], 0, 0, 0);
;         __builtin_amdgcn_sched_barrier(0);
;         if (wr_ok) *(uint4*)(nA + soff0 + 4096) = ra1;
;         if (ld_ok) ra1 = *(const uint4*)(Ab + (aoff + 32u * LDA + koa));
;         ga[1] = *(const bf16x8*)(sA + arow_off + 1 * 2048 + ch1); gb[1] = *(const bf16x8*)(sB + brow_off + 1 * 2048 + ch1);
;         __builtin_amdgcn_sched_barrier(0);
; #pragma unroll
;         for (int j = 0; j < 4; ++j) acc[1][j] = __builtin_amdgcn_mfma_f32_16x16x32_bf16(fb[j], fa[1], acc[1][j], 0, 0, 0);
;         __builtin_amdgcn_sched_barrier(0);
;         if (wr_ok) *(uint4*)(nA + soff0 + 8192) = ra2;
;         if (ld_ok) ra2 = *(const uint4*)(Ab + (aoff + 64u * LDA + koa));
;         ga[2] = *(const bf16x8*)(sA + arow_off + 2 * 2048 + ch1); gb[2] = *(const bf16x8*)(sB + brow_off + 2 * 2048 + ch1);
;         __builtin_amdgcn_sched_barrier(0);
; #pragma unroll
;         for (int j = 0; j < 4; ++j) acc[2][j] = __builtin_amdgcn_mfma_f32_16x16x32_bf16(fb[j], fa[2], acc[2][j], 0, 0, 0);
	ds_read_b128 v[58:61], v6
	ds_read_b128 v[118:121], v6 offset:2048
	ds_read_b128 v[122:125], v7 offset:16384
	ds_read_b128 v[126:129], v7 offset:18432
	ds_read_b128 v[132:135], v6 offset:4096
	ds_read_b128 v[150:153], v6 offset:6144
	ds_read_b128 v[154:157], v7 offset:20480
	ds_read_b128 v[158:161], v7 offset:22528
	s_setprio 2
	global_load_dwordx4 v[162:165], v8, s[36:37] offset:512
	s_waitcnt vmcnt(8)
	ds_write_b128 v2, v[166:169] offset:32768
	ds_read_b128 v[166:169], v4
	ds_read_b128 v[170:173], v5 offset:16384
	s_waitcnt lgkmcnt(8)
	v_mfma_f32_16x16x32_bf16 v[26:29], v[122:125], v[58:61], v[26:29]
	s_waitcnt lgkmcnt(3)
	v_mfma_f32_16x16x32_bf16 v[10:13], v[158:161], v[58:61], v[10:13]
	v_mfma_f32_16x16x32_bf16 v[86:89], v[126:129], v[58:61], v[86:89]
	v_mfma_f32_16x16x32_bf16 v[98:101], v[154:157], v[58:61], v[98:101]
	global_load_dwordx4 v[58:61], v228, s[36:37] offset:512
	s_waitcnt vmcnt(8)
	ds_write_b128 v2, v[62:65] offset:36864
	ds_read_b128 v[62:65], v4 offset:2048
	ds_read_b128 v[174:177], v5 offset:18432
	v_mfma_f32_16x16x32_bf16 v[30:33], v[122:125], v[118:121], v[30:33]
	v_mfma_f32_16x16x32_bf16 v[42:45], v[126:129], v[118:121], v[42:45]
	v_mfma_f32_16x16x32_bf16 v[14:17], v[158:161], v[118:121], v[14:17]
	v_mfma_f32_16x16x32_bf16 v[102:105], v[154:157], v[118:121], v[102:105]
	global_load_dwordx4 v[118:121], v229, s[36:37] offset:512
	s_waitcnt vmcnt(8)
	ds_write_b128 v2, v[82:85] offset:40960
	ds_read_b128 v[82:85], v4 offset:4096
	ds_read_b128 v[178:181], v5 offset:20480
	v_mfma_f32_16x16x32_bf16 v[34:37], v[122:125], v[132:135], v[34:37]
	v_mfma_f32_16x16x32_bf16 v[46:49], v[126:129], v[132:135], v[46:49]
	v_mfma_f32_16x16x32_bf16 v[18:21], v[158:161], v[132:135], v[18:21]
	v_mfma_f32_16x16x32_bf16 v[110:113], v[154:157], v[132:135], v[110:113]
	global_load_dwordx4 v[132:135], v230, s[36:37] offset:512
	s_waitcnt vmcnt(8)
	ds_write_b128 v2, v[146:149] offset:45056
	ds_read_b128 v[146:149], v4 offset:6144
	ds_read_b128 v[182:185], v5 offset:22528
	v_mfma_f32_16x16x32_bf16 v[38:41], v[122:125], v[150:153], v[38:41]
	v_mfma_f32_16x16x32_bf16 v[50:53], v[126:129], v[150:153], v[50:53]
	v_mfma_f32_16x16x32_bf16 v[54:57], v[154:157], v[150:153], v[54:57]
	v_mfma_f32_16x16x32_bf16 v[22:25], v[158:161], v[150:153], v[22:25]
	global_load_dwordx4 v[122:125], v3, s[0:1] offset:512
	s_waitcnt vmcnt(8)
	ds_write_b128 v2, v[94:97] offset:49152
	s_waitcnt lgkmcnt(10)
	v_mfma_f32_16x16x32_bf16 v[26:29], v[170:173], v[166:169], v[26:29]
	s_waitcnt lgkmcnt(1)
	v_mfma_f32_16x16x32_bf16 v[10:13], v[182:185], v[166:169], v[10:13]
	v_mfma_f32_16x16x32_bf16 v[86:89], v[174:177], v[166:169], v[86:89]
	v_mfma_f32_16x16x32_bf16 v[94:97], v[178:181], v[166:169], v[98:101]
	global_load_dwordx4 v[98:101], v231, s[0:1] offset:512
	s_waitcnt vmcnt(8)
	ds_write_b128 v2, v[90:93] offset:53248
	v_mfma_f32_16x16x32_bf16 v[30:33], v[170:173], v[62:65], v[30:33]
	v_mfma_f32_16x16x32_bf16 v[42:45], v[174:177], v[62:65], v[42:45]
	v_mfma_f32_16x16x32_bf16 v[14:17], v[182:185], v[62:65], v[14:17]
	v_mfma_f32_16x16x32_bf16 v[90:93], v[178:181], v[62:65], v[102:105]
	global_load_dwordx4 v[62:65], v232, s[0:1] offset:512
	s_waitcnt vmcnt(8)
	ds_write_b128 v2, v[106:109] offset:57344
	v_mfma_f32_16x16x32_bf16 v[34:37], v[170:173], v[82:85], v[34:37]
	v_mfma_f32_16x16x32_bf16 v[46:49], v[174:177], v[82:85], v[46:49]
	v_mfma_f32_16x16x32_bf16 v[18:21], v[182:185], v[82:85], v[18:21]
	v_mfma_f32_16x16x32_bf16 v[102:105], v[178:181], v[82:85], v[110:113]
	global_load_dwordx4 v[82:85], v233, s[0:1] offset:512
	s_waitcnt vmcnt(8)
	ds_write_b128 v2, v[114:117] offset:61440
	v_mfma_f32_16x16x32_bf16 v[38:41], v[170:173], v[146:149], v[38:41]
	v_mfma_f32_16x16x32_bf16 v[50:53], v[174:177], v[146:149], v[50:53]
	v_mfma_f32_16x16x32_bf16 v[54:57], v[178:181], v[146:149], v[54:57]
	v_mfma_f32_16x16x32_bf16 v[22:25], v[182:185], v[146:149], v[22:25]
	s_setprio 0
	s_waitcnt lgkmcnt(0)
	s_barrier
	ds_read_b128 v[106:109], v6 offset:32768
	ds_read_b128 v[110:113], v6 offset:34816
	ds_read_b128 v[114:117], v7 offset:49152
	ds_read_b128 v[126:129], v7 offset:51200
	ds_read_b128 v[146:149], v6 offset:36864
	ds_read_b128 v[150:153], v6 offset:38912
	ds_read_b128 v[154:157], v7 offset:53248
	ds_read_b128 v[158:161], v7 offset:55296
	s_setprio 2
	global_load_dwordx4 v[166:169], v8, s[36:37] offset:640
	s_waitcnt vmcnt(8)
	ds_write_b128 v2, v[162:165]
	ds_read_b128 v[162:165], v4 offset:32768
	ds_read_b128 v[170:173], v5 offset:49152
	s_waitcnt lgkmcnt(8)
	v_mfma_f32_16x16x32_bf16 v[26:29], v[114:117], v[106:109], v[26:29]
	s_waitcnt lgkmcnt(3)
	v_mfma_f32_16x16x32_bf16 v[10:13], v[158:161], v[106:109], v[10:13]
	v_mfma_f32_16x16x32_bf16 v[86:89], v[126:129], v[106:109], v[86:89]
	v_mfma_f32_16x16x32_bf16 v[94:97], v[154:157], v[106:109], v[94:97]
	global_load_dwordx4 v[106:109], v228, s[36:37] offset:640
	s_waitcnt vmcnt(8)
	ds_write_b128 v2, v[58:61] offset:4096
	ds_read_b128 v[58:61], v4 offset:34816
	ds_read_b128 v[174:177], v5 offset:51200
	v_mfma_f32_16x16x32_bf16 v[30:33], v[114:117], v[110:113], v[30:33]
	v_mfma_f32_16x16x32_bf16 v[42:45], v[126:129], v[110:113], v[42:45]
	v_mfma_f32_16x16x32_bf16 v[14:17], v[158:161], v[110:113], v[14:17]
	v_mfma_f32_16x16x32_bf16 v[90:93], v[154:157], v[110:113], v[90:93]
	global_load_dwordx4 v[110:113], v229, s[36:37] offset:640
	s_waitcnt vmcnt(8)
	ds_write_b128 v2, v[118:121] offset:8192
	ds_read_b128 v[118:121], v4 offset:36864
	ds_read_b128 v[178:181], v5 offset:53248
	v_mfma_f32_16x16x32_bf16 v[34:37], v[114:117], v[146:149], v[34:37]
	v_mfma_f32_16x16x32_bf16 v[46:49], v[126:129], v[146:149], v[46:49]
	v_mfma_f32_16x16x32_bf16 v[18:21], v[158:161], v[146:149], v[18:21]
	v_mfma_f32_16x16x32_bf16 v[102:105], v[154:157], v[146:149], v[102:105]
	global_load_dwordx4 v[146:149], v230, s[36:37] offset:640
	s_waitcnt vmcnt(8)
; template <int MODE>
; __device__ __forceinline__ void gemm_tile(const Params& P, int tm, int tn, unsigned char* smem) {
;     ...
;     for (int kt = 0; kt < 16; ++kt) {
;         unsigned char* sA = (kt & 1) ? sA1 : sA0; unsigned char* sB = (kt & 1) ? sB1 : sB0;
;         unsigned char* nA = (kt & 1) ? sA0 : sA1; unsigned char* nB = (kt & 1) ? sB0 : sB1;
;         bf16x8 fa[4], fb[4], ga[4], gb[4];
;         const int ch0 = ((g ^ sw) << 4), ch1 = (((4 + g) ^ sw) << 4);
;         const unsigned ko = (unsigned)(kt + 2) * 128u;
;         const unsigned koa = ko + ((MODE == 2 && kt + 2 >= 8) ? (unsigned)(ZC_FQ - 512) * 2u : 0u);
;         const bool wr_ok = kt < 15, ld_ok = kt < 14;
; #pragma unroll
;         for (int i = 0; i < 4; ++i) { fa[i] = *(const bf16x8*)(sA + arow_off + i * 2048 + ch0); fb[i] = *(const bf16x8*)(sB + brow_off + i * 2048 + ch0); }
;         __builtin_amdgcn_sched_barrier(0);
;         __builtin_amdgcn_s_setprio(2);
;         if (wr_ok) *(uint4*)(nA + soff0) = ra0;
;         if (ld_ok) ra0 = *(const uint4*)(Ab + (aoff + 0u * LDA + koa));
;         ga[0] = *(const bf16x8*)(sA + arow_off + 0 * 2048 + ch1); gb[0] = *(const bf16x8*)(sB + brow_off + 0 * 2048 + ch1);
;         __builtin_amdgcn_sched_barrier(0);
; #pragma unroll
;         for (int j = 0; j < 4; ++j) acc[0][j] = __builtin_amdgcn_mfma_f32_16x16x32_bf16(fb[j], fa[0], acc[0][j], 0, 0, 0);
;         __builtin_amdgcn_sched_barrier(0);
;         if (wr_ok) *(uint4*)(nA + soff0 + 4096) = ra1;
;         if (ld_ok) ra1 = *(const uint4*)(Ab + (aoff + 32u * LDA + koa));
;         ga[1] = *(const bf16x8*)(sA + arow_off + 1 * 2048 + ch1); gb[1] = *(const bf16x8*)(sB + brow_off + 1 * 2048 + ch1);
;         __builtin_amdgcn_sched_barrier(0);
; #pragma unroll
;         for (int j = 0; j < 4; ++j) acc[1][j] = __builtin_amdgcn_mfma_f32_16x16x32_bf16(fb[j], fa[1], acc[1][j], 0, 0, 0);
;         __builtin_amdgcn_sched_barrier(0);
;         if (wr_ok) *(uint4*)(nA + soff0 + 8192) = ra2;
;         if (ld_ok) ra2 = *(const uint4*)(Ab + (aoff + 64u * LDA + koa));
;         ga[2] = *(const bf16x8*)(sA + arow_off + 2 * 2048 + ch1); gb[2] = *(const bf16x8*)(sB + brow_off + 2 * 2048 + ch1);
;         __builtin_amdgcn_sched_barrier(0);
; #pragma unroll
;         for (int j = 0; j < 4; ++j) acc[2][j] = __builtin_amdgcn_mfma_f32_16x16x32_bf16(fb[j], fa[2], acc[2][j], 0, 0, 0);
	ds_write_b128 v2, v[132:135] offset:12288
	ds_read_b128 v[132:135], v4 offset:38912
	ds_read_b128 v[182:185], v5 offset:55296
	v_mfma_f32_16x16x32_bf16 v[38:41], v[114:117], v[150:153], v[38:41]
	v_mfma_f32_16x16x32_bf16 v[50:53], v[126:129], v[150:153], v[50:53]
	v_mfma_f32_16x16x32_bf16 v[54:57], v[154:157], v[150:153], v[54:57]
	v_mfma_f32_16x16x32_bf16 v[22:25], v[158:161], v[150:153], v[22:25]
	global_load_dwordx4 v[114:117], v3, s[0:1] offset:640
	s_waitcnt vmcnt(8)
	ds_write_b128 v2, v[122:125] offset:16384
	s_waitcnt lgkmcnt(10)
	v_mfma_f32_16x16x32_bf16 v[26:29], v[170:173], v[162:165], v[26:29]
	s_waitcnt lgkmcnt(1)
	v_mfma_f32_16x16x32_bf16 v[10:13], v[182:185], v[162:165], v[10:13]
	v_mfma_f32_16x16x32_bf16 v[86:89], v[174:177], v[162:165], v[86:89]
	v_mfma_f32_16x16x32_bf16 v[94:97], v[178:181], v[162:165], v[94:97]
	global_load_dwordx4 v[122:125], v231, s[0:1] offset:640
	s_waitcnt vmcnt(8)
	ds_write_b128 v2, v[98:101] offset:20480
	v_mfma_f32_16x16x32_bf16 v[30:33], v[170:173], v[58:61], v[30:33]
	v_mfma_f32_16x16x32_bf16 v[42:45], v[174:177], v[58:61], v[42:45]
	v_mfma_f32_16x16x32_bf16 v[14:17], v[182:185], v[58:61], v[14:17]
	v_mfma_f32_16x16x32_bf16 v[90:93], v[178:181], v[58:61], v[90:93]
	global_load_dwordx4 v[58:61], v232, s[0:1] offset:640
	s_waitcnt vmcnt(8)
	ds_write_b128 v2, v[62:65] offset:24576
	v_mfma_f32_16x16x32_bf16 v[34:37], v[170:173], v[118:121], v[34:37]
	v_mfma_f32_16x16x32_bf16 v[46:49], v[174:177], v[118:121], v[46:49]
	v_mfma_f32_16x16x32_bf16 v[62:65], v[178:181], v[118:121], v[102:105]
	v_mfma_f32_16x16x32_bf16 v[18:21], v[182:185], v[118:121], v[18:21]
	global_load_dwordx4 v[98:101], v233, s[0:1] offset:640
	s_waitcnt vmcnt(8)
	ds_write_b128 v2, v[82:85] offset:28672
	v_mfma_f32_16x16x32_bf16 v[38:41], v[170:173], v[132:135], v[38:41]
	v_mfma_f32_16x16x32_bf16 v[50:53], v[174:177], v[132:135], v[50:53]
	v_mfma_f32_16x16x32_bf16 v[54:57], v[178:181], v[132:135], v[54:57]
	v_mfma_f32_16x16x32_bf16 v[22:25], v[182:185], v[132:135], v[22:25]
	s_setprio 0
	s_waitcnt lgkmcnt(0)
	s_barrier
	ds_read_b128 v[82:85], v6
	ds_read_b128 v[102:105], v6 offset:2048
	ds_read_b128 v[118:121], v7 offset:16384
	ds_read_b128 v[126:129], v7 offset:18432
	ds_read_b128 v[132:135], v6 offset:4096
	ds_read_b128 v[150:153], v6 offset:6144
	ds_read_b128 v[154:157], v7 offset:20480
	ds_read_b128 v[158:161], v7 offset:22528
	s_setprio 2
	global_load_dwordx4 v[162:165], v8, s[36:37] offset:768
	s_waitcnt vmcnt(8)
	ds_write_b128 v2, v[166:169] offset:32768
	ds_read_b128 v[166:169], v4
	ds_read_b128 v[170:173], v5 offset:16384
	s_waitcnt lgkmcnt(8)
	v_mfma_f32_16x16x32_bf16 v[26:29], v[118:121], v[82:85], v[26:29]
	s_waitcnt lgkmcnt(3)
	v_mfma_f32_16x16x32_bf16 v[10:13], v[158:161], v[82:85], v[10:13]
	v_mfma_f32_16x16x32_bf16 v[86:89], v[126:129], v[82:85], v[86:89]
	v_mfma_f32_16x16x32_bf16 v[94:97], v[154:157], v[82:85], v[94:97]
	global_load_dwordx4 v[82:85], v228, s[36:37] offset:768
	s_waitcnt vmcnt(8)
	ds_write_b128 v2, v[106:109] offset:36864
	ds_read_b128 v[106:109], v4 offset:2048
	ds_read_b128 v[174:177], v5 offset:18432
	v_mfma_f32_16x16x32_bf16 v[30:33], v[118:121], v[102:105], v[30:33]
	v_mfma_f32_16x16x32_bf16 v[42:45], v[126:129], v[102:105], v[42:45]
	v_mfma_f32_16x16x32_bf16 v[14:17], v[158:161], v[102:105], v[14:17]
	v_mfma_f32_16x16x32_bf16 v[90:93], v[154:157], v[102:105], v[90:93]
	global_load_dwordx4 v[102:105], v229, s[36:37] offset:768
	s_waitcnt vmcnt(8)
	ds_write_b128 v2, v[110:113] offset:40960
	ds_read_b128 v[110:113], v4 offset:4096
	ds_read_b128 v[178:181], v5 offset:20480
	v_mfma_f32_16x16x32_bf16 v[34:37], v[118:121], v[132:135], v[34:37]
	v_mfma_f32_16x16x32_bf16 v[46:49], v[126:129], v[132:135], v[46:49]
	v_mfma_f32_16x16x32_bf16 v[62:65], v[154:157], v[132:135], v[62:65]
	v_mfma_f32_16x16x32_bf16 v[18:21], v[158:161], v[132:135], v[18:21]
	global_load_dwordx4 v[132:135], v230, s[36:37] offset:768
	s_waitcnt vmcnt(8)
	ds_write_b128 v2, v[146:149] offset:45056
	ds_read_b128 v[146:149], v4 offset:6144
	ds_read_b128 v[182:185], v5 offset:22528
	v_mfma_f32_16x16x32_bf16 v[38:41], v[118:121], v[150:153], v[38:41]
	v_mfma_f32_16x16x32_bf16 v[50:53], v[126:129], v[150:153], v[50:53]
	v_mfma_f32_16x16x32_bf16 v[54:57], v[154:157], v[150:153], v[54:57]
	v_mfma_f32_16x16x32_bf16 v[22:25], v[158:161], v[150:153], v[22:25]
	global_load_dwordx4 v[118:121], v3, s[0:1] offset:768
	s_waitcnt vmcnt(8)
	ds_write_b128 v2, v[114:117] offset:49152
	s_waitcnt lgkmcnt(10)
	v_mfma_f32_16x16x32_bf16 v[26:29], v[170:173], v[166:169], v[26:29]
	s_waitcnt lgkmcnt(1)
	v_mfma_f32_16x16x32_bf16 v[10:13], v[182:185], v[166:169], v[10:13]
	v_mfma_f32_16x16x32_bf16 v[86:89], v[174:177], v[166:169], v[86:89]
	v_mfma_f32_16x16x32_bf16 v[94:97], v[178:181], v[166:169], v[94:97]
	global_load_dwordx4 v[114:117], v231, s[0:1] offset:768
	s_waitcnt vmcnt(8)
	ds_write_b128 v2, v[122:125] offset:53248
	v_mfma_f32_16x16x32_bf16 v[30:33], v[170:173], v[106:109], v[30:33]
	v_mfma_f32_16x16x32_bf16 v[42:45], v[174:177], v[106:109], v[42:45]
	v_mfma_f32_16x16x32_bf16 v[14:17], v[182:185], v[106:109], v[14:17]
	v_mfma_f32_16x16x32_bf16 v[90:93], v[178:181], v[106:109], v[90:93]
	global_load_dwordx4 v[106:109], v232, s[0:1] offset:768
	s_waitcnt vmcnt(8)
	ds_write_b128 v2, v[58:61] offset:57344
	v_mfma_f32_16x16x32_bf16 v[34:37], v[170:173], v[110:113], v[34:37]
	v_mfma_f32_16x16x32_bf16 v[46:49], v[174:177], v[110:113], v[46:49]
	v_mfma_f32_16x16x32_bf16 v[58:61], v[178:181], v[110:113], v[62:65]
	v_mfma_f32_16x16x32_bf16 v[18:21], v[182:185], v[110:113], v[18:21]
	global_load_dwordx4 v[62:65], v233, s[0:1] offset:768
	s_waitcnt vmcnt(8)
	ds_write_b128 v2, v[98:101] offset:61440
	v_mfma_f32_16x16x32_bf16 v[38:41], v[170:173], v[146:149], v[38:41]
	v_mfma_f32_16x16x32_bf16 v[50:53], v[174:177], v[146:149], v[50:53]
	v_mfma_f32_16x16x32_bf16 v[54:57], v[178:181], v[146:149], v[54:57]
	v_mfma_f32_16x16x32_bf16 v[22:25], v[182:185], v[146:149], v[22:25]
	s_setprio 0
	s_waitcnt lgkmcnt(0)
	s_barrier
; template <int MODE>
; __device__ __forceinline__ void gemm_tile(const Params& P, int tm, int tn, unsigned char* smem) {
;     ...
;     for (int kt = 0; kt < 16; ++kt) {
;         unsigned char* sA = (kt & 1) ? sA1 : sA0; unsigned char* sB = (kt & 1) ? sB1 : sB0;
;         unsigned char* nA = (kt & 1) ? sA0 : sA1; unsigned char* nB = (kt & 1) ? sB0 : sB1;
;         bf16x8 fa[4], fb[4], ga[4], gb[4];
;         const int ch0 = ((g ^ sw) << 4), ch1 = (((4 + g) ^ sw) << 4);
;         const unsigned ko = (unsigned)(kt + 2) * 128u;
;         const unsigned koa = ko + ((MODE == 2 && kt + 2 >= 8) ? (unsigned)(ZC_FQ - 512) * 2u : 0u);
;         const bool wr_ok = kt < 15, ld_ok = kt < 14;
; #pragma unroll
;         for (int i = 0; i < 4; ++i) { fa[i] = *(const bf16x8*)(sA + arow_off + i * 2048 + ch0); fb[i] = *(const bf16x8*)(sB + brow_off + i * 2048 + ch0); }
;         __builtin_amdgcn_sched_barrier(0);
;         __builtin_amdgcn_s_setprio(2);
;         if (wr_ok) *(uint4*)(nA + soff0) = ra0;
;         if (ld_ok) ra0 = *(const uint4*)(Ab + (aoff + 0u * LDA + koa));
;         ga[0] = *(const bf16x8*)(sA + arow_off + 0 * 2048 + ch1); gb[0] = *(const bf16x8*)(sB + brow_off + 0 * 2048 + ch1);
;         __builtin_amdgcn_sched_barrier(0);
; #pragma unroll
;         for (int j = 0; j < 4; ++j) acc[0][j] = __builtin_amdgcn_mfma_f32_16x16x32_bf16(fb[j], fa[0], acc[0][j], 0, 0, 0);
;         __builtin_amdgcn_sched_barrier(0);
;         if (wr_ok) *(uint4*)(nA + soff0 + 4096) = ra1;
;         if (ld_ok) ra1 = *(const uint4*)(Ab + (aoff + 32u * LDA + koa));
;         ga[1] = *(const bf16x8*)(sA + arow_off + 1 * 2048 + ch1); gb[1] = *(const bf16x8*)(sB + brow_off + 1 * 2048 + ch1);
;         __builtin_amdgcn_sched_barrier(0);
; #pragma unroll
;         for (int j = 0; j < 4; ++j) acc[1][j] = __builtin_amdgcn_mfma_f32_16x16x32_bf16(fb[j], fa[1], acc[1][j], 0, 0, 0);
;         __builtin_amdgcn_sched_barrier(0);
;         if (wr_ok) *(uint4*)(nA + soff0 + 8192) = ra2;
;         if (ld_ok) ra2 = *(const uint4*)(Ab + (aoff + 64u * LDA + koa));
;         ga[2] = *(const bf16x8*)(sA + arow_off + 2 * 2048 + ch1); gb[2] = *(const bf16x8*)(sB + brow_off + 2 * 2048 + ch1);
;         __builtin_amdgcn_sched_barrier(0);
; #pragma unroll
;         for (int j = 0; j < 4; ++j) acc[2][j] = __builtin_amdgcn_mfma_f32_16x16x32_bf16(fb[j], fa[2], acc[2][j], 0, 0, 0);
	ds_read_b128 v[98:101], v6 offset:32768
	ds_read_b128 v[110:113], v6 offset:34816
	ds_read_b128 v[122:125], v7 offset:49152
	ds_read_b128 v[126:129], v7 offset:51200
	ds_read_b128 v[146:149], v6 offset:36864
	ds_read_b128 v[150:153], v6 offset:38912
	ds_read_b128 v[154:157], v7 offset:53248
	ds_read_b128 v[158:161], v7 offset:55296
	s_setprio 2
	global_load_dwordx4 v[166:169], v8, s[36:37] offset:896
	s_waitcnt vmcnt(8)
	ds_write_b128 v2, v[162:165]
	ds_read_b128 v[162:165], v4 offset:32768
	ds_read_b128 v[170:173], v5 offset:49152
	s_waitcnt lgkmcnt(8)
	v_mfma_f32_16x16x32_bf16 v[26:29], v[122:125], v[98:101], v[26:29]
	s_waitcnt lgkmcnt(3)
	v_mfma_f32_16x16x32_bf16 v[10:13], v[158:161], v[98:101], v[10:13]
	v_mfma_f32_16x16x32_bf16 v[86:89], v[126:129], v[98:101], v[86:89]
	v_mfma_f32_16x16x32_bf16 v[94:97], v[154:157], v[98:101], v[94:97]
	global_load_dwordx4 v[98:101], v228, s[36:37] offset:896
	s_waitcnt vmcnt(8)
	ds_write_b128 v2, v[82:85] offset:4096
	ds_read_b128 v[82:85], v4 offset:34816
	ds_read_b128 v[174:177], v5 offset:51200
	v_mfma_f32_16x16x32_bf16 v[30:33], v[122:125], v[110:113], v[30:33]
	v_mfma_f32_16x16x32_bf16 v[42:45], v[126:129], v[110:113], v[42:45]
	v_mfma_f32_16x16x32_bf16 v[14:17], v[158:161], v[110:113], v[14:17]
	v_mfma_f32_16x16x32_bf16 v[90:93], v[154:157], v[110:113], v[90:93]
	global_load_dwordx4 v[110:113], v229, s[36:37] offset:896
	s_waitcnt vmcnt(8)
	ds_write_b128 v2, v[102:105] offset:8192
	ds_read_b128 v[102:105], v4 offset:36864
	ds_read_b128 v[178:181], v5 offset:53248
	v_mfma_f32_16x16x32_bf16 v[34:37], v[122:125], v[146:149], v[34:37]
	v_mfma_f32_16x16x32_bf16 v[46:49], v[126:129], v[146:149], v[46:49]
	v_mfma_f32_16x16x32_bf16 v[58:61], v[154:157], v[146:149], v[58:61]
	v_mfma_f32_16x16x32_bf16 v[18:21], v[158:161], v[146:149], v[18:21]
	global_load_dwordx4 v[146:149], v230, s[36:37] offset:896
	s_waitcnt vmcnt(8)
	ds_write_b128 v2, v[132:135] offset:12288
	ds_read_b128 v[132:135], v4 offset:38912
	ds_read_b128 v[182:185], v5 offset:55296
	v_mfma_f32_16x16x32_bf16 v[38:41], v[122:125], v[150:153], v[38:41]
	v_mfma_f32_16x16x32_bf16 v[50:53], v[126:129], v[150:153], v[50:53]
	v_mfma_f32_16x16x32_bf16 v[54:57], v[154:157], v[150:153], v[54:57]
	v_mfma_f32_16x16x32_bf16 v[22:25], v[158:161], v[150:153], v[22:25]
	global_load_dwordx4 v[122:125], v3, s[0:1] offset:896
	s_waitcnt vmcnt(8)
	ds_write_b128 v2, v[118:121] offset:16384
	s_waitcnt lgkmcnt(10)
	v_mfma_f32_16x16x32_bf16 v[26:29], v[170:173], v[162:165], v[26:29]
	s_waitcnt lgkmcnt(1)
	v_mfma_f32_16x16x32_bf16 v[10:13], v[182:185], v[162:165], v[10:13]
	v_mfma_f32_16x16x32_bf16 v[86:89], v[174:177], v[162:165], v[86:89]
	v_mfma_f32_16x16x32_bf16 v[94:97], v[178:181], v[162:165], v[94:97]
	global_load_dwordx4 v[118:121], v231, s[0:1] offset:896
	s_waitcnt vmcnt(8)
	ds_write_b128 v2, v[114:117] offset:20480
	v_mfma_f32_16x16x32_bf16 v[30:33], v[170:173], v[82:85], v[30:33]
	v_mfma_f32_16x16x32_bf16 v[42:45], v[174:177], v[82:85], v[42:45]
	v_mfma_f32_16x16x32_bf16 v[14:17], v[182:185], v[82:85], v[14:17]
	v_mfma_f32_16x16x32_bf16 v[90:93], v[178:181], v[82:85], v[90:93]
	global_load_dwordx4 v[82:85], v232, s[0:1] offset:896
	s_waitcnt vmcnt(8)
	ds_write_b128 v2, v[106:109] offset:24576
	v_mfma_f32_16x16x32_bf16 v[34:37], v[170:173], v[102:105], v[34:37]
	v_mfma_f32_16x16x32_bf16 v[46:49], v[174:177], v[102:105], v[46:49]
	v_mfma_f32_16x16x32_bf16 v[58:61], v[178:181], v[102:105], v[58:61]
	v_mfma_f32_16x16x32_bf16 v[18:21], v[182:185], v[102:105], v[18:21]
	global_load_dwordx4 v[102:105], v233, s[0:1] offset:896
	s_waitcnt vmcnt(8)
	ds_write_b128 v2, v[62:65] offset:28672
	v_mfma_f32_16x16x32_bf16 v[38:41], v[170:173], v[132:135], v[38:41]
	v_mfma_f32_16x16x32_bf16 v[50:53], v[174:177], v[132:135], v[50:53]
	v_mfma_f32_16x16x32_bf16 v[54:57], v[178:181], v[132:135], v[54:57]
	v_mfma_f32_16x16x32_bf16 v[22:25], v[182:185], v[132:135], v[22:25]
	s_setprio 0
	s_waitcnt lgkmcnt(0)
	s_barrier
	ds_read_b128 v[62:65], v6
	ds_read_b128 v[106:109], v6 offset:2048
	ds_read_b128 v[114:117], v7 offset:16384
	ds_read_b128 v[126:129], v7 offset:18432
	ds_read_b128 v[132:135], v6 offset:4096
	ds_read_b128 v[150:153], v6 offset:6144
	ds_read_b128 v[154:157], v7 offset:20480
	ds_read_b128 v[158:161], v7 offset:22528
	s_setprio 2
	global_load_dwordx4 v[162:165], v8, s[36:37] offset:1024
	s_waitcnt vmcnt(8)
	ds_write_b128 v2, v[166:169] offset:32768
	ds_read_b128 v[166:169], v4
	ds_read_b128 v[170:173], v5 offset:16384
	s_waitcnt lgkmcnt(8)
	v_mfma_f32_16x16x32_bf16 v[26:29], v[114:117], v[62:65], v[26:29]
	s_waitcnt lgkmcnt(3)
	v_mfma_f32_16x16x32_bf16 v[10:13], v[158:161], v[62:65], v[10:13]
	v_mfma_f32_16x16x32_bf16 v[86:89], v[126:129], v[62:65], v[86:89]
	v_mfma_f32_16x16x32_bf16 v[94:97], v[154:157], v[62:65], v[94:97]
	global_load_dwordx4 v[62:65], v228, s[36:37] offset:1024
	s_waitcnt vmcnt(8)
	ds_write_b128 v2, v[98:101] offset:36864
	ds_read_b128 v[98:101], v4 offset:2048
	ds_read_b128 v[174:177], v5 offset:18432
	v_mfma_f32_16x16x32_bf16 v[30:33], v[114:117], v[106:109], v[30:33]
	v_mfma_f32_16x16x32_bf16 v[42:45], v[126:129], v[106:109], v[42:45]
	v_mfma_f32_16x16x32_bf16 v[14:17], v[158:161], v[106:109], v[14:17]
	v_mfma_f32_16x16x32_bf16 v[90:93], v[154:157], v[106:109], v[90:93]
	global_load_dwordx4 v[106:109], v229, s[36:37] offset:1024
	s_waitcnt vmcnt(8)
	ds_write_b128 v2, v[110:113] offset:40960
	ds_read_b128 v[110:113], v4 offset:4096
	ds_read_b128 v[178:181], v5 offset:20480
	v_mfma_f32_16x16x32_bf16 v[34:37], v[114:117], v[132:135], v[34:37]
	v_mfma_f32_16x16x32_bf16 v[46:49], v[126:129], v[132:135], v[46:49]
	v_mfma_f32_16x16x32_bf16 v[58:61], v[154:157], v[132:135], v[58:61]
	v_mfma_f32_16x16x32_bf16 v[18:21], v[158:161], v[132:135], v[18:21]
	global_load_dwordx4 v[132:135], v230, s[36:37] offset:1024
	s_waitcnt vmcnt(8)
; template <int MODE>
; __device__ __forceinline__ void gemm_tile(const Params& P, int tm, int tn, unsigned char* smem) {
;     ...
;     for (int kt = 0; kt < 16; ++kt) {
;         unsigned char* sA = (kt & 1) ? sA1 : sA0; unsigned char* sB = (kt & 1) ? sB1 : sB0;
;         unsigned char* nA = (kt & 1) ? sA0 : sA1; unsigned char* nB = (kt & 1) ? sB0 : sB1;
;         bf16x8 fa[4], fb[4], ga[4], gb[4];
;         const int ch0 = ((g ^ sw) << 4), ch1 = (((4 + g) ^ sw) << 4);
;         const unsigned ko = (unsigned)(kt + 2) * 128u;
;         const unsigned koa = ko + ((MODE == 2 && kt + 2 >= 8) ? (unsigned)(ZC_FQ - 512) * 2u : 0u);
;         const bool wr_ok = kt < 15, ld_ok = kt < 14;
; #pragma unroll
;         for (int i = 0; i < 4; ++i) { fa[i] = *(const bf16x8*)(sA + arow_off + i * 2048 + ch0); fb[i] = *(const bf16x8*)(sB + brow_off + i * 2048 + ch0); }
;         __builtin_amdgcn_sched_barrier(0);
;         __builtin_amdgcn_s_setprio(2);
;         if (wr_ok) *(uint4*)(nA + soff0) = ra0;
;         if (ld_ok) ra0 = *(const uint4*)(Ab + (aoff + 0u * LDA + koa));
;         ga[0] = *(const bf16x8*)(sA + arow_off + 0 * 2048 + ch1); gb[0] = *(const bf16x8*)(sB + brow_off + 0 * 2048 + ch1);
;         __builtin_amdgcn_sched_barrier(0);
; #pragma unroll
;         for (int j = 0; j < 4; ++j) acc[0][j] = __builtin_amdgcn_mfma_f32_16x16x32_bf16(fb[j], fa[0], acc[0][j], 0, 0, 0);
;         __builtin_amdgcn_sched_barrier(0);
;         if (wr_ok) *(uint4*)(nA + soff0 + 4096) = ra1;
;         if (ld_ok) ra1 = *(const uint4*)(Ab + (aoff + 32u * LDA + koa));
;         ga[1] = *(const bf16x8*)(sA + arow_off + 1 * 2048 + ch1); gb[1] = *(const bf16x8*)(sB + brow_off + 1 * 2048 + ch1);
;         __builtin_amdgcn_sched_barrier(0);
; #pragma unroll
;         for (int j = 0; j < 4; ++j) acc[1][j] = __builtin_amdgcn_mfma_f32_16x16x32_bf16(fb[j], fa[1], acc[1][j], 0, 0, 0);
;         __builtin_amdgcn_sched_barrier(0);
;         if (wr_ok) *(uint4*)(nA + soff0 + 8192) = ra2;
;         if (ld_ok) ra2 = *(const uint4*)(Ab + (aoff + 64u * LDA + koa));
;         ga[2] = *(const bf16x8*)(sA + arow_off + 2 * 2048 + ch1); gb[2] = *(const bf16x8*)(sB + brow_off + 2 * 2048 + ch1);
;         __builtin_amdgcn_sched_barrier(0);
; #pragma unroll
;         for (int j = 0; j < 4; ++j) acc[2][j] = __builtin_amdgcn_mfma_f32_16x16x32_bf16(fb[j], fa[2], acc[2][j], 0, 0, 0);
	ds_write_b128 v2, v[146:149] offset:45056
	ds_read_b128 v[146:149], v4 offset:6144
	ds_read_b128 v[182:185], v5 offset:22528
	v_mfma_f32_16x16x32_bf16 v[38:41], v[114:117], v[150:153], v[38:41]
	v_mfma_f32_16x16x32_bf16 v[50:53], v[126:129], v[150:153], v[50:53]
	v_mfma_f32_16x16x32_bf16 v[54:57], v[154:157], v[150:153], v[54:57]
	v_mfma_f32_16x16x32_bf16 v[22:25], v[158:161], v[150:153], v[22:25]
	global_load_dwordx4 v[114:117], v3, s[0:1] offset:1024
	s_waitcnt vmcnt(8)
	ds_write_b128 v2, v[122:125] offset:49152
	s_waitcnt lgkmcnt(10)
	v_mfma_f32_16x16x32_bf16 v[26:29], v[170:173], v[166:169], v[26:29]
	s_waitcnt lgkmcnt(1)
	v_mfma_f32_16x16x32_bf16 v[10:13], v[182:185], v[166:169], v[10:13]
	v_mfma_f32_16x16x32_bf16 v[86:89], v[174:177], v[166:169], v[86:89]
	v_mfma_f32_16x16x32_bf16 v[94:97], v[178:181], v[166:169], v[94:97]
	global_load_dwordx4 v[122:125], v231, s[0:1] offset:1024
	s_waitcnt vmcnt(8)
	ds_write_b128 v2, v[118:121] offset:53248
	v_mfma_f32_16x16x32_bf16 v[30:33], v[170:173], v[98:101], v[30:33]
	v_mfma_f32_16x16x32_bf16 v[42:45], v[174:177], v[98:101], v[42:45]
	v_mfma_f32_16x16x32_bf16 v[14:17], v[182:185], v[98:101], v[14:17]
	v_mfma_f32_16x16x32_bf16 v[90:93], v[178:181], v[98:101], v[90:93]
	global_load_dwordx4 v[98:101], v232, s[0:1] offset:1024
	s_waitcnt vmcnt(8)
	ds_write_b128 v2, v[82:85] offset:57344
	v_mfma_f32_16x16x32_bf16 v[34:37], v[170:173], v[110:113], v[34:37]
	v_mfma_f32_16x16x32_bf16 v[46:49], v[174:177], v[110:113], v[46:49]
	v_mfma_f32_16x16x32_bf16 v[58:61], v[178:181], v[110:113], v[58:61]
	v_mfma_f32_16x16x32_bf16 v[18:21], v[182:185], v[110:113], v[18:21]
	global_load_dwordx4 v[82:85], v233, s[0:1] offset:1024
	s_waitcnt vmcnt(8)
	ds_write_b128 v2, v[102:105] offset:61440
	v_mfma_f32_16x16x32_bf16 v[38:41], v[170:173], v[146:149], v[38:41]
	v_mfma_f32_16x16x32_bf16 v[50:53], v[174:177], v[146:149], v[50:53]
	v_mfma_f32_16x16x32_bf16 v[54:57], v[178:181], v[146:149], v[54:57]
	v_mfma_f32_16x16x32_bf16 v[22:25], v[182:185], v[146:149], v[22:25]
	s_setprio 0
	s_waitcnt lgkmcnt(0)
	s_barrier
	ds_read_b128 v[102:105], v6 offset:32768
	ds_read_b128 v[110:113], v6 offset:34816
	ds_read_b128 v[118:121], v7 offset:49152
	ds_read_b128 v[126:129], v7 offset:51200
	ds_read_b128 v[146:149], v6 offset:36864
	ds_read_b128 v[150:153], v6 offset:38912
	ds_read_b128 v[154:157], v7 offset:53248
	ds_read_b128 v[158:161], v7 offset:55296
	s_setprio 2
	global_load_dwordx4 v[166:169], v8, s[36:37] offset:1152
	s_waitcnt vmcnt(8)
	ds_write_b128 v2, v[162:165]
	ds_read_b128 v[162:165], v4 offset:32768
	ds_read_b128 v[170:173], v5 offset:49152
	s_waitcnt lgkmcnt(8)
	v_mfma_f32_16x16x32_bf16 v[26:29], v[118:121], v[102:105], v[26:29]
	s_waitcnt lgkmcnt(3)
	v_mfma_f32_16x16x32_bf16 v[10:13], v[158:161], v[102:105], v[10:13]
	v_mfma_f32_16x16x32_bf16 v[86:89], v[126:129], v[102:105], v[86:89]
	v_mfma_f32_16x16x32_bf16 v[94:97], v[154:157], v[102:105], v[94:97]
	global_load_dwordx4 v[102:105], v228, s[36:37] offset:1152
	s_waitcnt vmcnt(8)
	ds_write_b128 v2, v[62:65] offset:4096
	ds_read_b128 v[62:65], v4 offset:34816
	ds_read_b128 v[174:177], v5 offset:51200
	v_mfma_f32_16x16x32_bf16 v[30:33], v[118:121], v[110:113], v[30:33]
	v_mfma_f32_16x16x32_bf16 v[42:45], v[126:129], v[110:113], v[42:45]
	v_mfma_f32_16x16x32_bf16 v[14:17], v[158:161], v[110:113], v[14:17]
	v_mfma_f32_16x16x32_bf16 v[90:93], v[154:157], v[110:113], v[90:93]
	global_load_dwordx4 v[110:113], v229, s[36:37] offset:1152
	s_waitcnt vmcnt(8)
	ds_write_b128 v2, v[106:109] offset:8192
	ds_read_b128 v[106:109], v4 offset:36864
	ds_read_b128 v[178:181], v5 offset:53248
	v_mfma_f32_16x16x32_bf16 v[34:37], v[118:121], v[146:149], v[34:37]
	v_mfma_f32_16x16x32_bf16 v[46:49], v[126:129], v[146:149], v[46:49]
	v_mfma_f32_16x16x32_bf16 v[58:61], v[154:157], v[146:149], v[58:61]
	v_mfma_f32_16x16x32_bf16 v[18:21], v[158:161], v[146:149], v[18:21]
	global_load_dwordx4 v[146:149], v230, s[36:37] offset:1152
	s_waitcnt vmcnt(8)
	ds_write_b128 v2, v[132:135] offset:12288
	ds_read_b128 v[132:135], v4 offset:38912
	ds_read_b128 v[182:185], v5 offset:55296
	v_mfma_f32_16x16x32_bf16 v[38:41], v[118:121], v[150:153], v[38:41]
	v_mfma_f32_16x16x32_bf16 v[50:53], v[126:129], v[150:153], v[50:53]
	v_mfma_f32_16x16x32_bf16 v[54:57], v[154:157], v[150:153], v[54:57]
	v_mfma_f32_16x16x32_bf16 v[22:25], v[158:161], v[150:153], v[22:25]
	global_load_dwordx4 v[118:121], v3, s[0:1] offset:1152
	s_waitcnt vmcnt(8)
	ds_write_b128 v2, v[114:117] offset:16384
	s_waitcnt lgkmcnt(10)
	v_mfma_f32_16x16x32_bf16 v[26:29], v[170:173], v[162:165], v[26:29]
	s_waitcnt lgkmcnt(1)
	v_mfma_f32_16x16x32_bf16 v[10:13], v[182:185], v[162:165], v[10:13]
	v_mfma_f32_16x16x32_bf16 v[86:89], v[174:177], v[162:165], v[86:89]
	v_mfma_f32_16x16x32_bf16 v[94:97], v[178:181], v[162:165], v[94:97]
	global_load_dwordx4 v[114:117], v231, s[0:1] offset:1152
	s_waitcnt vmcnt(8)
	ds_write_b128 v2, v[122:125] offset:20480
	v_mfma_f32_16x16x32_bf16 v[30:33], v[170:173], v[62:65], v[30:33]
	v_mfma_f32_16x16x32_bf16 v[42:45], v[174:177], v[62:65], v[42:45]
	v_mfma_f32_16x16x32_bf16 v[14:17], v[182:185], v[62:65], v[14:17]
	v_mfma_f32_16x16x32_bf16 v[90:93], v[178:181], v[62:65], v[90:93]
	global_load_dwordx4 v[62:65], v232, s[0:1] offset:1152
	s_waitcnt vmcnt(8)
	ds_write_b128 v2, v[98:101] offset:24576
	v_mfma_f32_16x16x32_bf16 v[34:37], v[170:173], v[106:109], v[34:37]
	v_mfma_f32_16x16x32_bf16 v[46:49], v[174:177], v[106:109], v[46:49]
	v_mfma_f32_16x16x32_bf16 v[58:61], v[178:181], v[106:109], v[58:61]
	v_mfma_f32_16x16x32_bf16 v[18:21], v[182:185], v[106:109], v[18:21]
	global_load_dwordx4 v[98:101], v233, s[0:1] offset:1152
	s_waitcnt vmcnt(8)
	ds_write_b128 v2, v[82:85] offset:28672
	v_mfma_f32_16x16x32_bf16 v[38:41], v[170:173], v[132:135], v[38:41]
	v_mfma_f32_16x16x32_bf16 v[50:53], v[174:177], v[132:135], v[50:53]
	v_mfma_f32_16x16x32_bf16 v[54:57], v[178:181], v[132:135], v[54:57]
	v_mfma_f32_16x16x32_bf16 v[22:25], v[182:185], v[132:135], v[22:25]
	s_setprio 0
	s_waitcnt lgkmcnt(0)
	s_barrier
; template <int MODE>
; __device__ __forceinline__ void gemm_tile(const Params& P, int tm, int tn, unsigned char* smem) {
;     ...
;     for (int kt = 0; kt < 16; ++kt) {
;         unsigned char* sA = (kt & 1) ? sA1 : sA0; unsigned char* sB = (kt & 1) ? sB1 : sB0;
;         unsigned char* nA = (kt & 1) ? sA0 : sA1; unsigned char* nB = (kt & 1) ? sB0 : sB1;
;         bf16x8 fa[4], fb[4], ga[4], gb[4];
;         const int ch0 = ((g ^ sw) << 4), ch1 = (((4 + g) ^ sw) << 4);
;         const unsigned ko = (unsigned)(kt + 2) * 128u;
;         const unsigned koa = ko + ((MODE == 2 && kt + 2 >= 8) ? (unsigned)(ZC_FQ - 512) * 2u : 0u);
;         const bool wr_ok = kt < 15, ld_ok = kt < 14;
; #pragma unroll
;         for (int i = 0; i < 4; ++i) { fa[i] = *(const bf16x8*)(sA + arow_off + i * 2048 + ch0); fb[i] = *(const bf16x8*)(sB + brow_off + i * 2048 + ch0); }
;         __builtin_amdgcn_sched_barrier(0);
;         __builtin_amdgcn_s_setprio(2);
;         if (wr_ok) *(uint4*)(nA + soff0) = ra0;
;         if (ld_ok) ra0 = *(const uint4*)(Ab + (aoff + 0u * LDA + koa));
;         ga[0] = *(const bf16x8*)(sA + arow_off + 0 * 2048 + ch1); gb[0] = *(const bf16x8*)(sB + brow_off + 0 * 2048 + ch1);
;         __builtin_amdgcn_sched_barrier(0);
; #pragma unroll
;         for (int j = 0; j < 4; ++j) acc[0][j] = __builtin_amdgcn_mfma_f32_16x16x32_bf16(fb[j], fa[0], acc[0][j], 0, 0, 0);
;         __builtin_amdgcn_sched_barrier(0);
;         if (wr_ok) *(uint4*)(nA + soff0 + 4096) = ra1;
;         if (ld_ok) ra1 = *(const uint4*)(Ab + (aoff + 32u * LDA + koa));
;         ga[1] = *(const bf16x8*)(sA + arow_off + 1 * 2048 + ch1); gb[1] = *(const bf16x8*)(sB + brow_off + 1 * 2048 + ch1);
;         __builtin_amdgcn_sched_barrier(0);
; #pragma unroll
;         for (int j = 0; j < 4; ++j) acc[1][j] = __builtin_amdgcn_mfma_f32_16x16x32_bf16(fb[j], fa[1], acc[1][j], 0, 0, 0);
;         __builtin_amdgcn_sched_barrier(0);
;         if (wr_ok) *(uint4*)(nA + soff0 + 8192) = ra2;
;         if (ld_ok) ra2 = *(const uint4*)(Ab + (aoff + 64u * LDA + koa));
;         ga[2] = *(const bf16x8*)(sA + arow_off + 2 * 2048 + ch1); gb[2] = *(const bf16x8*)(sB + brow_off + 2 * 2048 + ch1);
;         __builtin_amdgcn_sched_barrier(0);
; #pragma unroll
;         for (int j = 0; j < 4; ++j) acc[2][j] = __builtin_amdgcn_mfma_f32_16x16x32_bf16(fb[j], fa[2], acc[2][j], 0, 0, 0);
	ds_read_b128 v[82:85], v6
	ds_read_b128 v[106:109], v6 offset:2048
	ds_read_b128 v[122:125], v7 offset:16384
	ds_read_b128 v[126:129], v7 offset:18432
	ds_read_b128 v[132:135], v6 offset:4096
	ds_read_b128 v[150:153], v6 offset:6144
	ds_read_b128 v[154:157], v7 offset:20480
	ds_read_b128 v[158:161], v7 offset:22528
	s_setprio 2
	global_load_dwordx4 v[162:165], v8, s[36:37] offset:1280
	s_waitcnt vmcnt(8)
	ds_write_b128 v2, v[166:169] offset:32768
	ds_read_b128 v[166:169], v4
	ds_read_b128 v[170:173], v5 offset:16384
	s_waitcnt lgkmcnt(8)
	v_mfma_f32_16x16x32_bf16 v[26:29], v[122:125], v[82:85], v[26:29]
	s_waitcnt lgkmcnt(3)
	v_mfma_f32_16x16x32_bf16 v[10:13], v[158:161], v[82:85], v[10:13]
	v_mfma_f32_16x16x32_bf16 v[86:89], v[126:129], v[82:85], v[86:89]
	v_mfma_f32_16x16x32_bf16 v[94:97], v[154:157], v[82:85], v[94:97]
	global_load_dwordx4 v[82:85], v228, s[36:37] offset:1280
	s_waitcnt vmcnt(8)
	ds_write_b128 v2, v[102:105] offset:36864
	ds_read_b128 v[102:105], v4 offset:2048
	ds_read_b128 v[174:177], v5 offset:18432
	v_mfma_f32_16x16x32_bf16 v[30:33], v[122:125], v[106:109], v[30:33]
	v_mfma_f32_16x16x32_bf16 v[42:45], v[126:129], v[106:109], v[42:45]
	v_mfma_f32_16x16x32_bf16 v[14:17], v[158:161], v[106:109], v[14:17]
	v_mfma_f32_16x16x32_bf16 v[90:93], v[154:157], v[106:109], v[90:93]
	global_load_dwordx4 v[106:109], v229, s[36:37] offset:1280
	s_waitcnt vmcnt(8)
	ds_write_b128 v2, v[110:113] offset:40960
	ds_read_b128 v[110:113], v4 offset:4096
	ds_read_b128 v[178:181], v5 offset:20480
	v_mfma_f32_16x16x32_bf16 v[34:37], v[122:125], v[132:135], v[34:37]
	v_mfma_f32_16x16x32_bf16 v[46:49], v[126:129], v[132:135], v[46:49]
	v_mfma_f32_16x16x32_bf16 v[58:61], v[154:157], v[132:135], v[58:61]
	v_mfma_f32_16x16x32_bf16 v[18:21], v[158:161], v[132:135], v[18:21]
	global_load_dwordx4 v[132:135], v230, s[36:37] offset:1280
	s_waitcnt vmcnt(8)
	ds_write_b128 v2, v[146:149] offset:45056
	ds_read_b128 v[146:149], v4 offset:6144
	ds_read_b128 v[182:185], v5 offset:22528
	v_mfma_f32_16x16x32_bf16 v[38:41], v[122:125], v[150:153], v[38:41]
	v_mfma_f32_16x16x32_bf16 v[50:53], v[126:129], v[150:153], v[50:53]
	v_mfma_f32_16x16x32_bf16 v[54:57], v[154:157], v[150:153], v[54:57]
	v_mfma_f32_16x16x32_bf16 v[22:25], v[158:161], v[150:153], v[22:25]
	global_load_dwordx4 v[122:125], v3, s[0:1] offset:1280
	s_waitcnt vmcnt(8)
	ds_write_b128 v2, v[118:121] offset:49152
	s_waitcnt lgkmcnt(10)
	v_mfma_f32_16x16x32_bf16 v[26:29], v[170:173], v[166:169], v[26:29]
	s_waitcnt lgkmcnt(1)
	v_mfma_f32_16x16x32_bf16 v[10:13], v[182:185], v[166:169], v[10:13]
	v_mfma_f32_16x16x32_bf16 v[86:89], v[174:177], v[166:169], v[86:89]
	v_mfma_f32_16x16x32_bf16 v[94:97], v[178:181], v[166:169], v[94:97]
	global_load_dwordx4 v[118:121], v231, s[0:1] offset:1280
	s_waitcnt vmcnt(8)
	ds_write_b128 v2, v[114:117] offset:53248
	v_mfma_f32_16x16x32_bf16 v[30:33], v[170:173], v[102:105], v[30:33]
	v_mfma_f32_16x16x32_bf16 v[42:45], v[174:177], v[102:105], v[42:45]
	v_mfma_f32_16x16x32_bf16 v[14:17], v[182:185], v[102:105], v[14:17]
	v_mfma_f32_16x16x32_bf16 v[90:93], v[178:181], v[102:105], v[90:93]
	global_load_dwordx4 v[102:105], v232, s[0:1] offset:1280
	s_waitcnt vmcnt(8)
	ds_write_b128 v2, v[62:65] offset:57344
	v_mfma_f32_16x16x32_bf16 v[34:37], v[170:173], v[110:113], v[34:37]
	v_mfma_f32_16x16x32_bf16 v[46:49], v[174:177], v[110:113], v[46:49]
	v_mfma_f32_16x16x32_bf16 v[58:61], v[178:181], v[110:113], v[58:61]
	v_mfma_f32_16x16x32_bf16 v[18:21], v[182:185], v[110:113], v[18:21]
	global_load_dwordx4 v[62:65], v233, s[0:1] offset:1280
	s_waitcnt vmcnt(8)
	ds_write_b128 v2, v[98:101] offset:61440
	v_mfma_f32_16x16x32_bf16 v[38:41], v[170:173], v[146:149], v[38:41]
	v_mfma_f32_16x16x32_bf16 v[50:53], v[174:177], v[146:149], v[50:53]
	v_mfma_f32_16x16x32_bf16 v[54:57], v[178:181], v[146:149], v[54:57]
	v_mfma_f32_16x16x32_bf16 v[22:25], v[182:185], v[146:149], v[22:25]
	s_setprio 0
	s_waitcnt lgkmcnt(0)
	s_barrier
	ds_read_b128 v[98:101], v6 offset:32768
	ds_read_b128 v[110:113], v6 offset:34816
	ds_read_b128 v[114:117], v7 offset:49152
	ds_read_b128 v[126:129], v7 offset:51200
	ds_read_b128 v[146:149], v6 offset:36864
	ds_read_b128 v[150:153], v6 offset:38912
	ds_read_b128 v[154:157], v7 offset:53248
	ds_read_b128 v[158:161], v7 offset:55296
	s_setprio 2
	global_load_dwordx4 v[166:169], v8, s[36:37] offset:1408
	s_waitcnt vmcnt(8)
	ds_write_b128 v2, v[162:165]
	ds_read_b128 v[162:165], v4 offset:32768
	ds_read_b128 v[170:173], v5 offset:49152
	s_waitcnt lgkmcnt(8)
	v_mfma_f32_16x16x32_bf16 v[26:29], v[114:117], v[98:101], v[26:29]
	s_waitcnt lgkmcnt(3)
	v_mfma_f32_16x16x32_bf16 v[10:13], v[158:161], v[98:101], v[10:13]
	v_mfma_f32_16x16x32_bf16 v[86:89], v[126:129], v[98:101], v[86:89]
	v_mfma_f32_16x16x32_bf16 v[94:97], v[154:157], v[98:101], v[94:97]
	global_load_dwordx4 v[98:101], v228, s[36:37] offset:1408
	s_waitcnt vmcnt(8)
	ds_write_b128 v2, v[82:85] offset:4096
	ds_read_b128 v[82:85], v4 offset:34816
	ds_read_b128 v[174:177], v5 offset:51200
	v_mfma_f32_16x16x32_bf16 v[30:33], v[114:117], v[110:113], v[30:33]
	v_mfma_f32_16x16x32_bf16 v[42:45], v[126:129], v[110:113], v[42:45]
	v_mfma_f32_16x16x32_bf16 v[14:17], v[158:161], v[110:113], v[14:17]
	v_mfma_f32_16x16x32_bf16 v[90:93], v[154:157], v[110:113], v[90:93]
	global_load_dwordx4 v[110:113], v229, s[36:37] offset:1408
	s_waitcnt vmcnt(8)
	ds_write_b128 v2, v[106:109] offset:8192
	ds_read_b128 v[106:109], v4 offset:36864
	ds_read_b128 v[178:181], v5 offset:53248
	v_mfma_f32_16x16x32_bf16 v[34:37], v[114:117], v[146:149], v[34:37]
	v_mfma_f32_16x16x32_bf16 v[46:49], v[126:129], v[146:149], v[46:49]
	v_mfma_f32_16x16x32_bf16 v[58:61], v[154:157], v[146:149], v[58:61]
	v_mfma_f32_16x16x32_bf16 v[18:21], v[158:161], v[146:149], v[18:21]
	global_load_dwordx4 v[146:149], v230, s[36:37] offset:1408
	s_waitcnt vmcnt(8)
; template <int MODE>
; __device__ __forceinline__ void gemm_tile(const Params& P, int tm, int tn, unsigned char* smem) {
;     ...
;     for (int kt = 0; kt < 16; ++kt) {
;         unsigned char* sA = (kt & 1) ? sA1 : sA0; unsigned char* sB = (kt & 1) ? sB1 : sB0;
;         unsigned char* nA = (kt & 1) ? sA0 : sA1; unsigned char* nB = (kt & 1) ? sB0 : sB1;
;         bf16x8 fa[4], fb[4], ga[4], gb[4];
;         const int ch0 = ((g ^ sw) << 4), ch1 = (((4 + g) ^ sw) << 4);
;         const unsigned ko = (unsigned)(kt + 2) * 128u;
;         const unsigned koa = ko + ((MODE == 2 && kt + 2 >= 8) ? (unsigned)(ZC_FQ - 512) * 2u : 0u);
;         const bool wr_ok = kt < 15, ld_ok = kt < 14;
; #pragma unroll
;         for (int i = 0; i < 4; ++i) { fa[i] = *(const bf16x8*)(sA + arow_off + i * 2048 + ch0); fb[i] = *(const bf16x8*)(sB + brow_off + i * 2048 + ch0); }
;         __builtin_amdgcn_sched_barrier(0);
;         __builtin_amdgcn_s_setprio(2);
;         if (wr_ok) *(uint4*)(nA + soff0) = ra0;
;         if (ld_ok) ra0 = *(const uint4*)(Ab + (aoff + 0u * LDA + koa));
;         ga[0] = *(const bf16x8*)(sA + arow_off + 0 * 2048 + ch1); gb[0] = *(const bf16x8*)(sB + brow_off + 0 * 2048 + ch1);
;         __builtin_amdgcn_sched_barrier(0);
; #pragma unroll
;         for (int j = 0; j < 4; ++j) acc[0][j] = __builtin_amdgcn_mfma_f32_16x16x32_bf16(fb[j], fa[0], acc[0][j], 0, 0, 0);
;         __builtin_amdgcn_sched_barrier(0);
;         if (wr_ok) *(uint4*)(nA + soff0 + 4096) = ra1;
;         if (ld_ok) ra1 = *(const uint4*)(Ab + (aoff + 32u * LDA + koa));
;         ga[1] = *(const bf16x8*)(sA + arow_off + 1 * 2048 + ch1); gb[1] = *(const bf16x8*)(sB + brow_off + 1 * 2048 + ch1);
;         __builtin_amdgcn_sched_barrier(0);
; #pragma unroll
;         for (int j = 0; j < 4; ++j) acc[1][j] = __builtin_amdgcn_mfma_f32_16x16x32_bf16(fb[j], fa[1], acc[1][j], 0, 0, 0);
;         __builtin_amdgcn_sched_barrier(0);
;         if (wr_ok) *(uint4*)(nA + soff0 + 8192) = ra2;
;         if (ld_ok) ra2 = *(const uint4*)(Ab + (aoff + 64u * LDA + koa));
;         ga[2] = *(const bf16x8*)(sA + arow_off + 2 * 2048 + ch1); gb[2] = *(const bf16x8*)(sB + brow_off + 2 * 2048 + ch1);
;         __builtin_amdgcn_sched_barrier(0);
; #pragma unroll
;         for (int j = 0; j < 4; ++j) acc[2][j] = __builtin_amdgcn_mfma_f32_16x16x32_bf16(fb[j], fa[2], acc[2][j], 0, 0, 0);
	ds_write_b128 v2, v[132:135] offset:12288
	ds_read_b128 v[132:135], v4 offset:38912
	ds_read_b128 v[182:185], v5 offset:55296
	v_mfma_f32_16x16x32_bf16 v[38:41], v[114:117], v[150:153], v[38:41]
	v_mfma_f32_16x16x32_bf16 v[50:53], v[126:129], v[150:153], v[50:53]
	v_mfma_f32_16x16x32_bf16 v[54:57], v[154:157], v[150:153], v[54:57]
	v_mfma_f32_16x16x32_bf16 v[22:25], v[158:161], v[150:153], v[22:25]
	global_load_dwordx4 v[114:117], v3, s[0:1] offset:1408
	s_waitcnt vmcnt(8)
	ds_write_b128 v2, v[122:125] offset:16384
	s_waitcnt lgkmcnt(10)
	v_mfma_f32_16x16x32_bf16 v[26:29], v[170:173], v[162:165], v[26:29]
	s_waitcnt lgkmcnt(1)
	v_mfma_f32_16x16x32_bf16 v[10:13], v[182:185], v[162:165], v[10:13]
	v_mfma_f32_16x16x32_bf16 v[86:89], v[174:177], v[162:165], v[86:89]
	v_mfma_f32_16x16x32_bf16 v[94:97], v[178:181], v[162:165], v[94:97]
	global_load_dwordx4 v[122:125], v231, s[0:1] offset:1408
	s_waitcnt vmcnt(8)
	ds_write_b128 v2, v[118:121] offset:20480
	v_mfma_f32_16x16x32_bf16 v[30:33], v[170:173], v[82:85], v[30:33]
	v_mfma_f32_16x16x32_bf16 v[42:45], v[174:177], v[82:85], v[42:45]
	v_mfma_f32_16x16x32_bf16 v[14:17], v[182:185], v[82:85], v[14:17]
	v_mfma_f32_16x16x32_bf16 v[90:93], v[178:181], v[82:85], v[90:93]
	global_load_dwordx4 v[82:85], v232, s[0:1] offset:1408
	s_waitcnt vmcnt(8)
	ds_write_b128 v2, v[102:105] offset:24576
	v_mfma_f32_16x16x32_bf16 v[34:37], v[170:173], v[106:109], v[34:37]
	v_mfma_f32_16x16x32_bf16 v[46:49], v[174:177], v[106:109], v[46:49]
	v_mfma_f32_16x16x32_bf16 v[58:61], v[178:181], v[106:109], v[58:61]
	v_mfma_f32_16x16x32_bf16 v[18:21], v[182:185], v[106:109], v[18:21]
	global_load_dwordx4 v[102:105], v233, s[0:1] offset:1408
	s_waitcnt vmcnt(8)
	ds_write_b128 v2, v[62:65] offset:28672
	v_mfma_f32_16x16x32_bf16 v[38:41], v[170:173], v[132:135], v[38:41]
	v_mfma_f32_16x16x32_bf16 v[50:53], v[174:177], v[132:135], v[50:53]
	v_mfma_f32_16x16x32_bf16 v[54:57], v[178:181], v[132:135], v[54:57]
	v_mfma_f32_16x16x32_bf16 v[22:25], v[182:185], v[132:135], v[22:25]
	s_setprio 0
	s_waitcnt lgkmcnt(0)
	s_barrier
	ds_read_b128 v[62:65], v6
	ds_read_b128 v[106:109], v6 offset:2048
	ds_read_b128 v[118:121], v7 offset:16384
	ds_read_b128 v[126:129], v7 offset:18432
	ds_read_b128 v[132:135], v6 offset:4096
	ds_read_b128 v[150:153], v6 offset:6144
	ds_read_b128 v[154:157], v7 offset:20480
	ds_read_b128 v[158:161], v7 offset:22528
	s_setprio 2
	global_load_dwordx4 v[162:165], v8, s[36:37] offset:1536
	s_waitcnt vmcnt(8)
	ds_write_b128 v2, v[166:169] offset:32768
	ds_read_b128 v[166:169], v4
	ds_read_b128 v[170:173], v5 offset:16384
	s_waitcnt lgkmcnt(8)
	v_mfma_f32_16x16x32_bf16 v[26:29], v[118:121], v[62:65], v[26:29]
	s_waitcnt lgkmcnt(3)
	v_mfma_f32_16x16x32_bf16 v[10:13], v[158:161], v[62:65], v[10:13]
	v_mfma_f32_16x16x32_bf16 v[86:89], v[126:129], v[62:65], v[86:89]
	v_mfma_f32_16x16x32_bf16 v[94:97], v[154:157], v[62:65], v[94:97]
	global_load_dwordx4 v[62:65], v228, s[36:37] offset:1536
	s_waitcnt vmcnt(8)
	ds_write_b128 v2, v[98:101] offset:36864
	ds_read_b128 v[98:101], v4 offset:2048
	ds_read_b128 v[174:177], v5 offset:18432
	v_mfma_f32_16x16x32_bf16 v[30:33], v[118:121], v[106:109], v[30:33]
	v_mfma_f32_16x16x32_bf16 v[42:45], v[126:129], v[106:109], v[42:45]
	v_mfma_f32_16x16x32_bf16 v[14:17], v[158:161], v[106:109], v[14:17]
	v_mfma_f32_16x16x32_bf16 v[90:93], v[154:157], v[106:109], v[90:93]
	global_load_dwordx4 v[106:109], v229, s[36:37] offset:1536
	s_waitcnt vmcnt(8)
	ds_write_b128 v2, v[110:113] offset:40960
	ds_read_b128 v[110:113], v4 offset:4096
	ds_read_b128 v[178:181], v5 offset:20480
	v_mfma_f32_16x16x32_bf16 v[34:37], v[118:121], v[132:135], v[34:37]
	v_mfma_f32_16x16x32_bf16 v[46:49], v[126:129], v[132:135], v[46:49]
	v_mfma_f32_16x16x32_bf16 v[58:61], v[154:157], v[132:135], v[58:61]
	v_mfma_f32_16x16x32_bf16 v[18:21], v[158:161], v[132:135], v[18:21]
	global_load_dwordx4 v[132:135], v230, s[36:37] offset:1536
	s_waitcnt vmcnt(8)
	ds_write_b128 v2, v[146:149] offset:45056
	ds_read_b128 v[146:149], v4 offset:6144
	ds_read_b128 v[182:185], v5 offset:22528
	v_mfma_f32_16x16x32_bf16 v[38:41], v[118:121], v[150:153], v[38:41]
	v_mfma_f32_16x16x32_bf16 v[50:53], v[126:129], v[150:153], v[50:53]
	v_mfma_f32_16x16x32_bf16 v[54:57], v[154:157], v[150:153], v[54:57]
	v_mfma_f32_16x16x32_bf16 v[22:25], v[158:161], v[150:153], v[22:25]
	global_load_dwordx4 v[118:121], v3, s[0:1] offset:1536
	s_waitcnt vmcnt(8)
	ds_write_b128 v2, v[114:117] offset:49152
	s_waitcnt lgkmcnt(10)
	v_mfma_f32_16x16x32_bf16 v[26:29], v[170:173], v[166:169], v[26:29]
	s_waitcnt lgkmcnt(1)
	v_mfma_f32_16x16x32_bf16 v[10:13], v[182:185], v[166:169], v[10:13]
	v_mfma_f32_16x16x32_bf16 v[86:89], v[174:177], v[166:169], v[86:89]
	v_mfma_f32_16x16x32_bf16 v[94:97], v[178:181], v[166:169], v[94:97]
	global_load_dwordx4 v[114:117], v231, s[0:1] offset:1536
	s_waitcnt vmcnt(8)
	ds_write_b128 v2, v[122:125] offset:53248
	v_mfma_f32_16x16x32_bf16 v[30:33], v[170:173], v[98:101], v[30:33]
	v_mfma_f32_16x16x32_bf16 v[42:45], v[174:177], v[98:101], v[42:45]
	v_mfma_f32_16x16x32_bf16 v[14:17], v[182:185], v[98:101], v[14:17]
	v_mfma_f32_16x16x32_bf16 v[90:93], v[178:181], v[98:101], v[90:93]
	global_load_dwordx4 v[98:101], v232, s[0:1] offset:1536
	s_waitcnt vmcnt(8)
	ds_write_b128 v2, v[82:85] offset:57344
	v_mfma_f32_16x16x32_bf16 v[34:37], v[170:173], v[110:113], v[34:37]
	v_mfma_f32_16x16x32_bf16 v[46:49], v[174:177], v[110:113], v[46:49]
	v_mfma_f32_16x16x32_bf16 v[58:61], v[178:181], v[110:113], v[58:61]
	v_mfma_f32_16x16x32_bf16 v[18:21], v[182:185], v[110:113], v[18:21]
	global_load_dwordx4 v[82:85], v233, s[0:1] offset:1536
	s_waitcnt vmcnt(8)
	ds_write_b128 v2, v[102:105] offset:61440
	v_mfma_f32_16x16x32_bf16 v[38:41], v[170:173], v[146:149], v[38:41]
	v_mfma_f32_16x16x32_bf16 v[50:53], v[174:177], v[146:149], v[50:53]
	v_mfma_f32_16x16x32_bf16 v[54:57], v[178:181], v[146:149], v[54:57]
	v_mfma_f32_16x16x32_bf16 v[22:25], v[182:185], v[146:149], v[22:25]
	s_setprio 0
	s_waitcnt lgkmcnt(0)
	s_barrier
; template <int MODE>
; __device__ __forceinline__ void gemm_tile(const Params& P, int tm, int tn, unsigned char* smem) {
;     ...
;     for (int kt = 0; kt < 16; ++kt) {
;         unsigned char* sA = (kt & 1) ? sA1 : sA0; unsigned char* sB = (kt & 1) ? sB1 : sB0;
;         unsigned char* nA = (kt & 1) ? sA0 : sA1; unsigned char* nB = (kt & 1) ? sB0 : sB1;
;         bf16x8 fa[4], fb[4], ga[4], gb[4];
;         const int ch0 = ((g ^ sw) << 4), ch1 = (((4 + g) ^ sw) << 4);
;         const unsigned ko = (unsigned)(kt + 2) * 128u;
;         const unsigned koa = ko + ((MODE == 2 && kt + 2 >= 8) ? (unsigned)(ZC_FQ - 512) * 2u : 0u);
;         const bool wr_ok = kt < 15, ld_ok = kt < 14;
; #pragma unroll
;         for (int i = 0; i < 4; ++i) { fa[i] = *(const bf16x8*)(sA + arow_off + i * 2048 + ch0); fb[i] = *(const bf16x8*)(sB + brow_off + i * 2048 + ch0); }
;         __builtin_amdgcn_sched_barrier(0);
;         __builtin_amdgcn_s_setprio(2);
;         if (wr_ok) *(uint4*)(nA + soff0) = ra0;
;         if (ld_ok) ra0 = *(const uint4*)(Ab + (aoff + 0u * LDA + koa));
;         ga[0] = *(const bf16x8*)(sA + arow_off + 0 * 2048 + ch1); gb[0] = *(const bf16x8*)(sB + brow_off + 0 * 2048 + ch1);
;         __builtin_amdgcn_sched_barrier(0);
; #pragma unroll
;         for (int j = 0; j < 4; ++j) acc[0][j] = __builtin_amdgcn_mfma_f32_16x16x32_bf16(fb[j], fa[0], acc[0][j], 0, 0, 0);
;         __builtin_amdgcn_sched_barrier(0);
;         if (wr_ok) *(uint4*)(nA + soff0 + 4096) = ra1;
;         if (ld_ok) ra1 = *(const uint4*)(Ab + (aoff + 32u * LDA + koa));
;         ga[1] = *(const bf16x8*)(sA + arow_off + 1 * 2048 + ch1); gb[1] = *(const bf16x8*)(sB + brow_off + 1 * 2048 + ch1);
;         __builtin_amdgcn_sched_barrier(0);
; #pragma unroll
;         for (int j = 0; j < 4; ++j) acc[1][j] = __builtin_amdgcn_mfma_f32_16x16x32_bf16(fb[j], fa[1], acc[1][j], 0, 0, 0);
;         __builtin_amdgcn_sched_barrier(0);
;         if (wr_ok) *(uint4*)(nA + soff0 + 8192) = ra2;
;         if (ld_ok) ra2 = *(const uint4*)(Ab + (aoff + 64u * LDA + koa));
;         ga[2] = *(const bf16x8*)(sA + arow_off + 2 * 2048 + ch1); gb[2] = *(const bf16x8*)(sB + brow_off + 2 * 2048 + ch1);
;         __builtin_amdgcn_sched_barrier(0);
; #pragma unroll
;         for (int j = 0; j < 4; ++j) acc[2][j] = __builtin_amdgcn_mfma_f32_16x16x32_bf16(fb[j], fa[2], acc[2][j], 0, 0, 0);
	ds_read_b128 v[102:105], v6 offset:32768
	ds_read_b128 v[110:113], v6 offset:34816
	ds_read_b128 v[122:125], v7 offset:49152
	ds_read_b128 v[126:129], v7 offset:51200
	ds_read_b128 v[146:149], v6 offset:36864
	ds_read_b128 v[150:153], v6 offset:38912
	ds_read_b128 v[154:157], v7 offset:53248
	ds_read_b128 v[158:161], v7 offset:55296
	s_setprio 2
	global_load_dwordx4 v[166:169], v8, s[36:37] offset:1664
	s_waitcnt vmcnt(8)
	ds_write_b128 v2, v[162:165]
	ds_read_b128 v[162:165], v4 offset:32768
	ds_read_b128 v[170:173], v5 offset:49152
	s_waitcnt lgkmcnt(8)
	v_mfma_f32_16x16x32_bf16 v[26:29], v[122:125], v[102:105], v[26:29]
	s_waitcnt lgkmcnt(3)
	v_mfma_f32_16x16x32_bf16 v[10:13], v[158:161], v[102:105], v[10:13]
	v_mfma_f32_16x16x32_bf16 v[86:89], v[126:129], v[102:105], v[86:89]
	v_mfma_f32_16x16x32_bf16 v[94:97], v[154:157], v[102:105], v[94:97]
	global_load_dwordx4 v[102:105], v228, s[36:37] offset:1664
	s_waitcnt vmcnt(8)
	ds_write_b128 v2, v[62:65] offset:4096
	ds_read_b128 v[62:65], v4 offset:34816
	ds_read_b128 v[174:177], v5 offset:51200
	v_mfma_f32_16x16x32_bf16 v[30:33], v[122:125], v[110:113], v[30:33]
	v_mfma_f32_16x16x32_bf16 v[42:45], v[126:129], v[110:113], v[42:45]
	v_mfma_f32_16x16x32_bf16 v[14:17], v[158:161], v[110:113], v[14:17]
	v_mfma_f32_16x16x32_bf16 v[90:93], v[154:157], v[110:113], v[90:93]
	global_load_dwordx4 v[110:113], v229, s[36:37] offset:1664
	s_waitcnt vmcnt(8)
	ds_write_b128 v2, v[106:109] offset:8192
	ds_read_b128 v[106:109], v4 offset:36864
	ds_read_b128 v[178:181], v5 offset:53248
	v_mfma_f32_16x16x32_bf16 v[34:37], v[122:125], v[146:149], v[34:37]
	v_mfma_f32_16x16x32_bf16 v[46:49], v[126:129], v[146:149], v[46:49]
	v_mfma_f32_16x16x32_bf16 v[58:61], v[154:157], v[146:149], v[58:61]
	v_mfma_f32_16x16x32_bf16 v[18:21], v[158:161], v[146:149], v[18:21]
	global_load_dwordx4 v[146:149], v230, s[36:37] offset:1664
	s_waitcnt vmcnt(8)
	ds_write_b128 v2, v[132:135] offset:12288
	ds_read_b128 v[132:135], v4 offset:38912
	ds_read_b128 v[182:185], v5 offset:55296
	v_mfma_f32_16x16x32_bf16 v[38:41], v[122:125], v[150:153], v[38:41]
	v_mfma_f32_16x16x32_bf16 v[50:53], v[126:129], v[150:153], v[50:53]
	v_mfma_f32_16x16x32_bf16 v[54:57], v[154:157], v[150:153], v[54:57]
	v_mfma_f32_16x16x32_bf16 v[22:25], v[158:161], v[150:153], v[22:25]
	global_load_dwordx4 v[122:125], v3, s[0:1] offset:1664
	s_waitcnt vmcnt(8)
	ds_write_b128 v2, v[118:121] offset:16384
	s_waitcnt lgkmcnt(10)
	v_mfma_f32_16x16x32_bf16 v[26:29], v[170:173], v[162:165], v[26:29]
	s_waitcnt lgkmcnt(1)
	v_mfma_f32_16x16x32_bf16 v[10:13], v[182:185], v[162:165], v[10:13]
	v_mfma_f32_16x16x32_bf16 v[86:89], v[174:177], v[162:165], v[86:89]
	v_mfma_f32_16x16x32_bf16 v[94:97], v[178:181], v[162:165], v[94:97]
	global_load_dwordx4 v[118:121], v231, s[0:1] offset:1664
	s_waitcnt vmcnt(8)
	ds_write_b128 v2, v[114:117] offset:20480
	v_mfma_f32_16x16x32_bf16 v[30:33], v[170:173], v[62:65], v[30:33]
	v_mfma_f32_16x16x32_bf16 v[42:45], v[174:177], v[62:65], v[42:45]
	v_mfma_f32_16x16x32_bf16 v[14:17], v[182:185], v[62:65], v[14:17]
	v_mfma_f32_16x16x32_bf16 v[90:93], v[178:181], v[62:65], v[90:93]
	global_load_dwordx4 v[62:65], v232, s[0:1] offset:1664
	s_waitcnt vmcnt(8)
	ds_write_b128 v2, v[98:101] offset:24576
	v_mfma_f32_16x16x32_bf16 v[34:37], v[170:173], v[106:109], v[34:37]
	v_mfma_f32_16x16x32_bf16 v[46:49], v[174:177], v[106:109], v[46:49]
	v_mfma_f32_16x16x32_bf16 v[58:61], v[178:181], v[106:109], v[58:61]
	v_mfma_f32_16x16x32_bf16 v[18:21], v[182:185], v[106:109], v[18:21]
	global_load_dwordx4 v[98:101], v233, s[0:1] offset:1664
	s_waitcnt vmcnt(8)
	ds_write_b128 v2, v[82:85] offset:28672
	v_mfma_f32_16x16x32_bf16 v[38:41], v[170:173], v[132:135], v[38:41]
	v_mfma_f32_16x16x32_bf16 v[50:53], v[174:177], v[132:135], v[50:53]
	v_mfma_f32_16x16x32_bf16 v[54:57], v[178:181], v[132:135], v[54:57]
	v_mfma_f32_16x16x32_bf16 v[22:25], v[182:185], v[132:135], v[22:25]
	s_setprio 0
	s_waitcnt lgkmcnt(0)
	s_barrier
	ds_read_b128 v[82:85], v6
	ds_read_b128 v[106:109], v6 offset:2048
	ds_read_b128 v[114:117], v7 offset:16384
	ds_read_b128 v[126:129], v7 offset:18432
	ds_read_b128 v[132:135], v6 offset:4096
	ds_read_b128 v[150:153], v6 offset:6144
	ds_read_b128 v[154:157], v7 offset:20480
	ds_read_b128 v[158:161], v7 offset:22528
	s_setprio 2
	global_load_dwordx4 v[162:165], v8, s[36:37] offset:1792
	s_waitcnt vmcnt(8)
	ds_write_b128 v2, v[166:169] offset:32768
	ds_read_b128 v[166:169], v4
	ds_read_b128 v[170:173], v5 offset:16384
	s_waitcnt lgkmcnt(8)
	v_mfma_f32_16x16x32_bf16 v[26:29], v[114:117], v[82:85], v[26:29]
	s_waitcnt lgkmcnt(3)
	v_mfma_f32_16x16x32_bf16 v[10:13], v[158:161], v[82:85], v[10:13]
	v_mfma_f32_16x16x32_bf16 v[86:89], v[126:129], v[82:85], v[86:89]
	v_mfma_f32_16x16x32_bf16 v[94:97], v[154:157], v[82:85], v[94:97]
	global_load_dwordx4 v[82:85], v228, s[36:37] offset:1792
	s_waitcnt vmcnt(8)
	ds_write_b128 v2, v[102:105] offset:36864
	ds_read_b128 v[102:105], v4 offset:2048
	ds_read_b128 v[174:177], v5 offset:18432
	v_mfma_f32_16x16x32_bf16 v[30:33], v[114:117], v[106:109], v[30:33]
	v_mfma_f32_16x16x32_bf16 v[42:45], v[126:129], v[106:109], v[42:45]
	v_mfma_f32_16x16x32_bf16 v[14:17], v[158:161], v[106:109], v[14:17]
	v_mfma_f32_16x16x32_bf16 v[90:93], v[154:157], v[106:109], v[90:93]
	global_load_dwordx4 v[106:109], v229, s[36:37] offset:1792
	s_waitcnt vmcnt(8)
	ds_write_b128 v2, v[110:113] offset:40960
	ds_read_b128 v[110:113], v4 offset:4096
	ds_read_b128 v[178:181], v5 offset:20480
	v_mfma_f32_16x16x32_bf16 v[34:37], v[114:117], v[132:135], v[34:37]
	v_mfma_f32_16x16x32_bf16 v[46:49], v[126:129], v[132:135], v[46:49]
	v_mfma_f32_16x16x32_bf16 v[58:61], v[154:157], v[132:135], v[58:61]
	v_mfma_f32_16x16x32_bf16 v[18:21], v[158:161], v[132:135], v[18:21]
	global_load_dwordx4 v[132:135], v230, s[36:37] offset:1792
	s_waitcnt vmcnt(8)
; template <int MODE>
; __device__ __forceinline__ void gemm_tile(const Params& P, int tm, int tn, unsigned char* smem) {
;     ...
;     for (int kt = 0; kt < 16; ++kt) {
;         unsigned char* sA = (kt & 1) ? sA1 : sA0; unsigned char* sB = (kt & 1) ? sB1 : sB0;
;         unsigned char* nA = (kt & 1) ? sA0 : sA1; unsigned char* nB = (kt & 1) ? sB0 : sB1;
;         bf16x8 fa[4], fb[4], ga[4], gb[4];
;         const int ch0 = ((g ^ sw) << 4), ch1 = (((4 + g) ^ sw) << 4);
;         const unsigned ko = (unsigned)(kt + 2) * 128u;
;         const unsigned koa = ko + ((MODE == 2 && kt + 2 >= 8) ? (unsigned)(ZC_FQ - 512) * 2u : 0u);
;         const bool wr_ok = kt < 15, ld_ok = kt < 14;
; #pragma unroll
;         for (int i = 0; i < 4; ++i) { fa[i] = *(const bf16x8*)(sA + arow_off + i * 2048 + ch0); fb[i] = *(const bf16x8*)(sB + brow_off + i * 2048 + ch0); }
;         __builtin_amdgcn_sched_barrier(0);
;         __builtin_amdgcn_s_setprio(2);
;         if (wr_ok) *(uint4*)(nA + soff0) = ra0;
;         if (ld_ok) ra0 = *(const uint4*)(Ab + (aoff + 0u * LDA + koa));
;         ga[0] = *(const bf16x8*)(sA + arow_off + 0 * 2048 + ch1); gb[0] = *(const bf16x8*)(sB + brow_off + 0 * 2048 + ch1);
;         __builtin_amdgcn_sched_barrier(0);
; #pragma unroll
;         for (int j = 0; j < 4; ++j) acc[0][j] = __builtin_amdgcn_mfma_f32_16x16x32_bf16(fb[j], fa[0], acc[0][j], 0, 0, 0);
;         __builtin_amdgcn_sched_barrier(0);
;         if (wr_ok) *(uint4*)(nA + soff0 + 4096) = ra1;
;         if (ld_ok) ra1 = *(const uint4*)(Ab + (aoff + 32u * LDA + koa));
;         ga[1] = *(const bf16x8*)(sA + arow_off + 1 * 2048 + ch1); gb[1] = *(const bf16x8*)(sB + brow_off + 1 * 2048 + ch1);
;         __builtin_amdgcn_sched_barrier(0);
; #pragma unroll
;         for (int j = 0; j < 4; ++j) acc[1][j] = __builtin_amdgcn_mfma_f32_16x16x32_bf16(fb[j], fa[1], acc[1][j], 0, 0, 0);
;         __builtin_amdgcn_sched_barrier(0);
;         if (wr_ok) *(uint4*)(nA + soff0 + 8192) = ra2;
;         if (ld_ok) ra2 = *(const uint4*)(Ab + (aoff + 64u * LDA + koa));
;         ga[2] = *(const bf16x8*)(sA + arow_off + 2 * 2048 + ch1); gb[2] = *(const bf16x8*)(sB + brow_off + 2 * 2048 + ch1);
;         __builtin_amdgcn_sched_barrier(0);
; #pragma unroll
;         for (int j = 0; j < 4; ++j) acc[2][j] = __builtin_amdgcn_mfma_f32_16x16x32_bf16(fb[j], fa[2], acc[2][j], 0, 0, 0);
	ds_write_b128 v2, v[146:149] offset:45056
	ds_read_b128 v[146:149], v4 offset:6144
	ds_read_b128 v[182:185], v5 offset:22528
	v_mfma_f32_16x16x32_bf16 v[38:41], v[114:117], v[150:153], v[38:41]
	v_mfma_f32_16x16x32_bf16 v[50:53], v[126:129], v[150:153], v[50:53]
	v_mfma_f32_16x16x32_bf16 v[54:57], v[154:157], v[150:153], v[54:57]
	v_mfma_f32_16x16x32_bf16 v[22:25], v[158:161], v[150:153], v[22:25]
	global_load_dwordx4 v[114:117], v3, s[0:1] offset:1792
	s_waitcnt vmcnt(8)
	ds_write_b128 v2, v[122:125] offset:49152
	s_waitcnt lgkmcnt(10)
	v_mfma_f32_16x16x32_bf16 v[26:29], v[170:173], v[166:169], v[26:29]
	s_waitcnt lgkmcnt(1)
	v_mfma_f32_16x16x32_bf16 v[10:13], v[182:185], v[166:169], v[10:13]
	v_mfma_f32_16x16x32_bf16 v[86:89], v[174:177], v[166:169], v[86:89]
	v_mfma_f32_16x16x32_bf16 v[94:97], v[178:181], v[166:169], v[94:97]
	global_load_dwordx4 v[122:125], v231, s[0:1] offset:1792
	s_waitcnt vmcnt(8)
	ds_write_b128 v2, v[118:121] offset:53248
	v_mfma_f32_16x16x32_bf16 v[30:33], v[170:173], v[102:105], v[30:33]
	v_mfma_f32_16x16x32_bf16 v[42:45], v[174:177], v[102:105], v[42:45]
	v_mfma_f32_16x16x32_bf16 v[14:17], v[182:185], v[102:105], v[14:17]
	v_mfma_f32_16x16x32_bf16 v[90:93], v[178:181], v[102:105], v[90:93]
	global_load_dwordx4 v[102:105], v232, s[0:1] offset:1792
	s_waitcnt vmcnt(8)
	ds_write_b128 v2, v[62:65] offset:57344
	v_mfma_f32_16x16x32_bf16 v[34:37], v[170:173], v[110:113], v[34:37]
	v_mfma_f32_16x16x32_bf16 v[46:49], v[174:177], v[110:113], v[46:49]
	v_mfma_f32_16x16x32_bf16 v[58:61], v[178:181], v[110:113], v[58:61]
	v_mfma_f32_16x16x32_bf16 v[18:21], v[182:185], v[110:113], v[18:21]
	global_load_dwordx4 v[62:65], v233, s[0:1] offset:1792
	s_waitcnt vmcnt(8)
	ds_write_b128 v2, v[98:101] offset:61440
	v_mfma_f32_16x16x32_bf16 v[38:41], v[170:173], v[146:149], v[38:41]
	v_mfma_f32_16x16x32_bf16 v[50:53], v[174:177], v[146:149], v[50:53]
	v_mfma_f32_16x16x32_bf16 v[54:57], v[178:181], v[146:149], v[54:57]
	v_mfma_f32_16x16x32_bf16 v[22:25], v[182:185], v[146:149], v[22:25]
	s_setprio 0
	s_waitcnt lgkmcnt(0)
	s_barrier
	ds_read_b128 v[98:101], v6 offset:32768
	ds_read_b128 v[110:113], v6 offset:34816
	ds_read_b128 v[118:121], v7 offset:49152
	ds_read_b128 v[126:129], v7 offset:51200
	ds_read_b128 v[146:149], v6 offset:36864
	ds_read_b128 v[150:153], v6 offset:38912
	ds_read_b128 v[154:157], v7 offset:53248
	ds_read_b128 v[158:161], v7 offset:55296
	s_setprio 2
	global_load_dwordx4 v[166:169], v8, s[36:37] offset:1920
	s_waitcnt vmcnt(8)
	ds_write_b128 v2, v[162:165]
	ds_read_b128 v[162:165], v4 offset:32768
	ds_read_b128 v[170:173], v5 offset:49152
	s_waitcnt lgkmcnt(8)
	v_mfma_f32_16x16x32_bf16 v[26:29], v[118:121], v[98:101], v[26:29]
	s_waitcnt lgkmcnt(3)
	v_mfma_f32_16x16x32_bf16 v[10:13], v[158:161], v[98:101], v[10:13]
	v_mfma_f32_16x16x32_bf16 v[86:89], v[126:129], v[98:101], v[86:89]
	v_mfma_f32_16x16x32_bf16 v[94:97], v[154:157], v[98:101], v[94:97]
	global_load_dwordx4 v[98:101], v228, s[36:37] offset:1920
	s_waitcnt vmcnt(8)
	ds_write_b128 v2, v[82:85] offset:4096
	ds_read_b128 v[82:85], v4 offset:34816
	ds_read_b128 v[174:177], v5 offset:51200
	v_mfma_f32_16x16x32_bf16 v[30:33], v[118:121], v[110:113], v[30:33]
	v_mfma_f32_16x16x32_bf16 v[42:45], v[126:129], v[110:113], v[42:45]
	v_mfma_f32_16x16x32_bf16 v[14:17], v[158:161], v[110:113], v[14:17]
	v_mfma_f32_16x16x32_bf16 v[90:93], v[154:157], v[110:113], v[90:93]
	global_load_dwordx4 v[110:113], v229, s[36:37] offset:1920
	s_waitcnt vmcnt(8)
	ds_write_b128 v2, v[106:109] offset:8192
	ds_read_b128 v[106:109], v4 offset:36864
	ds_read_b128 v[178:181], v5 offset:53248
	v_mfma_f32_16x16x32_bf16 v[34:37], v[118:121], v[146:149], v[34:37]
	v_mfma_f32_16x16x32_bf16 v[46:49], v[126:129], v[146:149], v[46:49]
	v_mfma_f32_16x16x32_bf16 v[58:61], v[154:157], v[146:149], v[58:61]
	v_mfma_f32_16x16x32_bf16 v[18:21], v[158:161], v[146:149], v[18:21]
	v_add_u32_e32 v8, 0x30780, v8
	global_load_dwordx4 v[146:149], v8, s[36:37]
	s_waitcnt vmcnt(8)
	ds_write_b128 v2, v[132:135] offset:12288
	ds_read_b128 v[132:135], v4 offset:38912
	ds_read_b128 v[182:185], v5 offset:55296
	v_mfma_f32_16x16x32_bf16 v[38:41], v[118:121], v[150:153], v[38:41]
	v_mfma_f32_16x16x32_bf16 v[50:53], v[126:129], v[150:153], v[50:53]
	v_mfma_f32_16x16x32_bf16 v[54:57], v[154:157], v[150:153], v[54:57]
	v_mfma_f32_16x16x32_bf16 v[22:25], v[158:161], v[150:153], v[22:25]
	global_load_dwordx4 v[118:121], v3, s[0:1] offset:1920
	s_waitcnt vmcnt(8)
	ds_write_b128 v2, v[114:117] offset:16384
	s_waitcnt lgkmcnt(10)
	v_mfma_f32_16x16x32_bf16 v[26:29], v[170:173], v[162:165], v[26:29]
	s_waitcnt lgkmcnt(1)
	v_mfma_f32_16x16x32_bf16 v[8:11], v[182:185], v[162:165], v[10:13]
	v_mfma_f32_16x16x32_bf16 v[86:89], v[174:177], v[162:165], v[86:89]
	v_mfma_f32_16x16x32_bf16 v[94:97], v[178:181], v[162:165], v[94:97]
	s_nop 0
	global_load_dwordx4 v[114:117], v231, s[0:1] offset:1920
	s_waitcnt vmcnt(8)
	ds_write_b128 v2, v[122:125] offset:20480
	v_mfma_f32_16x16x32_bf16 v[30:33], v[170:173], v[82:85], v[30:33]
	v_mfma_f32_16x16x32_bf16 v[42:45], v[174:177], v[82:85], v[42:45]
	v_mfma_f32_16x16x32_bf16 v[12:15], v[182:185], v[82:85], v[14:17]
	v_mfma_f32_16x16x32_bf16 v[90:93], v[178:181], v[82:85], v[90:93]
	s_nop 1
	global_load_dwordx4 v[82:85], v232, s[0:1] offset:1920
	s_waitcnt vmcnt(8)
	ds_write_b128 v2, v[102:105] offset:24576
	v_mfma_f32_16x16x32_bf16 v[34:37], v[170:173], v[106:109], v[34:37]
	v_mfma_f32_16x16x32_bf16 v[46:49], v[174:177], v[106:109], v[46:49]
	v_mfma_f32_16x16x32_bf16 v[58:61], v[178:181], v[106:109], v[58:61]
	v_mfma_f32_16x16x32_bf16 v[16:19], v[182:185], v[106:109], v[18:21]
	v_add_u32_e32 v3, 0x30780, v3
	global_load_dwordx4 v[102:105], v3, s[0:1]
	s_waitcnt vmcnt(8)
	ds_write_b128 v2, v[62:65] offset:28672
	v_mfma_f32_16x16x32_bf16 v[38:41], v[170:173], v[132:135], v[38:41]
	v_mfma_f32_16x16x32_bf16 v[50:53], v[174:177], v[132:135], v[50:53]
	v_mfma_f32_16x16x32_bf16 v[54:57], v[178:181], v[132:135], v[54:57]
	v_mfma_f32_16x16x32_bf16 v[20:23], v[182:185], v[132:135], v[22:25]
	s_setprio 0
	s_waitcnt lgkmcnt(0)
	s_barrier
; template <int MODE>
; __device__ __forceinline__ void gemm_tile(const Params& P, int tm, int tn, unsigned char* smem) {
;     ...
; #pragma unroll
;         for (int i = 0; i < 4; ++i) { fa[i] = *(const bf16x8*)(sA + arow_off + i * 2048 + ch0); fb[i] = *(const bf16x8*)(sB + brow_off + i * 2048 + ch0); }
;         __builtin_amdgcn_sched_barrier(0);
;         __builtin_amdgcn_s_setprio(2);
;         if (wr_ok) *(uint4*)(nA + soff0) = ra0;
;         if (ld_ok) ra0 = *(const uint4*)(Ab + (aoff + 0u * LDA + koa));
;         ga[0] = *(const bf16x8*)(sA + arow_off + 0 * 2048 + ch1); gb[0] = *(const bf16x8*)(sB + brow_off + 0 * 2048 + ch1);
;         __builtin_amdgcn_sched_barrier(0);
; #pragma unroll
;         for (int j = 0; j < 4; ++j) acc[0][j] = __builtin_amdgcn_mfma_f32_16x16x32_bf16(fb[j], fa[0], acc[0][j], 0, 0, 0);
;         __builtin_amdgcn_sched_barrier(0);
;         if (wr_ok) *(uint4*)(nA + soff0 + 4096) = ra1;
;         if (ld_ok) ra1 = *(const uint4*)(Ab + (aoff + 32u * LDA + koa));
;         ga[1] = *(const bf16x8*)(sA + arow_off + 1 * 2048 + ch1); gb[1] = *(const bf16x8*)(sB + brow_off + 1 * 2048 + ch1);
;         __builtin_amdgcn_sched_barrier(0);
; #pragma unroll
;         for (int j = 0; j < 4; ++j) acc[1][j] = __builtin_amdgcn_mfma_f32_16x16x32_bf16(fb[j], fa[1], acc[1][j], 0, 0, 0);
;         __builtin_amdgcn_sched_barrier(0);
;         if (wr_ok) *(uint4*)(nA + soff0 + 8192) = ra2;
;         if (ld_ok) ra2 = *(const uint4*)(Ab + (aoff + 64u * LDA + koa));
;         ga[2] = *(const bf16x8*)(sA + arow_off + 2 * 2048 + ch1); gb[2] = *(const bf16x8*)(sB + brow_off + 2 * 2048 + ch1);
;         __builtin_amdgcn_sched_barrier(0);
; #pragma unroll
;         for (int j = 0; j < 4; ++j) acc[2][j] = __builtin_amdgcn_mfma_f32_16x16x32_bf16(fb[j], fa[2], acc[2][j], 0, 0, 0);
;         __builtin_amdgcn_sched_barrier(0);
;         if (wr_ok) *(uint4*)(nA + soff0 + 12288) = ra3;
;         if (ld_ok) ra3 = *(const uint4*)(Ab + (aoff + 96u * LDA + koa));
;         ga[3] = *(const bf16x8*)(sA + arow_off + 3 * 2048 + ch1); gb[3] = *(const bf16x8*)(sB + brow_off + 3 * 2048 + ch1);
;         __builtin_amdgcn_sched_barrier(0);
; #pragma unroll
;         for (int j = 0; j < 4; ++j) acc[3][j] = __builtin_amdgcn_mfma_f32_16x16x32_bf16(fb[j], fa[3], acc[3][j], 0, 0, 0);
;         __builtin_amdgcn_sched_barrier(0);
;         if (wr_ok) *(uint4*)(nB + soff0) = rb0;
	ds_read_b128 v[62:65], v6
	ds_read_b128 v[106:109], v6 offset:2048
	ds_read_b128 v[122:125], v7 offset:16384
	ds_read_b128 v[126:129], v7 offset:18432
	ds_read_b128 v[132:135], v6 offset:4096
	ds_read_b128 v[150:153], v6 offset:6144
	ds_read_b128 v[154:157], v7 offset:20480
	ds_read_b128 v[158:161], v7 offset:22528
	s_setprio 2
	s_waitcnt vmcnt(7)
	ds_write_b128 v2, v[166:169] offset:32768
	ds_read_b128 v[162:165], v4
	ds_read_b128 v[166:169], v5 offset:16384
	s_waitcnt lgkmcnt(8)
	v_mfma_f32_16x16x32_bf16 v[24:27], v[122:125], v[62:65], v[26:29]
	s_waitcnt lgkmcnt(3)
	v_mfma_f32_16x16x32_bf16 v[8:11], v[158:161], v[62:65], v[8:11]
	v_mfma_f32_16x16x32_bf16 v[86:89], v[126:129], v[62:65], v[86:89]
	v_mfma_f32_16x16x32_bf16 v[94:97], v[154:157], v[62:65], v[94:97]
	s_waitcnt vmcnt(6)
	ds_write_b128 v2, v[98:101] offset:36864
	ds_read_b128 v[62:65], v4 offset:2048
	ds_read_b128 v[98:101], v5 offset:18432
	v_mfma_f32_16x16x32_bf16 v[28:31], v[122:125], v[106:109], v[30:33]
	v_mfma_f32_16x16x32_bf16 v[42:45], v[126:129], v[106:109], v[42:45]
	v_mfma_f32_16x16x32_bf16 v[12:15], v[158:161], v[106:109], v[12:15]
	v_mfma_f32_16x16x32_bf16 v[90:93], v[154:157], v[106:109], v[90:93]
	s_waitcnt vmcnt(5)
	ds_write_b128 v2, v[110:113] offset:40960
	ds_read_b128 v[106:109], v4 offset:4096
	ds_read_b128 v[110:113], v5 offset:20480
	v_mfma_f32_16x16x32_bf16 v[32:35], v[122:125], v[132:135], v[34:37]
	v_mfma_f32_16x16x32_bf16 v[46:49], v[126:129], v[132:135], v[46:49]
	v_mfma_f32_16x16x32_bf16 v[58:61], v[154:157], v[132:135], v[58:61]
	v_mfma_f32_16x16x32_bf16 v[16:19], v[158:161], v[132:135], v[16:19]
	s_waitcnt vmcnt(4)
	ds_write_b128 v2, v[146:149] offset:45056
	ds_read_b128 v[132:135], v4 offset:6144
	ds_read_b128 v[146:149], v5 offset:22528
	v_mfma_f32_16x16x32_bf16 v[36:39], v[122:125], v[150:153], v[38:41]
	v_mfma_f32_16x16x32_bf16 v[50:53], v[126:129], v[150:153], v[50:53]
	v_mfma_f32_16x16x32_bf16 v[54:57], v[154:157], v[150:153], v[54:57]
	v_mfma_f32_16x16x32_bf16 v[20:23], v[158:161], v[150:153], v[20:23]
	s_waitcnt vmcnt(3)
	ds_write_b128 v2, v[118:121] offset:49152
	s_waitcnt lgkmcnt(10)
	v_mfma_f32_16x16x32_bf16 v[24:27], v[166:169], v[162:165], v[24:27]
	s_waitcnt lgkmcnt(1)
	v_mfma_f32_16x16x32_bf16 v[8:11], v[146:149], v[162:165], v[8:11]
	v_mfma_f32_16x16x32_bf16 v[86:89], v[98:101], v[162:165], v[86:89]
	v_mfma_f32_16x16x32_bf16 v[94:97], v[110:113], v[162:165], v[94:97]
	s_waitcnt vmcnt(2)
	ds_write_b128 v2, v[114:117] offset:53248
	v_mfma_f32_16x16x32_bf16 v[28:31], v[166:169], v[62:65], v[28:31]
	v_mfma_f32_16x16x32_bf16 v[40:43], v[98:101], v[62:65], v[42:45]
	v_mfma_f32_16x16x32_bf16 v[12:15], v[146:149], v[62:65], v[12:15]
	v_mfma_f32_16x16x32_bf16 v[90:93], v[110:113], v[62:65], v[90:93]
	s_waitcnt vmcnt(1)
	ds_write_b128 v2, v[82:85] offset:57344
	v_mfma_f32_16x16x32_bf16 v[32:35], v[166:169], v[106:109], v[32:35]
	v_mfma_f32_16x16x32_bf16 v[44:47], v[98:101], v[106:109], v[46:49]
	v_mfma_f32_16x16x32_bf16 v[58:61], v[110:113], v[106:109], v[58:61]
	v_mfma_f32_16x16x32_bf16 v[16:19], v[146:149], v[106:109], v[16:19]
	s_waitcnt vmcnt(0)
	ds_write_b128 v2, v[102:105] offset:61440
	v_mfma_f32_16x16x32_bf16 v[36:39], v[166:169], v[132:135], v[36:39]
	v_mfma_f32_16x16x32_bf16 v[48:51], v[98:101], v[132:135], v[50:53]
	v_mfma_f32_16x16x32_bf16 v[52:55], v[110:113], v[132:135], v[54:57]
	v_mfma_f32_16x16x32_bf16 v[20:23], v[146:149], v[132:135], v[20:23]
	s_setprio 0
	s_waitcnt lgkmcnt(0)
	s_barrier
	ds_read_b128 v[62:65], v6 offset:32768
	ds_read_b128 v[82:85], v6 offset:34816
	ds_read_b128 v[98:101], v7 offset:49152
	ds_read_b128 v[102:105], v7 offset:51200
	ds_read_b128 v[106:109], v6 offset:36864
	ds_read_b128 v[110:113], v6 offset:38912
	ds_read_b128 v[114:117], v7 offset:53248
	ds_read_b128 v[118:121], v7 offset:55296
	s_setprio 2
	ds_read_b128 v[122:125], v4 offset:32768
	ds_read_b128 v[126:129], v5 offset:49152
	s_waitcnt lgkmcnt(7)
	v_mfma_f32_16x16x32_bf16 v[24:27], v[98:101], v[62:65], v[24:27]
	s_waitcnt lgkmcnt(2)
	v_mfma_f32_16x16x32_bf16 v[6:9], v[118:121], v[62:65], v[8:11]
	v_mfma_f32_16x16x32_bf16 v[86:89], v[102:105], v[62:65], v[86:89]
	v_mfma_f32_16x16x32_bf16 v[94:97], v[114:117], v[62:65], v[94:97]
	ds_read_b128 v[132:135], v4 offset:34816
	ds_read_b128 v[146:149], v5 offset:51200
	v_mfma_f32_16x16x32_bf16 v[28:31], v[98:101], v[82:85], v[28:31]
	v_mfma_f32_16x16x32_bf16 v[40:43], v[102:105], v[82:85], v[40:43]
	v_mfma_f32_16x16x32_bf16 v[10:13], v[118:121], v[82:85], v[12:15]
	v_mfma_f32_16x16x32_bf16 v[90:93], v[114:117], v[82:85], v[90:93]
	ds_read_b128 v[82:85], v4 offset:36864
	ds_read_b128 v[150:153], v5 offset:53248
	v_mfma_f32_16x16x32_bf16 v[14:17], v[118:121], v[106:109], v[16:19]
	v_mfma_f32_16x16x32_bf16 v[154:157], v[98:101], v[106:109], v[32:35]
	v_mfma_f32_16x16x32_bf16 v[158:161], v[102:105], v[106:109], v[44:47]
	v_mfma_f32_16x16x32_bf16 v[162:165], v[114:117], v[106:109], v[58:61]
	ds_read_b128 v[106:109], v4 offset:38912
	ds_read_b128 v[2:5], v5 offset:55296
	v_mfma_f32_16x16x32_bf16 v[98:101], v[98:101], v[110:113], v[36:39]
	v_mfma_f32_16x16x32_bf16 v[102:105], v[102:105], v[110:113], v[48:51]
	v_mfma_f32_16x16x32_bf16 v[114:117], v[114:117], v[110:113], v[52:55]
	v_mfma_f32_16x16x32_bf16 v[110:113], v[118:121], v[110:113], v[20:23]
	s_waitcnt lgkmcnt(6)
	v_mfma_f32_16x16x32_bf16 v[62:65], v[126:129], v[122:125], v[24:27]
	s_waitcnt lgkmcnt(4)
	v_mfma_f32_16x16x32_bf16 v[58:61], v[146:149], v[122:125], v[86:89]
	s_waitcnt lgkmcnt(2)
	v_mfma_f32_16x16x32_bf16 v[54:57], v[150:153], v[122:125], v[94:97]
	s_waitcnt lgkmcnt(0)
	v_mfma_f32_16x16x32_bf16 v[50:53], v[2:5], v[122:125], v[6:9]
	v_mfma_f32_16x16x32_bf16 v[46:49], v[126:129], v[132:135], v[28:31]
	v_mfma_f32_16x16x32_bf16 v[42:45], v[146:149], v[132:135], v[40:43]
	v_mfma_f32_16x16x32_bf16 v[38:41], v[150:153], v[132:135], v[90:93]
	v_mfma_f32_16x16x32_bf16 v[34:37], v[2:5], v[132:135], v[10:13]
	v_mfma_f32_16x16x32_bf16 v[30:33], v[126:129], v[82:85], v[154:157]
	v_mfma_f32_16x16x32_bf16 v[26:29], v[146:149], v[82:85], v[158:161]
	v_mfma_f32_16x16x32_bf16 v[22:25], v[150:153], v[82:85], v[162:165]
	v_mfma_f32_16x16x32_bf16 v[18:21], v[2:5], v[82:85], v[14:17]
	v_mfma_f32_16x16x32_bf16 v[14:17], v[126:129], v[106:109], v[98:101]
	v_mfma_f32_16x16x32_bf16 v[10:13], v[146:149], v[106:109], v[102:105]
	v_mfma_f32_16x16x32_bf16 v[6:9], v[150:153], v[106:109], v[114:117]
	v_mfma_f32_16x16x32_bf16 v[2:5], v[2:5], v[106:109], v[110:113]
	s_setprio 0
	s_and_b32 s0, s5, -8
	s_cmp_lg_u32 s0, 16
	s_barrier
; template <int MODE>
; __device__ __forceinline__ void gemm_tile(const Params& P, int tm, int tn, unsigned char* smem) {
;     ...
;     if (MODE == 1) {
;         if (n0 >= ZC_FQ && n0 < ZC_FV) {
;             const bool isk = n0 >= ZC_FK;
;             const float* gain = isk ? P.f_k_norm : P.f_q_norm;
;             const float scl = isk ? 1.0f : 0.125f * LOG2E;
;             float gn[4][4];
; #pragma unroll
;             for (int j = 0; j < 4; ++j)
; #pragma unroll
;                 for (int r = 0; r < 4; ++r) gn[j][r] = gain[16 * j + 4 * g + r];
; #pragma unroll
;             for (int i = 0; i < 4; ++i) {
;                 float ss = 0.f;
; #pragma unroll
;                 for (int j = 0; j < 4; ++j)
; #pragma unroll
;                     for (int r = 0; r < 4; ++r) ss += acc[i][j][r] * acc[i][j][r];
;                 ss = x4_sum(ss);
;                 const float rstd = rsqrtf(ss * (1.0f / 64.0f) + EPS) * scl;
	s_cbranch_scc1 .LBB0_244
	v_mul_f32_e32 v68, v63, v63
	v_fmac_f32_e32 v68, v62, v62
	v_fmac_f32_e32 v68, v64, v64
	v_fmac_f32_e32 v68, v65, v65
	v_fmac_f32_e32 v68, v58, v58
	v_fmac_f32_e32 v68, v59, v59
	v_fmac_f32_e32 v68, v60, v60
	v_fmac_f32_e32 v68, v61, v61
	v_fmac_f32_e32 v68, v54, v54
	v_fmac_f32_e32 v68, v55, v55
	v_fmac_f32_e32 v68, v56, v56
	s_cmp_gt_u32 s5, 19
	v_fmac_f32_e32 v68, v57, v57
	v_pk_mul_f32 v[82:83], v[50:51], v[50:51]
	v_mov_b32_e32 v66, 0x3e38aa3b
	s_cselect_b64 s[0:1], -1, 0
	v_add_f32_e32 v68, v82, v68
	v_cndmask_b32_e64 v106, v66, 1.0, s[0:1]
	v_pk_mul_f32 v[66:67], v[52:53], v[52:53]
	v_add_f32_e32 v68, v83, v68
	v_add_f32_e32 v66, v66, v68
	v_add_f32_e32 v66, v67, v66
	v_mov_b32_e32 v67, v66
	s_nop 1
	v_permlane32_swap_b32_e32 v66, v67
	v_add_f32_e32 v67, v66, v67
	v_mul_f32_e32 v66, v47, v47
	v_fmac_f32_e32 v66, v46, v46
	v_fmac_f32_e32 v66, v48, v48
	v_fmac_f32_e32 v66, v49, v49
	v_fmac_f32_e32 v66, v42, v42
	v_fmac_f32_e32 v66, v43, v43
	v_fmac_f32_e32 v66, v44, v44
	v_fmac_f32_e32 v66, v45, v45
	v_fmac_f32_e32 v66, v38, v38
	v_fmac_f32_e32 v66, v39, v39
	v_fmac_f32_e32 v66, v40, v40
	v_fmac_f32_e32 v66, v41, v41
	v_pk_mul_f32 v[86:87], v[34:35], v[34:35]
	v_pk_mul_f32 v[84:85], v[36:37], v[36:37]
	v_add_f32_e32 v66, v86, v66
	v_add_f32_e32 v66, v87, v66
	v_add_f32_e32 v66, v84, v66
	v_add_f32_e32 v66, v85, v66
	v_mov_b32_e32 v68, v66
	s_nop 1
	v_permlane32_swap_b32_e32 v66, v68
	v_add_f32_e32 v66, v66, v68
	s_and_b64 s[0:1], s[0:1], exec
	v_mov_b32_e32 v83, v67
	v_mov_b32_e32 v82, v66
	s_nop 0
	v_permlane16_swap_b32_e32 v67, v83
	v_permlane16_swap_b32_e32 v66, v82
	s_mov_b32 s0, 0x358637bd
	v_pk_add_f32 v[82:83], v[66:67], v[82:83]
	s_mov_b32 s8, 0x3c800000
	v_mov_b64_e32 v[66:67], s[0:1]
	v_mul_f32_e32 v95, v31, v31
	v_pk_fma_f32 v[86:87], v[82:83], s[8:9], v[66:67] op_sel_hi:[1,0,0]
	s_mov_b32 s5, 0x800000
	v_fmac_f32_e32 v95, v30, v30
	v_mul_f32_e32 v68, 0x4b800000, v87
	v_cmp_gt_f32_e32 vcc, s5, v87
	v_fmac_f32_e32 v95, v32, v32
	v_fmac_f32_e32 v95, v33, v33
	v_cndmask_b32_e32 v68, v87, v68, vcc
	v_rsq_f32_e32 v68, v68
	v_mul_f32_e32 v70, 0x4b800000, v86
	v_cmp_gt_f32_e64 s[0:1], s5, v86
	v_fmac_f32_e32 v95, v26, v26
	v_fmac_f32_e32 v95, v27, v27
	v_cndmask_b32_e64 v70, v86, v70, s[0:1]
	v_rsq_f32_e32 v86, v70
	v_fmac_f32_e32 v95, v28, v28
	s_cselect_b32 s7, s41, s39
	s_cselect_b32 s6, s40, s38
	v_lshlrev_b32_e32 v94, 4, v81
	v_fmac_f32_e32 v95, v29, v29
	global_load_dwordx4 v[82:85], v94, s[6:7]
	v_mul_f32_e32 v70, 0x45800000, v68
	v_fmac_f32_e32 v95, v22, v22
	v_cndmask_b32_e32 v68, v68, v70, vcc
	v_fmac_f32_e32 v95, v23, v23
	v_mul_f32_e32 v70, v106, v68
	v_mul_f32_e32 v68, 0x45800000, v86
	v_fmac_f32_e32 v95, v24, v24
	v_cndmask_b32_e64 v68, v86, v68, s[0:1]
	global_load_dwordx4 v[86:89], v94, s[6:7] offset:64
	v_fmac_f32_e32 v95, v25, v25
	v_pk_mul_f32 v[92:93], v[18:19], v[18:19]
	v_pk_mul_f32 v[90:91], v[20:21], v[20:21]
	v_add_f32_e32 v92, v92, v95
	v_add_f32_e32 v92, v93, v92
	v_add_f32_e32 v90, v90, v92
	v_add_f32_e32 v95, v91, v90
	global_load_dwordx4 v[90:93], v94, s[6:7] offset:128
	v_mov_b32_e32 v96, v95
	s_nop 1
	v_permlane32_swap_b32_e32 v95, v96
	v_add_f32_e32 v99, v95, v96
	global_load_dwordx4 v[94:97], v94, s[6:7] offset:192
	v_mul_f32_e32 v98, v15, v15
	v_fmac_f32_e32 v98, v14, v14
	v_fmac_f32_e32 v98, v16, v16
	v_fmac_f32_e32 v98, v17, v17
	v_fmac_f32_e32 v98, v10, v10
	v_fmac_f32_e32 v98, v11, v11
	v_fmac_f32_e32 v98, v12, v12
	v_fmac_f32_e32 v98, v13, v13
	v_fmac_f32_e32 v98, v6, v6
	v_fmac_f32_e32 v98, v7, v7
	v_fmac_f32_e32 v98, v8, v8
	v_fmac_f32_e32 v98, v9, v9
	v_pk_mul_f32 v[104:105], v[2:3], v[2:3]
	v_pk_mul_f32 v[102:103], v[4:5], v[4:5]
	v_add_f32_e32 v98, v104, v98
	v_add_f32_e32 v98, v105, v98
	v_add_f32_e32 v98, v102, v98
	v_add_f32_e32 v98, v103, v98
	v_mov_b32_e32 v100, v98
	s_nop 1
	v_permlane32_swap_b32_e32 v98, v100
	v_add_f32_e32 v98, v98, v100
	v_mov_b32_e32 v101, v99
	v_mov_b32_e32 v100, v98
	s_nop 0
	v_permlane16_swap_b32_e32 v99, v101
	v_permlane16_swap_b32_e32 v98, v100
	v_pk_add_f32 v[98:99], v[98:99], v[100:101]
	v_mul_f32_e32 v68, v106, v68
	v_pk_fma_f32 v[66:67], v[98:99], s[8:9], v[66:67] op_sel_hi:[1,0,0]
	s_waitcnt vmcnt(3)
; template <int MODE>
; __device__ __forceinline__ void gemm_tile(const Params& P, int tm, int tn, unsigned char* smem) {
;     ...
; #pragma unroll
;                 for (int j = 0; j < 4; ++j)
; #pragma unroll
;                     for (int r = 0; r < 4; ++r) acc[i][j][r] *= rstd * gn[j][r];
;             }
	v_pk_mul_f32 v[100:101], v[82:83], v[70:71] op_sel_hi:[1,0]
	v_mul_f32_e32 v98, 0x4b800000, v67
	v_cmp_gt_f32_e32 vcc, s5, v67
	v_cmp_gt_f32_e64 s[0:1], s5, v66
	v_pk_mul_f32 v[62:63], v[62:63], v[100:101]
	v_cndmask_b32_e32 v67, v67, v98, vcc
	v_mul_f32_e32 v98, 0x4b800000, v66
	v_rsq_f32_e32 v67, v67
	v_cndmask_b32_e64 v66, v66, v98, s[0:1]
	v_rsq_f32_e32 v98, v66
	v_pk_mul_f32 v[100:101], v[82:83], v[68:69] op_sel_hi:[1,0]
	v_mul_f32_e32 v66, 0x45800000, v67
	v_cndmask_b32_e32 v66, v67, v66, vcc
	v_mul_f32_e32 v67, 0x45800000, v98
	v_cndmask_b32_e64 v67, v98, v67, s[0:1]
	v_mul_f32_e32 v66, v106, v66
	v_mul_f32_e32 v98, v106, v67
	v_pk_mul_f32 v[102:103], v[84:85], v[70:71] op_sel_hi:[1,0]
	v_pk_mul_f32 v[46:47], v[46:47], v[100:101]
	v_pk_mul_f32 v[100:101], v[82:83], v[66:67] op_sel_hi:[1,0]
	v_pk_mul_f32 v[82:83], v[82:83], v[98:99] op_sel_hi:[1,0]
	v_pk_mul_f32 v[64:65], v[64:65], v[102:103]
	v_pk_mul_f32 v[102:103], v[84:85], v[68:69] op_sel_hi:[1,0]
	v_pk_mul_f32 v[14:15], v[14:15], v[82:83]
	s_waitcnt vmcnt(2)
	v_pk_mul_f32 v[82:83], v[86:87], v[70:71] op_sel_hi:[1,0]
	v_pk_mul_f32 v[48:49], v[48:49], v[102:103]
	v_pk_mul_f32 v[102:103], v[84:85], v[66:67] op_sel_hi:[1,0]
	v_pk_mul_f32 v[84:85], v[84:85], v[98:99] op_sel_hi:[1,0]
	v_pk_mul_f32 v[58:59], v[58:59], v[82:83]
	v_pk_mul_f32 v[82:83], v[86:87], v[68:69] op_sel_hi:[1,0]
	v_pk_mul_f32 v[16:17], v[16:17], v[84:85]
	v_pk_mul_f32 v[84:85], v[88:89], v[70:71] op_sel_hi:[1,0]
	v_pk_mul_f32 v[42:43], v[42:43], v[82:83]
	v_pk_mul_f32 v[82:83], v[86:87], v[66:67] op_sel_hi:[1,0]
	v_pk_mul_f32 v[60:61], v[60:61], v[84:85]
	v_pk_mul_f32 v[84:85], v[88:89], v[68:69] op_sel_hi:[1,0]
	v_pk_mul_f32 v[26:27], v[26:27], v[82:83]
	v_pk_mul_f32 v[82:83], v[86:87], v[98:99] op_sel_hi:[1,0]
	v_pk_mul_f32 v[44:45], v[44:45], v[84:85]
	v_pk_mul_f32 v[84:85], v[88:89], v[66:67] op_sel_hi:[1,0]
	v_pk_mul_f32 v[10:11], v[10:11], v[82:83]
	s_waitcnt vmcnt(1)
	v_pk_mul_f32 v[82:83], v[90:91], v[70:71] op_sel_hi:[1,0]
	v_pk_mul_f32 v[28:29], v[28:29], v[84:85]
	v_pk_mul_f32 v[84:85], v[88:89], v[98:99] op_sel_hi:[1,0]
	v_pk_mul_f32 v[54:55], v[54:55], v[82:83]
	v_pk_mul_f32 v[82:83], v[90:91], v[68:69] op_sel_hi:[1,0]
	v_pk_mul_f32 v[12:13], v[12:13], v[84:85]
	v_pk_mul_f32 v[84:85], v[92:93], v[70:71] op_sel_hi:[1,0]
	v_pk_mul_f32 v[38:39], v[38:39], v[82:83]
	v_pk_mul_f32 v[82:83], v[90:91], v[66:67] op_sel_hi:[1,0]
	v_pk_mul_f32 v[56:57], v[56:57], v[84:85]
	v_pk_mul_f32 v[84:85], v[92:93], v[68:69] op_sel_hi:[1,0]
	v_pk_mul_f32 v[22:23], v[22:23], v[82:83]
	v_pk_mul_f32 v[82:83], v[90:91], v[98:99] op_sel_hi:[1,0]
	v_pk_mul_f32 v[40:41], v[40:41], v[84:85]
	v_pk_mul_f32 v[84:85], v[92:93], v[66:67] op_sel_hi:[1,0]
	v_pk_mul_f32 v[6:7], v[6:7], v[82:83]
	s_waitcnt vmcnt(0)
	v_pk_mul_f32 v[82:83], v[94:95], v[70:71] op_sel_hi:[1,0]
	v_pk_mul_f32 v[24:25], v[24:25], v[84:85]
	v_pk_mul_f32 v[84:85], v[92:93], v[98:99] op_sel_hi:[1,0]
	v_pk_mul_f32 v[50:51], v[50:51], v[82:83]
	v_pk_mul_f32 v[82:83], v[94:95], v[68:69] op_sel_hi:[1,0]
	v_pk_mul_f32 v[8:9], v[8:9], v[84:85]
	v_pk_mul_f32 v[84:85], v[96:97], v[70:71] op_sel_hi:[1,0]
	v_pk_mul_f32 v[34:35], v[34:35], v[82:83]
	v_pk_mul_f32 v[82:83], v[94:95], v[66:67] op_sel_hi:[1,0]
	v_pk_mul_f32 v[66:67], v[96:97], v[66:67] op_sel_hi:[1,0]
	v_pk_mul_f32 v[52:53], v[52:53], v[84:85]
	v_pk_mul_f32 v[84:85], v[96:97], v[68:69] op_sel_hi:[1,0]
	v_pk_mul_f32 v[20:21], v[20:21], v[66:67]
	v_pk_mul_f32 v[18:19], v[18:19], v[82:83]
	v_pk_mul_f32 v[66:67], v[94:95], v[98:99] op_sel_hi:[1,0]
	v_pk_mul_f32 v[82:83], v[96:97], v[98:99] op_sel_hi:[1,0]
	v_pk_mul_f32 v[32:33], v[32:33], v[102:103]
	v_pk_mul_f32 v[30:31], v[30:31], v[100:101]
	v_pk_mul_f32 v[36:37], v[36:37], v[84:85]
	v_pk_mul_f32 v[4:5], v[4:5], v[82:83]
	v_pk_mul_f32 v[2:3], v[2:3], v[66:67]

; template <int MODE>
; __device__ __forceinline__ void gemm_tile(const Params& P, int tm, int tn, unsigned char* smem) {
;     ...
;     const int tid = opaque_tid(), lane = tid & 63, wave = tid >> 6, wr = wave >> 1, wc = wave & 1, g = lane >> 4, lr = lane & 15;
;     const int m0 = tm * 128, n0 = tn * 128;
;     const int srow = tid >> 3, sc = tid & 7;
;     constexpr unsigned LDA = (MODE == 2 ? NZ : 1024) * 2u;
;     unsigned aoff, boff; int soff0;
;     {
;         int ar = m0 + srow;
;         if (MODE == 2) { const int b = ar >> 11, t = ar & 2047; ar = b * L + NMETA + t; }
;         aoff = (unsigned)ar * LDA + (unsigned)sc * 16u;
;         boff = (unsigned)(n0 + srow) * 2048u + (unsigned)sc * 16u;
;         soff0 = srow * 128 + ((sc ^ (srow & 7)) << 4);
;     }
;     const unsigned char* Ab = (const unsigned char*)A; const unsigned char* Bb = (const unsigned char*)Bt;
;     float4 ssp0, ssp1, ssp2, ssp3;
;     if (MODE == 3) {
;         const float* ssq = (const float*)(P.ws + WS_SSQ) + (size_t)(m0 + wr * 64 + lr) * 16 + 4 * g;
;         ssp0 = *(const float4*)(ssq); ssp1 = *(const float4*)(ssq + 16 * 16); ssp2 = *(const float4*)(ssq + 32 * 16); ssp3 = *(const float4*)(ssq + 48 * 16);
;     }
;     f32x4 acc[4][4];
; #pragma unroll
;     for (int i = 0; i < 4; ++i)
; #pragma unroll
;         for (int j = 0; j < 4; ++j) acc[i][j] = (f32x4){0.f, 0.f, 0.f, 0.f};
;     uint4 ra0, ra1, ra2, ra3, rb0, rb1, rb2, rb3;
;     ...
;     unsigned char* sA0 = smem; unsigned char* sB0 = smem + 16384; unsigned char* sA1 = smem + 32768; unsigned char* sB1 = smem + 49152;
;     G_LOAD(0)
;     G_WRITE(sA0, sB0)
;     __syncthreads();
;     const int arow_off = (wr * 64 + lr) * 128, brow_off = (wc * 64 + lr) * 128, sw = lr & 7;
;     G_LOAD(1)
;     ...
; #pragma unroll
;         for (int i = 0; i < 4; ++i) { fa[i] = *(const bf16x8*)(sA + arow_off + i * 2048 + ch0); fb[i] = *(const bf16x8*)(sB + brow_off + i * 2048 + ch0); }
;         __builtin_amdgcn_sched_barrier(0);
;         __builtin_amdgcn_s_setprio(2);
;         if (wr_ok) *(uint4*)(nA + soff0) = ra0;
;         if (ld_ok) ra0 = *(const uint4*)(Ab + (aoff + 0u * LDA + koa));
;         ga[0] = *(const bf16x8*)(sA + arow_off + 0 * 2048 + ch1); gb[0] = *(const bf16x8*)(sB + brow_off + 0 * 2048 + ch1);
;         __builtin_amdgcn_sched_barrier(0);
; #pragma unroll
.LBB0_1154:
	v_mov_b32_e32 v142, v0
	s_and_b32 s15, s9, 0xffffff80
	v_ashrrev_i32_e32 v2, 3, v142
	v_add_u32_e32 v3, s15, v2
	v_ashrrev_i32_e32 v4, 11, v3
	v_and_b32_e32 v3, 0x7ff, v3
	s_and_b32 s4, s6, 7
	v_mad_i32_i24 v3, v4, s11, v3
	v_lshlrev_b32_e32 v4, 4, v142
	s_lshl_b32 s18, s4, 7
	v_mul_lo_u32 v3, v3, s12
	v_and_b32_e32 v5, 0x70, v4
	v_add_u32_e32 v4, s18, v2
	v_or_b32_e32 v9, v3, v5
	v_lshl_or_b32 v4, v4, 11, v5
	v_add_u32_e32 v234, 0x1c000, v9
	global_load_dwordx4 v[10:13], v234, s[0:1]
	v_add_u32_e32 v3, 0x54000, v9
	v_add_u32_e32 v6, 0x20000, v4
	v_add_u32_e32 v5, 0x8c000, v9
	v_add_u32_e32 v7, 0x30000, v4
	global_load_dwordx4 v[14:17], v6, s[2:3]
	global_load_dwordx4 v[18:21], v7, s[2:3]
	global_load_dwordx4 v[22:25], v3, s[0:1]
	global_load_dwordx4 v[26:29], v5, s[0:1]
	v_add_u32_e32 v235, 0xc4000, v9
	global_load_dwordx4 v[30:33], v235, s[0:1]
	global_load_dwordx4 v[34:37], v4, s[2:3]
	v_add_u32_e32 v236, 0x10000, v4
	global_load_dwordx4 v[38:41], v236, s[2:3]
	v_xor_b32_e32 v3, v2, v142
	v_lshlrev_b32_e32 v2, 7, v2
	v_lshlrev_b32_e32 v3, 4, v3
	v_and_or_b32 v2, v3, s13, v2
	v_add_u32_e32 v3, 0, v2
	v_add_u32_e32 v2, 0x1c080, v9
	v_or_b32_e32 v5, 0x80, v4
	v_add_u32_e32 v6, 0x10080, v4
	v_add_u32_e32 v7, 0x20080, v4
	v_add_u32_e32 v8, 0x30080, v4
	v_add_u32_e32 v44, 0x54080, v9
	v_add_u32_e32 v45, 0x8c080, v9
	v_add_u32_e32 v46, 0xc4080, v9
	v_bfe_u32 v144, v142, 6, 1
	v_and_b32_e32 v143, 15, v142
	v_bfe_u32 v146, v142, 4, 2
	s_waitcnt vmcnt(6)
	ds_write_b128 v3, v[14:17] offset:24576
	s_waitcnt vmcnt(5)
	ds_write_b128 v3, v[18:21] offset:28672
	ds_write_b128 v3, v[10:13]
	s_waitcnt vmcnt(4)
	ds_write_b128 v3, v[22:25] offset:4096
	s_waitcnt vmcnt(3)
	ds_write_b128 v3, v[26:29] offset:8192
	s_waitcnt vmcnt(2)
	ds_write_b128 v3, v[30:33] offset:12288
	s_waitcnt vmcnt(1)
	ds_write_b128 v3, v[34:37] offset:16384
	s_waitcnt vmcnt(0)
	ds_write_b128 v3, v[38:41] offset:20480
	s_waitcnt lgkmcnt(0)
	s_barrier
	global_load_dwordx4 v[12:15], v2, s[0:1]
	global_load_dwordx4 v[16:19], v44, s[0:1]
	global_load_dwordx4 v[20:23], v45, s[0:1]
	global_load_dwordx4 v[24:27], v46, s[0:1]
	global_load_dwordx4 v[28:31], v5, s[2:3]
	global_load_dwordx4 v[32:35], v6, s[2:3]
	global_load_dwordx4 v[36:39], v7, s[2:3]
	global_load_dwordx4 v[40:43], v8, s[2:3]
	v_ashrrev_i32_e32 v2, 1, v142
	v_lshrrev_b32_e32 v5, 4, v142
	v_and_b32_e32 v10, 0xffffffc0, v2
	v_and_b32_e32 v11, 7, v142
	v_or_b32_e32 v145, v10, v143
	v_lshlrev_b32_e32 v2, 6, v144
	v_bitop3_b32 v5, v5, v11, 3 bitop3:0x6c
	v_or_b32_e32 v6, v2, v143
	v_lshlrev_b32_e32 v5, 4, v5
	v_lshl_add_u32 v80, v145, 7, 0
	v_add_u32_e32 v7, v80, v5
	v_lshl_add_u32 v6, v6, 7, 0
	v_add_u32_e32 v8, v6, v5
	ds_read_b128 v[44:47], v7
	ds_read_b128 v[48:51], v7 offset:2048
	ds_read_b128 v[52:55], v8 offset:16384
	ds_read_b128 v[56:59], v8 offset:18432
	ds_read_b128 v[60:63], v7 offset:4096
	ds_read_b128 v[64:67], v7 offset:6144
	ds_read_b128 v[68:71], v8 offset:20480
	ds_read_b128 v[72:75], v8 offset:22528
	v_bitop3_b32 v5, v146, v11, 4 bitop3:0x36
	v_lshlrev_b32_e32 v11, 4, v5
	s_setprio 2
	global_load_dwordx4 v[76:79], v234, s[0:1] offset:256
	s_waitcnt vmcnt(8)
	ds_write_b128 v3, v[12:15] offset:32768
	v_add_u32_e32 v5, v80, v11
	v_add_u32_e32 v6, v6, v11
	ds_read_b128 v[12:15], v5
	ds_read_b128 v[80:83], v6 offset:16384
	s_waitcnt lgkmcnt(8)
	v_mfma_f32_16x16x32_bf16 v[84:87], v[52:55], v[44:47], 0
	s_waitcnt lgkmcnt(7)
	v_mfma_f32_16x16x32_bf16 v[88:91], v[56:59], v[44:47], 0
	s_waitcnt lgkmcnt(4)
	v_mfma_f32_16x16x32_bf16 v[92:95], v[68:71], v[44:47], 0
	s_waitcnt lgkmcnt(3)
	v_mfma_f32_16x16x32_bf16 v[44:47], v[72:75], v[44:47], 0
	v_add_u32_e32 v237, 0x54000, v9
	global_load_dwordx4 v[100:103], v237, s[0:1] offset:256
	s_waitcnt vmcnt(8)
	ds_write_b128 v3, v[16:19] offset:36864
	ds_read_b128 v[16:19], v5 offset:2048
	ds_read_b128 v[104:107], v6 offset:18432
	v_mfma_f32_16x16x32_bf16 v[108:111], v[52:55], v[48:51], 0
	v_mfma_f32_16x16x32_bf16 v[112:115], v[56:59], v[48:51], 0
	v_mfma_f32_16x16x32_bf16 v[116:119], v[68:71], v[48:51], 0
	v_mfma_f32_16x16x32_bf16 v[48:51], v[72:75], v[48:51], 0
	v_add_u32_e32 v238, 0x8c000, v9
	global_load_dwordx4 v[120:123], v238, s[0:1] offset:256
	s_waitcnt vmcnt(8)
	ds_write_b128 v3, v[20:23] offset:40960
	ds_read_b128 v[20:23], v5 offset:4096
	ds_read_b128 v[124:127], v6 offset:20480
	v_mfma_f32_16x16x32_bf16 v[132:135], v[52:55], v[60:63], 0
	v_mfma_f32_16x16x32_bf16 v[136:139], v[56:59], v[60:63], 0
	v_mfma_f32_16x16x32_bf16 v[148:151], v[68:71], v[60:63], 0
	v_mfma_f32_16x16x32_bf16 v[60:63], v[72:75], v[60:63], 0
	global_load_dwordx4 v[152:155], v235, s[0:1] offset:256
	s_waitcnt vmcnt(8)
	ds_write_b128 v3, v[24:27] offset:45056
	ds_read_b128 v[24:27], v5 offset:6144
	ds_read_b128 v[156:159], v6 offset:22528
	v_mfma_f32_16x16x32_bf16 v[52:55], v[52:55], v[64:67], 0
	v_mfma_f32_16x16x32_bf16 v[56:59], v[56:59], v[64:67], 0
	v_mfma_f32_16x16x32_bf16 v[68:71], v[68:71], v[64:67], 0
	v_mfma_f32_16x16x32_bf16 v[64:67], v[72:75], v[64:67], 0
	global_load_dwordx4 v[72:75], v4, s[2:3] offset:256
	s_waitcnt vmcnt(8)
	ds_write_b128 v3, v[28:31] offset:49152
	s_waitcnt lgkmcnt(10)
	v_mfma_f32_16x16x32_bf16 v[28:31], v[80:83], v[12:15], v[84:87]
	s_waitcnt lgkmcnt(7)
	v_mfma_f32_16x16x32_bf16 v[84:87], v[104:107], v[12:15], v[88:91]
	s_waitcnt lgkmcnt(4)
	v_mfma_f32_16x16x32_bf16 v[88:91], v[124:127], v[12:15], v[92:95]
	s_waitcnt lgkmcnt(1)
	v_mfma_f32_16x16x32_bf16 v[12:15], v[156:159], v[12:15], v[44:47]
	global_load_dwordx4 v[44:47], v236, s[2:3] offset:256
	s_waitcnt vmcnt(8)
	ds_write_b128 v3, v[32:35] offset:53248
	v_mfma_f32_16x16x32_bf16 v[32:35], v[80:83], v[16:19], v[108:111]
	v_mfma_f32_16x16x32_bf16 v[92:95], v[104:107], v[16:19], v[112:115]
	v_mfma_f32_16x16x32_bf16 v[108:111], v[124:127], v[16:19], v[116:119]
	v_mfma_f32_16x16x32_bf16 v[16:19], v[156:159], v[16:19], v[48:51]
	v_add_u32_e32 v239, 0x20000, v4
	global_load_dwordx4 v[48:51], v239, s[2:3] offset:256
	s_waitcnt vmcnt(8)
	ds_write_b128 v3, v[36:39] offset:57344
	v_mfma_f32_16x16x32_bf16 v[36:39], v[80:83], v[20:23], v[132:135]
	v_mfma_f32_16x16x32_bf16 v[112:115], v[104:107], v[20:23], v[136:139]
	v_mfma_f32_16x16x32_bf16 v[116:119], v[124:127], v[20:23], v[148:151]
	v_mfma_f32_16x16x32_bf16 v[20:23], v[156:159], v[20:23], v[60:63]
	v_add_u32_e32 v240, 0x30000, v4
	global_load_dwordx4 v[60:63], v240, s[2:3] offset:256
	s_waitcnt vmcnt(8)
	ds_write_b128 v3, v[40:43] offset:61440
	v_mfma_f32_16x16x32_bf16 v[40:43], v[80:83], v[24:27], v[52:55]
	v_mfma_f32_16x16x32_bf16 v[52:55], v[104:107], v[24:27], v[56:59]
	v_mfma_f32_16x16x32_bf16 v[56:59], v[124:127], v[24:27], v[68:71]
	v_mfma_f32_16x16x32_bf16 v[24:27], v[156:159], v[24:27], v[64:67]
	s_setprio 0
	s_waitcnt lgkmcnt(0)
	s_barrier
; template <int MODE>
; __device__ __forceinline__ void gemm_tile(const Params& P, int tm, int tn, unsigned char* smem) {
;     ...
;     for (int kt = 0; kt < 16; ++kt) {
;         unsigned char* sA = (kt & 1) ? sA1 : sA0; unsigned char* sB = (kt & 1) ? sB1 : sB0;
;         unsigned char* nA = (kt & 1) ? sA0 : sA1; unsigned char* nB = (kt & 1) ? sB0 : sB1;
;         bf16x8 fa[4], fb[4], ga[4], gb[4];
;         const int ch0 = ((g ^ sw) << 4), ch1 = (((4 + g) ^ sw) << 4);
;         const unsigned ko = (unsigned)(kt + 2) * 128u;
;         const unsigned koa = ko + ((MODE == 2 && kt + 2 >= 8) ? (unsigned)(ZC_FQ - 512) * 2u : 0u);
;         const bool wr_ok = kt < 15, ld_ok = kt < 14;
; #pragma unroll
;         for (int i = 0; i < 4; ++i) { fa[i] = *(const bf16x8*)(sA + arow_off + i * 2048 + ch0); fb[i] = *(const bf16x8*)(sB + brow_off + i * 2048 + ch0); }
;         __builtin_amdgcn_sched_barrier(0);
;         __builtin_amdgcn_s_setprio(2);
;         if (wr_ok) *(uint4*)(nA + soff0) = ra0;
;         if (ld_ok) ra0 = *(const uint4*)(Ab + (aoff + 0u * LDA + koa));
;         ga[0] = *(const bf16x8*)(sA + arow_off + 0 * 2048 + ch1); gb[0] = *(const bf16x8*)(sB + brow_off + 0 * 2048 + ch1);
;         __builtin_amdgcn_sched_barrier(0);
; #pragma unroll
;         for (int j = 0; j < 4; ++j) acc[0][j] = __builtin_amdgcn_mfma_f32_16x16x32_bf16(fb[j], fa[0], acc[0][j], 0, 0, 0);
;         __builtin_amdgcn_sched_barrier(0);
;         if (wr_ok) *(uint4*)(nA + soff0 + 4096) = ra1;
;         if (ld_ok) ra1 = *(const uint4*)(Ab + (aoff + 32u * LDA + koa));
;         ga[1] = *(const bf16x8*)(sA + arow_off + 1 * 2048 + ch1); gb[1] = *(const bf16x8*)(sB + brow_off + 1 * 2048 + ch1);
;         __builtin_amdgcn_sched_barrier(0);
; #pragma unroll
;         for (int j = 0; j < 4; ++j) acc[1][j] = __builtin_amdgcn_mfma_f32_16x16x32_bf16(fb[j], fa[1], acc[1][j], 0, 0, 0);
;         __builtin_amdgcn_sched_barrier(0);
;         if (wr_ok) *(uint4*)(nA + soff0 + 8192) = ra2;
;         if (ld_ok) ra2 = *(const uint4*)(Ab + (aoff + 64u * LDA + koa));
;         ga[2] = *(const bf16x8*)(sA + arow_off + 2 * 2048 + ch1); gb[2] = *(const bf16x8*)(sB + brow_off + 2 * 2048 + ch1);
;         __builtin_amdgcn_sched_barrier(0);
; #pragma unroll
;         for (int j = 0; j < 4; ++j) acc[2][j] = __builtin_amdgcn_mfma_f32_16x16x32_bf16(fb[j], fa[2], acc[2][j], 0, 0, 0);
	ds_read_b128 v[64:67], v7 offset:32768
	ds_read_b128 v[68:71], v7 offset:34816
	ds_read_b128 v[80:83], v8 offset:49152
	ds_read_b128 v[104:107], v8 offset:51200
	ds_read_b128 v[124:127], v7 offset:36864
	ds_read_b128 v[132:135], v7 offset:38912
	ds_read_b128 v[136:139], v8 offset:53248
	ds_read_b128 v[148:151], v8 offset:55296
	s_setprio 2
	global_load_dwordx4 v[156:159], v234, s[0:1] offset:384
	s_waitcnt vmcnt(8)
	ds_write_b128 v3, v[76:79]
	ds_read_b128 v[76:79], v5 offset:32768
	ds_read_b128 v[160:163], v6 offset:49152
	s_waitcnt lgkmcnt(8)
	v_mfma_f32_16x16x32_bf16 v[28:31], v[80:83], v[64:67], v[28:31]
	s_waitcnt lgkmcnt(7)
	v_mfma_f32_16x16x32_bf16 v[84:87], v[104:107], v[64:67], v[84:87]
	s_waitcnt lgkmcnt(4)
	v_mfma_f32_16x16x32_bf16 v[88:91], v[136:139], v[64:67], v[88:91]
	s_waitcnt lgkmcnt(3)
	v_mfma_f32_16x16x32_bf16 v[12:15], v[148:151], v[64:67], v[12:15]
	global_load_dwordx4 v[64:67], v237, s[0:1] offset:384
	s_waitcnt vmcnt(8)
	ds_write_b128 v3, v[100:103] offset:4096
	ds_read_b128 v[100:103], v5 offset:34816
	ds_read_b128 v[164:167], v6 offset:51200
	v_mfma_f32_16x16x32_bf16 v[32:35], v[80:83], v[68:71], v[32:35]
	v_mfma_f32_16x16x32_bf16 v[92:95], v[104:107], v[68:71], v[92:95]
	v_mfma_f32_16x16x32_bf16 v[108:111], v[136:139], v[68:71], v[108:111]
	v_mfma_f32_16x16x32_bf16 v[16:19], v[148:151], v[68:71], v[16:19]
	global_load_dwordx4 v[68:71], v238, s[0:1] offset:384
	s_waitcnt vmcnt(8)
	ds_write_b128 v3, v[120:123] offset:8192
	ds_read_b128 v[120:123], v5 offset:36864
	ds_read_b128 v[168:171], v6 offset:53248
	v_mfma_f32_16x16x32_bf16 v[36:39], v[80:83], v[124:127], v[36:39]
	v_mfma_f32_16x16x32_bf16 v[112:115], v[104:107], v[124:127], v[112:115]
	v_mfma_f32_16x16x32_bf16 v[116:119], v[136:139], v[124:127], v[116:119]
	v_mfma_f32_16x16x32_bf16 v[20:23], v[148:151], v[124:127], v[20:23]
	global_load_dwordx4 v[124:127], v235, s[0:1] offset:384
	s_waitcnt vmcnt(8)
	ds_write_b128 v3, v[152:155] offset:12288
	ds_read_b128 v[152:155], v5 offset:38912
	ds_read_b128 v[172:175], v6 offset:55296
	v_mfma_f32_16x16x32_bf16 v[40:43], v[80:83], v[132:135], v[40:43]
	v_mfma_f32_16x16x32_bf16 v[52:55], v[104:107], v[132:135], v[52:55]
	v_mfma_f32_16x16x32_bf16 v[56:59], v[136:139], v[132:135], v[56:59]
	v_mfma_f32_16x16x32_bf16 v[24:27], v[148:151], v[132:135], v[24:27]
	global_load_dwordx4 v[80:83], v4, s[2:3] offset:384
	s_waitcnt vmcnt(8)
	ds_write_b128 v3, v[72:75] offset:16384
	s_waitcnt lgkmcnt(10)
	v_mfma_f32_16x16x32_bf16 v[28:31], v[160:163], v[76:79], v[28:31]
	s_waitcnt lgkmcnt(7)
	v_mfma_f32_16x16x32_bf16 v[72:75], v[164:167], v[76:79], v[84:87]
	s_waitcnt lgkmcnt(4)
	v_mfma_f32_16x16x32_bf16 v[84:87], v[168:171], v[76:79], v[88:91]
	s_waitcnt lgkmcnt(1)
	v_mfma_f32_16x16x32_bf16 v[12:15], v[172:175], v[76:79], v[12:15]
	global_load_dwordx4 v[76:79], v236, s[2:3] offset:384
	s_waitcnt vmcnt(8)
	ds_write_b128 v3, v[44:47] offset:20480
	v_mfma_f32_16x16x32_bf16 v[32:35], v[160:163], v[100:103], v[32:35]
	v_mfma_f32_16x16x32_bf16 v[44:47], v[164:167], v[100:103], v[92:95]
	v_mfma_f32_16x16x32_bf16 v[88:91], v[168:171], v[100:103], v[108:111]
	v_mfma_f32_16x16x32_bf16 v[16:19], v[172:175], v[100:103], v[16:19]
	global_load_dwordx4 v[92:95], v239, s[2:3] offset:384
	s_waitcnt vmcnt(8)
	ds_write_b128 v3, v[48:51] offset:24576
	v_mfma_f32_16x16x32_bf16 v[36:39], v[160:163], v[120:123], v[36:39]
	v_mfma_f32_16x16x32_bf16 v[48:51], v[164:167], v[120:123], v[112:115]
	v_mfma_f32_16x16x32_bf16 v[100:103], v[168:171], v[120:123], v[116:119]
	v_mfma_f32_16x16x32_bf16 v[20:23], v[172:175], v[120:123], v[20:23]
	global_load_dwordx4 v[104:107], v240, s[2:3] offset:384
	s_waitcnt vmcnt(8)
	ds_write_b128 v3, v[60:63] offset:28672
	v_mfma_f32_16x16x32_bf16 v[40:43], v[160:163], v[152:155], v[40:43]
	v_mfma_f32_16x16x32_bf16 v[52:55], v[164:167], v[152:155], v[52:55]
	v_mfma_f32_16x16x32_bf16 v[56:59], v[168:171], v[152:155], v[56:59]
	v_mfma_f32_16x16x32_bf16 v[24:27], v[172:175], v[152:155], v[24:27]
	s_setprio 0
	s_waitcnt lgkmcnt(0)
	s_barrier
	ds_read_b128 v[60:63], v7
	ds_read_b128 v[108:111], v7 offset:2048
	ds_read_b128 v[112:115], v8 offset:16384
	ds_read_b128 v[116:119], v8 offset:18432
	ds_read_b128 v[120:123], v7 offset:4096
	ds_read_b128 v[132:135], v7 offset:6144
	ds_read_b128 v[136:139], v8 offset:20480
	ds_read_b128 v[148:151], v8 offset:22528
	s_setprio 2
	global_load_dwordx4 v[152:155], v234, s[0:1] offset:512
	s_waitcnt vmcnt(8)
	ds_write_b128 v3, v[156:159] offset:32768
	ds_read_b128 v[156:159], v5
	ds_read_b128 v[160:163], v6 offset:16384
	s_waitcnt lgkmcnt(8)
	v_mfma_f32_16x16x32_bf16 v[28:31], v[112:115], v[60:63], v[28:31]
	s_waitcnt lgkmcnt(4)
	v_mfma_f32_16x16x32_bf16 v[84:87], v[136:139], v[60:63], v[84:87]
	s_waitcnt lgkmcnt(3)
	v_mfma_f32_16x16x32_bf16 v[12:15], v[148:151], v[60:63], v[12:15]
	v_mfma_f32_16x16x32_bf16 v[72:75], v[116:119], v[60:63], v[72:75]
	global_load_dwordx4 v[60:63], v237, s[0:1] offset:512
	s_waitcnt vmcnt(8)
	ds_write_b128 v3, v[64:67] offset:36864
	ds_read_b128 v[64:67], v5 offset:2048
	ds_read_b128 v[164:167], v6 offset:18432
	v_mfma_f32_16x16x32_bf16 v[32:35], v[112:115], v[108:111], v[32:35]
	v_mfma_f32_16x16x32_bf16 v[44:47], v[116:119], v[108:111], v[44:47]
	v_mfma_f32_16x16x32_bf16 v[88:91], v[136:139], v[108:111], v[88:91]
	v_mfma_f32_16x16x32_bf16 v[16:19], v[148:151], v[108:111], v[16:19]
	global_load_dwordx4 v[108:111], v238, s[0:1] offset:512
	s_waitcnt vmcnt(8)
; template <int MODE>
; __device__ __forceinline__ void gemm_tile(const Params& P, int tm, int tn, unsigned char* smem) {
;     ...
;     for (int kt = 0; kt < 16; ++kt) {
;         unsigned char* sA = (kt & 1) ? sA1 : sA0; unsigned char* sB = (kt & 1) ? sB1 : sB0;
;         unsigned char* nA = (kt & 1) ? sA0 : sA1; unsigned char* nB = (kt & 1) ? sB0 : sB1;
;         bf16x8 fa[4], fb[4], ga[4], gb[4];
;         const int ch0 = ((g ^ sw) << 4), ch1 = (((4 + g) ^ sw) << 4);
;         const unsigned ko = (unsigned)(kt + 2) * 128u;
;         const unsigned koa = ko + ((MODE == 2 && kt + 2 >= 8) ? (unsigned)(ZC_FQ - 512) * 2u : 0u);
;         const bool wr_ok = kt < 15, ld_ok = kt < 14;
; #pragma unroll
;         for (int i = 0; i < 4; ++i) { fa[i] = *(const bf16x8*)(sA + arow_off + i * 2048 + ch0); fb[i] = *(const bf16x8*)(sB + brow_off + i * 2048 + ch0); }
;         __builtin_amdgcn_sched_barrier(0);
;         __builtin_amdgcn_s_setprio(2);
;         if (wr_ok) *(uint4*)(nA + soff0) = ra0;
;         if (ld_ok) ra0 = *(const uint4*)(Ab + (aoff + 0u * LDA + koa));
;         ga[0] = *(const bf16x8*)(sA + arow_off + 0 * 2048 + ch1); gb[0] = *(const bf16x8*)(sB + brow_off + 0 * 2048 + ch1);
;         __builtin_amdgcn_sched_barrier(0);
; #pragma unroll
;         for (int j = 0; j < 4; ++j) acc[0][j] = __builtin_amdgcn_mfma_f32_16x16x32_bf16(fb[j], fa[0], acc[0][j], 0, 0, 0);
;         __builtin_amdgcn_sched_barrier(0);
;         if (wr_ok) *(uint4*)(nA + soff0 + 4096) = ra1;
;         if (ld_ok) ra1 = *(const uint4*)(Ab + (aoff + 32u * LDA + koa));
;         ga[1] = *(const bf16x8*)(sA + arow_off + 1 * 2048 + ch1); gb[1] = *(const bf16x8*)(sB + brow_off + 1 * 2048 + ch1);
;         __builtin_amdgcn_sched_barrier(0);
; #pragma unroll
;         for (int j = 0; j < 4; ++j) acc[1][j] = __builtin_amdgcn_mfma_f32_16x16x32_bf16(fb[j], fa[1], acc[1][j], 0, 0, 0);
;         __builtin_amdgcn_sched_barrier(0);
;         if (wr_ok) *(uint4*)(nA + soff0 + 8192) = ra2;
;         if (ld_ok) ra2 = *(const uint4*)(Ab + (aoff + 64u * LDA + koa));
;         ga[2] = *(const bf16x8*)(sA + arow_off + 2 * 2048 + ch1); gb[2] = *(const bf16x8*)(sB + brow_off + 2 * 2048 + ch1);
;         __builtin_amdgcn_sched_barrier(0);
; #pragma unroll
;         for (int j = 0; j < 4; ++j) acc[2][j] = __builtin_amdgcn_mfma_f32_16x16x32_bf16(fb[j], fa[2], acc[2][j], 0, 0, 0);
	ds_write_b128 v3, v[68:71] offset:40960
	ds_read_b128 v[68:71], v5 offset:4096
	ds_read_b128 v[168:171], v6 offset:20480
	v_mfma_f32_16x16x32_bf16 v[36:39], v[112:115], v[120:123], v[36:39]
	v_mfma_f32_16x16x32_bf16 v[48:51], v[116:119], v[120:123], v[48:51]
	v_mfma_f32_16x16x32_bf16 v[100:103], v[136:139], v[120:123], v[100:103]
	v_mfma_f32_16x16x32_bf16 v[20:23], v[148:151], v[120:123], v[20:23]
	global_load_dwordx4 v[120:123], v235, s[0:1] offset:512
	s_waitcnt vmcnt(8)
	ds_write_b128 v3, v[124:127] offset:45056
	ds_read_b128 v[124:127], v5 offset:6144
	ds_read_b128 v[172:175], v6 offset:22528
	v_mfma_f32_16x16x32_bf16 v[40:43], v[112:115], v[132:135], v[40:43]
	v_mfma_f32_16x16x32_bf16 v[52:55], v[116:119], v[132:135], v[52:55]
	v_mfma_f32_16x16x32_bf16 v[56:59], v[136:139], v[132:135], v[56:59]
	v_mfma_f32_16x16x32_bf16 v[24:27], v[148:151], v[132:135], v[24:27]
	global_load_dwordx4 v[112:115], v4, s[2:3] offset:512
	s_waitcnt vmcnt(8)
	ds_write_b128 v3, v[80:83] offset:49152
	s_waitcnt lgkmcnt(10)
	v_mfma_f32_16x16x32_bf16 v[28:31], v[160:163], v[156:159], v[28:31]
	s_waitcnt lgkmcnt(4)
	v_mfma_f32_16x16x32_bf16 v[80:83], v[168:171], v[156:159], v[84:87]
	s_waitcnt lgkmcnt(1)
	v_mfma_f32_16x16x32_bf16 v[12:15], v[172:175], v[156:159], v[12:15]
	v_mfma_f32_16x16x32_bf16 v[72:75], v[164:167], v[156:159], v[72:75]
	global_load_dwordx4 v[84:87], v236, s[2:3] offset:512
	s_waitcnt vmcnt(8)
	ds_write_b128 v3, v[76:79] offset:53248
	v_mfma_f32_16x16x32_bf16 v[32:35], v[160:163], v[64:67], v[32:35]
	v_mfma_f32_16x16x32_bf16 v[44:47], v[164:167], v[64:67], v[44:47]
	v_mfma_f32_16x16x32_bf16 v[16:19], v[172:175], v[64:67], v[16:19]
	v_mfma_f32_16x16x32_bf16 v[76:79], v[168:171], v[64:67], v[88:91]
	global_load_dwordx4 v[64:67], v239, s[2:3] offset:512
	s_waitcnt vmcnt(8)
	ds_write_b128 v3, v[92:95] offset:57344
	v_mfma_f32_16x16x32_bf16 v[36:39], v[160:163], v[68:71], v[36:39]
	v_mfma_f32_16x16x32_bf16 v[48:51], v[164:167], v[68:71], v[48:51]
	v_mfma_f32_16x16x32_bf16 v[88:91], v[168:171], v[68:71], v[100:103]
	v_mfma_f32_16x16x32_bf16 v[20:23], v[172:175], v[68:71], v[20:23]
	global_load_dwordx4 v[68:71], v240, s[2:3] offset:512
	s_waitcnt vmcnt(8)
	ds_write_b128 v3, v[104:107] offset:61440
	v_mfma_f32_16x16x32_bf16 v[40:43], v[160:163], v[124:127], v[40:43]
	v_mfma_f32_16x16x32_bf16 v[52:55], v[164:167], v[124:127], v[52:55]
	v_mfma_f32_16x16x32_bf16 v[56:59], v[168:171], v[124:127], v[56:59]
	v_mfma_f32_16x16x32_bf16 v[24:27], v[172:175], v[124:127], v[24:27]
	s_setprio 0
	s_waitcnt lgkmcnt(0)
	s_barrier
	ds_read_b128 v[92:95], v7 offset:32768
	ds_read_b128 v[100:103], v7 offset:34816
	ds_read_b128 v[104:107], v8 offset:49152
	ds_read_b128 v[116:119], v8 offset:51200
	ds_read_b128 v[124:127], v7 offset:36864
	ds_read_b128 v[132:135], v7 offset:38912
	ds_read_b128 v[136:139], v8 offset:53248
	ds_read_b128 v[148:151], v8 offset:55296
	s_setprio 2
	global_load_dwordx4 v[156:159], v234, s[0:1] offset:640
	s_waitcnt vmcnt(8)
	ds_write_b128 v3, v[152:155]
	ds_read_b128 v[152:155], v5 offset:32768
	ds_read_b128 v[160:163], v6 offset:49152
	s_waitcnt lgkmcnt(8)
	v_mfma_f32_16x16x32_bf16 v[28:31], v[104:107], v[92:95], v[28:31]
	s_waitcnt lgkmcnt(4)
	v_mfma_f32_16x16x32_bf16 v[80:83], v[136:139], v[92:95], v[80:83]
	s_waitcnt lgkmcnt(3)
	v_mfma_f32_16x16x32_bf16 v[12:15], v[148:151], v[92:95], v[12:15]
	v_mfma_f32_16x16x32_bf16 v[72:75], v[116:119], v[92:95], v[72:75]
	global_load_dwordx4 v[92:95], v237, s[0:1] offset:640
	s_waitcnt vmcnt(8)
	ds_write_b128 v3, v[60:63] offset:4096
	ds_read_b128 v[60:63], v5 offset:34816
	ds_read_b128 v[164:167], v6 offset:51200
	v_mfma_f32_16x16x32_bf16 v[32:35], v[104:107], v[100:103], v[32:35]
	v_mfma_f32_16x16x32_bf16 v[44:47], v[116:119], v[100:103], v[44:47]
	v_mfma_f32_16x16x32_bf16 v[16:19], v[148:151], v[100:103], v[16:19]
	v_mfma_f32_16x16x32_bf16 v[76:79], v[136:139], v[100:103], v[76:79]
	global_load_dwordx4 v[100:103], v238, s[0:1] offset:640
	s_waitcnt vmcnt(8)
	ds_write_b128 v3, v[108:111] offset:8192
	ds_read_b128 v[108:111], v5 offset:36864
	ds_read_b128 v[168:171], v6 offset:53248
	v_mfma_f32_16x16x32_bf16 v[36:39], v[104:107], v[124:127], v[36:39]
	v_mfma_f32_16x16x32_bf16 v[48:51], v[116:119], v[124:127], v[48:51]
	v_mfma_f32_16x16x32_bf16 v[88:91], v[136:139], v[124:127], v[88:91]
	v_mfma_f32_16x16x32_bf16 v[20:23], v[148:151], v[124:127], v[20:23]
	global_load_dwordx4 v[124:127], v235, s[0:1] offset:640
	s_waitcnt vmcnt(8)
	ds_write_b128 v3, v[120:123] offset:12288
	ds_read_b128 v[120:123], v5 offset:38912
	ds_read_b128 v[172:175], v6 offset:55296
	v_mfma_f32_16x16x32_bf16 v[40:43], v[104:107], v[132:135], v[40:43]
	v_mfma_f32_16x16x32_bf16 v[52:55], v[116:119], v[132:135], v[52:55]
	v_mfma_f32_16x16x32_bf16 v[56:59], v[136:139], v[132:135], v[56:59]
	v_mfma_f32_16x16x32_bf16 v[24:27], v[148:151], v[132:135], v[24:27]
	global_load_dwordx4 v[104:107], v4, s[2:3] offset:640
	s_waitcnt vmcnt(8)
	ds_write_b128 v3, v[112:115] offset:16384
	s_waitcnt lgkmcnt(10)
	v_mfma_f32_16x16x32_bf16 v[28:31], v[160:163], v[152:155], v[28:31]
	s_waitcnt lgkmcnt(4)
	v_mfma_f32_16x16x32_bf16 v[80:83], v[168:171], v[152:155], v[80:83]
	s_waitcnt lgkmcnt(1)
	v_mfma_f32_16x16x32_bf16 v[12:15], v[172:175], v[152:155], v[12:15]
	v_mfma_f32_16x16x32_bf16 v[72:75], v[164:167], v[152:155], v[72:75]
	global_load_dwordx4 v[112:115], v236, s[2:3] offset:640
	s_waitcnt vmcnt(8)
	ds_write_b128 v3, v[84:87] offset:20480
	v_mfma_f32_16x16x32_bf16 v[32:35], v[160:163], v[60:63], v[32:35]
	v_mfma_f32_16x16x32_bf16 v[44:47], v[164:167], v[60:63], v[44:47]
	v_mfma_f32_16x16x32_bf16 v[16:19], v[172:175], v[60:63], v[16:19]
	v_mfma_f32_16x16x32_bf16 v[76:79], v[168:171], v[60:63], v[76:79]
	global_load_dwordx4 v[60:63], v239, s[2:3] offset:640
	s_waitcnt vmcnt(8)
	ds_write_b128 v3, v[64:67] offset:24576
	v_mfma_f32_16x16x32_bf16 v[36:39], v[160:163], v[108:111], v[36:39]
	v_mfma_f32_16x16x32_bf16 v[48:51], v[164:167], v[108:111], v[48:51]
	v_mfma_f32_16x16x32_bf16 v[64:67], v[168:171], v[108:111], v[88:91]
	v_mfma_f32_16x16x32_bf16 v[20:23], v[172:175], v[108:111], v[20:23]
	global_load_dwordx4 v[84:87], v240, s[2:3] offset:640
	s_waitcnt vmcnt(8)
	ds_write_b128 v3, v[68:71] offset:28672
	v_mfma_f32_16x16x32_bf16 v[40:43], v[160:163], v[120:123], v[40:43]
	v_mfma_f32_16x16x32_bf16 v[52:55], v[164:167], v[120:123], v[52:55]
	v_mfma_f32_16x16x32_bf16 v[56:59], v[168:171], v[120:123], v[56:59]
	v_mfma_f32_16x16x32_bf16 v[24:27], v[172:175], v[120:123], v[24:27]
	s_setprio 0
	s_waitcnt lgkmcnt(0)
	s_barrier
; template <int MODE>
; __device__ __forceinline__ void gemm_tile(const Params& P, int tm, int tn, unsigned char* smem) {
;     ...
;     for (int kt = 0; kt < 16; ++kt) {
;         unsigned char* sA = (kt & 1) ? sA1 : sA0; unsigned char* sB = (kt & 1) ? sB1 : sB0;
;         unsigned char* nA = (kt & 1) ? sA0 : sA1; unsigned char* nB = (kt & 1) ? sB0 : sB1;
;         bf16x8 fa[4], fb[4], ga[4], gb[4];
;         const int ch0 = ((g ^ sw) << 4), ch1 = (((4 + g) ^ sw) << 4);
;         const unsigned ko = (unsigned)(kt + 2) * 128u;
;         const unsigned koa = ko + ((MODE == 2 && kt + 2 >= 8) ? (unsigned)(ZC_FQ - 512) * 2u : 0u);
;         const bool wr_ok = kt < 15, ld_ok = kt < 14;
; #pragma unroll
;         for (int i = 0; i < 4; ++i) { fa[i] = *(const bf16x8*)(sA + arow_off + i * 2048 + ch0); fb[i] = *(const bf16x8*)(sB + brow_off + i * 2048 + ch0); }
;         __builtin_amdgcn_sched_barrier(0);
;         __builtin_amdgcn_s_setprio(2);
;         if (wr_ok) *(uint4*)(nA + soff0) = ra0;
;         if (ld_ok) ra0 = *(const uint4*)(Ab + (aoff + 0u * LDA + koa));
;         ga[0] = *(const bf16x8*)(sA + arow_off + 0 * 2048 + ch1); gb[0] = *(const bf16x8*)(sB + brow_off + 0 * 2048 + ch1);
;         __builtin_amdgcn_sched_barrier(0);
; #pragma unroll
;         for (int j = 0; j < 4; ++j) acc[0][j] = __builtin_amdgcn_mfma_f32_16x16x32_bf16(fb[j], fa[0], acc[0][j], 0, 0, 0);
;         __builtin_amdgcn_sched_barrier(0);
;         if (wr_ok) *(uint4*)(nA + soff0 + 4096) = ra1;
;         if (ld_ok) ra1 = *(const uint4*)(Ab + (aoff + 32u * LDA + koa));
;         ga[1] = *(const bf16x8*)(sA + arow_off + 1 * 2048 + ch1); gb[1] = *(const bf16x8*)(sB + brow_off + 1 * 2048 + ch1);
;         __builtin_amdgcn_sched_barrier(0);
; #pragma unroll
;         for (int j = 0; j < 4; ++j) acc[1][j] = __builtin_amdgcn_mfma_f32_16x16x32_bf16(fb[j], fa[1], acc[1][j], 0, 0, 0);
;         __builtin_amdgcn_sched_barrier(0);
;         if (wr_ok) *(uint4*)(nA + soff0 + 8192) = ra2;
;         if (ld_ok) ra2 = *(const uint4*)(Ab + (aoff + 64u * LDA + koa));
;         ga[2] = *(const bf16x8*)(sA + arow_off + 2 * 2048 + ch1); gb[2] = *(const bf16x8*)(sB + brow_off + 2 * 2048 + ch1);
;         __builtin_amdgcn_sched_barrier(0);
; #pragma unroll
;         for (int j = 0; j < 4; ++j) acc[2][j] = __builtin_amdgcn_mfma_f32_16x16x32_bf16(fb[j], fa[2], acc[2][j], 0, 0, 0);
	ds_read_b128 v[68:71], v7
	ds_read_b128 v[88:91], v7 offset:2048
	ds_read_b128 v[108:111], v8 offset:16384
	ds_read_b128 v[116:119], v8 offset:18432
	ds_read_b128 v[120:123], v7 offset:4096
	ds_read_b128 v[132:135], v7 offset:6144
	ds_read_b128 v[136:139], v8 offset:20480
	ds_read_b128 v[148:151], v8 offset:22528
	s_setprio 2
	global_load_dwordx4 v[152:155], v234, s[0:1] offset:768
	s_waitcnt vmcnt(8)
	ds_write_b128 v3, v[156:159] offset:32768
	ds_read_b128 v[156:159], v5
	ds_read_b128 v[160:163], v6 offset:16384
	s_waitcnt lgkmcnt(8)
	v_mfma_f32_16x16x32_bf16 v[28:31], v[108:111], v[68:71], v[28:31]
	s_waitcnt lgkmcnt(4)
	v_mfma_f32_16x16x32_bf16 v[80:83], v[136:139], v[68:71], v[80:83]
	s_waitcnt lgkmcnt(3)
	v_mfma_f32_16x16x32_bf16 v[12:15], v[148:151], v[68:71], v[12:15]
	v_mfma_f32_16x16x32_bf16 v[72:75], v[116:119], v[68:71], v[72:75]
	global_load_dwordx4 v[68:71], v237, s[0:1] offset:768
	s_waitcnt vmcnt(8)
	ds_write_b128 v3, v[92:95] offset:36864
	ds_read_b128 v[92:95], v5 offset:2048
	ds_read_b128 v[164:167], v6 offset:18432
	v_mfma_f32_16x16x32_bf16 v[32:35], v[108:111], v[88:91], v[32:35]
	v_mfma_f32_16x16x32_bf16 v[44:47], v[116:119], v[88:91], v[44:47]
	v_mfma_f32_16x16x32_bf16 v[16:19], v[148:151], v[88:91], v[16:19]
	v_mfma_f32_16x16x32_bf16 v[76:79], v[136:139], v[88:91], v[76:79]
	global_load_dwordx4 v[88:91], v238, s[0:1] offset:768
	s_waitcnt vmcnt(8)
	ds_write_b128 v3, v[100:103] offset:40960
	ds_read_b128 v[100:103], v5 offset:4096
	ds_read_b128 v[168:171], v6 offset:20480
	v_mfma_f32_16x16x32_bf16 v[36:39], v[108:111], v[120:123], v[36:39]
	v_mfma_f32_16x16x32_bf16 v[48:51], v[116:119], v[120:123], v[48:51]
	v_mfma_f32_16x16x32_bf16 v[64:67], v[136:139], v[120:123], v[64:67]
	v_mfma_f32_16x16x32_bf16 v[20:23], v[148:151], v[120:123], v[20:23]
	global_load_dwordx4 v[120:123], v235, s[0:1] offset:768
	s_waitcnt vmcnt(8)
	ds_write_b128 v3, v[124:127] offset:45056
	ds_read_b128 v[124:127], v5 offset:6144
	ds_read_b128 v[172:175], v6 offset:22528
	v_mfma_f32_16x16x32_bf16 v[40:43], v[108:111], v[132:135], v[40:43]
	v_mfma_f32_16x16x32_bf16 v[52:55], v[116:119], v[132:135], v[52:55]
	v_mfma_f32_16x16x32_bf16 v[56:59], v[136:139], v[132:135], v[56:59]
	v_mfma_f32_16x16x32_bf16 v[24:27], v[148:151], v[132:135], v[24:27]
	global_load_dwordx4 v[108:111], v4, s[2:3] offset:768
	s_waitcnt vmcnt(8)
	ds_write_b128 v3, v[104:107] offset:49152
	s_waitcnt lgkmcnt(10)
	v_mfma_f32_16x16x32_bf16 v[28:31], v[160:163], v[156:159], v[28:31]
	s_waitcnt lgkmcnt(4)
	v_mfma_f32_16x16x32_bf16 v[80:83], v[168:171], v[156:159], v[80:83]
	s_waitcnt lgkmcnt(1)
	v_mfma_f32_16x16x32_bf16 v[12:15], v[172:175], v[156:159], v[12:15]
	v_mfma_f32_16x16x32_bf16 v[72:75], v[164:167], v[156:159], v[72:75]
	global_load_dwordx4 v[104:107], v236, s[2:3] offset:768
	s_waitcnt vmcnt(8)
	ds_write_b128 v3, v[112:115] offset:53248
	v_mfma_f32_16x16x32_bf16 v[32:35], v[160:163], v[92:95], v[32:35]
	v_mfma_f32_16x16x32_bf16 v[44:47], v[164:167], v[92:95], v[44:47]
	v_mfma_f32_16x16x32_bf16 v[16:19], v[172:175], v[92:95], v[16:19]
	v_mfma_f32_16x16x32_bf16 v[76:79], v[168:171], v[92:95], v[76:79]
	global_load_dwordx4 v[92:95], v239, s[2:3] offset:768
	s_waitcnt vmcnt(8)
	ds_write_b128 v3, v[60:63] offset:57344
	v_mfma_f32_16x16x32_bf16 v[36:39], v[160:163], v[100:103], v[36:39]
	v_mfma_f32_16x16x32_bf16 v[48:51], v[164:167], v[100:103], v[48:51]
	v_mfma_f32_16x16x32_bf16 v[60:63], v[168:171], v[100:103], v[64:67]
	v_mfma_f32_16x16x32_bf16 v[20:23], v[172:175], v[100:103], v[20:23]
	global_load_dwordx4 v[64:67], v240, s[2:3] offset:768
	s_waitcnt vmcnt(8)
	ds_write_b128 v3, v[84:87] offset:61440
	v_mfma_f32_16x16x32_bf16 v[40:43], v[160:163], v[124:127], v[40:43]
	v_mfma_f32_16x16x32_bf16 v[52:55], v[164:167], v[124:127], v[52:55]
	v_mfma_f32_16x16x32_bf16 v[56:59], v[168:171], v[124:127], v[56:59]
	v_mfma_f32_16x16x32_bf16 v[24:27], v[172:175], v[124:127], v[24:27]
	s_setprio 0
	s_waitcnt lgkmcnt(0)
	s_barrier
	ds_read_b128 v[84:87], v7 offset:32768
	ds_read_b128 v[100:103], v7 offset:34816
	ds_read_b128 v[112:115], v8 offset:49152
	ds_read_b128 v[116:119], v8 offset:51200
	ds_read_b128 v[124:127], v7 offset:36864
	ds_read_b128 v[132:135], v7 offset:38912
	ds_read_b128 v[136:139], v8 offset:53248
	ds_read_b128 v[148:151], v8 offset:55296
	s_setprio 2
	global_load_dwordx4 v[156:159], v234, s[0:1] offset:896
	s_waitcnt vmcnt(8)
	ds_write_b128 v3, v[152:155]
	ds_read_b128 v[152:155], v5 offset:32768
	ds_read_b128 v[160:163], v6 offset:49152
	s_waitcnt lgkmcnt(8)
	v_mfma_f32_16x16x32_bf16 v[28:31], v[112:115], v[84:87], v[28:31]
	s_waitcnt lgkmcnt(4)
	v_mfma_f32_16x16x32_bf16 v[80:83], v[136:139], v[84:87], v[80:83]
	s_waitcnt lgkmcnt(3)
	v_mfma_f32_16x16x32_bf16 v[12:15], v[148:151], v[84:87], v[12:15]
	v_mfma_f32_16x16x32_bf16 v[72:75], v[116:119], v[84:87], v[72:75]
	global_load_dwordx4 v[84:87], v237, s[0:1] offset:896
	s_waitcnt vmcnt(8)
	ds_write_b128 v3, v[68:71] offset:4096
	ds_read_b128 v[68:71], v5 offset:34816
	ds_read_b128 v[164:167], v6 offset:51200
	v_mfma_f32_16x16x32_bf16 v[32:35], v[112:115], v[100:103], v[32:35]
	v_mfma_f32_16x16x32_bf16 v[44:47], v[116:119], v[100:103], v[44:47]
	v_mfma_f32_16x16x32_bf16 v[16:19], v[148:151], v[100:103], v[16:19]
	v_mfma_f32_16x16x32_bf16 v[76:79], v[136:139], v[100:103], v[76:79]
	global_load_dwordx4 v[100:103], v238, s[0:1] offset:896
	s_waitcnt vmcnt(8)
	ds_write_b128 v3, v[88:91] offset:8192
	ds_read_b128 v[88:91], v5 offset:36864
	ds_read_b128 v[168:171], v6 offset:53248
	v_mfma_f32_16x16x32_bf16 v[36:39], v[112:115], v[124:127], v[36:39]
	v_mfma_f32_16x16x32_bf16 v[48:51], v[116:119], v[124:127], v[48:51]
	v_mfma_f32_16x16x32_bf16 v[60:63], v[136:139], v[124:127], v[60:63]
	v_mfma_f32_16x16x32_bf16 v[20:23], v[148:151], v[124:127], v[20:23]
	global_load_dwordx4 v[124:127], v235, s[0:1] offset:896
	s_waitcnt vmcnt(8)
; template <int MODE>
; __device__ __forceinline__ void gemm_tile(const Params& P, int tm, int tn, unsigned char* smem) {
;     ...
;     for (int kt = 0; kt < 16; ++kt) {
;         unsigned char* sA = (kt & 1) ? sA1 : sA0; unsigned char* sB = (kt & 1) ? sB1 : sB0;
;         unsigned char* nA = (kt & 1) ? sA0 : sA1; unsigned char* nB = (kt & 1) ? sB0 : sB1;
;         bf16x8 fa[4], fb[4], ga[4], gb[4];
;         const int ch0 = ((g ^ sw) << 4), ch1 = (((4 + g) ^ sw) << 4);
;         const unsigned ko = (unsigned)(kt + 2) * 128u;
;         const unsigned koa = ko + ((MODE == 2 && kt + 2 >= 8) ? (unsigned)(ZC_FQ - 512) * 2u : 0u);
;         const bool wr_ok = kt < 15, ld_ok = kt < 14;
; #pragma unroll
;         for (int i = 0; i < 4; ++i) { fa[i] = *(const bf16x8*)(sA + arow_off + i * 2048 + ch0); fb[i] = *(const bf16x8*)(sB + brow_off + i * 2048 + ch0); }
;         __builtin_amdgcn_sched_barrier(0);
;         __builtin_amdgcn_s_setprio(2);
;         if (wr_ok) *(uint4*)(nA + soff0) = ra0;
;         if (ld_ok) ra0 = *(const uint4*)(Ab + (aoff + 0u * LDA + koa));
;         ga[0] = *(const bf16x8*)(sA + arow_off + 0 * 2048 + ch1); gb[0] = *(const bf16x8*)(sB + brow_off + 0 * 2048 + ch1);
;         __builtin_amdgcn_sched_barrier(0);
; #pragma unroll
;         for (int j = 0; j < 4; ++j) acc[0][j] = __builtin_amdgcn_mfma_f32_16x16x32_bf16(fb[j], fa[0], acc[0][j], 0, 0, 0);
;         __builtin_amdgcn_sched_barrier(0);
;         if (wr_ok) *(uint4*)(nA + soff0 + 4096) = ra1;
;         if (ld_ok) ra1 = *(const uint4*)(Ab + (aoff + 32u * LDA + koa));
;         ga[1] = *(const bf16x8*)(sA + arow_off + 1 * 2048 + ch1); gb[1] = *(const bf16x8*)(sB + brow_off + 1 * 2048 + ch1);
;         __builtin_amdgcn_sched_barrier(0);
; #pragma unroll
;         for (int j = 0; j < 4; ++j) acc[1][j] = __builtin_amdgcn_mfma_f32_16x16x32_bf16(fb[j], fa[1], acc[1][j], 0, 0, 0);
;         __builtin_amdgcn_sched_barrier(0);
;         if (wr_ok) *(uint4*)(nA + soff0 + 8192) = ra2;
;         if (ld_ok) ra2 = *(const uint4*)(Ab + (aoff + 64u * LDA + koa));
;         ga[2] = *(const bf16x8*)(sA + arow_off + 2 * 2048 + ch1); gb[2] = *(const bf16x8*)(sB + brow_off + 2 * 2048 + ch1);
;         __builtin_amdgcn_sched_barrier(0);
; #pragma unroll
;         for (int j = 0; j < 4; ++j) acc[2][j] = __builtin_amdgcn_mfma_f32_16x16x32_bf16(fb[j], fa[2], acc[2][j], 0, 0, 0);
	ds_write_b128 v3, v[120:123] offset:12288
	ds_read_b128 v[120:123], v5 offset:38912
	ds_read_b128 v[172:175], v6 offset:55296
	v_mfma_f32_16x16x32_bf16 v[40:43], v[112:115], v[132:135], v[40:43]
	v_mfma_f32_16x16x32_bf16 v[52:55], v[116:119], v[132:135], v[52:55]
	v_mfma_f32_16x16x32_bf16 v[56:59], v[136:139], v[132:135], v[56:59]
	v_mfma_f32_16x16x32_bf16 v[24:27], v[148:151], v[132:135], v[24:27]
	global_load_dwordx4 v[112:115], v4, s[2:3] offset:896
	s_waitcnt vmcnt(8)
	ds_write_b128 v3, v[108:111] offset:16384
	s_waitcnt lgkmcnt(10)
	v_mfma_f32_16x16x32_bf16 v[28:31], v[160:163], v[152:155], v[28:31]
	s_waitcnt lgkmcnt(4)
	v_mfma_f32_16x16x32_bf16 v[80:83], v[168:171], v[152:155], v[80:83]
	s_waitcnt lgkmcnt(1)
	v_mfma_f32_16x16x32_bf16 v[12:15], v[172:175], v[152:155], v[12:15]
	v_mfma_f32_16x16x32_bf16 v[72:75], v[164:167], v[152:155], v[72:75]
	global_load_dwordx4 v[108:111], v236, s[2:3] offset:896
	s_waitcnt vmcnt(8)
	ds_write_b128 v3, v[104:107] offset:20480
	v_mfma_f32_16x16x32_bf16 v[32:35], v[160:163], v[68:71], v[32:35]
	v_mfma_f32_16x16x32_bf16 v[44:47], v[164:167], v[68:71], v[44:47]
	v_mfma_f32_16x16x32_bf16 v[16:19], v[172:175], v[68:71], v[16:19]
	v_mfma_f32_16x16x32_bf16 v[76:79], v[168:171], v[68:71], v[76:79]
	global_load_dwordx4 v[68:71], v239, s[2:3] offset:896
	s_waitcnt vmcnt(8)
	ds_write_b128 v3, v[92:95] offset:24576
	v_mfma_f32_16x16x32_bf16 v[36:39], v[160:163], v[88:91], v[36:39]
	v_mfma_f32_16x16x32_bf16 v[48:51], v[164:167], v[88:91], v[48:51]
	v_mfma_f32_16x16x32_bf16 v[60:63], v[168:171], v[88:91], v[60:63]
	v_mfma_f32_16x16x32_bf16 v[20:23], v[172:175], v[88:91], v[20:23]
	global_load_dwordx4 v[88:91], v240, s[2:3] offset:896
	s_waitcnt vmcnt(8)
	ds_write_b128 v3, v[64:67] offset:28672
	v_mfma_f32_16x16x32_bf16 v[40:43], v[160:163], v[120:123], v[40:43]
	v_mfma_f32_16x16x32_bf16 v[52:55], v[164:167], v[120:123], v[52:55]
	v_mfma_f32_16x16x32_bf16 v[56:59], v[168:171], v[120:123], v[56:59]
	v_mfma_f32_16x16x32_bf16 v[24:27], v[172:175], v[120:123], v[24:27]
	s_setprio 0
	s_waitcnt lgkmcnt(0)
	s_barrier
	ds_read_b128 v[64:67], v7
	ds_read_b128 v[92:95], v7 offset:2048
	ds_read_b128 v[104:107], v8 offset:16384
	ds_read_b128 v[116:119], v8 offset:18432
	ds_read_b128 v[120:123], v7 offset:4096
	ds_read_b128 v[132:135], v7 offset:6144
	ds_read_b128 v[136:139], v8 offset:20480
	ds_read_b128 v[148:151], v8 offset:22528
	s_setprio 2
	v_add_u32_e32 v241, 0x1d000, v9
	global_load_dwordx4 v[152:155], v241, s[0:1]
	s_waitcnt vmcnt(8)
	ds_write_b128 v3, v[156:159] offset:32768
	ds_read_b128 v[156:159], v5
	ds_read_b128 v[160:163], v6 offset:16384
	s_waitcnt lgkmcnt(8)
	v_mfma_f32_16x16x32_bf16 v[28:31], v[104:107], v[64:67], v[28:31]
	s_waitcnt lgkmcnt(4)
	v_mfma_f32_16x16x32_bf16 v[80:83], v[136:139], v[64:67], v[80:83]
	s_waitcnt lgkmcnt(3)
	v_mfma_f32_16x16x32_bf16 v[12:15], v[148:151], v[64:67], v[12:15]
	v_mfma_f32_16x16x32_bf16 v[72:75], v[116:119], v[64:67], v[72:75]
	v_add_u32_e32 v242, 0x55000, v9
	global_load_dwordx4 v[64:67], v242, s[0:1]
	s_waitcnt vmcnt(8)
	ds_write_b128 v3, v[84:87] offset:36864
	ds_read_b128 v[84:87], v5 offset:2048
	ds_read_b128 v[164:167], v6 offset:18432
	v_mfma_f32_16x16x32_bf16 v[32:35], v[104:107], v[92:95], v[32:35]
	v_mfma_f32_16x16x32_bf16 v[44:47], v[116:119], v[92:95], v[44:47]
	v_mfma_f32_16x16x32_bf16 v[16:19], v[148:151], v[92:95], v[16:19]
	v_mfma_f32_16x16x32_bf16 v[76:79], v[136:139], v[92:95], v[76:79]
	v_add_u32_e32 v243, 0x8d000, v9
	global_load_dwordx4 v[92:95], v243, s[0:1]
	s_waitcnt vmcnt(8)
	ds_write_b128 v3, v[100:103] offset:40960
	ds_read_b128 v[100:103], v5 offset:4096
	ds_read_b128 v[168:171], v6 offset:20480
	v_mfma_f32_16x16x32_bf16 v[36:39], v[104:107], v[120:123], v[36:39]
	v_mfma_f32_16x16x32_bf16 v[48:51], v[116:119], v[120:123], v[48:51]
	v_mfma_f32_16x16x32_bf16 v[60:63], v[136:139], v[120:123], v[60:63]
	v_mfma_f32_16x16x32_bf16 v[20:23], v[148:151], v[120:123], v[20:23]
	v_add_u32_e32 v244, 0xc5000, v9
	global_load_dwordx4 v[120:123], v244, s[0:1]
	s_waitcnt vmcnt(8)
	ds_write_b128 v3, v[124:127] offset:45056
	ds_read_b128 v[124:127], v5 offset:6144
	ds_read_b128 v[172:175], v6 offset:22528
	v_mfma_f32_16x16x32_bf16 v[40:43], v[104:107], v[132:135], v[40:43]
	v_mfma_f32_16x16x32_bf16 v[52:55], v[116:119], v[132:135], v[52:55]
	v_mfma_f32_16x16x32_bf16 v[56:59], v[136:139], v[132:135], v[56:59]
	v_mfma_f32_16x16x32_bf16 v[24:27], v[148:151], v[132:135], v[24:27]
	global_load_dwordx4 v[104:107], v4, s[2:3] offset:1024
	s_waitcnt vmcnt(8)
	ds_write_b128 v3, v[112:115] offset:49152
	s_waitcnt lgkmcnt(10)
	v_mfma_f32_16x16x32_bf16 v[28:31], v[160:163], v[156:159], v[28:31]
	s_waitcnt lgkmcnt(4)
	v_mfma_f32_16x16x32_bf16 v[80:83], v[168:171], v[156:159], v[80:83]
	s_waitcnt lgkmcnt(1)
	v_mfma_f32_16x16x32_bf16 v[12:15], v[172:175], v[156:159], v[12:15]
	v_mfma_f32_16x16x32_bf16 v[72:75], v[164:167], v[156:159], v[72:75]
	global_load_dwordx4 v[112:115], v236, s[2:3] offset:1024
	s_waitcnt vmcnt(8)
	ds_write_b128 v3, v[108:111] offset:53248
	v_mfma_f32_16x16x32_bf16 v[32:35], v[160:163], v[84:87], v[32:35]
	v_mfma_f32_16x16x32_bf16 v[44:47], v[164:167], v[84:87], v[44:47]
	v_mfma_f32_16x16x32_bf16 v[16:19], v[172:175], v[84:87], v[16:19]
	v_mfma_f32_16x16x32_bf16 v[76:79], v[168:171], v[84:87], v[76:79]
	global_load_dwordx4 v[84:87], v239, s[2:3] offset:1024
	s_waitcnt vmcnt(8)
	ds_write_b128 v3, v[68:71] offset:57344
	v_mfma_f32_16x16x32_bf16 v[36:39], v[160:163], v[100:103], v[36:39]
	v_mfma_f32_16x16x32_bf16 v[48:51], v[164:167], v[100:103], v[48:51]
	v_mfma_f32_16x16x32_bf16 v[60:63], v[168:171], v[100:103], v[60:63]
	v_mfma_f32_16x16x32_bf16 v[20:23], v[172:175], v[100:103], v[20:23]
	global_load_dwordx4 v[68:71], v240, s[2:3] offset:1024
	s_waitcnt vmcnt(8)
	ds_write_b128 v3, v[88:91] offset:61440
	v_mfma_f32_16x16x32_bf16 v[40:43], v[160:163], v[124:127], v[40:43]
	v_mfma_f32_16x16x32_bf16 v[52:55], v[164:167], v[124:127], v[52:55]
	v_mfma_f32_16x16x32_bf16 v[56:59], v[168:171], v[124:127], v[56:59]
	v_mfma_f32_16x16x32_bf16 v[24:27], v[172:175], v[124:127], v[24:27]
	s_setprio 0
	s_waitcnt lgkmcnt(0)
	s_barrier
; template <int MODE>
; __device__ __forceinline__ void gemm_tile(const Params& P, int tm, int tn, unsigned char* smem) {
;     ...
;     for (int kt = 0; kt < 16; ++kt) {
;         unsigned char* sA = (kt & 1) ? sA1 : sA0; unsigned char* sB = (kt & 1) ? sB1 : sB0;
;         unsigned char* nA = (kt & 1) ? sA0 : sA1; unsigned char* nB = (kt & 1) ? sB0 : sB1;
;         bf16x8 fa[4], fb[4], ga[4], gb[4];
;         const int ch0 = ((g ^ sw) << 4), ch1 = (((4 + g) ^ sw) << 4);
;         const unsigned ko = (unsigned)(kt + 2) * 128u;
;         const unsigned koa = ko + ((MODE == 2 && kt + 2 >= 8) ? (unsigned)(ZC_FQ - 512) * 2u : 0u);
;         const bool wr_ok = kt < 15, ld_ok = kt < 14;
; #pragma unroll
;         for (int i = 0; i < 4; ++i) { fa[i] = *(const bf16x8*)(sA + arow_off + i * 2048 + ch0); fb[i] = *(const bf16x8*)(sB + brow_off + i * 2048 + ch0); }
;         __builtin_amdgcn_sched_barrier(0);
;         __builtin_amdgcn_s_setprio(2);
;         if (wr_ok) *(uint4*)(nA + soff0) = ra0;
;         if (ld_ok) ra0 = *(const uint4*)(Ab + (aoff + 0u * LDA + koa));
;         ga[0] = *(const bf16x8*)(sA + arow_off + 0 * 2048 + ch1); gb[0] = *(const bf16x8*)(sB + brow_off + 0 * 2048 + ch1);
;         __builtin_amdgcn_sched_barrier(0);
; #pragma unroll
;         for (int j = 0; j < 4; ++j) acc[0][j] = __builtin_amdgcn_mfma_f32_16x16x32_bf16(fb[j], fa[0], acc[0][j], 0, 0, 0);
;         __builtin_amdgcn_sched_barrier(0);
;         if (wr_ok) *(uint4*)(nA + soff0 + 4096) = ra1;
;         if (ld_ok) ra1 = *(const uint4*)(Ab + (aoff + 32u * LDA + koa));
;         ga[1] = *(const bf16x8*)(sA + arow_off + 1 * 2048 + ch1); gb[1] = *(const bf16x8*)(sB + brow_off + 1 * 2048 + ch1);
;         __builtin_amdgcn_sched_barrier(0);
; #pragma unroll
;         for (int j = 0; j < 4; ++j) acc[1][j] = __builtin_amdgcn_mfma_f32_16x16x32_bf16(fb[j], fa[1], acc[1][j], 0, 0, 0);
;         __builtin_amdgcn_sched_barrier(0);
;         if (wr_ok) *(uint4*)(nA + soff0 + 8192) = ra2;
;         if (ld_ok) ra2 = *(const uint4*)(Ab + (aoff + 64u * LDA + koa));
;         ga[2] = *(const bf16x8*)(sA + arow_off + 2 * 2048 + ch1); gb[2] = *(const bf16x8*)(sB + brow_off + 2 * 2048 + ch1);
;         __builtin_amdgcn_sched_barrier(0);
; #pragma unroll
;         for (int j = 0; j < 4; ++j) acc[2][j] = __builtin_amdgcn_mfma_f32_16x16x32_bf16(fb[j], fa[2], acc[2][j], 0, 0, 0);
	ds_read_b128 v[88:91], v7 offset:32768
	ds_read_b128 v[100:103], v7 offset:34816
	ds_read_b128 v[108:111], v8 offset:49152
	ds_read_b128 v[116:119], v8 offset:51200
	ds_read_b128 v[124:127], v7 offset:36864
	ds_read_b128 v[132:135], v7 offset:38912
	ds_read_b128 v[136:139], v8 offset:53248
	ds_read_b128 v[148:151], v8 offset:55296
	s_setprio 2
	global_load_dwordx4 v[156:159], v241, s[0:1] offset:128
	s_waitcnt vmcnt(8)
	ds_write_b128 v3, v[152:155]
	ds_read_b128 v[152:155], v5 offset:32768
	ds_read_b128 v[160:163], v6 offset:49152
	s_waitcnt lgkmcnt(8)
	v_mfma_f32_16x16x32_bf16 v[28:31], v[108:111], v[88:91], v[28:31]
	s_waitcnt lgkmcnt(4)
	v_mfma_f32_16x16x32_bf16 v[80:83], v[136:139], v[88:91], v[80:83]
	s_waitcnt lgkmcnt(3)
	v_mfma_f32_16x16x32_bf16 v[12:15], v[148:151], v[88:91], v[12:15]
	v_mfma_f32_16x16x32_bf16 v[72:75], v[116:119], v[88:91], v[72:75]
	global_load_dwordx4 v[88:91], v242, s[0:1] offset:128
	s_waitcnt vmcnt(8)
	ds_write_b128 v3, v[64:67] offset:4096
	ds_read_b128 v[64:67], v5 offset:34816
	ds_read_b128 v[164:167], v6 offset:51200
	v_mfma_f32_16x16x32_bf16 v[32:35], v[108:111], v[100:103], v[32:35]
	v_mfma_f32_16x16x32_bf16 v[44:47], v[116:119], v[100:103], v[44:47]
	v_mfma_f32_16x16x32_bf16 v[16:19], v[148:151], v[100:103], v[16:19]
	v_mfma_f32_16x16x32_bf16 v[76:79], v[136:139], v[100:103], v[76:79]
	global_load_dwordx4 v[100:103], v243, s[0:1] offset:128
	s_waitcnt vmcnt(8)
	ds_write_b128 v3, v[92:95] offset:8192
	ds_read_b128 v[92:95], v5 offset:36864
	ds_read_b128 v[168:171], v6 offset:53248
	v_mfma_f32_16x16x32_bf16 v[36:39], v[108:111], v[124:127], v[36:39]
	v_mfma_f32_16x16x32_bf16 v[48:51], v[116:119], v[124:127], v[48:51]
	v_mfma_f32_16x16x32_bf16 v[60:63], v[136:139], v[124:127], v[60:63]
	v_mfma_f32_16x16x32_bf16 v[20:23], v[148:151], v[124:127], v[20:23]
	global_load_dwordx4 v[124:127], v244, s[0:1] offset:128
	s_waitcnt vmcnt(8)
	ds_write_b128 v3, v[120:123] offset:12288
	ds_read_b128 v[120:123], v5 offset:38912
	ds_read_b128 v[172:175], v6 offset:55296
	v_mfma_f32_16x16x32_bf16 v[40:43], v[108:111], v[132:135], v[40:43]
	v_mfma_f32_16x16x32_bf16 v[52:55], v[116:119], v[132:135], v[52:55]
	v_mfma_f32_16x16x32_bf16 v[56:59], v[136:139], v[132:135], v[56:59]
	v_mfma_f32_16x16x32_bf16 v[24:27], v[148:151], v[132:135], v[24:27]
	global_load_dwordx4 v[108:111], v4, s[2:3] offset:1152
	s_waitcnt vmcnt(8)
	ds_write_b128 v3, v[104:107] offset:16384
	s_waitcnt lgkmcnt(10)
	v_mfma_f32_16x16x32_bf16 v[28:31], v[160:163], v[152:155], v[28:31]
	s_waitcnt lgkmcnt(4)
	v_mfma_f32_16x16x32_bf16 v[80:83], v[168:171], v[152:155], v[80:83]
	s_waitcnt lgkmcnt(1)
	v_mfma_f32_16x16x32_bf16 v[12:15], v[172:175], v[152:155], v[12:15]
	v_mfma_f32_16x16x32_bf16 v[72:75], v[164:167], v[152:155], v[72:75]
	global_load_dwordx4 v[104:107], v236, s[2:3] offset:1152
	s_waitcnt vmcnt(8)
	ds_write_b128 v3, v[112:115] offset:20480
	v_mfma_f32_16x16x32_bf16 v[32:35], v[160:163], v[64:67], v[32:35]
	v_mfma_f32_16x16x32_bf16 v[44:47], v[164:167], v[64:67], v[44:47]
	v_mfma_f32_16x16x32_bf16 v[16:19], v[172:175], v[64:67], v[16:19]
	v_mfma_f32_16x16x32_bf16 v[76:79], v[168:171], v[64:67], v[76:79]
	global_load_dwordx4 v[64:67], v239, s[2:3] offset:1152
	s_waitcnt vmcnt(8)
	ds_write_b128 v3, v[84:87] offset:24576
	v_mfma_f32_16x16x32_bf16 v[36:39], v[160:163], v[92:95], v[36:39]
	v_mfma_f32_16x16x32_bf16 v[48:51], v[164:167], v[92:95], v[48:51]
	v_mfma_f32_16x16x32_bf16 v[60:63], v[168:171], v[92:95], v[60:63]
	v_mfma_f32_16x16x32_bf16 v[20:23], v[172:175], v[92:95], v[20:23]
	global_load_dwordx4 v[84:87], v240, s[2:3] offset:1152
	s_waitcnt vmcnt(8)
	ds_write_b128 v3, v[68:71] offset:28672
	v_mfma_f32_16x16x32_bf16 v[40:43], v[160:163], v[120:123], v[40:43]
	v_mfma_f32_16x16x32_bf16 v[52:55], v[164:167], v[120:123], v[52:55]
	v_mfma_f32_16x16x32_bf16 v[56:59], v[168:171], v[120:123], v[56:59]
	v_mfma_f32_16x16x32_bf16 v[24:27], v[172:175], v[120:123], v[24:27]
	s_setprio 0
	s_waitcnt lgkmcnt(0)
	s_barrier
	ds_read_b128 v[68:71], v7
	ds_read_b128 v[92:95], v7 offset:2048
	ds_read_b128 v[112:115], v8 offset:16384
	ds_read_b128 v[116:119], v8 offset:18432
	ds_read_b128 v[120:123], v7 offset:4096
	ds_read_b128 v[132:135], v7 offset:6144
	ds_read_b128 v[136:139], v8 offset:20480
	ds_read_b128 v[148:151], v8 offset:22528
	s_setprio 2
	global_load_dwordx4 v[152:155], v241, s[0:1] offset:256
	s_waitcnt vmcnt(8)
	ds_write_b128 v3, v[156:159] offset:32768
	ds_read_b128 v[156:159], v5
	ds_read_b128 v[160:163], v6 offset:16384
	s_waitcnt lgkmcnt(8)
	v_mfma_f32_16x16x32_bf16 v[28:31], v[112:115], v[68:71], v[28:31]
	s_waitcnt lgkmcnt(4)
	v_mfma_f32_16x16x32_bf16 v[80:83], v[136:139], v[68:71], v[80:83]
	s_waitcnt lgkmcnt(3)
	v_mfma_f32_16x16x32_bf16 v[12:15], v[148:151], v[68:71], v[12:15]
	v_mfma_f32_16x16x32_bf16 v[72:75], v[116:119], v[68:71], v[72:75]
	global_load_dwordx4 v[68:71], v242, s[0:1] offset:256
	s_waitcnt vmcnt(8)
	ds_write_b128 v3, v[88:91] offset:36864
	ds_read_b128 v[88:91], v5 offset:2048
	ds_read_b128 v[164:167], v6 offset:18432
	v_mfma_f32_16x16x32_bf16 v[32:35], v[112:115], v[92:95], v[32:35]
	v_mfma_f32_16x16x32_bf16 v[44:47], v[116:119], v[92:95], v[44:47]
	v_mfma_f32_16x16x32_bf16 v[16:19], v[148:151], v[92:95], v[16:19]
	v_mfma_f32_16x16x32_bf16 v[76:79], v[136:139], v[92:95], v[76:79]
	global_load_dwordx4 v[92:95], v243, s[0:1] offset:256
	s_waitcnt vmcnt(8)
	ds_write_b128 v3, v[100:103] offset:40960
	ds_read_b128 v[100:103], v5 offset:4096
	ds_read_b128 v[168:171], v6 offset:20480
	v_mfma_f32_16x16x32_bf16 v[36:39], v[112:115], v[120:123], v[36:39]
	v_mfma_f32_16x16x32_bf16 v[48:51], v[116:119], v[120:123], v[48:51]
	v_mfma_f32_16x16x32_bf16 v[60:63], v[136:139], v[120:123], v[60:63]
	v_mfma_f32_16x16x32_bf16 v[20:23], v[148:151], v[120:123], v[20:23]
	global_load_dwordx4 v[120:123], v244, s[0:1] offset:256
	s_waitcnt vmcnt(8)
; template <int MODE>
; __device__ __forceinline__ void gemm_tile(const Params& P, int tm, int tn, unsigned char* smem) {
;     ...
;     for (int kt = 0; kt < 16; ++kt) {
;         unsigned char* sA = (kt & 1) ? sA1 : sA0; unsigned char* sB = (kt & 1) ? sB1 : sB0;
;         unsigned char* nA = (kt & 1) ? sA0 : sA1; unsigned char* nB = (kt & 1) ? sB0 : sB1;
;         bf16x8 fa[4], fb[4], ga[4], gb[4];
;         const int ch0 = ((g ^ sw) << 4), ch1 = (((4 + g) ^ sw) << 4);
;         const unsigned ko = (unsigned)(kt + 2) * 128u;
;         const unsigned koa = ko + ((MODE == 2 && kt + 2 >= 8) ? (unsigned)(ZC_FQ - 512) * 2u : 0u);
;         const bool wr_ok = kt < 15, ld_ok = kt < 14;
; #pragma unroll
;         for (int i = 0; i < 4; ++i) { fa[i] = *(const bf16x8*)(sA + arow_off + i * 2048 + ch0); fb[i] = *(const bf16x8*)(sB + brow_off + i * 2048 + ch0); }
;         __builtin_amdgcn_sched_barrier(0);
;         __builtin_amdgcn_s_setprio(2);
;         if (wr_ok) *(uint4*)(nA + soff0) = ra0;
;         if (ld_ok) ra0 = *(const uint4*)(Ab + (aoff + 0u * LDA + koa));
;         ga[0] = *(const bf16x8*)(sA + arow_off + 0 * 2048 + ch1); gb[0] = *(const bf16x8*)(sB + brow_off + 0 * 2048 + ch1);
;         __builtin_amdgcn_sched_barrier(0);
; #pragma unroll
;         for (int j = 0; j < 4; ++j) acc[0][j] = __builtin_amdgcn_mfma_f32_16x16x32_bf16(fb[j], fa[0], acc[0][j], 0, 0, 0);
;         __builtin_amdgcn_sched_barrier(0);
;         if (wr_ok) *(uint4*)(nA + soff0 + 4096) = ra1;
;         if (ld_ok) ra1 = *(const uint4*)(Ab + (aoff + 32u * LDA + koa));
;         ga[1] = *(const bf16x8*)(sA + arow_off + 1 * 2048 + ch1); gb[1] = *(const bf16x8*)(sB + brow_off + 1 * 2048 + ch1);
;         __builtin_amdgcn_sched_barrier(0);
; #pragma unroll
;         for (int j = 0; j < 4; ++j) acc[1][j] = __builtin_amdgcn_mfma_f32_16x16x32_bf16(fb[j], fa[1], acc[1][j], 0, 0, 0);
;         __builtin_amdgcn_sched_barrier(0);
;         if (wr_ok) *(uint4*)(nA + soff0 + 8192) = ra2;
;         if (ld_ok) ra2 = *(const uint4*)(Ab + (aoff + 64u * LDA + koa));
;         ga[2] = *(const bf16x8*)(sA + arow_off + 2 * 2048 + ch1); gb[2] = *(const bf16x8*)(sB + brow_off + 2 * 2048 + ch1);
;         __builtin_amdgcn_sched_barrier(0);
; #pragma unroll
;         for (int j = 0; j < 4; ++j) acc[2][j] = __builtin_amdgcn_mfma_f32_16x16x32_bf16(fb[j], fa[2], acc[2][j], 0, 0, 0);
	ds_write_b128 v3, v[124:127] offset:45056
	ds_read_b128 v[124:127], v5 offset:6144
	ds_read_b128 v[172:175], v6 offset:22528
	v_mfma_f32_16x16x32_bf16 v[40:43], v[112:115], v[132:135], v[40:43]
	v_mfma_f32_16x16x32_bf16 v[52:55], v[116:119], v[132:135], v[52:55]
	v_mfma_f32_16x16x32_bf16 v[56:59], v[136:139], v[132:135], v[56:59]
	v_mfma_f32_16x16x32_bf16 v[24:27], v[148:151], v[132:135], v[24:27]
	global_load_dwordx4 v[112:115], v4, s[2:3] offset:1280
	s_waitcnt vmcnt(8)
	ds_write_b128 v3, v[108:111] offset:49152
	s_waitcnt lgkmcnt(10)
	v_mfma_f32_16x16x32_bf16 v[28:31], v[160:163], v[156:159], v[28:31]
	s_waitcnt lgkmcnt(4)
	v_mfma_f32_16x16x32_bf16 v[80:83], v[168:171], v[156:159], v[80:83]
	s_waitcnt lgkmcnt(1)
	v_mfma_f32_16x16x32_bf16 v[12:15], v[172:175], v[156:159], v[12:15]
	v_mfma_f32_16x16x32_bf16 v[72:75], v[164:167], v[156:159], v[72:75]
	global_load_dwordx4 v[108:111], v236, s[2:3] offset:1280
	s_waitcnt vmcnt(8)
	ds_write_b128 v3, v[104:107] offset:53248
	v_mfma_f32_16x16x32_bf16 v[32:35], v[160:163], v[88:91], v[32:35]
	v_mfma_f32_16x16x32_bf16 v[44:47], v[164:167], v[88:91], v[44:47]
	v_mfma_f32_16x16x32_bf16 v[16:19], v[172:175], v[88:91], v[16:19]
	v_mfma_f32_16x16x32_bf16 v[76:79], v[168:171], v[88:91], v[76:79]
	global_load_dwordx4 v[88:91], v239, s[2:3] offset:1280
	s_waitcnt vmcnt(8)
	ds_write_b128 v3, v[64:67] offset:57344
	v_mfma_f32_16x16x32_bf16 v[36:39], v[160:163], v[100:103], v[36:39]
	v_mfma_f32_16x16x32_bf16 v[48:51], v[164:167], v[100:103], v[48:51]
	v_mfma_f32_16x16x32_bf16 v[60:63], v[168:171], v[100:103], v[60:63]
	v_mfma_f32_16x16x32_bf16 v[20:23], v[172:175], v[100:103], v[20:23]
	global_load_dwordx4 v[64:67], v240, s[2:3] offset:1280
	s_waitcnt vmcnt(8)
	ds_write_b128 v3, v[84:87] offset:61440
	v_mfma_f32_16x16x32_bf16 v[40:43], v[160:163], v[124:127], v[40:43]
	v_mfma_f32_16x16x32_bf16 v[52:55], v[164:167], v[124:127], v[52:55]
	v_mfma_f32_16x16x32_bf16 v[56:59], v[168:171], v[124:127], v[56:59]
	v_mfma_f32_16x16x32_bf16 v[24:27], v[172:175], v[124:127], v[24:27]
	s_setprio 0
	s_waitcnt lgkmcnt(0)
	s_barrier
	ds_read_b128 v[84:87], v7 offset:32768
	ds_read_b128 v[100:103], v7 offset:34816
	ds_read_b128 v[104:107], v8 offset:49152
	ds_read_b128 v[116:119], v8 offset:51200
	ds_read_b128 v[124:127], v7 offset:36864
	ds_read_b128 v[132:135], v7 offset:38912
	ds_read_b128 v[136:139], v8 offset:53248
	ds_read_b128 v[148:151], v8 offset:55296
	s_setprio 2
	global_load_dwordx4 v[156:159], v241, s[0:1] offset:384
	s_waitcnt vmcnt(8)
	ds_write_b128 v3, v[152:155]
	ds_read_b128 v[152:155], v5 offset:32768
	ds_read_b128 v[160:163], v6 offset:49152
	s_waitcnt lgkmcnt(8)
	v_mfma_f32_16x16x32_bf16 v[28:31], v[104:107], v[84:87], v[28:31]
	s_waitcnt lgkmcnt(4)
	v_mfma_f32_16x16x32_bf16 v[80:83], v[136:139], v[84:87], v[80:83]
	s_waitcnt lgkmcnt(3)
	v_mfma_f32_16x16x32_bf16 v[12:15], v[148:151], v[84:87], v[12:15]
	v_mfma_f32_16x16x32_bf16 v[72:75], v[116:119], v[84:87], v[72:75]
	global_load_dwordx4 v[84:87], v242, s[0:1] offset:384
	s_waitcnt vmcnt(8)
	ds_write_b128 v3, v[68:71] offset:4096
	ds_read_b128 v[68:71], v5 offset:34816
	ds_read_b128 v[164:167], v6 offset:51200
	v_mfma_f32_16x16x32_bf16 v[32:35], v[104:107], v[100:103], v[32:35]
	v_mfma_f32_16x16x32_bf16 v[44:47], v[116:119], v[100:103], v[44:47]
	v_mfma_f32_16x16x32_bf16 v[16:19], v[148:151], v[100:103], v[16:19]
	v_mfma_f32_16x16x32_bf16 v[76:79], v[136:139], v[100:103], v[76:79]
	global_load_dwordx4 v[100:103], v243, s[0:1] offset:384
	s_waitcnt vmcnt(8)
	ds_write_b128 v3, v[92:95] offset:8192
	ds_read_b128 v[92:95], v5 offset:36864
	ds_read_b128 v[168:171], v6 offset:53248
	v_mfma_f32_16x16x32_bf16 v[36:39], v[104:107], v[124:127], v[36:39]
	v_mfma_f32_16x16x32_bf16 v[48:51], v[116:119], v[124:127], v[48:51]
	v_mfma_f32_16x16x32_bf16 v[60:63], v[136:139], v[124:127], v[60:63]
	v_mfma_f32_16x16x32_bf16 v[20:23], v[148:151], v[124:127], v[20:23]
	global_load_dwordx4 v[124:127], v244, s[0:1] offset:384
	s_waitcnt vmcnt(8)
	ds_write_b128 v3, v[120:123] offset:12288
	ds_read_b128 v[120:123], v5 offset:38912
	ds_read_b128 v[172:175], v6 offset:55296
	v_mfma_f32_16x16x32_bf16 v[40:43], v[104:107], v[132:135], v[40:43]
	v_mfma_f32_16x16x32_bf16 v[52:55], v[116:119], v[132:135], v[52:55]
	v_mfma_f32_16x16x32_bf16 v[56:59], v[136:139], v[132:135], v[56:59]
	v_mfma_f32_16x16x32_bf16 v[24:27], v[148:151], v[132:135], v[24:27]
	global_load_dwordx4 v[104:107], v4, s[2:3] offset:1408
	s_waitcnt vmcnt(8)
	ds_write_b128 v3, v[112:115] offset:16384
	s_waitcnt lgkmcnt(10)
	v_mfma_f32_16x16x32_bf16 v[28:31], v[160:163], v[152:155], v[28:31]
	s_waitcnt lgkmcnt(4)
	v_mfma_f32_16x16x32_bf16 v[80:83], v[168:171], v[152:155], v[80:83]
	s_waitcnt lgkmcnt(1)
	v_mfma_f32_16x16x32_bf16 v[12:15], v[172:175], v[152:155], v[12:15]
	v_mfma_f32_16x16x32_bf16 v[72:75], v[164:167], v[152:155], v[72:75]
	global_load_dwordx4 v[112:115], v236, s[2:3] offset:1408
	s_waitcnt vmcnt(8)
	ds_write_b128 v3, v[108:111] offset:20480
	v_mfma_f32_16x16x32_bf16 v[32:35], v[160:163], v[68:71], v[32:35]
	v_mfma_f32_16x16x32_bf16 v[44:47], v[164:167], v[68:71], v[44:47]
	v_mfma_f32_16x16x32_bf16 v[16:19], v[172:175], v[68:71], v[16:19]
	v_mfma_f32_16x16x32_bf16 v[76:79], v[168:171], v[68:71], v[76:79]
	global_load_dwordx4 v[68:71], v239, s[2:3] offset:1408
	s_waitcnt vmcnt(8)
	ds_write_b128 v3, v[88:91] offset:24576
	v_mfma_f32_16x16x32_bf16 v[36:39], v[160:163], v[92:95], v[36:39]
	v_mfma_f32_16x16x32_bf16 v[48:51], v[164:167], v[92:95], v[48:51]
	v_mfma_f32_16x16x32_bf16 v[60:63], v[168:171], v[92:95], v[60:63]
	v_mfma_f32_16x16x32_bf16 v[20:23], v[172:175], v[92:95], v[20:23]
	global_load_dwordx4 v[88:91], v240, s[2:3] offset:1408
	s_waitcnt vmcnt(8)
	ds_write_b128 v3, v[64:67] offset:28672
	v_mfma_f32_16x16x32_bf16 v[40:43], v[160:163], v[120:123], v[40:43]
	v_mfma_f32_16x16x32_bf16 v[52:55], v[164:167], v[120:123], v[52:55]
	v_mfma_f32_16x16x32_bf16 v[56:59], v[168:171], v[120:123], v[56:59]
	v_mfma_f32_16x16x32_bf16 v[24:27], v[172:175], v[120:123], v[24:27]
	s_setprio 0
	s_waitcnt lgkmcnt(0)
	s_barrier
; template <int MODE>
; __device__ __forceinline__ void gemm_tile(const Params& P, int tm, int tn, unsigned char* smem) {
;     ...
;     for (int kt = 0; kt < 16; ++kt) {
;         unsigned char* sA = (kt & 1) ? sA1 : sA0; unsigned char* sB = (kt & 1) ? sB1 : sB0;
;         unsigned char* nA = (kt & 1) ? sA0 : sA1; unsigned char* nB = (kt & 1) ? sB0 : sB1;
;         bf16x8 fa[4], fb[4], ga[4], gb[4];
;         const int ch0 = ((g ^ sw) << 4), ch1 = (((4 + g) ^ sw) << 4);
;         const unsigned ko = (unsigned)(kt + 2) * 128u;
;         const unsigned koa = ko + ((MODE == 2 && kt + 2 >= 8) ? (unsigned)(ZC_FQ - 512) * 2u : 0u);
;         const bool wr_ok = kt < 15, ld_ok = kt < 14;
; #pragma unroll
;         for (int i = 0; i < 4; ++i) { fa[i] = *(const bf16x8*)(sA + arow_off + i * 2048 + ch0); fb[i] = *(const bf16x8*)(sB + brow_off + i * 2048 + ch0); }
;         __builtin_amdgcn_sched_barrier(0);
;         __builtin_amdgcn_s_setprio(2);
;         if (wr_ok) *(uint4*)(nA + soff0) = ra0;
;         if (ld_ok) ra0 = *(const uint4*)(Ab + (aoff + 0u * LDA + koa));
;         ga[0] = *(const bf16x8*)(sA + arow_off + 0 * 2048 + ch1); gb[0] = *(const bf16x8*)(sB + brow_off + 0 * 2048 + ch1);
;         __builtin_amdgcn_sched_barrier(0);
; #pragma unroll
;         for (int j = 0; j < 4; ++j) acc[0][j] = __builtin_amdgcn_mfma_f32_16x16x32_bf16(fb[j], fa[0], acc[0][j], 0, 0, 0);
;         __builtin_amdgcn_sched_barrier(0);
;         if (wr_ok) *(uint4*)(nA + soff0 + 4096) = ra1;
;         if (ld_ok) ra1 = *(const uint4*)(Ab + (aoff + 32u * LDA + koa));
;         ga[1] = *(const bf16x8*)(sA + arow_off + 1 * 2048 + ch1); gb[1] = *(const bf16x8*)(sB + brow_off + 1 * 2048 + ch1);
;         __builtin_amdgcn_sched_barrier(0);
; #pragma unroll
;         for (int j = 0; j < 4; ++j) acc[1][j] = __builtin_amdgcn_mfma_f32_16x16x32_bf16(fb[j], fa[1], acc[1][j], 0, 0, 0);
;         __builtin_amdgcn_sched_barrier(0);
;         if (wr_ok) *(uint4*)(nA + soff0 + 8192) = ra2;
;         if (ld_ok) ra2 = *(const uint4*)(Ab + (aoff + 64u * LDA + koa));
;         ga[2] = *(const bf16x8*)(sA + arow_off + 2 * 2048 + ch1); gb[2] = *(const bf16x8*)(sB + brow_off + 2 * 2048 + ch1);
;         __builtin_amdgcn_sched_barrier(0);
; #pragma unroll
;         for (int j = 0; j < 4; ++j) acc[2][j] = __builtin_amdgcn_mfma_f32_16x16x32_bf16(fb[j], fa[2], acc[2][j], 0, 0, 0);
	ds_read_b128 v[64:67], v7
	ds_read_b128 v[92:95], v7 offset:2048
	ds_read_b128 v[108:111], v8 offset:16384
	ds_read_b128 v[116:119], v8 offset:18432
	ds_read_b128 v[120:123], v7 offset:4096
	ds_read_b128 v[132:135], v7 offset:6144
	ds_read_b128 v[136:139], v8 offset:20480
	ds_read_b128 v[148:151], v8 offset:22528
	s_setprio 2
	global_load_dwordx4 v[152:155], v241, s[0:1] offset:512
	s_waitcnt vmcnt(8)
	ds_write_b128 v3, v[156:159] offset:32768
	ds_read_b128 v[156:159], v5
	ds_read_b128 v[160:163], v6 offset:16384
	s_waitcnt lgkmcnt(8)
	v_mfma_f32_16x16x32_bf16 v[28:31], v[108:111], v[64:67], v[28:31]
	s_waitcnt lgkmcnt(4)
	v_mfma_f32_16x16x32_bf16 v[80:83], v[136:139], v[64:67], v[80:83]
	s_waitcnt lgkmcnt(3)
	v_mfma_f32_16x16x32_bf16 v[12:15], v[148:151], v[64:67], v[12:15]
	v_mfma_f32_16x16x32_bf16 v[72:75], v[116:119], v[64:67], v[72:75]
	global_load_dwordx4 v[64:67], v242, s[0:1] offset:512
	s_waitcnt vmcnt(8)
	ds_write_b128 v3, v[84:87] offset:36864
	ds_read_b128 v[84:87], v5 offset:2048
	ds_read_b128 v[164:167], v6 offset:18432
	v_mfma_f32_16x16x32_bf16 v[32:35], v[108:111], v[92:95], v[32:35]
	v_mfma_f32_16x16x32_bf16 v[44:47], v[116:119], v[92:95], v[44:47]
	v_mfma_f32_16x16x32_bf16 v[16:19], v[148:151], v[92:95], v[16:19]
	v_mfma_f32_16x16x32_bf16 v[76:79], v[136:139], v[92:95], v[76:79]
	global_load_dwordx4 v[92:95], v243, s[0:1] offset:512
	s_waitcnt vmcnt(8)
	ds_write_b128 v3, v[100:103] offset:40960
	ds_read_b128 v[100:103], v5 offset:4096
	ds_read_b128 v[168:171], v6 offset:20480
	v_mfma_f32_16x16x32_bf16 v[36:39], v[108:111], v[120:123], v[36:39]
	v_mfma_f32_16x16x32_bf16 v[48:51], v[116:119], v[120:123], v[48:51]
	v_mfma_f32_16x16x32_bf16 v[60:63], v[136:139], v[120:123], v[60:63]
	v_mfma_f32_16x16x32_bf16 v[20:23], v[148:151], v[120:123], v[20:23]
	global_load_dwordx4 v[120:123], v244, s[0:1] offset:512
	s_waitcnt vmcnt(8)
	ds_write_b128 v3, v[124:127] offset:45056
	ds_read_b128 v[124:127], v5 offset:6144
	ds_read_b128 v[172:175], v6 offset:22528
	v_mfma_f32_16x16x32_bf16 v[40:43], v[108:111], v[132:135], v[40:43]
	v_mfma_f32_16x16x32_bf16 v[52:55], v[116:119], v[132:135], v[52:55]
	v_mfma_f32_16x16x32_bf16 v[56:59], v[136:139], v[132:135], v[56:59]
	v_mfma_f32_16x16x32_bf16 v[24:27], v[148:151], v[132:135], v[24:27]
	global_load_dwordx4 v[108:111], v4, s[2:3] offset:1536
	s_waitcnt vmcnt(8)
	ds_write_b128 v3, v[104:107] offset:49152
	s_waitcnt lgkmcnt(10)
	v_mfma_f32_16x16x32_bf16 v[28:31], v[160:163], v[156:159], v[28:31]
	s_waitcnt lgkmcnt(4)
	v_mfma_f32_16x16x32_bf16 v[80:83], v[168:171], v[156:159], v[80:83]
	s_waitcnt lgkmcnt(1)
	v_mfma_f32_16x16x32_bf16 v[12:15], v[172:175], v[156:159], v[12:15]
	v_mfma_f32_16x16x32_bf16 v[72:75], v[164:167], v[156:159], v[72:75]
	global_load_dwordx4 v[104:107], v236, s[2:3] offset:1536
	s_waitcnt vmcnt(8)
	ds_write_b128 v3, v[112:115] offset:53248
	v_mfma_f32_16x16x32_bf16 v[32:35], v[160:163], v[84:87], v[32:35]
	v_mfma_f32_16x16x32_bf16 v[44:47], v[164:167], v[84:87], v[44:47]
	v_mfma_f32_16x16x32_bf16 v[16:19], v[172:175], v[84:87], v[16:19]
	v_mfma_f32_16x16x32_bf16 v[76:79], v[168:171], v[84:87], v[76:79]
	global_load_dwordx4 v[84:87], v239, s[2:3] offset:1536
	s_waitcnt vmcnt(8)
	ds_write_b128 v3, v[68:71] offset:57344
	v_mfma_f32_16x16x32_bf16 v[36:39], v[160:163], v[100:103], v[36:39]
	v_mfma_f32_16x16x32_bf16 v[48:51], v[164:167], v[100:103], v[48:51]
	v_mfma_f32_16x16x32_bf16 v[60:63], v[168:171], v[100:103], v[60:63]
	v_mfma_f32_16x16x32_bf16 v[20:23], v[172:175], v[100:103], v[20:23]
	global_load_dwordx4 v[68:71], v240, s[2:3] offset:1536
	s_waitcnt vmcnt(8)
	ds_write_b128 v3, v[88:91] offset:61440
	v_mfma_f32_16x16x32_bf16 v[40:43], v[160:163], v[124:127], v[40:43]
	v_mfma_f32_16x16x32_bf16 v[52:55], v[164:167], v[124:127], v[52:55]
	v_mfma_f32_16x16x32_bf16 v[56:59], v[168:171], v[124:127], v[56:59]
	v_mfma_f32_16x16x32_bf16 v[24:27], v[172:175], v[124:127], v[24:27]
	s_setprio 0
	s_waitcnt lgkmcnt(0)
	s_barrier
	ds_read_b128 v[88:91], v7 offset:32768
	ds_read_b128 v[100:103], v7 offset:34816
	ds_read_b128 v[112:115], v8 offset:49152
	ds_read_b128 v[116:119], v8 offset:51200
	ds_read_b128 v[124:127], v7 offset:36864
	ds_read_b128 v[132:135], v7 offset:38912
	ds_read_b128 v[136:139], v8 offset:53248
	ds_read_b128 v[148:151], v8 offset:55296
	s_setprio 2
	global_load_dwordx4 v[156:159], v241, s[0:1] offset:640
	s_waitcnt vmcnt(8)
	ds_write_b128 v3, v[152:155]
	ds_read_b128 v[152:155], v5 offset:32768
	ds_read_b128 v[160:163], v6 offset:49152
	s_waitcnt lgkmcnt(8)
	v_mfma_f32_16x16x32_bf16 v[28:31], v[112:115], v[88:91], v[28:31]
	s_waitcnt lgkmcnt(4)
	v_mfma_f32_16x16x32_bf16 v[80:83], v[136:139], v[88:91], v[80:83]
	s_waitcnt lgkmcnt(3)
	v_mfma_f32_16x16x32_bf16 v[12:15], v[148:151], v[88:91], v[12:15]
	v_mfma_f32_16x16x32_bf16 v[72:75], v[116:119], v[88:91], v[72:75]
	global_load_dwordx4 v[88:91], v242, s[0:1] offset:640
	s_waitcnt vmcnt(8)
	ds_write_b128 v3, v[64:67] offset:4096
	ds_read_b128 v[64:67], v5 offset:34816
	ds_read_b128 v[164:167], v6 offset:51200
	v_mfma_f32_16x16x32_bf16 v[32:35], v[112:115], v[100:103], v[32:35]
	v_mfma_f32_16x16x32_bf16 v[44:47], v[116:119], v[100:103], v[44:47]
	v_mfma_f32_16x16x32_bf16 v[16:19], v[148:151], v[100:103], v[16:19]
	v_mfma_f32_16x16x32_bf16 v[76:79], v[136:139], v[100:103], v[76:79]
	global_load_dwordx4 v[100:103], v243, s[0:1] offset:640
	s_waitcnt vmcnt(8)
	ds_write_b128 v3, v[92:95] offset:8192
	ds_read_b128 v[92:95], v5 offset:36864
	ds_read_b128 v[168:171], v6 offset:53248
	v_mfma_f32_16x16x32_bf16 v[36:39], v[112:115], v[124:127], v[36:39]
	v_mfma_f32_16x16x32_bf16 v[48:51], v[116:119], v[124:127], v[48:51]
	v_mfma_f32_16x16x32_bf16 v[60:63], v[136:139], v[124:127], v[60:63]
	v_mfma_f32_16x16x32_bf16 v[20:23], v[148:151], v[124:127], v[20:23]
	global_load_dwordx4 v[124:127], v244, s[0:1] offset:640
	s_waitcnt vmcnt(8)
; template <int MODE>
; __device__ __forceinline__ void gemm_tile(const Params& P, int tm, int tn, unsigned char* smem) {
;     ...
;     for (int kt = 0; kt < 16; ++kt) {
;         unsigned char* sA = (kt & 1) ? sA1 : sA0; unsigned char* sB = (kt & 1) ? sB1 : sB0;
;         unsigned char* nA = (kt & 1) ? sA0 : sA1; unsigned char* nB = (kt & 1) ? sB0 : sB1;
;         bf16x8 fa[4], fb[4], ga[4], gb[4];
;         const int ch0 = ((g ^ sw) << 4), ch1 = (((4 + g) ^ sw) << 4);
;         const unsigned ko = (unsigned)(kt + 2) * 128u;
;         const unsigned koa = ko + ((MODE == 2 && kt + 2 >= 8) ? (unsigned)(ZC_FQ - 512) * 2u : 0u);
;         const bool wr_ok = kt < 15, ld_ok = kt < 14;
; #pragma unroll
;         for (int i = 0; i < 4; ++i) { fa[i] = *(const bf16x8*)(sA + arow_off + i * 2048 + ch0); fb[i] = *(const bf16x8*)(sB + brow_off + i * 2048 + ch0); }
;         __builtin_amdgcn_sched_barrier(0);
;         __builtin_amdgcn_s_setprio(2);
;         if (wr_ok) *(uint4*)(nA + soff0) = ra0;
;         if (ld_ok) ra0 = *(const uint4*)(Ab + (aoff + 0u * LDA + koa));
;         ga[0] = *(const bf16x8*)(sA + arow_off + 0 * 2048 + ch1); gb[0] = *(const bf16x8*)(sB + brow_off + 0 * 2048 + ch1);
;         __builtin_amdgcn_sched_barrier(0);
; #pragma unroll
;         for (int j = 0; j < 4; ++j) acc[0][j] = __builtin_amdgcn_mfma_f32_16x16x32_bf16(fb[j], fa[0], acc[0][j], 0, 0, 0);
;         __builtin_amdgcn_sched_barrier(0);
;         if (wr_ok) *(uint4*)(nA + soff0 + 4096) = ra1;
;         if (ld_ok) ra1 = *(const uint4*)(Ab + (aoff + 32u * LDA + koa));
;         ga[1] = *(const bf16x8*)(sA + arow_off + 1 * 2048 + ch1); gb[1] = *(const bf16x8*)(sB + brow_off + 1 * 2048 + ch1);
;         __builtin_amdgcn_sched_barrier(0);
; #pragma unroll
;         for (int j = 0; j < 4; ++j) acc[1][j] = __builtin_amdgcn_mfma_f32_16x16x32_bf16(fb[j], fa[1], acc[1][j], 0, 0, 0);
;         __builtin_amdgcn_sched_barrier(0);
;         if (wr_ok) *(uint4*)(nA + soff0 + 8192) = ra2;
;         if (ld_ok) ra2 = *(const uint4*)(Ab + (aoff + 64u * LDA + koa));
;         ga[2] = *(const bf16x8*)(sA + arow_off + 2 * 2048 + ch1); gb[2] = *(const bf16x8*)(sB + brow_off + 2 * 2048 + ch1);
;         __builtin_amdgcn_sched_barrier(0);
; #pragma unroll
;         for (int j = 0; j < 4; ++j) acc[2][j] = __builtin_amdgcn_mfma_f32_16x16x32_bf16(fb[j], fa[2], acc[2][j], 0, 0, 0);
	ds_write_b128 v3, v[120:123] offset:12288
	ds_read_b128 v[120:123], v5 offset:38912
	ds_read_b128 v[172:175], v6 offset:55296
	v_mfma_f32_16x16x32_bf16 v[40:43], v[112:115], v[132:135], v[40:43]
	v_mfma_f32_16x16x32_bf16 v[52:55], v[116:119], v[132:135], v[52:55]
	v_mfma_f32_16x16x32_bf16 v[56:59], v[136:139], v[132:135], v[56:59]
	v_mfma_f32_16x16x32_bf16 v[24:27], v[148:151], v[132:135], v[24:27]
	global_load_dwordx4 v[112:115], v4, s[2:3] offset:1664
	s_waitcnt vmcnt(8)
	ds_write_b128 v3, v[108:111] offset:16384
	s_waitcnt lgkmcnt(10)
	v_mfma_f32_16x16x32_bf16 v[28:31], v[160:163], v[152:155], v[28:31]
	s_waitcnt lgkmcnt(4)
	v_mfma_f32_16x16x32_bf16 v[80:83], v[168:171], v[152:155], v[80:83]
	s_waitcnt lgkmcnt(1)
	v_mfma_f32_16x16x32_bf16 v[12:15], v[172:175], v[152:155], v[12:15]
	v_mfma_f32_16x16x32_bf16 v[72:75], v[164:167], v[152:155], v[72:75]
	global_load_dwordx4 v[108:111], v236, s[2:3] offset:1664
	s_waitcnt vmcnt(8)
	ds_write_b128 v3, v[104:107] offset:20480
	v_mfma_f32_16x16x32_bf16 v[32:35], v[160:163], v[64:67], v[32:35]
	v_mfma_f32_16x16x32_bf16 v[44:47], v[164:167], v[64:67], v[44:47]
	v_mfma_f32_16x16x32_bf16 v[16:19], v[172:175], v[64:67], v[16:19]
	v_mfma_f32_16x16x32_bf16 v[76:79], v[168:171], v[64:67], v[76:79]
	global_load_dwordx4 v[64:67], v239, s[2:3] offset:1664
	s_waitcnt vmcnt(8)
	ds_write_b128 v3, v[84:87] offset:24576
	v_mfma_f32_16x16x32_bf16 v[36:39], v[160:163], v[92:95], v[36:39]
	v_mfma_f32_16x16x32_bf16 v[48:51], v[164:167], v[92:95], v[48:51]
	v_mfma_f32_16x16x32_bf16 v[60:63], v[168:171], v[92:95], v[60:63]
	v_mfma_f32_16x16x32_bf16 v[20:23], v[172:175], v[92:95], v[20:23]
	global_load_dwordx4 v[84:87], v240, s[2:3] offset:1664
	s_waitcnt vmcnt(8)
	ds_write_b128 v3, v[68:71] offset:28672
	v_mfma_f32_16x16x32_bf16 v[40:43], v[160:163], v[120:123], v[40:43]
	v_mfma_f32_16x16x32_bf16 v[52:55], v[164:167], v[120:123], v[52:55]
	v_mfma_f32_16x16x32_bf16 v[56:59], v[168:171], v[120:123], v[56:59]
	v_mfma_f32_16x16x32_bf16 v[24:27], v[172:175], v[120:123], v[24:27]
	s_setprio 0
	s_waitcnt lgkmcnt(0)
	s_barrier
	ds_read_b128 v[68:71], v7
	ds_read_b128 v[92:95], v7 offset:2048
	ds_read_b128 v[104:107], v8 offset:16384
	ds_read_b128 v[116:119], v8 offset:18432
	ds_read_b128 v[120:123], v7 offset:4096
	ds_read_b128 v[132:135], v7 offset:6144
	ds_read_b128 v[136:139], v8 offset:20480
	ds_read_b128 v[148:151], v8 offset:22528
	s_setprio 2
	global_load_dwordx4 v[152:155], v241, s[0:1] offset:768
	s_waitcnt vmcnt(8)
	ds_write_b128 v3, v[156:159] offset:32768
	ds_read_b128 v[156:159], v5
	ds_read_b128 v[160:163], v6 offset:16384
	s_waitcnt lgkmcnt(8)
	v_mfma_f32_16x16x32_bf16 v[28:31], v[104:107], v[68:71], v[28:31]
	s_waitcnt lgkmcnt(4)
	v_mfma_f32_16x16x32_bf16 v[80:83], v[136:139], v[68:71], v[80:83]
	s_waitcnt lgkmcnt(3)
	v_mfma_f32_16x16x32_bf16 v[12:15], v[148:151], v[68:71], v[12:15]
	v_mfma_f32_16x16x32_bf16 v[72:75], v[116:119], v[68:71], v[72:75]
	global_load_dwordx4 v[68:71], v242, s[0:1] offset:768
	s_waitcnt vmcnt(8)
	ds_write_b128 v3, v[88:91] offset:36864
	ds_read_b128 v[88:91], v5 offset:2048
	ds_read_b128 v[164:167], v6 offset:18432
	v_mfma_f32_16x16x32_bf16 v[32:35], v[104:107], v[92:95], v[32:35]
	v_mfma_f32_16x16x32_bf16 v[44:47], v[116:119], v[92:95], v[44:47]
	v_mfma_f32_16x16x32_bf16 v[16:19], v[148:151], v[92:95], v[16:19]
	v_mfma_f32_16x16x32_bf16 v[76:79], v[136:139], v[92:95], v[76:79]
	global_load_dwordx4 v[92:95], v243, s[0:1] offset:768
	s_waitcnt vmcnt(8)
	ds_write_b128 v3, v[100:103] offset:40960
	ds_read_b128 v[100:103], v5 offset:4096
	ds_read_b128 v[168:171], v6 offset:20480
	v_mfma_f32_16x16x32_bf16 v[36:39], v[104:107], v[120:123], v[36:39]
	v_mfma_f32_16x16x32_bf16 v[48:51], v[116:119], v[120:123], v[48:51]
	v_mfma_f32_16x16x32_bf16 v[60:63], v[136:139], v[120:123], v[60:63]
	v_mfma_f32_16x16x32_bf16 v[20:23], v[148:151], v[120:123], v[20:23]
	global_load_dwordx4 v[120:123], v244, s[0:1] offset:768
	s_waitcnt vmcnt(8)
	ds_write_b128 v3, v[124:127] offset:45056
	ds_read_b128 v[124:127], v5 offset:6144
	ds_read_b128 v[172:175], v6 offset:22528
	v_mfma_f32_16x16x32_bf16 v[40:43], v[104:107], v[132:135], v[40:43]
	v_mfma_f32_16x16x32_bf16 v[52:55], v[116:119], v[132:135], v[52:55]
	v_mfma_f32_16x16x32_bf16 v[56:59], v[136:139], v[132:135], v[56:59]
	v_mfma_f32_16x16x32_bf16 v[24:27], v[148:151], v[132:135], v[24:27]
	global_load_dwordx4 v[104:107], v4, s[2:3] offset:1792
	s_waitcnt vmcnt(8)
	ds_write_b128 v3, v[112:115] offset:49152
	s_waitcnt lgkmcnt(10)
	v_mfma_f32_16x16x32_bf16 v[28:31], v[160:163], v[156:159], v[28:31]
	s_waitcnt lgkmcnt(4)
	v_mfma_f32_16x16x32_bf16 v[80:83], v[168:171], v[156:159], v[80:83]
	s_waitcnt lgkmcnt(1)
	v_mfma_f32_16x16x32_bf16 v[12:15], v[172:175], v[156:159], v[12:15]
	v_mfma_f32_16x16x32_bf16 v[72:75], v[164:167], v[156:159], v[72:75]
	global_load_dwordx4 v[112:115], v236, s[2:3] offset:1792
	s_waitcnt vmcnt(8)
	ds_write_b128 v3, v[108:111] offset:53248
	v_mfma_f32_16x16x32_bf16 v[32:35], v[160:163], v[88:91], v[32:35]
	v_mfma_f32_16x16x32_bf16 v[44:47], v[164:167], v[88:91], v[44:47]
	v_mfma_f32_16x16x32_bf16 v[16:19], v[172:175], v[88:91], v[16:19]
	v_mfma_f32_16x16x32_bf16 v[76:79], v[168:171], v[88:91], v[76:79]
	global_load_dwordx4 v[88:91], v239, s[2:3] offset:1792
	s_waitcnt vmcnt(8)
	ds_write_b128 v3, v[64:67] offset:57344
	v_mfma_f32_16x16x32_bf16 v[36:39], v[160:163], v[100:103], v[36:39]
	v_mfma_f32_16x16x32_bf16 v[48:51], v[164:167], v[100:103], v[48:51]
	v_mfma_f32_16x16x32_bf16 v[60:63], v[168:171], v[100:103], v[60:63]
	v_mfma_f32_16x16x32_bf16 v[20:23], v[172:175], v[100:103], v[20:23]
	global_load_dwordx4 v[64:67], v240, s[2:3] offset:1792
	s_waitcnt vmcnt(8)
	ds_write_b128 v3, v[84:87] offset:61440
	v_mfma_f32_16x16x32_bf16 v[40:43], v[160:163], v[124:127], v[40:43]
	v_mfma_f32_16x16x32_bf16 v[52:55], v[164:167], v[124:127], v[52:55]
	v_mfma_f32_16x16x32_bf16 v[56:59], v[168:171], v[124:127], v[56:59]
	v_mfma_f32_16x16x32_bf16 v[24:27], v[172:175], v[124:127], v[24:27]
	s_setprio 0
	s_waitcnt lgkmcnt(0)
	s_barrier
; template <int MODE>
; __device__ __forceinline__ void gemm_tile(const Params& P, int tm, int tn, unsigned char* smem) {
;     ...
;     for (int kt = 0; kt < 16; ++kt) {
;         unsigned char* sA = (kt & 1) ? sA1 : sA0; unsigned char* sB = (kt & 1) ? sB1 : sB0;
;         unsigned char* nA = (kt & 1) ? sA0 : sA1; unsigned char* nB = (kt & 1) ? sB0 : sB1;
;         bf16x8 fa[4], fb[4], ga[4], gb[4];
;         const int ch0 = ((g ^ sw) << 4), ch1 = (((4 + g) ^ sw) << 4);
;         const unsigned ko = (unsigned)(kt + 2) * 128u;
;         const unsigned koa = ko + ((MODE == 2 && kt + 2 >= 8) ? (unsigned)(ZC_FQ - 512) * 2u : 0u);
;         const bool wr_ok = kt < 15, ld_ok = kt < 14;
; #pragma unroll
;         for (int i = 0; i < 4; ++i) { fa[i] = *(const bf16x8*)(sA + arow_off + i * 2048 + ch0); fb[i] = *(const bf16x8*)(sB + brow_off + i * 2048 + ch0); }
;         __builtin_amdgcn_sched_barrier(0);
;         __builtin_amdgcn_s_setprio(2);
;         if (wr_ok) *(uint4*)(nA + soff0) = ra0;
;         if (ld_ok) ra0 = *(const uint4*)(Ab + (aoff + 0u * LDA + koa));
;         ga[0] = *(const bf16x8*)(sA + arow_off + 0 * 2048 + ch1); gb[0] = *(const bf16x8*)(sB + brow_off + 0 * 2048 + ch1);
;         __builtin_amdgcn_sched_barrier(0);
; #pragma unroll
;         for (int j = 0; j < 4; ++j) acc[0][j] = __builtin_amdgcn_mfma_f32_16x16x32_bf16(fb[j], fa[0], acc[0][j], 0, 0, 0);
;         __builtin_amdgcn_sched_barrier(0);
;         if (wr_ok) *(uint4*)(nA + soff0 + 4096) = ra1;
;         if (ld_ok) ra1 = *(const uint4*)(Ab + (aoff + 32u * LDA + koa));
;         ga[1] = *(const bf16x8*)(sA + arow_off + 1 * 2048 + ch1); gb[1] = *(const bf16x8*)(sB + brow_off + 1 * 2048 + ch1);
;         __builtin_amdgcn_sched_barrier(0);
; #pragma unroll
;         for (int j = 0; j < 4; ++j) acc[1][j] = __builtin_amdgcn_mfma_f32_16x16x32_bf16(fb[j], fa[1], acc[1][j], 0, 0, 0);
;         __builtin_amdgcn_sched_barrier(0);
;         if (wr_ok) *(uint4*)(nA + soff0 + 8192) = ra2;
;         if (ld_ok) ra2 = *(const uint4*)(Ab + (aoff + 64u * LDA + koa));
;         ga[2] = *(const bf16x8*)(sA + arow_off + 2 * 2048 + ch1); gb[2] = *(const bf16x8*)(sB + brow_off + 2 * 2048 + ch1);
;         __builtin_amdgcn_sched_barrier(0);
; #pragma unroll
;         for (int j = 0; j < 4; ++j) acc[2][j] = __builtin_amdgcn_mfma_f32_16x16x32_bf16(fb[j], fa[2], acc[2][j], 0, 0, 0);
	ds_read_b128 v[84:87], v7 offset:32768
	ds_read_b128 v[100:103], v7 offset:34816
	ds_read_b128 v[108:111], v8 offset:49152
	ds_read_b128 v[116:119], v8 offset:51200
	ds_read_b128 v[124:127], v7 offset:36864
	ds_read_b128 v[132:135], v7 offset:38912
	ds_read_b128 v[136:139], v8 offset:53248
	ds_read_b128 v[148:151], v8 offset:55296
	s_setprio 2
	global_load_dwordx4 v[156:159], v241, s[0:1] offset:896
	s_waitcnt vmcnt(8)
	ds_write_b128 v3, v[152:155]
	ds_read_b128 v[152:155], v5 offset:32768
	ds_read_b128 v[160:163], v6 offset:49152
	s_waitcnt lgkmcnt(8)
	v_mfma_f32_16x16x32_bf16 v[28:31], v[108:111], v[84:87], v[28:31]
	s_waitcnt lgkmcnt(4)
	v_mfma_f32_16x16x32_bf16 v[80:83], v[136:139], v[84:87], v[80:83]
	s_waitcnt lgkmcnt(3)
	v_mfma_f32_16x16x32_bf16 v[12:15], v[148:151], v[84:87], v[12:15]
	v_mfma_f32_16x16x32_bf16 v[72:75], v[116:119], v[84:87], v[72:75]
	global_load_dwordx4 v[84:87], v242, s[0:1] offset:896
	s_waitcnt vmcnt(8)
	ds_write_b128 v3, v[68:71] offset:4096
	ds_read_b128 v[68:71], v5 offset:34816
	ds_read_b128 v[164:167], v6 offset:51200
	v_mfma_f32_16x16x32_bf16 v[32:35], v[108:111], v[100:103], v[32:35]
	v_mfma_f32_16x16x32_bf16 v[44:47], v[116:119], v[100:103], v[44:47]
	v_mfma_f32_16x16x32_bf16 v[16:19], v[148:151], v[100:103], v[16:19]
	v_mfma_f32_16x16x32_bf16 v[76:79], v[136:139], v[100:103], v[76:79]
	global_load_dwordx4 v[100:103], v243, s[0:1] offset:896
	s_waitcnt vmcnt(8)
	ds_write_b128 v3, v[92:95] offset:8192
	ds_read_b128 v[92:95], v5 offset:36864
	ds_read_b128 v[168:171], v6 offset:53248
	v_mfma_f32_16x16x32_bf16 v[36:39], v[108:111], v[124:127], v[36:39]
	v_mfma_f32_16x16x32_bf16 v[48:51], v[116:119], v[124:127], v[48:51]
	v_mfma_f32_16x16x32_bf16 v[60:63], v[136:139], v[124:127], v[60:63]
	v_mfma_f32_16x16x32_bf16 v[20:23], v[148:151], v[124:127], v[20:23]
	v_add_u32_e32 v9, 0xc5380, v9
	global_load_dwordx4 v[124:127], v9, s[0:1]
	s_waitcnt vmcnt(8)
	ds_write_b128 v3, v[120:123] offset:12288
	ds_read_b128 v[120:123], v5 offset:38912
	ds_read_b128 v[172:175], v6 offset:55296
	v_mfma_f32_16x16x32_bf16 v[40:43], v[108:111], v[132:135], v[40:43]
	v_mfma_f32_16x16x32_bf16 v[52:55], v[116:119], v[132:135], v[52:55]
	v_mfma_f32_16x16x32_bf16 v[56:59], v[136:139], v[132:135], v[56:59]
	v_mfma_f32_16x16x32_bf16 v[24:27], v[148:151], v[132:135], v[24:27]
	global_load_dwordx4 v[108:111], v4, s[2:3] offset:1920
	s_waitcnt vmcnt(8)
	ds_write_b128 v3, v[104:107] offset:16384
	s_waitcnt lgkmcnt(10)
	v_mfma_f32_16x16x32_bf16 v[28:31], v[160:163], v[152:155], v[28:31]
	s_waitcnt lgkmcnt(4)
	v_mfma_f32_16x16x32_bf16 v[80:83], v[168:171], v[152:155], v[80:83]
	s_waitcnt lgkmcnt(1)
	v_mfma_f32_16x16x32_bf16 v[12:15], v[172:175], v[152:155], v[12:15]
	v_mfma_f32_16x16x32_bf16 v[72:75], v[164:167], v[152:155], v[72:75]
	global_load_dwordx4 v[104:107], v236, s[2:3] offset:1920
	s_waitcnt vmcnt(8)
	ds_write_b128 v3, v[112:115] offset:20480
	v_mfma_f32_16x16x32_bf16 v[32:35], v[160:163], v[68:71], v[32:35]
	v_mfma_f32_16x16x32_bf16 v[44:47], v[164:167], v[68:71], v[44:47]
	v_mfma_f32_16x16x32_bf16 v[16:19], v[172:175], v[68:71], v[16:19]
	v_mfma_f32_16x16x32_bf16 v[76:79], v[168:171], v[68:71], v[76:79]
	global_load_dwordx4 v[68:71], v239, s[2:3] offset:1920
	s_waitcnt vmcnt(8)
	ds_write_b128 v3, v[88:91] offset:24576
	v_mfma_f32_16x16x32_bf16 v[36:39], v[160:163], v[92:95], v[36:39]
	v_mfma_f32_16x16x32_bf16 v[48:51], v[164:167], v[92:95], v[48:51]
	v_mfma_f32_16x16x32_bf16 v[60:63], v[168:171], v[92:95], v[60:63]
	v_mfma_f32_16x16x32_bf16 v[20:23], v[172:175], v[92:95], v[20:23]
	v_add_u32_e32 v4, 0x30780, v4
	global_load_dwordx4 v[88:91], v4, s[2:3]
	s_waitcnt vmcnt(8)
	ds_write_b128 v3, v[64:67] offset:28672
	v_mfma_f32_16x16x32_bf16 v[40:43], v[160:163], v[120:123], v[40:43]
	v_mfma_f32_16x16x32_bf16 v[52:55], v[164:167], v[120:123], v[52:55]
	v_mfma_f32_16x16x32_bf16 v[56:59], v[168:171], v[120:123], v[56:59]
	v_mfma_f32_16x16x32_bf16 v[24:27], v[172:175], v[120:123], v[24:27]
	s_setprio 0
	s_waitcnt lgkmcnt(0)
	s_barrier
	ds_read_b128 v[64:67], v7
	ds_read_b128 v[92:95], v7 offset:2048
	ds_read_b128 v[112:115], v8 offset:16384
	ds_read_b128 v[116:119], v8 offset:18432
	ds_read_b128 v[120:123], v7 offset:4096
	ds_read_b128 v[132:135], v7 offset:6144
	ds_read_b128 v[136:139], v8 offset:20480
	ds_read_b128 v[148:151], v8 offset:22528
	s_setprio 2
	s_waitcnt vmcnt(7)
	ds_write_b128 v3, v[156:159] offset:32768
	ds_read_b128 v[152:155], v5
	ds_read_b128 v[156:159], v6 offset:16384
	s_waitcnt lgkmcnt(8)
	v_mfma_f32_16x16x32_bf16 v[28:31], v[112:115], v[64:67], v[28:31]
	s_waitcnt lgkmcnt(4)
	v_mfma_f32_16x16x32_bf16 v[80:83], v[136:139], v[64:67], v[80:83]
	s_waitcnt lgkmcnt(3)
	v_mfma_f32_16x16x32_bf16 v[12:15], v[148:151], v[64:67], v[12:15]
	v_mfma_f32_16x16x32_bf16 v[72:75], v[116:119], v[64:67], v[72:75]
	s_waitcnt vmcnt(6)
	ds_write_b128 v3, v[84:87] offset:36864
	ds_read_b128 v[64:67], v5 offset:2048
	ds_read_b128 v[84:87], v6 offset:18432
	v_mfma_f32_16x16x32_bf16 v[32:35], v[112:115], v[92:95], v[32:35]
	v_mfma_f32_16x16x32_bf16 v[44:47], v[116:119], v[92:95], v[44:47]
	v_mfma_f32_16x16x32_bf16 v[16:19], v[148:151], v[92:95], v[16:19]
	v_mfma_f32_16x16x32_bf16 v[76:79], v[136:139], v[92:95], v[76:79]
	s_waitcnt vmcnt(5)
	ds_write_b128 v3, v[100:103] offset:40960
	ds_read_b128 v[92:95], v5 offset:4096
	ds_read_b128 v[100:103], v6 offset:20480
	v_mfma_f32_16x16x32_bf16 v[36:39], v[112:115], v[120:123], v[36:39]
	v_mfma_f32_16x16x32_bf16 v[48:51], v[116:119], v[120:123], v[48:51]
	v_mfma_f32_16x16x32_bf16 v[60:63], v[136:139], v[120:123], v[60:63]
	v_mfma_f32_16x16x32_bf16 v[20:23], v[148:151], v[120:123], v[20:23]
	s_waitcnt vmcnt(4)
; template <int MODE>
; __device__ __forceinline__ void gemm_tile(const Params& P, int tm, int tn, unsigned char* smem) {
;     ...
; #pragma unroll
;         for (int i = 0; i < 4; ++i) { fa[i] = *(const bf16x8*)(sA + arow_off + i * 2048 + ch0); fb[i] = *(const bf16x8*)(sB + brow_off + i * 2048 + ch0); }
;         __builtin_amdgcn_sched_barrier(0);
;         __builtin_amdgcn_s_setprio(2);
;         if (wr_ok) *(uint4*)(nA + soff0) = ra0;
;         if (ld_ok) ra0 = *(const uint4*)(Ab + (aoff + 0u * LDA + koa));
;         ga[0] = *(const bf16x8*)(sA + arow_off + 0 * 2048 + ch1); gb[0] = *(const bf16x8*)(sB + brow_off + 0 * 2048 + ch1);
;         __builtin_amdgcn_sched_barrier(0);
; #pragma unroll
;         for (int j = 0; j < 4; ++j) acc[0][j] = __builtin_amdgcn_mfma_f32_16x16x32_bf16(fb[j], fa[0], acc[0][j], 0, 0, 0);
;         __builtin_amdgcn_sched_barrier(0);
;         if (wr_ok) *(uint4*)(nA + soff0 + 4096) = ra1;
;         if (ld_ok) ra1 = *(const uint4*)(Ab + (aoff + 32u * LDA + koa));
;         ga[1] = *(const bf16x8*)(sA + arow_off + 1 * 2048 + ch1); gb[1] = *(const bf16x8*)(sB + brow_off + 1 * 2048 + ch1);
;         __builtin_amdgcn_sched_barrier(0);
; #pragma unroll
;         for (int j = 0; j < 4; ++j) acc[1][j] = __builtin_amdgcn_mfma_f32_16x16x32_bf16(fb[j], fa[1], acc[1][j], 0, 0, 0);
;         __builtin_amdgcn_sched_barrier(0);
;         if (wr_ok) *(uint4*)(nA + soff0 + 8192) = ra2;
;         if (ld_ok) ra2 = *(const uint4*)(Ab + (aoff + 64u * LDA + koa));
;         ga[2] = *(const bf16x8*)(sA + arow_off + 2 * 2048 + ch1); gb[2] = *(const bf16x8*)(sB + brow_off + 2 * 2048 + ch1);
;         __builtin_amdgcn_sched_barrier(0);
; #pragma unroll
;         for (int j = 0; j < 4; ++j) acc[2][j] = __builtin_amdgcn_mfma_f32_16x16x32_bf16(fb[j], fa[2], acc[2][j], 0, 0, 0);
;         __builtin_amdgcn_sched_barrier(0);
;         if (wr_ok) *(uint4*)(nA + soff0 + 12288) = ra3;
;         if (ld_ok) ra3 = *(const uint4*)(Ab + (aoff + 96u * LDA + koa));
;         ga[3] = *(const bf16x8*)(sA + arow_off + 3 * 2048 + ch1); gb[3] = *(const bf16x8*)(sB + brow_off + 3 * 2048 + ch1);
;         __builtin_amdgcn_sched_barrier(0);
; #pragma unroll
;         for (int j = 0; j < 4; ++j) acc[3][j] = __builtin_amdgcn_mfma_f32_16x16x32_bf16(fb[j], fa[3], acc[3][j], 0, 0, 0);
;         __builtin_amdgcn_sched_barrier(0);
;         if (wr_ok) *(uint4*)(nB + soff0) = rb0;
	ds_write_b128 v3, v[124:127] offset:45056
	ds_read_b128 v[120:123], v5 offset:6144
	ds_read_b128 v[124:127], v6 offset:22528
	v_mfma_f32_16x16x32_bf16 v[40:43], v[112:115], v[132:135], v[40:43]
	v_mfma_f32_16x16x32_bf16 v[52:55], v[116:119], v[132:135], v[52:55]
	v_mfma_f32_16x16x32_bf16 v[56:59], v[136:139], v[132:135], v[56:59]
	v_mfma_f32_16x16x32_bf16 v[24:27], v[148:151], v[132:135], v[24:27]
	s_waitcnt vmcnt(3)
	ds_write_b128 v3, v[108:111] offset:49152
	s_waitcnt lgkmcnt(10)
	v_mfma_f32_16x16x32_bf16 v[28:31], v[156:159], v[152:155], v[28:31]
	s_waitcnt lgkmcnt(4)
	v_mfma_f32_16x16x32_bf16 v[80:83], v[100:103], v[152:155], v[80:83]
	s_waitcnt lgkmcnt(1)
	v_mfma_f32_16x16x32_bf16 v[12:15], v[124:127], v[152:155], v[12:15]
	v_mfma_f32_16x16x32_bf16 v[72:75], v[84:87], v[152:155], v[72:75]
	s_waitcnt vmcnt(2)
	ds_write_b128 v3, v[104:107] offset:53248
	v_mfma_f32_16x16x32_bf16 v[32:35], v[156:159], v[64:67], v[32:35]
	v_mfma_f32_16x16x32_bf16 v[44:47], v[84:87], v[64:67], v[44:47]
	v_mfma_f32_16x16x32_bf16 v[16:19], v[124:127], v[64:67], v[16:19]
	v_mfma_f32_16x16x32_bf16 v[76:79], v[100:103], v[64:67], v[76:79]
	s_waitcnt vmcnt(1)
	ds_write_b128 v3, v[68:71] offset:57344
	v_mfma_f32_16x16x32_bf16 v[36:39], v[156:159], v[92:95], v[36:39]
	v_mfma_f32_16x16x32_bf16 v[48:51], v[84:87], v[92:95], v[48:51]
	v_mfma_f32_16x16x32_bf16 v[60:63], v[100:103], v[92:95], v[60:63]
	v_mfma_f32_16x16x32_bf16 v[20:23], v[124:127], v[92:95], v[20:23]
	s_waitcnt vmcnt(0)
	ds_write_b128 v3, v[88:91] offset:61440
	v_mfma_f32_16x16x32_bf16 v[40:43], v[156:159], v[120:123], v[40:43]
	v_mfma_f32_16x16x32_bf16 v[52:55], v[84:87], v[120:123], v[52:55]
	v_mfma_f32_16x16x32_bf16 v[56:59], v[100:103], v[120:123], v[56:59]
	v_mfma_f32_16x16x32_bf16 v[24:27], v[124:127], v[120:123], v[24:27]
	s_setprio 0
	s_waitcnt lgkmcnt(0)
	s_barrier
	ds_read_b128 v[64:67], v7 offset:32768
	ds_read_b128 v[68:71], v7 offset:34816
	ds_read_b128 v[84:87], v8 offset:49152
	ds_read_b128 v[88:91], v8 offset:51200
	ds_read_b128 v[92:95], v7 offset:36864
	ds_read_b128 v[100:103], v7 offset:38912
	ds_read_b128 v[104:107], v8 offset:53248
	ds_read_b128 v[108:111], v8 offset:55296
	s_setprio 2
	ds_read_b128 v[112:115], v5 offset:32768
	ds_read_b128 v[116:119], v6 offset:49152
	s_waitcnt lgkmcnt(7)
	v_mfma_f32_16x16x32_bf16 v[28:31], v[84:87], v[64:67], v[28:31]
	s_waitcnt lgkmcnt(3)
	v_mfma_f32_16x16x32_bf16 v[80:83], v[104:107], v[64:67], v[80:83]
	s_waitcnt lgkmcnt(2)
	v_mfma_f32_16x16x32_bf16 v[12:15], v[108:111], v[64:67], v[12:15]
	v_mfma_f32_16x16x32_bf16 v[72:75], v[88:91], v[64:67], v[72:75]
	ds_read_b128 v[64:67], v5 offset:34816
	ds_read_b128 v[120:123], v6 offset:51200
	v_mfma_f32_16x16x32_bf16 v[32:35], v[84:87], v[68:71], v[32:35]
	v_mfma_f32_16x16x32_bf16 v[44:47], v[88:91], v[68:71], v[44:47]
	v_mfma_f32_16x16x32_bf16 v[16:19], v[108:111], v[68:71], v[16:19]
	v_mfma_f32_16x16x32_bf16 v[76:79], v[104:107], v[68:71], v[76:79]
	ds_read_b128 v[124:127], v5 offset:36864
	ds_read_b128 v[132:135], v6 offset:53248
	v_mfma_f32_16x16x32_bf16 v[36:39], v[84:87], v[92:95], v[36:39]
	v_mfma_f32_16x16x32_bf16 v[48:51], v[88:91], v[92:95], v[48:51]
	v_mfma_f32_16x16x32_bf16 v[20:23], v[108:111], v[92:95], v[20:23]
	v_mfma_f32_16x16x32_bf16 v[136:139], v[104:107], v[92:95], v[60:63]
	ds_read_b128 v[148:151], v5 offset:38912
	ds_read_b128 v[4:7], v6 offset:55296
	v_mfma_f32_16x16x32_bf16 v[40:43], v[84:87], v[100:103], v[40:43]
	v_mfma_f32_16x16x32_bf16 v[152:155], v[88:91], v[100:103], v[52:55]
	v_mfma_f32_16x16x32_bf16 v[104:107], v[104:107], v[100:103], v[56:59]
	v_mfma_f32_16x16x32_bf16 v[100:103], v[108:111], v[100:103], v[24:27]
	s_waitcnt lgkmcnt(6)
	v_mfma_f32_16x16x32_bf16 v[108:111], v[116:119], v[112:115], v[28:31]
	s_waitcnt lgkmcnt(4)
	v_mfma_f32_16x16x32_bf16 v[70:73], v[120:123], v[112:115], v[72:75]
	s_waitcnt lgkmcnt(2)
	v_mfma_f32_16x16x32_bf16 v[156:159], v[132:135], v[112:115], v[80:83]
	s_waitcnt lgkmcnt(0)
	v_mfma_f32_16x16x32_bf16 v[160:163], v[4:7], v[112:115], v[12:15]
	v_mfma_f32_16x16x32_bf16 v[94:97], v[116:119], v[64:67], v[32:35]
	v_mfma_f32_16x16x32_bf16 v[90:93], v[120:123], v[64:67], v[44:47]
	v_mfma_f32_16x16x32_bf16 v[86:89], v[132:135], v[64:67], v[76:79]
	v_mfma_f32_16x16x32_bf16 v[82:85], v[4:7], v[64:67], v[16:19]
	v_mfma_f32_16x16x32_bf16 v[66:69], v[116:119], v[124:127], v[36:39]
	v_mfma_f32_16x16x32_bf16 v[62:65], v[120:123], v[124:127], v[48:51]
	v_mfma_f32_16x16x32_bf16 v[58:61], v[132:135], v[124:127], v[136:139]
	v_mfma_f32_16x16x32_bf16 v[54:57], v[4:7], v[124:127], v[20:23]
	v_mfma_f32_16x16x32_bf16 v[26:29], v[116:119], v[148:151], v[40:43]
	v_mfma_f32_16x16x32_bf16 v[22:25], v[120:123], v[148:151], v[152:155]
	v_mfma_f32_16x16x32_bf16 v[18:21], v[132:135], v[148:151], v[104:107]
	v_mfma_f32_16x16x32_bf16 v[14:17], v[4:7], v[148:151], v[100:103]
	s_setprio 0
	v_add_u32_e32 v10, s15, v10
	s_lshl_b32 s4, s4, 3
	v_or_b32_e32 v120, v10, v143
	v_lshlrev_b32_e32 v3, 2, v146
	s_add_u32 s4, s7, s4
	v_ashrrev_i32_e32 v121, 31, v120
	v_or3_b32 v2, v3, v2, s18
	s_addc_u32 s5, s8, 0
	v_lshlrev_b32_e32 v98, 2, v144
	v_lshlrev_b64 v[10:11], 12, v[120:121]
	v_lshl_add_u64 v[100:101], s[4:5], 0, v[98:99]
	v_lshlrev_b32_e32 v98, 2, v2
	v_lshl_add_u64 v[30:31], s[52:53], 0, v[10:11]
	s_barrier
; template <int MODE>
; __device__ __forceinline__ void gemm_tile(const Params& P, int tm, int tn, unsigned char* smem) {
;     ...
;         for (int i = 0; i < 4; ++i) {
;             const int row = m0 + wr * 64 + 16 * i + lr;
;             float ss = 0.f;
; #pragma unroll
;             for (int j = 0; j < 4; ++j) {
;                 const int col = n0 + wc * 64 + 16 * j + 4 * g;
;                 const float4 xv = *(const float4*)(P.x + (size_t)row * DM + col);
;                 const float4 gv = *(const float4*)(P.norm_ffn + col);
;                 float4 hv; hv.x = acc[i][j][0] + xv.x; hv.y = acc[i][j][1] + xv.y; hv.z = acc[i][j][2] + xv.z; hv.w = acc[i][j][3] + xv.w;
;                 ss += hv.x * hv.x + hv.y * hv.y + hv.z * hv.z + hv.w * hv.w;
;                 acc[i][j][0] = hv.x * gv.x; acc[i][j][1] = hv.y * gv.y; acc[i][j][2] = hv.z * gv.z; acc[i][j][3] = hv.w * gv.w;
;             }
;             ss = x4_sum(ss);
;             if (g == 0) ssq[(size_t)row * 16 + tn * 2 + wc] = ss;
	global_load_dwordx4 v[6:9], v98, s[44:45] offset:64
	global_load_dwordx4 v[2:5], v98, s[44:45]
	global_load_dwordx4 v[10:13], v98, s[44:45] offset:128
	v_lshl_add_u64 v[34:35], v[30:31], 0, v[98:99]
	global_load_dwordx4 v[30:33], v98, s[44:45] offset:192
	global_load_dwordx4 v[74:77], v[34:35], off
	global_load_dwordx4 v[78:81], v[34:35], off offset:64
	global_load_dwordx4 v[112:115], v[34:35], off offset:128
	global_load_dwordx4 v[124:127], v[34:35], off offset:192
	v_cmp_eq_u32_e32 vcc, 0, v146
	v_lshl_add_u64 v[122:123], s[44:45], 0, v[98:99]
	s_waitcnt vmcnt(4)
	v_mov_b64_e32 v[48:49], v[32:33]
	s_waitcnt vmcnt(3)
	v_pk_add_f32 v[102:103], v[108:109], v[74:75]
	s_waitcnt vmcnt(2)
	v_pk_add_f32 v[106:107], v[70:71], v[78:79]
	v_pk_add_f32 v[104:105], v[110:111], v[76:77]
	s_waitcnt vmcnt(1)
	v_pk_add_f32 v[110:111], v[156:157], v[112:113]
	v_mul_f32_e32 v46, v103, v103
	v_mul_f32_e32 v52, v107, v107
	v_pk_add_f32 v[108:109], v[72:73], v[80:81]
	v_pk_add_f32 v[112:113], v[158:159], v[114:115]
	s_waitcnt vmcnt(0)
	v_pk_add_f32 v[114:115], v[160:161], v[124:125]
	v_mul_f32_e32 v72, v111, v111
	v_pk_fma_f32 v[46:47], v[102:103], v[102:103], v[46:47] op_sel_hi:[1,1,0]
	v_pk_fma_f32 v[52:53], v[106:107], v[106:107], v[52:53] op_sel_hi:[1,1,0]
	v_mov_b32_e32 v51, v7
	v_mul_f32_e32 v50, v105, v105
	v_mul_f32_e32 v70, v109, v109
	v_mul_f32_e32 v76, v115, v115
	v_pk_fma_f32 v[72:73], v[110:111], v[110:111], v[72:73] op_sel_hi:[1,1,0]
	v_pk_fma_f32 v[46:47], v[104:105], v[104:105], v[46:47]
	v_pk_fma_f32 v[52:53], v[108:109], v[108:109], v[52:53]
	v_pk_add_f32 v[116:117], v[162:163], v[126:127]
	v_mul_f32_e32 v74, v113, v113
	v_pk_fma_f32 v[76:77], v[114:115], v[114:115], v[76:77] op_sel_hi:[1,1,0]
	v_pk_fma_f32 v[72:73], v[112:113], v[112:113], v[72:73]
	v_pk_add_f32 v[46:47], v[50:51], v[46:47] op_sel_hi:[0,1]
	v_pk_add_f32 v[52:53], v[70:71], v[52:53] op_sel_hi:[0,1]
	v_mul_f32_e32 v78, v117, v117
	v_pk_fma_f32 v[76:77], v[116:117], v[116:117], v[76:77]
	v_pk_add_f32 v[70:71], v[74:75], v[72:73] op_sel_hi:[0,1]
	v_pk_add_f32 v[46:47], v[46:47], v[52:53]
	v_pk_add_f32 v[72:73], v[78:79], v[76:77] op_sel_hi:[0,1]
	v_pk_add_f32 v[46:47], v[46:47], v[70:71]
	v_mov_b32_e32 v34, v6
	v_pk_add_f32 v[46:47], v[46:47], v[72:73]
	v_mov_b32_e32 v40, v4
	v_mov_b32_e32 v41, v46
	s_nop 1
	v_permlane32_swap_b32_e32 v46, v41
	v_add_f32_e32 v41, v46, v41
	v_mov_b32_e32 v50, v41
	v_mov_b64_e32 v[118:119], v[4:5]
	v_mov_b64_e32 v[38:39], v[2:3]
	v_mov_b32_e32 v35, v7
	v_mov_b64_e32 v[36:37], v[8:9]
	v_mov_b64_e32 v[44:45], v[12:13]
	v_mov_b64_e32 v[42:43], v[10:11]
	v_permlane16_swap_b32_e32 v41, v50
	v_mov_b64_e32 v[46:47], v[30:31]
	s_and_saveexec_b64 s[4:5], vcc
	s_cbranch_execz .LBB0_1156
	v_lshlrev_b64 v[34:35], 6, v[120:121]
	v_lshl_add_u64 v[34:35], v[100:101], 0, v[34:35]
	v_add_f32_e32 v36, v41, v50
	global_store_dword v[34:35], v36, off
	global_load_dwordx4 v[34:37], v[122:123], off offset:64
	s_nop 0
	global_load_dwordx4 v[38:41], v[122:123], off
	global_load_dwordx4 v[42:45], v[122:123], off offset:128
	global_load_dwordx4 v[46:49], v[122:123], off offset:192
	s_waitcnt vmcnt(3)
	v_mov_b32_e32 v51, v35
	s_waitcnt vmcnt(2)
	v_mov_b64_e32 v[118:119], v[40:41]

; template <int MODE>
; __device__ __forceinline__ void gemm_tile(const Params& P, int tm, int tn, unsigned char* smem) {
;     ...
;     const int tid = opaque_tid(), lane = tid & 63, wave = tid >> 6, wr = wave >> 1, wc = wave & 1, g = lane >> 4, lr = lane & 15;
;     const int m0 = tm * 128, n0 = tn * 128;
;     const int srow = tid >> 3, sc = tid & 7;
;     constexpr unsigned LDA = (MODE == 2 ? NZ : 1024) * 2u;
;     unsigned aoff, boff; int soff0;
;     {
;         int ar = m0 + srow;
;         if (MODE == 2) { const int b = ar >> 11, t = ar & 2047; ar = b * L + NMETA + t; }
;         aoff = (unsigned)ar * LDA + (unsigned)sc * 16u;
;         boff = (unsigned)(n0 + srow) * 2048u + (unsigned)sc * 16u;
;         soff0 = srow * 128 + ((sc ^ (srow & 7)) << 4);
;     }
;     const unsigned char* Ab = (const unsigned char*)A; const unsigned char* Bb = (const unsigned char*)Bt;
;     float4 ssp0, ssp1, ssp2, ssp3;
;     if (MODE == 3) {
;         const float* ssq = (const float*)(P.ws + WS_SSQ) + (size_t)(m0 + wr * 64 + lr) * 16 + 4 * g;
;         ssp0 = *(const float4*)(ssq); ssp1 = *(const float4*)(ssq + 16 * 16); ssp2 = *(const float4*)(ssq + 32 * 16); ssp3 = *(const float4*)(ssq + 48 * 16);
;     }
;     f32x4 acc[4][4];
; #pragma unroll
;     for (int i = 0; i < 4; ++i)
; #pragma unroll
;         for (int j = 0; j < 4; ++j) acc[i][j] = (f32x4){0.f, 0.f, 0.f, 0.f};
;     uint4 ra0, ra1, ra2, ra3, rb0, rb1, rb2, rb3;
;     ...
;     unsigned char* sA0 = smem; unsigned char* sB0 = smem + 16384; unsigned char* sA1 = smem + 32768; unsigned char* sB1 = smem + 49152;
;     G_LOAD(0)
;     G_WRITE(sA0, sB0)
;     __syncthreads();
;     const int arow_off = (wr * 64 + lr) * 128, brow_off = (wc * 64 + lr) * 128, sw = lr & 7;
;     G_LOAD(1)
;     for (int kt = 0; kt < 16; ++kt) {
;         unsigned char* sA = (kt & 1) ? sA1 : sA0; unsigned char* sB = (kt & 1) ? sB1 : sB0;
;         unsigned char* nA = (kt & 1) ? sA0 : sA1; unsigned char* nB = (kt & 1) ? sB0 : sB1;
;         bf16x8 fa[4], fb[4], ga[4], gb[4];
;         const int ch0 = ((g ^ sw) << 4), ch1 = (((4 + g) ^ sw) << 4);
;         const unsigned ko = (unsigned)(kt + 2) * 128u;
;         const unsigned koa = ko + ((MODE == 2 && kt + 2 >= 8) ? (unsigned)(ZC_FQ - 512) * 2u : 0u);
;         const bool wr_ok = kt < 15, ld_ok = kt < 14;
; #pragma unroll
.LBB0_1263:
	s_lshr_b32 s0, s14, 4
	s_and_b32 s0, s0, 0x1fffff8
	s_and_b32 s1, s14, 7
	s_or_b32 s0, s0, s1
	v_mov_b32_e32 v88, v0
	s_bfe_u32 s2, s14, 0x40003
	s_lshl_b32 s23, s0, 7
	v_ashrrev_i32_e32 v6, 3, v88
	v_lshlrev_b32_e32 v3, 4, v88
	v_add_u32_e32 v2, s23, v6
	v_and_b32_e32 v3, 0x70, v3
	s_lshl_b32 s0, s2, 18
	v_lshl_add_u32 v4, v6, 11, s0
	v_lshl_or_b32 v24, v2, 11, v3
	v_or_b32_e32 v18, v4, v3
	v_add_u32_e32 v2, 0x10000, v24
	v_add_u32_e32 v3, 0x20000, v24
	global_load_dwordx4 v[20:23], v2, s[36:37]
	global_load_dwordx4 v[26:29], v3, s[36:37]
	v_add_u32_e32 v2, 0x20000, v18
	v_add_u32_e32 v3, 0x30000, v18
	global_load_dwordx4 v[30:33], v2, s[6:7]
	global_load_dwordx4 v[34:37], v3, s[6:7]
	v_add_u32_e32 v2, 0x30000, v24
	v_add_u32_e32 v3, 0x10000, v18
	global_load_dwordx4 v[38:41], v2, s[36:37]
	global_load_dwordx4 v[42:45], v3, s[6:7]
	global_load_dwordx4 v[46:49], v24, s[36:37]
	global_load_dwordx4 v[50:53], v18, s[6:7]
	v_ashrrev_i32_e32 v2, 1, v88
	v_and_b32_e32 v25, 0xffffffc0, v2
	v_and_b32_e32 v90, 15, v88
	v_add_u32_e32 v2, s23, v25
	v_or_b32_e32 v84, v2, v90
	v_ashrrev_i32_e32 v85, 31, v84
	v_xor_b32_e32 v7, v6, v88
	v_bfe_u32 v89, v88, 4, 2
	v_lshlrev_b64 v[2:3], 6, v[84:85]
	v_lshlrev_b32_e32 v6, 7, v6
	v_lshlrev_b32_e32 v7, 4, v7
	v_lshlrev_b32_e32 v82, 4, v89
	v_lshl_add_u64 v[2:3], s[4:5], 0, v[2:3]
	v_and_or_b32 v6, v7, s15, v6
	v_lshl_add_u64 v[54:55], v[2:3], 0, v[82:83]
	v_add_u32_e32 v19, 0, v6
	v_or_b32_e32 v62, 0x80, v24
	global_load_dwordx4 v[10:13], v[54:55], off
	global_load_dwordx4 v[2:5], v[54:55], off offset:3072
	v_or_b32_e32 v58, 0x80, v18
	v_add_u32_e32 v59, 0x10080, v18
	v_add_u32_e32 v60, 0x20080, v18
	v_add_u32_e32 v61, 0x30080, v18
	v_add_u32_e32 v63, 0x10080, v24
	v_add_u32_e32 v64, 0x20080, v24
	v_add_u32_e32 v65, 0x30080, v24
	global_load_dwordx4 v[14:17], v[54:55], off offset:1024
	global_load_dwordx4 v[6:9], v[54:55], off offset:2048
	v_or_b32_e32 v82, v25, v90
	v_and_b32_e32 v25, 7, v88
	v_bfe_u32 v91, v88, 6, 1
	v_lshl_add_u32 v104, v82, 7, 0
	s_waitcnt vmcnt(9)
	ds_write_b128 v19, v[30:33] offset:24576
	s_waitcnt vmcnt(8)
	ds_write_b128 v19, v[34:37] offset:28672
	ds_write_b128 v19, v[20:23] offset:4096
	ds_write_b128 v19, v[26:29] offset:8192
	s_waitcnt vmcnt(7)
	ds_write_b128 v19, v[38:41] offset:12288
	s_waitcnt vmcnt(6)
	ds_write_b128 v19, v[42:45] offset:20480
	s_waitcnt vmcnt(5)
	ds_write_b128 v19, v[46:49]
	s_waitcnt vmcnt(4)
	ds_write_b128 v19, v[50:53] offset:16384
	s_waitcnt lgkmcnt(0)
	s_barrier
	global_load_dwordx4 v[26:29], v62, s[36:37]
	global_load_dwordx4 v[30:33], v63, s[36:37]
	global_load_dwordx4 v[34:37], v64, s[36:37]
	global_load_dwordx4 v[38:41], v65, s[36:37]
	global_load_dwordx4 v[42:45], v58, s[6:7]
	global_load_dwordx4 v[46:49], v59, s[6:7]
	global_load_dwordx4 v[50:53], v60, s[6:7]
	global_load_dwordx4 v[54:57], v61, s[6:7]
	v_lshrrev_b32_e32 v20, 4, v88
	v_lshlrev_b32_e32 v21, 7, v90
	v_bitop3_b32 v20, v20, v25, 3 bitop3:0x6c
	v_lshl_or_b32 v21, v91, 13, v21
	v_lshlrev_b32_e32 v20, 4, v20
	v_add_u32_e32 v22, v104, v20
	v_add_u32_e32 v21, 0, v21
	v_add_u32_e32 v23, v21, v20
	ds_read_b128 v[58:61], v22
	ds_read_b128 v[62:65], v22 offset:2048
	ds_read_b128 v[66:69], v23 offset:16384
	ds_read_b128 v[70:73], v23 offset:18432
	ds_read_b128 v[74:77], v22 offset:4096
	ds_read_b128 v[78:81], v22 offset:6144
	ds_read_b128 v[92:95], v23 offset:20480
	ds_read_b128 v[96:99], v23 offset:22528
	v_bitop3_b32 v20, v89, v25, 4 bitop3:0x36
	v_lshlrev_b32_e32 v25, 4, v20
	s_setprio 2
	global_load_dwordx4 v[100:103], v24, s[36:37] offset:256
	s_waitcnt vmcnt(8)
	ds_write_b128 v19, v[26:29] offset:32768
	v_add_u32_e32 v20, v104, v25
	v_add_u32_e32 v21, v21, v25
	ds_read_b128 v[26:29], v20
	ds_read_b128 v[104:107], v21 offset:16384
	s_waitcnt lgkmcnt(8)
	v_mfma_f32_16x16x32_bf16 v[108:111], v[66:69], v[58:61], 0
	s_waitcnt lgkmcnt(7)
	v_mfma_f32_16x16x32_bf16 v[112:115], v[70:73], v[58:61], 0
	s_waitcnt lgkmcnt(4)
	v_mfma_f32_16x16x32_bf16 v[116:119], v[92:95], v[58:61], 0
	s_waitcnt lgkmcnt(3)
	v_mfma_f32_16x16x32_bf16 v[58:61], v[96:99], v[58:61], 0
	v_add_u32_e32 v245, 0x10000, v24
	global_load_dwordx4 v[120:123], v245, s[36:37] offset:256
	s_waitcnt vmcnt(8)
	ds_write_b128 v19, v[30:33] offset:36864
	ds_read_b128 v[30:33], v20 offset:2048
	ds_read_b128 v[124:127], v21 offset:18432
	v_mfma_f32_16x16x32_bf16 v[132:135], v[66:69], v[62:65], 0
	v_mfma_f32_16x16x32_bf16 v[136:139], v[70:73], v[62:65], 0
	v_mfma_f32_16x16x32_bf16 v[140:143], v[92:95], v[62:65], 0
	v_mfma_f32_16x16x32_bf16 v[62:65], v[96:99], v[62:65], 0
	v_add_u32_e32 v246, 0x20000, v24
	global_load_dwordx4 v[144:147], v246, s[36:37] offset:256
	s_waitcnt vmcnt(8)
	ds_write_b128 v19, v[34:37] offset:40960
	ds_read_b128 v[34:37], v20 offset:4096
	ds_read_b128 v[148:151], v21 offset:20480
	v_mfma_f32_16x16x32_bf16 v[152:155], v[66:69], v[74:77], 0
	v_mfma_f32_16x16x32_bf16 v[156:159], v[70:73], v[74:77], 0
	v_mfma_f32_16x16x32_bf16 v[160:163], v[92:95], v[74:77], 0
	v_mfma_f32_16x16x32_bf16 v[74:77], v[96:99], v[74:77], 0
	v_add_u32_e32 v247, 0x30000, v24
	global_load_dwordx4 v[164:167], v247, s[36:37] offset:256
	s_waitcnt vmcnt(8)
	ds_write_b128 v19, v[38:41] offset:45056
	ds_read_b128 v[38:41], v20 offset:6144
	ds_read_b128 v[168:171], v21 offset:22528
	v_mfma_f32_16x16x32_bf16 v[66:69], v[66:69], v[78:81], 0
	v_mfma_f32_16x16x32_bf16 v[70:73], v[70:73], v[78:81], 0
	v_mfma_f32_16x16x32_bf16 v[92:95], v[92:95], v[78:81], 0
	v_mfma_f32_16x16x32_bf16 v[78:81], v[96:99], v[78:81], 0
	global_load_dwordx4 v[96:99], v18, s[6:7] offset:256
	s_waitcnt vmcnt(8)
	ds_write_b128 v19, v[42:45] offset:49152
	s_waitcnt lgkmcnt(10)
; template <int MODE>
; __device__ __forceinline__ void gemm_tile(const Params& P, int tm, int tn, unsigned char* smem) {
;     ...
;     for (int kt = 0; kt < 16; ++kt) {
;         unsigned char* sA = (kt & 1) ? sA1 : sA0; unsigned char* sB = (kt & 1) ? sB1 : sB0;
;         unsigned char* nA = (kt & 1) ? sA0 : sA1; unsigned char* nB = (kt & 1) ? sB0 : sB1;
;         bf16x8 fa[4], fb[4], ga[4], gb[4];
;         const int ch0 = ((g ^ sw) << 4), ch1 = (((4 + g) ^ sw) << 4);
;         const unsigned ko = (unsigned)(kt + 2) * 128u;
;         const unsigned koa = ko + ((MODE == 2 && kt + 2 >= 8) ? (unsigned)(ZC_FQ - 512) * 2u : 0u);
;         const bool wr_ok = kt < 15, ld_ok = kt < 14;
; #pragma unroll
;         for (int i = 0; i < 4; ++i) { fa[i] = *(const bf16x8*)(sA + arow_off + i * 2048 + ch0); fb[i] = *(const bf16x8*)(sB + brow_off + i * 2048 + ch0); }
;         __builtin_amdgcn_sched_barrier(0);
;         __builtin_amdgcn_s_setprio(2);
;         if (wr_ok) *(uint4*)(nA + soff0) = ra0;
;         if (ld_ok) ra0 = *(const uint4*)(Ab + (aoff + 0u * LDA + koa));
;         ga[0] = *(const bf16x8*)(sA + arow_off + 0 * 2048 + ch1); gb[0] = *(const bf16x8*)(sB + brow_off + 0 * 2048 + ch1);
;         __builtin_amdgcn_sched_barrier(0);
; #pragma unroll
;         for (int j = 0; j < 4; ++j) acc[0][j] = __builtin_amdgcn_mfma_f32_16x16x32_bf16(fb[j], fa[0], acc[0][j], 0, 0, 0);
;         __builtin_amdgcn_sched_barrier(0);
;         if (wr_ok) *(uint4*)(nA + soff0 + 4096) = ra1;
;         if (ld_ok) ra1 = *(const uint4*)(Ab + (aoff + 32u * LDA + koa));
;         ga[1] = *(const bf16x8*)(sA + arow_off + 1 * 2048 + ch1); gb[1] = *(const bf16x8*)(sB + brow_off + 1 * 2048 + ch1);
;         __builtin_amdgcn_sched_barrier(0);
; #pragma unroll
;         for (int j = 0; j < 4; ++j) acc[1][j] = __builtin_amdgcn_mfma_f32_16x16x32_bf16(fb[j], fa[1], acc[1][j], 0, 0, 0);
;         __builtin_amdgcn_sched_barrier(0);
;         if (wr_ok) *(uint4*)(nA + soff0 + 8192) = ra2;
;         if (ld_ok) ra2 = *(const uint4*)(Ab + (aoff + 64u * LDA + koa));
;         ga[2] = *(const bf16x8*)(sA + arow_off + 2 * 2048 + ch1); gb[2] = *(const bf16x8*)(sB + brow_off + 2 * 2048 + ch1);
;         __builtin_amdgcn_sched_barrier(0);
; #pragma unroll
;         for (int j = 0; j < 4; ++j) acc[2][j] = __builtin_amdgcn_mfma_f32_16x16x32_bf16(fb[j], fa[2], acc[2][j], 0, 0, 0);
	v_mfma_f32_16x16x32_bf16 v[42:45], v[104:107], v[26:29], v[108:111]
	s_waitcnt lgkmcnt(7)
	v_mfma_f32_16x16x32_bf16 v[108:111], v[124:127], v[26:29], v[112:115]
	s_waitcnt lgkmcnt(4)
	v_mfma_f32_16x16x32_bf16 v[112:115], v[148:151], v[26:29], v[116:119]
	s_waitcnt lgkmcnt(1)
	v_mfma_f32_16x16x32_bf16 v[26:29], v[168:171], v[26:29], v[58:61]
	v_add_u32_e32 v248, 0x10000, v18
	global_load_dwordx4 v[58:61], v248, s[6:7] offset:256
	s_waitcnt vmcnt(8)
	ds_write_b128 v19, v[46:49] offset:53248
	v_mfma_f32_16x16x32_bf16 v[46:49], v[104:107], v[30:33], v[132:135]
	v_mfma_f32_16x16x32_bf16 v[116:119], v[124:127], v[30:33], v[136:139]
	v_mfma_f32_16x16x32_bf16 v[132:135], v[148:151], v[30:33], v[140:143]
	v_mfma_f32_16x16x32_bf16 v[30:33], v[168:171], v[30:33], v[62:65]
	v_add_u32_e32 v249, 0x20000, v18
	global_load_dwordx4 v[62:65], v249, s[6:7] offset:256
	s_waitcnt vmcnt(8)
	ds_write_b128 v19, v[50:53] offset:57344
	v_mfma_f32_16x16x32_bf16 v[50:53], v[104:107], v[34:37], v[152:155]
	v_mfma_f32_16x16x32_bf16 v[136:139], v[124:127], v[34:37], v[156:159]
	v_mfma_f32_16x16x32_bf16 v[140:143], v[148:151], v[34:37], v[160:163]
	v_mfma_f32_16x16x32_bf16 v[34:37], v[168:171], v[34:37], v[74:77]
	v_add_u32_e32 v250, 0x30000, v18
	global_load_dwordx4 v[74:77], v250, s[6:7] offset:256
	s_waitcnt vmcnt(8)
	ds_write_b128 v19, v[54:57] offset:61440
	v_mfma_f32_16x16x32_bf16 v[54:57], v[104:107], v[38:41], v[66:69]
	v_mfma_f32_16x16x32_bf16 v[66:69], v[124:127], v[38:41], v[70:73]
	v_mfma_f32_16x16x32_bf16 v[70:73], v[148:151], v[38:41], v[92:95]
	v_mfma_f32_16x16x32_bf16 v[38:41], v[168:171], v[38:41], v[78:81]
	s_setprio 0
	s_waitcnt lgkmcnt(0)
	s_barrier
	ds_read_b128 v[78:81], v22 offset:32768
	ds_read_b128 v[92:95], v22 offset:34816
	ds_read_b128 v[104:107], v23 offset:49152
	ds_read_b128 v[124:127], v23 offset:51200
	ds_read_b128 v[148:151], v22 offset:36864
	ds_read_b128 v[152:155], v22 offset:38912
	ds_read_b128 v[156:159], v23 offset:53248
	ds_read_b128 v[160:163], v23 offset:55296
	s_setprio 2
	global_load_dwordx4 v[168:171], v24, s[36:37] offset:384
	s_waitcnt vmcnt(8)
	ds_write_b128 v19, v[100:103]
	ds_read_b128 v[100:103], v20 offset:32768
	ds_read_b128 v[172:175], v21 offset:49152
	s_waitcnt lgkmcnt(8)
	v_mfma_f32_16x16x32_bf16 v[42:45], v[104:107], v[78:81], v[42:45]
	s_waitcnt lgkmcnt(3)
	v_mfma_f32_16x16x32_bf16 v[26:29], v[160:163], v[78:81], v[26:29]
	v_mfma_f32_16x16x32_bf16 v[108:111], v[124:127], v[78:81], v[108:111]
	v_mfma_f32_16x16x32_bf16 v[112:115], v[156:159], v[78:81], v[112:115]
	global_load_dwordx4 v[78:81], v245, s[36:37] offset:384
	s_waitcnt vmcnt(8)
	ds_write_b128 v19, v[120:123] offset:4096
	ds_read_b128 v[120:123], v20 offset:34816
	ds_read_b128 v[176:179], v21 offset:51200
	v_mfma_f32_16x16x32_bf16 v[46:49], v[104:107], v[92:95], v[46:49]
	v_mfma_f32_16x16x32_bf16 v[30:33], v[160:163], v[92:95], v[30:33]
	v_mfma_f32_16x16x32_bf16 v[116:119], v[124:127], v[92:95], v[116:119]
	v_mfma_f32_16x16x32_bf16 v[132:135], v[156:159], v[92:95], v[132:135]
	global_load_dwordx4 v[92:95], v246, s[36:37] offset:384
	s_waitcnt vmcnt(8)
	ds_write_b128 v19, v[144:147] offset:8192
	ds_read_b128 v[144:147], v20 offset:36864
	ds_read_b128 v[180:183], v21 offset:53248
	v_mfma_f32_16x16x32_bf16 v[50:53], v[104:107], v[148:151], v[50:53]
	v_mfma_f32_16x16x32_bf16 v[34:37], v[160:163], v[148:151], v[34:37]
	v_mfma_f32_16x16x32_bf16 v[136:139], v[124:127], v[148:151], v[136:139]
	v_mfma_f32_16x16x32_bf16 v[140:143], v[156:159], v[148:151], v[140:143]
	global_load_dwordx4 v[148:151], v247, s[36:37] offset:384
	s_waitcnt vmcnt(8)
	ds_write_b128 v19, v[164:167] offset:12288
	ds_read_b128 v[164:167], v20 offset:38912
	ds_read_b128 v[184:187], v21 offset:55296
	v_mfma_f32_16x16x32_bf16 v[54:57], v[104:107], v[152:155], v[54:57]
	v_mfma_f32_16x16x32_bf16 v[66:69], v[124:127], v[152:155], v[66:69]
	v_mfma_f32_16x16x32_bf16 v[70:73], v[156:159], v[152:155], v[70:73]
	v_mfma_f32_16x16x32_bf16 v[38:41], v[160:163], v[152:155], v[38:41]
	global_load_dwordx4 v[104:107], v18, s[6:7] offset:384
	s_waitcnt vmcnt(8)
	ds_write_b128 v19, v[96:99] offset:16384
	s_waitcnt lgkmcnt(10)
	v_mfma_f32_16x16x32_bf16 v[42:45], v[172:175], v[100:103], v[42:45]
	s_waitcnt lgkmcnt(1)
	v_mfma_f32_16x16x32_bf16 v[26:29], v[184:187], v[100:103], v[26:29]
	v_mfma_f32_16x16x32_bf16 v[96:99], v[176:179], v[100:103], v[108:111]
	v_mfma_f32_16x16x32_bf16 v[108:111], v[180:183], v[100:103], v[112:115]
	global_load_dwordx4 v[100:103], v248, s[6:7] offset:384
	s_waitcnt vmcnt(8)
	ds_write_b128 v19, v[58:61] offset:20480
	v_mfma_f32_16x16x32_bf16 v[46:49], v[172:175], v[120:123], v[46:49]
	v_mfma_f32_16x16x32_bf16 v[58:61], v[176:179], v[120:123], v[116:119]
	v_mfma_f32_16x16x32_bf16 v[30:33], v[184:187], v[120:123], v[30:33]
	v_mfma_f32_16x16x32_bf16 v[112:115], v[180:183], v[120:123], v[132:135]
	global_load_dwordx4 v[116:119], v249, s[6:7] offset:384
	s_waitcnt vmcnt(8)
	ds_write_b128 v19, v[62:65] offset:24576
	v_mfma_f32_16x16x32_bf16 v[50:53], v[172:175], v[144:147], v[50:53]
	v_mfma_f32_16x16x32_bf16 v[62:65], v[176:179], v[144:147], v[136:139]
	v_mfma_f32_16x16x32_bf16 v[34:37], v[184:187], v[144:147], v[34:37]
	v_mfma_f32_16x16x32_bf16 v[120:123], v[180:183], v[144:147], v[140:143]
	global_load_dwordx4 v[124:127], v250, s[6:7] offset:384
	s_waitcnt vmcnt(8)
	ds_write_b128 v19, v[74:77] offset:28672
	v_mfma_f32_16x16x32_bf16 v[54:57], v[172:175], v[164:167], v[54:57]
	v_mfma_f32_16x16x32_bf16 v[66:69], v[176:179], v[164:167], v[66:69]
	v_mfma_f32_16x16x32_bf16 v[70:73], v[180:183], v[164:167], v[70:73]
	v_mfma_f32_16x16x32_bf16 v[38:41], v[184:187], v[164:167], v[38:41]
	s_setprio 0
	s_waitcnt lgkmcnt(0)
	s_barrier
; template <int MODE>
; __device__ __forceinline__ void gemm_tile(const Params& P, int tm, int tn, unsigned char* smem) {
;     ...
;     for (int kt = 0; kt < 16; ++kt) {
;         unsigned char* sA = (kt & 1) ? sA1 : sA0; unsigned char* sB = (kt & 1) ? sB1 : sB0;
;         unsigned char* nA = (kt & 1) ? sA0 : sA1; unsigned char* nB = (kt & 1) ? sB0 : sB1;
;         bf16x8 fa[4], fb[4], ga[4], gb[4];
;         const int ch0 = ((g ^ sw) << 4), ch1 = (((4 + g) ^ sw) << 4);
;         const unsigned ko = (unsigned)(kt + 2) * 128u;
;         const unsigned koa = ko + ((MODE == 2 && kt + 2 >= 8) ? (unsigned)(ZC_FQ - 512) * 2u : 0u);
;         const bool wr_ok = kt < 15, ld_ok = kt < 14;
; #pragma unroll
;         for (int i = 0; i < 4; ++i) { fa[i] = *(const bf16x8*)(sA + arow_off + i * 2048 + ch0); fb[i] = *(const bf16x8*)(sB + brow_off + i * 2048 + ch0); }
;         __builtin_amdgcn_sched_barrier(0);
;         __builtin_amdgcn_s_setprio(2);
;         if (wr_ok) *(uint4*)(nA + soff0) = ra0;
;         if (ld_ok) ra0 = *(const uint4*)(Ab + (aoff + 0u * LDA + koa));
;         ga[0] = *(const bf16x8*)(sA + arow_off + 0 * 2048 + ch1); gb[0] = *(const bf16x8*)(sB + brow_off + 0 * 2048 + ch1);
;         __builtin_amdgcn_sched_barrier(0);
; #pragma unroll
;         for (int j = 0; j < 4; ++j) acc[0][j] = __builtin_amdgcn_mfma_f32_16x16x32_bf16(fb[j], fa[0], acc[0][j], 0, 0, 0);
;         __builtin_amdgcn_sched_barrier(0);
;         if (wr_ok) *(uint4*)(nA + soff0 + 4096) = ra1;
;         if (ld_ok) ra1 = *(const uint4*)(Ab + (aoff + 32u * LDA + koa));
;         ga[1] = *(const bf16x8*)(sA + arow_off + 1 * 2048 + ch1); gb[1] = *(const bf16x8*)(sB + brow_off + 1 * 2048 + ch1);
;         __builtin_amdgcn_sched_barrier(0);
; #pragma unroll
;         for (int j = 0; j < 4; ++j) acc[1][j] = __builtin_amdgcn_mfma_f32_16x16x32_bf16(fb[j], fa[1], acc[1][j], 0, 0, 0);
;         __builtin_amdgcn_sched_barrier(0);
;         if (wr_ok) *(uint4*)(nA + soff0 + 8192) = ra2;
;         if (ld_ok) ra2 = *(const uint4*)(Ab + (aoff + 64u * LDA + koa));
;         ga[2] = *(const bf16x8*)(sA + arow_off + 2 * 2048 + ch1); gb[2] = *(const bf16x8*)(sB + brow_off + 2 * 2048 + ch1);
;         __builtin_amdgcn_sched_barrier(0);
; #pragma unroll
;         for (int j = 0; j < 4; ++j) acc[2][j] = __builtin_amdgcn_mfma_f32_16x16x32_bf16(fb[j], fa[2], acc[2][j], 0, 0, 0);
	ds_read_b128 v[74:77], v22
	ds_read_b128 v[132:135], v22 offset:2048
	ds_read_b128 v[136:139], v23 offset:16384
	ds_read_b128 v[140:143], v23 offset:18432
	ds_read_b128 v[144:147], v22 offset:4096
	ds_read_b128 v[152:155], v22 offset:6144
	ds_read_b128 v[156:159], v23 offset:20480
	ds_read_b128 v[160:163], v23 offset:22528
	s_setprio 2
	global_load_dwordx4 v[164:167], v24, s[36:37] offset:512
	s_waitcnt vmcnt(8)
	ds_write_b128 v19, v[168:171] offset:32768
	ds_read_b128 v[168:171], v20
	ds_read_b128 v[172:175], v21 offset:16384
	s_waitcnt lgkmcnt(8)
	v_mfma_f32_16x16x32_bf16 v[42:45], v[136:139], v[74:77], v[42:45]
	s_waitcnt lgkmcnt(3)
	v_mfma_f32_16x16x32_bf16 v[26:29], v[160:163], v[74:77], v[26:29]
	v_mfma_f32_16x16x32_bf16 v[96:99], v[140:143], v[74:77], v[96:99]
	v_mfma_f32_16x16x32_bf16 v[108:111], v[156:159], v[74:77], v[108:111]
	global_load_dwordx4 v[74:77], v245, s[36:37] offset:512
	s_waitcnt vmcnt(8)
	ds_write_b128 v19, v[78:81] offset:36864
	ds_read_b128 v[78:81], v20 offset:2048
	ds_read_b128 v[176:179], v21 offset:18432
	v_mfma_f32_16x16x32_bf16 v[46:49], v[136:139], v[132:135], v[46:49]
	v_mfma_f32_16x16x32_bf16 v[58:61], v[140:143], v[132:135], v[58:61]
	v_mfma_f32_16x16x32_bf16 v[30:33], v[160:163], v[132:135], v[30:33]
	v_mfma_f32_16x16x32_bf16 v[112:115], v[156:159], v[132:135], v[112:115]
	global_load_dwordx4 v[132:135], v246, s[36:37] offset:512
	s_waitcnt vmcnt(8)
	ds_write_b128 v19, v[92:95] offset:40960
	ds_read_b128 v[92:95], v20 offset:4096
	ds_read_b128 v[180:183], v21 offset:20480
	v_mfma_f32_16x16x32_bf16 v[50:53], v[136:139], v[144:147], v[50:53]
	v_mfma_f32_16x16x32_bf16 v[62:65], v[140:143], v[144:147], v[62:65]
	v_mfma_f32_16x16x32_bf16 v[34:37], v[160:163], v[144:147], v[34:37]
	v_mfma_f32_16x16x32_bf16 v[120:123], v[156:159], v[144:147], v[120:123]
	global_load_dwordx4 v[144:147], v247, s[36:37] offset:512
	s_waitcnt vmcnt(8)
	ds_write_b128 v19, v[148:151] offset:45056
	ds_read_b128 v[148:151], v20 offset:6144
	ds_read_b128 v[184:187], v21 offset:22528
	v_mfma_f32_16x16x32_bf16 v[54:57], v[136:139], v[152:155], v[54:57]
	v_mfma_f32_16x16x32_bf16 v[66:69], v[140:143], v[152:155], v[66:69]
	v_mfma_f32_16x16x32_bf16 v[70:73], v[156:159], v[152:155], v[70:73]
	v_mfma_f32_16x16x32_bf16 v[38:41], v[160:163], v[152:155], v[38:41]
	global_load_dwordx4 v[136:139], v18, s[6:7] offset:512
	s_waitcnt vmcnt(8)
	ds_write_b128 v19, v[104:107] offset:49152
	s_waitcnt lgkmcnt(10)
	v_mfma_f32_16x16x32_bf16 v[42:45], v[172:175], v[168:171], v[42:45]
	s_waitcnt lgkmcnt(1)
	v_mfma_f32_16x16x32_bf16 v[26:29], v[184:187], v[168:171], v[26:29]
	v_mfma_f32_16x16x32_bf16 v[96:99], v[176:179], v[168:171], v[96:99]
	v_mfma_f32_16x16x32_bf16 v[104:107], v[180:183], v[168:171], v[108:111]
	global_load_dwordx4 v[108:111], v248, s[6:7] offset:512
	s_waitcnt vmcnt(8)
	ds_write_b128 v19, v[100:103] offset:53248
	v_mfma_f32_16x16x32_bf16 v[46:49], v[172:175], v[78:81], v[46:49]
	v_mfma_f32_16x16x32_bf16 v[58:61], v[176:179], v[78:81], v[58:61]
	v_mfma_f32_16x16x32_bf16 v[30:33], v[184:187], v[78:81], v[30:33]
	v_mfma_f32_16x16x32_bf16 v[100:103], v[180:183], v[78:81], v[112:115]
	global_load_dwordx4 v[78:81], v249, s[6:7] offset:512
	s_waitcnt vmcnt(8)
	ds_write_b128 v19, v[116:119] offset:57344
	v_mfma_f32_16x16x32_bf16 v[50:53], v[172:175], v[92:95], v[50:53]
	v_mfma_f32_16x16x32_bf16 v[62:65], v[176:179], v[92:95], v[62:65]
	v_mfma_f32_16x16x32_bf16 v[34:37], v[184:187], v[92:95], v[34:37]
	v_mfma_f32_16x16x32_bf16 v[112:115], v[180:183], v[92:95], v[120:123]
	global_load_dwordx4 v[92:95], v250, s[6:7] offset:512
	s_waitcnt vmcnt(8)
	ds_write_b128 v19, v[124:127] offset:61440
	v_mfma_f32_16x16x32_bf16 v[54:57], v[172:175], v[148:151], v[54:57]
	v_mfma_f32_16x16x32_bf16 v[66:69], v[176:179], v[148:151], v[66:69]
	v_mfma_f32_16x16x32_bf16 v[70:73], v[180:183], v[148:151], v[70:73]
	v_mfma_f32_16x16x32_bf16 v[38:41], v[184:187], v[148:151], v[38:41]
	s_setprio 0
	s_waitcnt lgkmcnt(0)
	s_barrier
	ds_read_b128 v[116:119], v22 offset:32768
	ds_read_b128 v[120:123], v22 offset:34816
	ds_read_b128 v[124:127], v23 offset:49152
	ds_read_b128 v[140:143], v23 offset:51200
	ds_read_b128 v[148:151], v22 offset:36864
	ds_read_b128 v[152:155], v22 offset:38912
	ds_read_b128 v[156:159], v23 offset:53248
	ds_read_b128 v[160:163], v23 offset:55296
	s_setprio 2
	global_load_dwordx4 v[168:171], v24, s[36:37] offset:640
	s_waitcnt vmcnt(8)
	ds_write_b128 v19, v[164:167]
	ds_read_b128 v[164:167], v20 offset:32768
	ds_read_b128 v[172:175], v21 offset:49152
	s_waitcnt lgkmcnt(8)
	v_mfma_f32_16x16x32_bf16 v[42:45], v[124:127], v[116:119], v[42:45]
	s_waitcnt lgkmcnt(3)
	v_mfma_f32_16x16x32_bf16 v[26:29], v[160:163], v[116:119], v[26:29]
	v_mfma_f32_16x16x32_bf16 v[96:99], v[140:143], v[116:119], v[96:99]
	v_mfma_f32_16x16x32_bf16 v[104:107], v[156:159], v[116:119], v[104:107]
	global_load_dwordx4 v[116:119], v245, s[36:37] offset:640
	s_waitcnt vmcnt(8)
	ds_write_b128 v19, v[74:77] offset:4096
	ds_read_b128 v[74:77], v20 offset:34816
	ds_read_b128 v[176:179], v21 offset:51200
	v_mfma_f32_16x16x32_bf16 v[46:49], v[124:127], v[120:123], v[46:49]
	v_mfma_f32_16x16x32_bf16 v[58:61], v[140:143], v[120:123], v[58:61]
	v_mfma_f32_16x16x32_bf16 v[30:33], v[160:163], v[120:123], v[30:33]
	v_mfma_f32_16x16x32_bf16 v[100:103], v[156:159], v[120:123], v[100:103]
	global_load_dwordx4 v[120:123], v246, s[36:37] offset:640
	s_waitcnt vmcnt(8)
; template <int MODE>
; __device__ __forceinline__ void gemm_tile(const Params& P, int tm, int tn, unsigned char* smem) {
;     ...
;     for (int kt = 0; kt < 16; ++kt) {
;         unsigned char* sA = (kt & 1) ? sA1 : sA0; unsigned char* sB = (kt & 1) ? sB1 : sB0;
;         unsigned char* nA = (kt & 1) ? sA0 : sA1; unsigned char* nB = (kt & 1) ? sB0 : sB1;
;         bf16x8 fa[4], fb[4], ga[4], gb[4];
;         const int ch0 = ((g ^ sw) << 4), ch1 = (((4 + g) ^ sw) << 4);
;         const unsigned ko = (unsigned)(kt + 2) * 128u;
;         const unsigned koa = ko + ((MODE == 2 && kt + 2 >= 8) ? (unsigned)(ZC_FQ - 512) * 2u : 0u);
;         const bool wr_ok = kt < 15, ld_ok = kt < 14;
; #pragma unroll
;         for (int i = 0; i < 4; ++i) { fa[i] = *(const bf16x8*)(sA + arow_off + i * 2048 + ch0); fb[i] = *(const bf16x8*)(sB + brow_off + i * 2048 + ch0); }
;         __builtin_amdgcn_sched_barrier(0);
;         __builtin_amdgcn_s_setprio(2);
;         if (wr_ok) *(uint4*)(nA + soff0) = ra0;
;         if (ld_ok) ra0 = *(const uint4*)(Ab + (aoff + 0u * LDA + koa));
;         ga[0] = *(const bf16x8*)(sA + arow_off + 0 * 2048 + ch1); gb[0] = *(const bf16x8*)(sB + brow_off + 0 * 2048 + ch1);
;         __builtin_amdgcn_sched_barrier(0);
; #pragma unroll
;         for (int j = 0; j < 4; ++j) acc[0][j] = __builtin_amdgcn_mfma_f32_16x16x32_bf16(fb[j], fa[0], acc[0][j], 0, 0, 0);
;         __builtin_amdgcn_sched_barrier(0);
;         if (wr_ok) *(uint4*)(nA + soff0 + 4096) = ra1;
;         if (ld_ok) ra1 = *(const uint4*)(Ab + (aoff + 32u * LDA + koa));
;         ga[1] = *(const bf16x8*)(sA + arow_off + 1 * 2048 + ch1); gb[1] = *(const bf16x8*)(sB + brow_off + 1 * 2048 + ch1);
;         __builtin_amdgcn_sched_barrier(0);
; #pragma unroll
;         for (int j = 0; j < 4; ++j) acc[1][j] = __builtin_amdgcn_mfma_f32_16x16x32_bf16(fb[j], fa[1], acc[1][j], 0, 0, 0);
;         __builtin_amdgcn_sched_barrier(0);
;         if (wr_ok) *(uint4*)(nA + soff0 + 8192) = ra2;
;         if (ld_ok) ra2 = *(const uint4*)(Ab + (aoff + 64u * LDA + koa));
;         ga[2] = *(const bf16x8*)(sA + arow_off + 2 * 2048 + ch1); gb[2] = *(const bf16x8*)(sB + brow_off + 2 * 2048 + ch1);
;         __builtin_amdgcn_sched_barrier(0);
; #pragma unroll
;         for (int j = 0; j < 4; ++j) acc[2][j] = __builtin_amdgcn_mfma_f32_16x16x32_bf16(fb[j], fa[2], acc[2][j], 0, 0, 0);
	ds_write_b128 v19, v[132:135] offset:8192
	ds_read_b128 v[132:135], v20 offset:36864
	ds_read_b128 v[180:183], v21 offset:53248
	v_mfma_f32_16x16x32_bf16 v[50:53], v[124:127], v[148:151], v[50:53]
	v_mfma_f32_16x16x32_bf16 v[62:65], v[140:143], v[148:151], v[62:65]
	v_mfma_f32_16x16x32_bf16 v[34:37], v[160:163], v[148:151], v[34:37]
	v_mfma_f32_16x16x32_bf16 v[112:115], v[156:159], v[148:151], v[112:115]
	global_load_dwordx4 v[148:151], v247, s[36:37] offset:640
	s_waitcnt vmcnt(8)
	ds_write_b128 v19, v[144:147] offset:12288
	ds_read_b128 v[144:147], v20 offset:38912
	ds_read_b128 v[184:187], v21 offset:55296
	v_mfma_f32_16x16x32_bf16 v[54:57], v[124:127], v[152:155], v[54:57]
	v_mfma_f32_16x16x32_bf16 v[66:69], v[140:143], v[152:155], v[66:69]
	v_mfma_f32_16x16x32_bf16 v[70:73], v[156:159], v[152:155], v[70:73]
	v_mfma_f32_16x16x32_bf16 v[38:41], v[160:163], v[152:155], v[38:41]
	global_load_dwordx4 v[124:127], v18, s[6:7] offset:640
	s_waitcnt vmcnt(8)
	ds_write_b128 v19, v[136:139] offset:16384
	s_waitcnt lgkmcnt(10)
	v_mfma_f32_16x16x32_bf16 v[42:45], v[172:175], v[164:167], v[42:45]
	s_waitcnt lgkmcnt(1)
	v_mfma_f32_16x16x32_bf16 v[26:29], v[184:187], v[164:167], v[26:29]
	v_mfma_f32_16x16x32_bf16 v[96:99], v[176:179], v[164:167], v[96:99]
	v_mfma_f32_16x16x32_bf16 v[104:107], v[180:183], v[164:167], v[104:107]
	global_load_dwordx4 v[136:139], v248, s[6:7] offset:640
	s_waitcnt vmcnt(8)
	ds_write_b128 v19, v[108:111] offset:20480
	v_mfma_f32_16x16x32_bf16 v[46:49], v[172:175], v[74:77], v[46:49]
	v_mfma_f32_16x16x32_bf16 v[58:61], v[176:179], v[74:77], v[58:61]
	v_mfma_f32_16x16x32_bf16 v[30:33], v[184:187], v[74:77], v[30:33]
	v_mfma_f32_16x16x32_bf16 v[100:103], v[180:183], v[74:77], v[100:103]
	global_load_dwordx4 v[74:77], v249, s[6:7] offset:640
	s_waitcnt vmcnt(8)
	ds_write_b128 v19, v[78:81] offset:24576
	v_mfma_f32_16x16x32_bf16 v[50:53], v[172:175], v[132:135], v[50:53]
	v_mfma_f32_16x16x32_bf16 v[62:65], v[176:179], v[132:135], v[62:65]
	v_mfma_f32_16x16x32_bf16 v[78:81], v[180:183], v[132:135], v[112:115]
	v_mfma_f32_16x16x32_bf16 v[34:37], v[184:187], v[132:135], v[34:37]
	global_load_dwordx4 v[108:111], v250, s[6:7] offset:640
	s_waitcnt vmcnt(8)
	ds_write_b128 v19, v[92:95] offset:28672
	v_mfma_f32_16x16x32_bf16 v[54:57], v[172:175], v[144:147], v[54:57]
	v_mfma_f32_16x16x32_bf16 v[66:69], v[176:179], v[144:147], v[66:69]
	v_mfma_f32_16x16x32_bf16 v[70:73], v[180:183], v[144:147], v[70:73]
	v_mfma_f32_16x16x32_bf16 v[38:41], v[184:187], v[144:147], v[38:41]
	s_setprio 0
	s_waitcnt lgkmcnt(0)
	s_barrier
	ds_read_b128 v[92:95], v22
	ds_read_b128 v[112:115], v22 offset:2048
	ds_read_b128 v[132:135], v23 offset:16384
	ds_read_b128 v[140:143], v23 offset:18432
	ds_read_b128 v[144:147], v22 offset:4096
	ds_read_b128 v[152:155], v22 offset:6144
	ds_read_b128 v[156:159], v23 offset:20480
	ds_read_b128 v[160:163], v23 offset:22528
	s_setprio 2
	global_load_dwordx4 v[164:167], v24, s[36:37] offset:768
	s_waitcnt vmcnt(8)
	ds_write_b128 v19, v[168:171] offset:32768
	ds_read_b128 v[168:171], v20
	ds_read_b128 v[172:175], v21 offset:16384
	s_waitcnt lgkmcnt(8)
	v_mfma_f32_16x16x32_bf16 v[42:45], v[132:135], v[92:95], v[42:45]
	s_waitcnt lgkmcnt(3)
	v_mfma_f32_16x16x32_bf16 v[26:29], v[160:163], v[92:95], v[26:29]
	v_mfma_f32_16x16x32_bf16 v[96:99], v[140:143], v[92:95], v[96:99]
	v_mfma_f32_16x16x32_bf16 v[104:107], v[156:159], v[92:95], v[104:107]
	global_load_dwordx4 v[92:95], v245, s[36:37] offset:768
	s_waitcnt vmcnt(8)
	ds_write_b128 v19, v[116:119] offset:36864
	ds_read_b128 v[116:119], v20 offset:2048
	ds_read_b128 v[176:179], v21 offset:18432
	v_mfma_f32_16x16x32_bf16 v[46:49], v[132:135], v[112:115], v[46:49]
	v_mfma_f32_16x16x32_bf16 v[58:61], v[140:143], v[112:115], v[58:61]
	v_mfma_f32_16x16x32_bf16 v[30:33], v[160:163], v[112:115], v[30:33]
	v_mfma_f32_16x16x32_bf16 v[100:103], v[156:159], v[112:115], v[100:103]
	global_load_dwordx4 v[112:115], v246, s[36:37] offset:768
	s_waitcnt vmcnt(8)
	ds_write_b128 v19, v[120:123] offset:40960
	ds_read_b128 v[120:123], v20 offset:4096
	ds_read_b128 v[180:183], v21 offset:20480
	v_mfma_f32_16x16x32_bf16 v[50:53], v[132:135], v[144:147], v[50:53]
	v_mfma_f32_16x16x32_bf16 v[62:65], v[140:143], v[144:147], v[62:65]
	v_mfma_f32_16x16x32_bf16 v[78:81], v[156:159], v[144:147], v[78:81]
	v_mfma_f32_16x16x32_bf16 v[34:37], v[160:163], v[144:147], v[34:37]
	global_load_dwordx4 v[144:147], v247, s[36:37] offset:768
	s_waitcnt vmcnt(8)
	ds_write_b128 v19, v[148:151] offset:45056
	ds_read_b128 v[148:151], v20 offset:6144
	ds_read_b128 v[184:187], v21 offset:22528
	v_mfma_f32_16x16x32_bf16 v[54:57], v[132:135], v[152:155], v[54:57]
	v_mfma_f32_16x16x32_bf16 v[66:69], v[140:143], v[152:155], v[66:69]
	v_mfma_f32_16x16x32_bf16 v[70:73], v[156:159], v[152:155], v[70:73]
	v_mfma_f32_16x16x32_bf16 v[38:41], v[160:163], v[152:155], v[38:41]
	global_load_dwordx4 v[132:135], v18, s[6:7] offset:768
	s_waitcnt vmcnt(8)
	ds_write_b128 v19, v[124:127] offset:49152
	s_waitcnt lgkmcnt(10)
	v_mfma_f32_16x16x32_bf16 v[42:45], v[172:175], v[168:171], v[42:45]
	s_waitcnt lgkmcnt(1)
	v_mfma_f32_16x16x32_bf16 v[26:29], v[184:187], v[168:171], v[26:29]
	v_mfma_f32_16x16x32_bf16 v[96:99], v[176:179], v[168:171], v[96:99]
	v_mfma_f32_16x16x32_bf16 v[104:107], v[180:183], v[168:171], v[104:107]
	global_load_dwordx4 v[124:127], v248, s[6:7] offset:768
	s_waitcnt vmcnt(8)
	ds_write_b128 v19, v[136:139] offset:53248
	v_mfma_f32_16x16x32_bf16 v[46:49], v[172:175], v[116:119], v[46:49]
	v_mfma_f32_16x16x32_bf16 v[58:61], v[176:179], v[116:119], v[58:61]
	v_mfma_f32_16x16x32_bf16 v[30:33], v[184:187], v[116:119], v[30:33]
	v_mfma_f32_16x16x32_bf16 v[100:103], v[180:183], v[116:119], v[100:103]
	global_load_dwordx4 v[116:119], v249, s[6:7] offset:768
	s_waitcnt vmcnt(8)
	ds_write_b128 v19, v[74:77] offset:57344
	v_mfma_f32_16x16x32_bf16 v[50:53], v[172:175], v[120:123], v[50:53]
	v_mfma_f32_16x16x32_bf16 v[62:65], v[176:179], v[120:123], v[62:65]
	v_mfma_f32_16x16x32_bf16 v[74:77], v[180:183], v[120:123], v[78:81]
	v_mfma_f32_16x16x32_bf16 v[34:37], v[184:187], v[120:123], v[34:37]
	global_load_dwordx4 v[78:81], v250, s[6:7] offset:768
	s_waitcnt vmcnt(8)
	ds_write_b128 v19, v[108:111] offset:61440
	v_mfma_f32_16x16x32_bf16 v[54:57], v[172:175], v[148:151], v[54:57]
	v_mfma_f32_16x16x32_bf16 v[66:69], v[176:179], v[148:151], v[66:69]
	v_mfma_f32_16x16x32_bf16 v[70:73], v[180:183], v[148:151], v[70:73]
	v_mfma_f32_16x16x32_bf16 v[38:41], v[184:187], v[148:151], v[38:41]
	s_setprio 0
	s_waitcnt lgkmcnt(0)
	s_barrier
; template <int MODE>
; __device__ __forceinline__ void gemm_tile(const Params& P, int tm, int tn, unsigned char* smem) {
;     ...
;     for (int kt = 0; kt < 16; ++kt) {
;         unsigned char* sA = (kt & 1) ? sA1 : sA0; unsigned char* sB = (kt & 1) ? sB1 : sB0;
;         unsigned char* nA = (kt & 1) ? sA0 : sA1; unsigned char* nB = (kt & 1) ? sB0 : sB1;
;         bf16x8 fa[4], fb[4], ga[4], gb[4];
;         const int ch0 = ((g ^ sw) << 4), ch1 = (((4 + g) ^ sw) << 4);
;         const unsigned ko = (unsigned)(kt + 2) * 128u;
;         const unsigned koa = ko + ((MODE == 2 && kt + 2 >= 8) ? (unsigned)(ZC_FQ - 512) * 2u : 0u);
;         const bool wr_ok = kt < 15, ld_ok = kt < 14;
; #pragma unroll
;         for (int i = 0; i < 4; ++i) { fa[i] = *(const bf16x8*)(sA + arow_off + i * 2048 + ch0); fb[i] = *(const bf16x8*)(sB + brow_off + i * 2048 + ch0); }
;         __builtin_amdgcn_sched_barrier(0);
;         __builtin_amdgcn_s_setprio(2);
;         if (wr_ok) *(uint4*)(nA + soff0) = ra0;
;         if (ld_ok) ra0 = *(const uint4*)(Ab + (aoff + 0u * LDA + koa));
;         ga[0] = *(const bf16x8*)(sA + arow_off + 0 * 2048 + ch1); gb[0] = *(const bf16x8*)(sB + brow_off + 0 * 2048 + ch1);
;         __builtin_amdgcn_sched_barrier(0);
; #pragma unroll
;         for (int j = 0; j < 4; ++j) acc[0][j] = __builtin_amdgcn_mfma_f32_16x16x32_bf16(fb[j], fa[0], acc[0][j], 0, 0, 0);
;         __builtin_amdgcn_sched_barrier(0);
;         if (wr_ok) *(uint4*)(nA + soff0 + 4096) = ra1;
;         if (ld_ok) ra1 = *(const uint4*)(Ab + (aoff + 32u * LDA + koa));
;         ga[1] = *(const bf16x8*)(sA + arow_off + 1 * 2048 + ch1); gb[1] = *(const bf16x8*)(sB + brow_off + 1 * 2048 + ch1);
;         __builtin_amdgcn_sched_barrier(0);
; #pragma unroll
;         for (int j = 0; j < 4; ++j) acc[1][j] = __builtin_amdgcn_mfma_f32_16x16x32_bf16(fb[j], fa[1], acc[1][j], 0, 0, 0);
;         __builtin_amdgcn_sched_barrier(0);
;         if (wr_ok) *(uint4*)(nA + soff0 + 8192) = ra2;
;         if (ld_ok) ra2 = *(const uint4*)(Ab + (aoff + 64u * LDA + koa));
;         ga[2] = *(const bf16x8*)(sA + arow_off + 2 * 2048 + ch1); gb[2] = *(const bf16x8*)(sB + brow_off + 2 * 2048 + ch1);
;         __builtin_amdgcn_sched_barrier(0);
; #pragma unroll
;         for (int j = 0; j < 4; ++j) acc[2][j] = __builtin_amdgcn_mfma_f32_16x16x32_bf16(fb[j], fa[2], acc[2][j], 0, 0, 0);
	ds_read_b128 v[108:111], v22 offset:32768
	ds_read_b128 v[120:123], v22 offset:34816
	ds_read_b128 v[136:139], v23 offset:49152
	ds_read_b128 v[140:143], v23 offset:51200
	ds_read_b128 v[148:151], v22 offset:36864
	ds_read_b128 v[152:155], v22 offset:38912
	ds_read_b128 v[156:159], v23 offset:53248
	ds_read_b128 v[160:163], v23 offset:55296
	s_setprio 2
	global_load_dwordx4 v[168:171], v24, s[36:37] offset:896
	s_waitcnt vmcnt(8)
	ds_write_b128 v19, v[164:167]
	ds_read_b128 v[164:167], v20 offset:32768
	ds_read_b128 v[172:175], v21 offset:49152
	s_waitcnt lgkmcnt(8)
	v_mfma_f32_16x16x32_bf16 v[42:45], v[136:139], v[108:111], v[42:45]
	s_waitcnt lgkmcnt(3)
	v_mfma_f32_16x16x32_bf16 v[26:29], v[160:163], v[108:111], v[26:29]
	v_mfma_f32_16x16x32_bf16 v[96:99], v[140:143], v[108:111], v[96:99]
	v_mfma_f32_16x16x32_bf16 v[104:107], v[156:159], v[108:111], v[104:107]
	global_load_dwordx4 v[108:111], v245, s[36:37] offset:896
	s_waitcnt vmcnt(8)
	ds_write_b128 v19, v[92:95] offset:4096
	ds_read_b128 v[92:95], v20 offset:34816
	ds_read_b128 v[176:179], v21 offset:51200
	v_mfma_f32_16x16x32_bf16 v[46:49], v[136:139], v[120:123], v[46:49]
	v_mfma_f32_16x16x32_bf16 v[58:61], v[140:143], v[120:123], v[58:61]
	v_mfma_f32_16x16x32_bf16 v[30:33], v[160:163], v[120:123], v[30:33]
	v_mfma_f32_16x16x32_bf16 v[100:103], v[156:159], v[120:123], v[100:103]
	global_load_dwordx4 v[120:123], v246, s[36:37] offset:896
	s_waitcnt vmcnt(8)
	ds_write_b128 v19, v[112:115] offset:8192
	ds_read_b128 v[112:115], v20 offset:36864
	ds_read_b128 v[180:183], v21 offset:53248
	v_mfma_f32_16x16x32_bf16 v[50:53], v[136:139], v[148:151], v[50:53]
	v_mfma_f32_16x16x32_bf16 v[62:65], v[140:143], v[148:151], v[62:65]
	v_mfma_f32_16x16x32_bf16 v[74:77], v[156:159], v[148:151], v[74:77]
	v_mfma_f32_16x16x32_bf16 v[34:37], v[160:163], v[148:151], v[34:37]
	global_load_dwordx4 v[148:151], v247, s[36:37] offset:896
	s_waitcnt vmcnt(8)
	ds_write_b128 v19, v[144:147] offset:12288
	ds_read_b128 v[144:147], v20 offset:38912
	ds_read_b128 v[184:187], v21 offset:55296
	v_mfma_f32_16x16x32_bf16 v[54:57], v[136:139], v[152:155], v[54:57]
	v_mfma_f32_16x16x32_bf16 v[66:69], v[140:143], v[152:155], v[66:69]
	v_mfma_f32_16x16x32_bf16 v[70:73], v[156:159], v[152:155], v[70:73]
	v_mfma_f32_16x16x32_bf16 v[38:41], v[160:163], v[152:155], v[38:41]
	global_load_dwordx4 v[136:139], v18, s[6:7] offset:896
	s_waitcnt vmcnt(8)
	ds_write_b128 v19, v[132:135] offset:16384
	s_waitcnt lgkmcnt(10)
	v_mfma_f32_16x16x32_bf16 v[42:45], v[172:175], v[164:167], v[42:45]
	s_waitcnt lgkmcnt(1)
	v_mfma_f32_16x16x32_bf16 v[26:29], v[184:187], v[164:167], v[26:29]
	v_mfma_f32_16x16x32_bf16 v[96:99], v[176:179], v[164:167], v[96:99]
	v_mfma_f32_16x16x32_bf16 v[104:107], v[180:183], v[164:167], v[104:107]
	global_load_dwordx4 v[132:135], v248, s[6:7] offset:896
	s_waitcnt vmcnt(8)
	ds_write_b128 v19, v[124:127] offset:20480
	v_mfma_f32_16x16x32_bf16 v[46:49], v[172:175], v[92:95], v[46:49]
	v_mfma_f32_16x16x32_bf16 v[58:61], v[176:179], v[92:95], v[58:61]
	v_mfma_f32_16x16x32_bf16 v[30:33], v[184:187], v[92:95], v[30:33]
	v_mfma_f32_16x16x32_bf16 v[100:103], v[180:183], v[92:95], v[100:103]
	global_load_dwordx4 v[92:95], v249, s[6:7] offset:896
	s_waitcnt vmcnt(8)
	ds_write_b128 v19, v[116:119] offset:24576
	v_mfma_f32_16x16x32_bf16 v[50:53], v[172:175], v[112:115], v[50:53]
	v_mfma_f32_16x16x32_bf16 v[62:65], v[176:179], v[112:115], v[62:65]
	v_mfma_f32_16x16x32_bf16 v[74:77], v[180:183], v[112:115], v[74:77]
	v_mfma_f32_16x16x32_bf16 v[34:37], v[184:187], v[112:115], v[34:37]
	global_load_dwordx4 v[112:115], v250, s[6:7] offset:896
	s_waitcnt vmcnt(8)
	ds_write_b128 v19, v[78:81] offset:28672
	v_mfma_f32_16x16x32_bf16 v[54:57], v[172:175], v[144:147], v[54:57]
	v_mfma_f32_16x16x32_bf16 v[66:69], v[176:179], v[144:147], v[66:69]
	v_mfma_f32_16x16x32_bf16 v[70:73], v[180:183], v[144:147], v[70:73]
	v_mfma_f32_16x16x32_bf16 v[38:41], v[184:187], v[144:147], v[38:41]
	s_setprio 0
	s_waitcnt lgkmcnt(0)
	s_barrier
	ds_read_b128 v[78:81], v22
	ds_read_b128 v[116:119], v22 offset:2048
	ds_read_b128 v[124:127], v23 offset:16384
	ds_read_b128 v[140:143], v23 offset:18432
	ds_read_b128 v[144:147], v22 offset:4096
	ds_read_b128 v[152:155], v22 offset:6144
	ds_read_b128 v[156:159], v23 offset:20480
	ds_read_b128 v[160:163], v23 offset:22528
	s_setprio 2
	global_load_dwordx4 v[164:167], v24, s[36:37] offset:1024
	s_waitcnt vmcnt(8)
	ds_write_b128 v19, v[168:171] offset:32768
	ds_read_b128 v[168:171], v20
	ds_read_b128 v[172:175], v21 offset:16384
	s_waitcnt lgkmcnt(8)
	v_mfma_f32_16x16x32_bf16 v[42:45], v[124:127], v[78:81], v[42:45]
	s_waitcnt lgkmcnt(3)
	v_mfma_f32_16x16x32_bf16 v[26:29], v[160:163], v[78:81], v[26:29]
	v_mfma_f32_16x16x32_bf16 v[96:99], v[140:143], v[78:81], v[96:99]
	v_mfma_f32_16x16x32_bf16 v[104:107], v[156:159], v[78:81], v[104:107]
	global_load_dwordx4 v[78:81], v245, s[36:37] offset:1024
	s_waitcnt vmcnt(8)
	ds_write_b128 v19, v[108:111] offset:36864
	ds_read_b128 v[108:111], v20 offset:2048
	ds_read_b128 v[176:179], v21 offset:18432
	v_mfma_f32_16x16x32_bf16 v[46:49], v[124:127], v[116:119], v[46:49]
	v_mfma_f32_16x16x32_bf16 v[58:61], v[140:143], v[116:119], v[58:61]
	v_mfma_f32_16x16x32_bf16 v[30:33], v[160:163], v[116:119], v[30:33]
	v_mfma_f32_16x16x32_bf16 v[100:103], v[156:159], v[116:119], v[100:103]
	global_load_dwordx4 v[116:119], v246, s[36:37] offset:1024
	s_waitcnt vmcnt(8)
; template <int MODE>
; __device__ __forceinline__ void gemm_tile(const Params& P, int tm, int tn, unsigned char* smem) {
;     ...
;     for (int kt = 0; kt < 16; ++kt) {
;         unsigned char* sA = (kt & 1) ? sA1 : sA0; unsigned char* sB = (kt & 1) ? sB1 : sB0;
;         unsigned char* nA = (kt & 1) ? sA0 : sA1; unsigned char* nB = (kt & 1) ? sB0 : sB1;
;         bf16x8 fa[4], fb[4], ga[4], gb[4];
;         const int ch0 = ((g ^ sw) << 4), ch1 = (((4 + g) ^ sw) << 4);
;         const unsigned ko = (unsigned)(kt + 2) * 128u;
;         const unsigned koa = ko + ((MODE == 2 && kt + 2 >= 8) ? (unsigned)(ZC_FQ - 512) * 2u : 0u);
;         const bool wr_ok = kt < 15, ld_ok = kt < 14;
; #pragma unroll
;         for (int i = 0; i < 4; ++i) { fa[i] = *(const bf16x8*)(sA + arow_off + i * 2048 + ch0); fb[i] = *(const bf16x8*)(sB + brow_off + i * 2048 + ch0); }
;         __builtin_amdgcn_sched_barrier(0);
;         __builtin_amdgcn_s_setprio(2);
;         if (wr_ok) *(uint4*)(nA + soff0) = ra0;
;         if (ld_ok) ra0 = *(const uint4*)(Ab + (aoff + 0u * LDA + koa));
;         ga[0] = *(const bf16x8*)(sA + arow_off + 0 * 2048 + ch1); gb[0] = *(const bf16x8*)(sB + brow_off + 0 * 2048 + ch1);
;         __builtin_amdgcn_sched_barrier(0);
; #pragma unroll
;         for (int j = 0; j < 4; ++j) acc[0][j] = __builtin_amdgcn_mfma_f32_16x16x32_bf16(fb[j], fa[0], acc[0][j], 0, 0, 0);
;         __builtin_amdgcn_sched_barrier(0);
;         if (wr_ok) *(uint4*)(nA + soff0 + 4096) = ra1;
;         if (ld_ok) ra1 = *(const uint4*)(Ab + (aoff + 32u * LDA + koa));
;         ga[1] = *(const bf16x8*)(sA + arow_off + 1 * 2048 + ch1); gb[1] = *(const bf16x8*)(sB + brow_off + 1 * 2048 + ch1);
;         __builtin_amdgcn_sched_barrier(0);
; #pragma unroll
;         for (int j = 0; j < 4; ++j) acc[1][j] = __builtin_amdgcn_mfma_f32_16x16x32_bf16(fb[j], fa[1], acc[1][j], 0, 0, 0);
;         __builtin_amdgcn_sched_barrier(0);
;         if (wr_ok) *(uint4*)(nA + soff0 + 8192) = ra2;
;         if (ld_ok) ra2 = *(const uint4*)(Ab + (aoff + 64u * LDA + koa));
;         ga[2] = *(const bf16x8*)(sA + arow_off + 2 * 2048 + ch1); gb[2] = *(const bf16x8*)(sB + brow_off + 2 * 2048 + ch1);
;         __builtin_amdgcn_sched_barrier(0);
; #pragma unroll
;         for (int j = 0; j < 4; ++j) acc[2][j] = __builtin_amdgcn_mfma_f32_16x16x32_bf16(fb[j], fa[2], acc[2][j], 0, 0, 0);
	ds_write_b128 v19, v[120:123] offset:40960
	ds_read_b128 v[120:123], v20 offset:4096
	ds_read_b128 v[180:183], v21 offset:20480
	v_mfma_f32_16x16x32_bf16 v[50:53], v[124:127], v[144:147], v[50:53]
	v_mfma_f32_16x16x32_bf16 v[62:65], v[140:143], v[144:147], v[62:65]
	v_mfma_f32_16x16x32_bf16 v[74:77], v[156:159], v[144:147], v[74:77]
	v_mfma_f32_16x16x32_bf16 v[34:37], v[160:163], v[144:147], v[34:37]
	global_load_dwordx4 v[144:147], v247, s[36:37] offset:1024
	s_waitcnt vmcnt(8)
	ds_write_b128 v19, v[148:151] offset:45056
	ds_read_b128 v[148:151], v20 offset:6144
	ds_read_b128 v[184:187], v21 offset:22528
	v_mfma_f32_16x16x32_bf16 v[54:57], v[124:127], v[152:155], v[54:57]
	v_mfma_f32_16x16x32_bf16 v[66:69], v[140:143], v[152:155], v[66:69]
	v_mfma_f32_16x16x32_bf16 v[70:73], v[156:159], v[152:155], v[70:73]
	v_mfma_f32_16x16x32_bf16 v[38:41], v[160:163], v[152:155], v[38:41]
	global_load_dwordx4 v[124:127], v18, s[6:7] offset:1024
	s_waitcnt vmcnt(8)
	ds_write_b128 v19, v[136:139] offset:49152
	s_waitcnt lgkmcnt(10)
	v_mfma_f32_16x16x32_bf16 v[42:45], v[172:175], v[168:171], v[42:45]
	s_waitcnt lgkmcnt(1)
	v_mfma_f32_16x16x32_bf16 v[26:29], v[184:187], v[168:171], v[26:29]
	v_mfma_f32_16x16x32_bf16 v[96:99], v[176:179], v[168:171], v[96:99]
	v_mfma_f32_16x16x32_bf16 v[104:107], v[180:183], v[168:171], v[104:107]
	global_load_dwordx4 v[136:139], v248, s[6:7] offset:1024
	s_waitcnt vmcnt(8)
	ds_write_b128 v19, v[132:135] offset:53248
	v_mfma_f32_16x16x32_bf16 v[46:49], v[172:175], v[108:111], v[46:49]
	v_mfma_f32_16x16x32_bf16 v[58:61], v[176:179], v[108:111], v[58:61]
	v_mfma_f32_16x16x32_bf16 v[30:33], v[184:187], v[108:111], v[30:33]
	v_mfma_f32_16x16x32_bf16 v[100:103], v[180:183], v[108:111], v[100:103]
	global_load_dwordx4 v[108:111], v249, s[6:7] offset:1024
	s_waitcnt vmcnt(8)
	ds_write_b128 v19, v[92:95] offset:57344
	v_mfma_f32_16x16x32_bf16 v[50:53], v[172:175], v[120:123], v[50:53]
	v_mfma_f32_16x16x32_bf16 v[62:65], v[176:179], v[120:123], v[62:65]
	v_mfma_f32_16x16x32_bf16 v[74:77], v[180:183], v[120:123], v[74:77]
	v_mfma_f32_16x16x32_bf16 v[34:37], v[184:187], v[120:123], v[34:37]
	global_load_dwordx4 v[92:95], v250, s[6:7] offset:1024
	s_waitcnt vmcnt(8)
	ds_write_b128 v19, v[112:115] offset:61440
	v_mfma_f32_16x16x32_bf16 v[54:57], v[172:175], v[148:151], v[54:57]
	v_mfma_f32_16x16x32_bf16 v[66:69], v[176:179], v[148:151], v[66:69]
	v_mfma_f32_16x16x32_bf16 v[70:73], v[180:183], v[148:151], v[70:73]
	v_mfma_f32_16x16x32_bf16 v[38:41], v[184:187], v[148:151], v[38:41]
	s_setprio 0
	s_waitcnt lgkmcnt(0)
	s_barrier
	ds_read_b128 v[112:115], v22 offset:32768
	ds_read_b128 v[120:123], v22 offset:34816
	ds_read_b128 v[132:135], v23 offset:49152
	ds_read_b128 v[140:143], v23 offset:51200
	ds_read_b128 v[148:151], v22 offset:36864
	ds_read_b128 v[152:155], v22 offset:38912
	ds_read_b128 v[156:159], v23 offset:53248
	ds_read_b128 v[160:163], v23 offset:55296
	s_setprio 2
	global_load_dwordx4 v[168:171], v24, s[36:37] offset:1152
	s_waitcnt vmcnt(8)
	ds_write_b128 v19, v[164:167]
	ds_read_b128 v[164:167], v20 offset:32768
	ds_read_b128 v[172:175], v21 offset:49152
	s_waitcnt lgkmcnt(8)
	v_mfma_f32_16x16x32_bf16 v[42:45], v[132:135], v[112:115], v[42:45]
	s_waitcnt lgkmcnt(3)
	v_mfma_f32_16x16x32_bf16 v[26:29], v[160:163], v[112:115], v[26:29]
	v_mfma_f32_16x16x32_bf16 v[96:99], v[140:143], v[112:115], v[96:99]
	v_mfma_f32_16x16x32_bf16 v[104:107], v[156:159], v[112:115], v[104:107]
	global_load_dwordx4 v[112:115], v245, s[36:37] offset:1152
	s_waitcnt vmcnt(8)
	ds_write_b128 v19, v[78:81] offset:4096
	ds_read_b128 v[78:81], v20 offset:34816
	ds_read_b128 v[176:179], v21 offset:51200
	v_mfma_f32_16x16x32_bf16 v[46:49], v[132:135], v[120:123], v[46:49]
	v_mfma_f32_16x16x32_bf16 v[58:61], v[140:143], v[120:123], v[58:61]
	v_mfma_f32_16x16x32_bf16 v[30:33], v[160:163], v[120:123], v[30:33]
	v_mfma_f32_16x16x32_bf16 v[100:103], v[156:159], v[120:123], v[100:103]
	global_load_dwordx4 v[120:123], v246, s[36:37] offset:1152
	s_waitcnt vmcnt(8)
	ds_write_b128 v19, v[116:119] offset:8192
	ds_read_b128 v[116:119], v20 offset:36864
	ds_read_b128 v[180:183], v21 offset:53248
	v_mfma_f32_16x16x32_bf16 v[50:53], v[132:135], v[148:151], v[50:53]
	v_mfma_f32_16x16x32_bf16 v[62:65], v[140:143], v[148:151], v[62:65]
	v_mfma_f32_16x16x32_bf16 v[74:77], v[156:159], v[148:151], v[74:77]
	v_mfma_f32_16x16x32_bf16 v[34:37], v[160:163], v[148:151], v[34:37]
	global_load_dwordx4 v[148:151], v247, s[36:37] offset:1152
	s_waitcnt vmcnt(8)
	ds_write_b128 v19, v[144:147] offset:12288
	ds_read_b128 v[144:147], v20 offset:38912
	ds_read_b128 v[184:187], v21 offset:55296
	v_mfma_f32_16x16x32_bf16 v[54:57], v[132:135], v[152:155], v[54:57]
	v_mfma_f32_16x16x32_bf16 v[66:69], v[140:143], v[152:155], v[66:69]
	v_mfma_f32_16x16x32_bf16 v[70:73], v[156:159], v[152:155], v[70:73]
	v_mfma_f32_16x16x32_bf16 v[38:41], v[160:163], v[152:155], v[38:41]
	global_load_dwordx4 v[132:135], v18, s[6:7] offset:1152
	s_waitcnt vmcnt(8)
	ds_write_b128 v19, v[124:127] offset:16384
	s_waitcnt lgkmcnt(10)
	v_mfma_f32_16x16x32_bf16 v[42:45], v[172:175], v[164:167], v[42:45]
	s_waitcnt lgkmcnt(1)
	v_mfma_f32_16x16x32_bf16 v[26:29], v[184:187], v[164:167], v[26:29]
	v_mfma_f32_16x16x32_bf16 v[96:99], v[176:179], v[164:167], v[96:99]
	v_mfma_f32_16x16x32_bf16 v[104:107], v[180:183], v[164:167], v[104:107]
	global_load_dwordx4 v[124:127], v248, s[6:7] offset:1152
	s_waitcnt vmcnt(8)
	ds_write_b128 v19, v[136:139] offset:20480
	v_mfma_f32_16x16x32_bf16 v[46:49], v[172:175], v[78:81], v[46:49]
	v_mfma_f32_16x16x32_bf16 v[58:61], v[176:179], v[78:81], v[58:61]
	v_mfma_f32_16x16x32_bf16 v[30:33], v[184:187], v[78:81], v[30:33]
	v_mfma_f32_16x16x32_bf16 v[100:103], v[180:183], v[78:81], v[100:103]
	global_load_dwordx4 v[78:81], v249, s[6:7] offset:1152
	s_waitcnt vmcnt(8)
	ds_write_b128 v19, v[108:111] offset:24576
	v_mfma_f32_16x16x32_bf16 v[50:53], v[172:175], v[116:119], v[50:53]
	v_mfma_f32_16x16x32_bf16 v[62:65], v[176:179], v[116:119], v[62:65]
	v_mfma_f32_16x16x32_bf16 v[74:77], v[180:183], v[116:119], v[74:77]
	v_mfma_f32_16x16x32_bf16 v[34:37], v[184:187], v[116:119], v[34:37]
	global_load_dwordx4 v[108:111], v250, s[6:7] offset:1152
	s_waitcnt vmcnt(8)
	ds_write_b128 v19, v[92:95] offset:28672
	v_mfma_f32_16x16x32_bf16 v[54:57], v[172:175], v[144:147], v[54:57]
	v_mfma_f32_16x16x32_bf16 v[66:69], v[176:179], v[144:147], v[66:69]
	v_mfma_f32_16x16x32_bf16 v[70:73], v[180:183], v[144:147], v[70:73]
	v_mfma_f32_16x16x32_bf16 v[38:41], v[184:187], v[144:147], v[38:41]
	s_setprio 0
	s_waitcnt lgkmcnt(0)
	s_barrier
; template <int MODE>
; __device__ __forceinline__ void gemm_tile(const Params& P, int tm, int tn, unsigned char* smem) {
;     ...
;     for (int kt = 0; kt < 16; ++kt) {
;         unsigned char* sA = (kt & 1) ? sA1 : sA0; unsigned char* sB = (kt & 1) ? sB1 : sB0;
;         unsigned char* nA = (kt & 1) ? sA0 : sA1; unsigned char* nB = (kt & 1) ? sB0 : sB1;
;         bf16x8 fa[4], fb[4], ga[4], gb[4];
;         const int ch0 = ((g ^ sw) << 4), ch1 = (((4 + g) ^ sw) << 4);
;         const unsigned ko = (unsigned)(kt + 2) * 128u;
;         const unsigned koa = ko + ((MODE == 2 && kt + 2 >= 8) ? (unsigned)(ZC_FQ - 512) * 2u : 0u);
;         const bool wr_ok = kt < 15, ld_ok = kt < 14;
; #pragma unroll
;         for (int i = 0; i < 4; ++i) { fa[i] = *(const bf16x8*)(sA + arow_off + i * 2048 + ch0); fb[i] = *(const bf16x8*)(sB + brow_off + i * 2048 + ch0); }
;         __builtin_amdgcn_sched_barrier(0);
;         __builtin_amdgcn_s_setprio(2);
;         if (wr_ok) *(uint4*)(nA + soff0) = ra0;
;         if (ld_ok) ra0 = *(const uint4*)(Ab + (aoff + 0u * LDA + koa));
;         ga[0] = *(const bf16x8*)(sA + arow_off + 0 * 2048 + ch1); gb[0] = *(const bf16x8*)(sB + brow_off + 0 * 2048 + ch1);
;         __builtin_amdgcn_sched_barrier(0);
; #pragma unroll
;         for (int j = 0; j < 4; ++j) acc[0][j] = __builtin_amdgcn_mfma_f32_16x16x32_bf16(fb[j], fa[0], acc[0][j], 0, 0, 0);
;         __builtin_amdgcn_sched_barrier(0);
;         if (wr_ok) *(uint4*)(nA + soff0 + 4096) = ra1;
;         if (ld_ok) ra1 = *(const uint4*)(Ab + (aoff + 32u * LDA + koa));
;         ga[1] = *(const bf16x8*)(sA + arow_off + 1 * 2048 + ch1); gb[1] = *(const bf16x8*)(sB + brow_off + 1 * 2048 + ch1);
;         __builtin_amdgcn_sched_barrier(0);
; #pragma unroll
;         for (int j = 0; j < 4; ++j) acc[1][j] = __builtin_amdgcn_mfma_f32_16x16x32_bf16(fb[j], fa[1], acc[1][j], 0, 0, 0);
;         __builtin_amdgcn_sched_barrier(0);
;         if (wr_ok) *(uint4*)(nA + soff0 + 8192) = ra2;
;         if (ld_ok) ra2 = *(const uint4*)(Ab + (aoff + 64u * LDA + koa));
;         ga[2] = *(const bf16x8*)(sA + arow_off + 2 * 2048 + ch1); gb[2] = *(const bf16x8*)(sB + brow_off + 2 * 2048 + ch1);
;         __builtin_amdgcn_sched_barrier(0);
; #pragma unroll
;         for (int j = 0; j < 4; ++j) acc[2][j] = __builtin_amdgcn_mfma_f32_16x16x32_bf16(fb[j], fa[2], acc[2][j], 0, 0, 0);
	ds_read_b128 v[92:95], v22
	ds_read_b128 v[116:119], v22 offset:2048
	ds_read_b128 v[136:139], v23 offset:16384
	ds_read_b128 v[140:143], v23 offset:18432
	ds_read_b128 v[144:147], v22 offset:4096
	ds_read_b128 v[152:155], v22 offset:6144
	ds_read_b128 v[156:159], v23 offset:20480
	ds_read_b128 v[160:163], v23 offset:22528
	s_setprio 2
	global_load_dwordx4 v[164:167], v24, s[36:37] offset:1280
	s_waitcnt vmcnt(8)
	ds_write_b128 v19, v[168:171] offset:32768
	ds_read_b128 v[168:171], v20
	ds_read_b128 v[172:175], v21 offset:16384
	s_waitcnt lgkmcnt(8)
	v_mfma_f32_16x16x32_bf16 v[42:45], v[136:139], v[92:95], v[42:45]
	s_waitcnt lgkmcnt(3)
	v_mfma_f32_16x16x32_bf16 v[26:29], v[160:163], v[92:95], v[26:29]
	v_mfma_f32_16x16x32_bf16 v[96:99], v[140:143], v[92:95], v[96:99]
	v_mfma_f32_16x16x32_bf16 v[104:107], v[156:159], v[92:95], v[104:107]
	global_load_dwordx4 v[92:95], v245, s[36:37] offset:1280
	s_waitcnt vmcnt(8)
	ds_write_b128 v19, v[112:115] offset:36864
	ds_read_b128 v[112:115], v20 offset:2048
	ds_read_b128 v[176:179], v21 offset:18432
	v_mfma_f32_16x16x32_bf16 v[46:49], v[136:139], v[116:119], v[46:49]
	v_mfma_f32_16x16x32_bf16 v[58:61], v[140:143], v[116:119], v[58:61]
	v_mfma_f32_16x16x32_bf16 v[30:33], v[160:163], v[116:119], v[30:33]
	v_mfma_f32_16x16x32_bf16 v[100:103], v[156:159], v[116:119], v[100:103]
	global_load_dwordx4 v[116:119], v246, s[36:37] offset:1280
	s_waitcnt vmcnt(8)
	ds_write_b128 v19, v[120:123] offset:40960
	ds_read_b128 v[120:123], v20 offset:4096
	ds_read_b128 v[180:183], v21 offset:20480
	v_mfma_f32_16x16x32_bf16 v[50:53], v[136:139], v[144:147], v[50:53]
	v_mfma_f32_16x16x32_bf16 v[62:65], v[140:143], v[144:147], v[62:65]
	v_mfma_f32_16x16x32_bf16 v[74:77], v[156:159], v[144:147], v[74:77]
	v_mfma_f32_16x16x32_bf16 v[34:37], v[160:163], v[144:147], v[34:37]
	global_load_dwordx4 v[144:147], v247, s[36:37] offset:1280
	s_waitcnt vmcnt(8)
	ds_write_b128 v19, v[148:151] offset:45056
	ds_read_b128 v[148:151], v20 offset:6144
	ds_read_b128 v[184:187], v21 offset:22528
	v_mfma_f32_16x16x32_bf16 v[54:57], v[136:139], v[152:155], v[54:57]
	v_mfma_f32_16x16x32_bf16 v[66:69], v[140:143], v[152:155], v[66:69]
	v_mfma_f32_16x16x32_bf16 v[70:73], v[156:159], v[152:155], v[70:73]
	v_mfma_f32_16x16x32_bf16 v[38:41], v[160:163], v[152:155], v[38:41]
	global_load_dwordx4 v[136:139], v18, s[6:7] offset:1280
	s_waitcnt vmcnt(8)
	ds_write_b128 v19, v[132:135] offset:49152
	s_waitcnt lgkmcnt(10)
	v_mfma_f32_16x16x32_bf16 v[42:45], v[172:175], v[168:171], v[42:45]
	s_waitcnt lgkmcnt(1)
	v_mfma_f32_16x16x32_bf16 v[26:29], v[184:187], v[168:171], v[26:29]
	v_mfma_f32_16x16x32_bf16 v[96:99], v[176:179], v[168:171], v[96:99]
	v_mfma_f32_16x16x32_bf16 v[104:107], v[180:183], v[168:171], v[104:107]
	global_load_dwordx4 v[132:135], v248, s[6:7] offset:1280
	s_waitcnt vmcnt(8)
	ds_write_b128 v19, v[124:127] offset:53248
	v_mfma_f32_16x16x32_bf16 v[46:49], v[172:175], v[112:115], v[46:49]
	v_mfma_f32_16x16x32_bf16 v[58:61], v[176:179], v[112:115], v[58:61]
	v_mfma_f32_16x16x32_bf16 v[30:33], v[184:187], v[112:115], v[30:33]
	v_mfma_f32_16x16x32_bf16 v[100:103], v[180:183], v[112:115], v[100:103]
	global_load_dwordx4 v[112:115], v249, s[6:7] offset:1280
	s_waitcnt vmcnt(8)
	ds_write_b128 v19, v[78:81] offset:57344
	v_mfma_f32_16x16x32_bf16 v[50:53], v[172:175], v[120:123], v[50:53]
	v_mfma_f32_16x16x32_bf16 v[62:65], v[176:179], v[120:123], v[62:65]
	v_mfma_f32_16x16x32_bf16 v[74:77], v[180:183], v[120:123], v[74:77]
	v_mfma_f32_16x16x32_bf16 v[34:37], v[184:187], v[120:123], v[34:37]
	global_load_dwordx4 v[78:81], v250, s[6:7] offset:1280
	s_waitcnt vmcnt(8)
	ds_write_b128 v19, v[108:111] offset:61440
	v_mfma_f32_16x16x32_bf16 v[54:57], v[172:175], v[148:151], v[54:57]
	v_mfma_f32_16x16x32_bf16 v[66:69], v[176:179], v[148:151], v[66:69]
	v_mfma_f32_16x16x32_bf16 v[70:73], v[180:183], v[148:151], v[70:73]
	v_mfma_f32_16x16x32_bf16 v[38:41], v[184:187], v[148:151], v[38:41]
	s_setprio 0
	s_waitcnt lgkmcnt(0)
	s_barrier
	ds_read_b128 v[108:111], v22 offset:32768
	ds_read_b128 v[120:123], v22 offset:34816
	ds_read_b128 v[124:127], v23 offset:49152
	ds_read_b128 v[140:143], v23 offset:51200
	ds_read_b128 v[148:151], v22 offset:36864
	ds_read_b128 v[152:155], v22 offset:38912
	ds_read_b128 v[156:159], v23 offset:53248
	ds_read_b128 v[160:163], v23 offset:55296
	s_setprio 2
	global_load_dwordx4 v[168:171], v24, s[36:37] offset:1408
	s_waitcnt vmcnt(8)
	ds_write_b128 v19, v[164:167]
	ds_read_b128 v[164:167], v20 offset:32768
	ds_read_b128 v[172:175], v21 offset:49152
	s_waitcnt lgkmcnt(8)
	v_mfma_f32_16x16x32_bf16 v[42:45], v[124:127], v[108:111], v[42:45]
	s_waitcnt lgkmcnt(3)
	v_mfma_f32_16x16x32_bf16 v[26:29], v[160:163], v[108:111], v[26:29]
	v_mfma_f32_16x16x32_bf16 v[96:99], v[140:143], v[108:111], v[96:99]
	v_mfma_f32_16x16x32_bf16 v[104:107], v[156:159], v[108:111], v[104:107]
	global_load_dwordx4 v[108:111], v245, s[36:37] offset:1408
	s_waitcnt vmcnt(8)
	ds_write_b128 v19, v[92:95] offset:4096
	ds_read_b128 v[92:95], v20 offset:34816
	ds_read_b128 v[176:179], v21 offset:51200
	v_mfma_f32_16x16x32_bf16 v[46:49], v[124:127], v[120:123], v[46:49]
	v_mfma_f32_16x16x32_bf16 v[58:61], v[140:143], v[120:123], v[58:61]
	v_mfma_f32_16x16x32_bf16 v[30:33], v[160:163], v[120:123], v[30:33]
	v_mfma_f32_16x16x32_bf16 v[100:103], v[156:159], v[120:123], v[100:103]
	global_load_dwordx4 v[120:123], v246, s[36:37] offset:1408
	s_waitcnt vmcnt(8)
; template <int MODE>
; __device__ __forceinline__ void gemm_tile(const Params& P, int tm, int tn, unsigned char* smem) {
;     ...
;     for (int kt = 0; kt < 16; ++kt) {
;         unsigned char* sA = (kt & 1) ? sA1 : sA0; unsigned char* sB = (kt & 1) ? sB1 : sB0;
;         unsigned char* nA = (kt & 1) ? sA0 : sA1; unsigned char* nB = (kt & 1) ? sB0 : sB1;
;         bf16x8 fa[4], fb[4], ga[4], gb[4];
;         const int ch0 = ((g ^ sw) << 4), ch1 = (((4 + g) ^ sw) << 4);
;         const unsigned ko = (unsigned)(kt + 2) * 128u;
;         const unsigned koa = ko + ((MODE == 2 && kt + 2 >= 8) ? (unsigned)(ZC_FQ - 512) * 2u : 0u);
;         const bool wr_ok = kt < 15, ld_ok = kt < 14;
; #pragma unroll
;         for (int i = 0; i < 4; ++i) { fa[i] = *(const bf16x8*)(sA + arow_off + i * 2048 + ch0); fb[i] = *(const bf16x8*)(sB + brow_off + i * 2048 + ch0); }
;         __builtin_amdgcn_sched_barrier(0);
;         __builtin_amdgcn_s_setprio(2);
;         if (wr_ok) *(uint4*)(nA + soff0) = ra0;
;         if (ld_ok) ra0 = *(const uint4*)(Ab + (aoff + 0u * LDA + koa));
;         ga[0] = *(const bf16x8*)(sA + arow_off + 0 * 2048 + ch1); gb[0] = *(const bf16x8*)(sB + brow_off + 0 * 2048 + ch1);
;         __builtin_amdgcn_sched_barrier(0);
; #pragma unroll
;         for (int j = 0; j < 4; ++j) acc[0][j] = __builtin_amdgcn_mfma_f32_16x16x32_bf16(fb[j], fa[0], acc[0][j], 0, 0, 0);
;         __builtin_amdgcn_sched_barrier(0);
;         if (wr_ok) *(uint4*)(nA + soff0 + 4096) = ra1;
;         if (ld_ok) ra1 = *(const uint4*)(Ab + (aoff + 32u * LDA + koa));
;         ga[1] = *(const bf16x8*)(sA + arow_off + 1 * 2048 + ch1); gb[1] = *(const bf16x8*)(sB + brow_off + 1 * 2048 + ch1);
;         __builtin_amdgcn_sched_barrier(0);
; #pragma unroll
;         for (int j = 0; j < 4; ++j) acc[1][j] = __builtin_amdgcn_mfma_f32_16x16x32_bf16(fb[j], fa[1], acc[1][j], 0, 0, 0);
;         __builtin_amdgcn_sched_barrier(0);
;         if (wr_ok) *(uint4*)(nA + soff0 + 8192) = ra2;
;         if (ld_ok) ra2 = *(const uint4*)(Ab + (aoff + 64u * LDA + koa));
;         ga[2] = *(const bf16x8*)(sA + arow_off + 2 * 2048 + ch1); gb[2] = *(const bf16x8*)(sB + brow_off + 2 * 2048 + ch1);
;         __builtin_amdgcn_sched_barrier(0);
; #pragma unroll
;         for (int j = 0; j < 4; ++j) acc[2][j] = __builtin_amdgcn_mfma_f32_16x16x32_bf16(fb[j], fa[2], acc[2][j], 0, 0, 0);
	ds_write_b128 v19, v[116:119] offset:8192
	ds_read_b128 v[116:119], v20 offset:36864
	ds_read_b128 v[180:183], v21 offset:53248
	v_mfma_f32_16x16x32_bf16 v[50:53], v[124:127], v[148:151], v[50:53]
	v_mfma_f32_16x16x32_bf16 v[62:65], v[140:143], v[148:151], v[62:65]
	v_mfma_f32_16x16x32_bf16 v[74:77], v[156:159], v[148:151], v[74:77]
	v_mfma_f32_16x16x32_bf16 v[34:37], v[160:163], v[148:151], v[34:37]
	global_load_dwordx4 v[148:151], v247, s[36:37] offset:1408
	s_waitcnt vmcnt(8)
	ds_write_b128 v19, v[144:147] offset:12288
	ds_read_b128 v[144:147], v20 offset:38912
	ds_read_b128 v[184:187], v21 offset:55296
	v_mfma_f32_16x16x32_bf16 v[54:57], v[124:127], v[152:155], v[54:57]
	v_mfma_f32_16x16x32_bf16 v[66:69], v[140:143], v[152:155], v[66:69]
	v_mfma_f32_16x16x32_bf16 v[70:73], v[156:159], v[152:155], v[70:73]
	v_mfma_f32_16x16x32_bf16 v[38:41], v[160:163], v[152:155], v[38:41]
	global_load_dwordx4 v[124:127], v18, s[6:7] offset:1408
	s_waitcnt vmcnt(8)
	ds_write_b128 v19, v[136:139] offset:16384
	s_waitcnt lgkmcnt(10)
	v_mfma_f32_16x16x32_bf16 v[42:45], v[172:175], v[164:167], v[42:45]
	s_waitcnt lgkmcnt(1)
	v_mfma_f32_16x16x32_bf16 v[26:29], v[184:187], v[164:167], v[26:29]
	v_mfma_f32_16x16x32_bf16 v[96:99], v[176:179], v[164:167], v[96:99]
	v_mfma_f32_16x16x32_bf16 v[104:107], v[180:183], v[164:167], v[104:107]
	global_load_dwordx4 v[136:139], v248, s[6:7] offset:1408
	s_waitcnt vmcnt(8)
	ds_write_b128 v19, v[132:135] offset:20480
	v_mfma_f32_16x16x32_bf16 v[46:49], v[172:175], v[92:95], v[46:49]
	v_mfma_f32_16x16x32_bf16 v[58:61], v[176:179], v[92:95], v[58:61]
	v_mfma_f32_16x16x32_bf16 v[30:33], v[184:187], v[92:95], v[30:33]
	v_mfma_f32_16x16x32_bf16 v[100:103], v[180:183], v[92:95], v[100:103]
	global_load_dwordx4 v[92:95], v249, s[6:7] offset:1408
	s_waitcnt vmcnt(8)
	ds_write_b128 v19, v[112:115] offset:24576
	v_mfma_f32_16x16x32_bf16 v[50:53], v[172:175], v[116:119], v[50:53]
	v_mfma_f32_16x16x32_bf16 v[62:65], v[176:179], v[116:119], v[62:65]
	v_mfma_f32_16x16x32_bf16 v[74:77], v[180:183], v[116:119], v[74:77]
	v_mfma_f32_16x16x32_bf16 v[34:37], v[184:187], v[116:119], v[34:37]
	global_load_dwordx4 v[112:115], v250, s[6:7] offset:1408
	s_waitcnt vmcnt(8)
	ds_write_b128 v19, v[78:81] offset:28672
	v_mfma_f32_16x16x32_bf16 v[54:57], v[172:175], v[144:147], v[54:57]
	v_mfma_f32_16x16x32_bf16 v[66:69], v[176:179], v[144:147], v[66:69]
	v_mfma_f32_16x16x32_bf16 v[70:73], v[180:183], v[144:147], v[70:73]
	v_mfma_f32_16x16x32_bf16 v[38:41], v[184:187], v[144:147], v[38:41]
	s_setprio 0
	s_waitcnt lgkmcnt(0)
	s_barrier
	ds_read_b128 v[78:81], v22
	ds_read_b128 v[116:119], v22 offset:2048
	ds_read_b128 v[132:135], v23 offset:16384
	ds_read_b128 v[140:143], v23 offset:18432
	ds_read_b128 v[144:147], v22 offset:4096
	ds_read_b128 v[152:155], v22 offset:6144
	ds_read_b128 v[156:159], v23 offset:20480
	ds_read_b128 v[160:163], v23 offset:22528
	s_setprio 2
	global_load_dwordx4 v[164:167], v24, s[36:37] offset:1536
	s_waitcnt vmcnt(8)
	ds_write_b128 v19, v[168:171] offset:32768
	ds_read_b128 v[168:171], v20
	ds_read_b128 v[172:175], v21 offset:16384
	s_waitcnt lgkmcnt(8)
	v_mfma_f32_16x16x32_bf16 v[42:45], v[132:135], v[78:81], v[42:45]
	s_waitcnt lgkmcnt(3)
	v_mfma_f32_16x16x32_bf16 v[26:29], v[160:163], v[78:81], v[26:29]
	v_mfma_f32_16x16x32_bf16 v[96:99], v[140:143], v[78:81], v[96:99]
	v_mfma_f32_16x16x32_bf16 v[104:107], v[156:159], v[78:81], v[104:107]
	global_load_dwordx4 v[78:81], v245, s[36:37] offset:1536
	s_waitcnt vmcnt(8)
	ds_write_b128 v19, v[108:111] offset:36864
	ds_read_b128 v[108:111], v20 offset:2048
	ds_read_b128 v[176:179], v21 offset:18432
	v_mfma_f32_16x16x32_bf16 v[46:49], v[132:135], v[116:119], v[46:49]
	v_mfma_f32_16x16x32_bf16 v[58:61], v[140:143], v[116:119], v[58:61]
	v_mfma_f32_16x16x32_bf16 v[30:33], v[160:163], v[116:119], v[30:33]
	v_mfma_f32_16x16x32_bf16 v[100:103], v[156:159], v[116:119], v[100:103]
	global_load_dwordx4 v[116:119], v246, s[36:37] offset:1536
	s_waitcnt vmcnt(8)
	ds_write_b128 v19, v[120:123] offset:40960
	ds_read_b128 v[120:123], v20 offset:4096
	ds_read_b128 v[180:183], v21 offset:20480
	v_mfma_f32_16x16x32_bf16 v[50:53], v[132:135], v[144:147], v[50:53]
	v_mfma_f32_16x16x32_bf16 v[62:65], v[140:143], v[144:147], v[62:65]
	v_mfma_f32_16x16x32_bf16 v[74:77], v[156:159], v[144:147], v[74:77]
	v_mfma_f32_16x16x32_bf16 v[34:37], v[160:163], v[144:147], v[34:37]
	global_load_dwordx4 v[144:147], v247, s[36:37] offset:1536
	s_waitcnt vmcnt(8)
	ds_write_b128 v19, v[148:151] offset:45056
	ds_read_b128 v[148:151], v20 offset:6144
	ds_read_b128 v[184:187], v21 offset:22528
	v_mfma_f32_16x16x32_bf16 v[54:57], v[132:135], v[152:155], v[54:57]
	v_mfma_f32_16x16x32_bf16 v[66:69], v[140:143], v[152:155], v[66:69]
	v_mfma_f32_16x16x32_bf16 v[70:73], v[156:159], v[152:155], v[70:73]
	v_mfma_f32_16x16x32_bf16 v[38:41], v[160:163], v[152:155], v[38:41]
	global_load_dwordx4 v[132:135], v18, s[6:7] offset:1536
	s_waitcnt vmcnt(8)
	ds_write_b128 v19, v[124:127] offset:49152
	s_waitcnt lgkmcnt(10)
	v_mfma_f32_16x16x32_bf16 v[42:45], v[172:175], v[168:171], v[42:45]
	s_waitcnt lgkmcnt(1)
	v_mfma_f32_16x16x32_bf16 v[26:29], v[184:187], v[168:171], v[26:29]
	v_mfma_f32_16x16x32_bf16 v[96:99], v[176:179], v[168:171], v[96:99]
	v_mfma_f32_16x16x32_bf16 v[104:107], v[180:183], v[168:171], v[104:107]
	global_load_dwordx4 v[124:127], v248, s[6:7] offset:1536
	s_waitcnt vmcnt(8)
	ds_write_b128 v19, v[136:139] offset:53248
	v_mfma_f32_16x16x32_bf16 v[46:49], v[172:175], v[108:111], v[46:49]
	v_mfma_f32_16x16x32_bf16 v[58:61], v[176:179], v[108:111], v[58:61]
	v_mfma_f32_16x16x32_bf16 v[30:33], v[184:187], v[108:111], v[30:33]
	v_mfma_f32_16x16x32_bf16 v[100:103], v[180:183], v[108:111], v[100:103]
	global_load_dwordx4 v[108:111], v249, s[6:7] offset:1536
	s_waitcnt vmcnt(8)
	ds_write_b128 v19, v[92:95] offset:57344
	v_mfma_f32_16x16x32_bf16 v[50:53], v[172:175], v[120:123], v[50:53]
	v_mfma_f32_16x16x32_bf16 v[62:65], v[176:179], v[120:123], v[62:65]
	v_mfma_f32_16x16x32_bf16 v[74:77], v[180:183], v[120:123], v[74:77]
	v_mfma_f32_16x16x32_bf16 v[34:37], v[184:187], v[120:123], v[34:37]
	global_load_dwordx4 v[92:95], v250, s[6:7] offset:1536
	s_waitcnt vmcnt(8)
	ds_write_b128 v19, v[112:115] offset:61440
	v_mfma_f32_16x16x32_bf16 v[54:57], v[172:175], v[148:151], v[54:57]
	v_mfma_f32_16x16x32_bf16 v[66:69], v[176:179], v[148:151], v[66:69]
	v_mfma_f32_16x16x32_bf16 v[70:73], v[180:183], v[148:151], v[70:73]
	v_mfma_f32_16x16x32_bf16 v[38:41], v[184:187], v[148:151], v[38:41]
	s_setprio 0
	s_waitcnt lgkmcnt(0)
	s_barrier
; template <int MODE>
; __device__ __forceinline__ void gemm_tile(const Params& P, int tm, int tn, unsigned char* smem) {
;     ...
;     for (int kt = 0; kt < 16; ++kt) {
;         unsigned char* sA = (kt & 1) ? sA1 : sA0; unsigned char* sB = (kt & 1) ? sB1 : sB0;
;         unsigned char* nA = (kt & 1) ? sA0 : sA1; unsigned char* nB = (kt & 1) ? sB0 : sB1;
;         bf16x8 fa[4], fb[4], ga[4], gb[4];
;         const int ch0 = ((g ^ sw) << 4), ch1 = (((4 + g) ^ sw) << 4);
;         const unsigned ko = (unsigned)(kt + 2) * 128u;
;         const unsigned koa = ko + ((MODE == 2 && kt + 2 >= 8) ? (unsigned)(ZC_FQ - 512) * 2u : 0u);
;         const bool wr_ok = kt < 15, ld_ok = kt < 14;
; #pragma unroll
;         for (int i = 0; i < 4; ++i) { fa[i] = *(const bf16x8*)(sA + arow_off + i * 2048 + ch0); fb[i] = *(const bf16x8*)(sB + brow_off + i * 2048 + ch0); }
;         __builtin_amdgcn_sched_barrier(0);
;         __builtin_amdgcn_s_setprio(2);
;         if (wr_ok) *(uint4*)(nA + soff0) = ra0;
;         if (ld_ok) ra0 = *(const uint4*)(Ab + (aoff + 0u * LDA + koa));
;         ga[0] = *(const bf16x8*)(sA + arow_off + 0 * 2048 + ch1); gb[0] = *(const bf16x8*)(sB + brow_off + 0 * 2048 + ch1);
;         __builtin_amdgcn_sched_barrier(0);
; #pragma unroll
;         for (int j = 0; j < 4; ++j) acc[0][j] = __builtin_amdgcn_mfma_f32_16x16x32_bf16(fb[j], fa[0], acc[0][j], 0, 0, 0);
;         __builtin_amdgcn_sched_barrier(0);
;         if (wr_ok) *(uint4*)(nA + soff0 + 4096) = ra1;
;         if (ld_ok) ra1 = *(const uint4*)(Ab + (aoff + 32u * LDA + koa));
;         ga[1] = *(const bf16x8*)(sA + arow_off + 1 * 2048 + ch1); gb[1] = *(const bf16x8*)(sB + brow_off + 1 * 2048 + ch1);
;         __builtin_amdgcn_sched_barrier(0);
; #pragma unroll
;         for (int j = 0; j < 4; ++j) acc[1][j] = __builtin_amdgcn_mfma_f32_16x16x32_bf16(fb[j], fa[1], acc[1][j], 0, 0, 0);
;         __builtin_amdgcn_sched_barrier(0);
;         if (wr_ok) *(uint4*)(nA + soff0 + 8192) = ra2;
;         if (ld_ok) ra2 = *(const uint4*)(Ab + (aoff + 64u * LDA + koa));
;         ga[2] = *(const bf16x8*)(sA + arow_off + 2 * 2048 + ch1); gb[2] = *(const bf16x8*)(sB + brow_off + 2 * 2048 + ch1);
;         __builtin_amdgcn_sched_barrier(0);
; #pragma unroll
;         for (int j = 0; j < 4; ++j) acc[2][j] = __builtin_amdgcn_mfma_f32_16x16x32_bf16(fb[j], fa[2], acc[2][j], 0, 0, 0);
	ds_read_b128 v[112:115], v22 offset:32768
	ds_read_b128 v[120:123], v22 offset:34816
	ds_read_b128 v[136:139], v23 offset:49152
	ds_read_b128 v[140:143], v23 offset:51200
	ds_read_b128 v[148:151], v22 offset:36864
	ds_read_b128 v[152:155], v22 offset:38912
	ds_read_b128 v[156:159], v23 offset:53248
	ds_read_b128 v[160:163], v23 offset:55296
	s_setprio 2
	global_load_dwordx4 v[168:171], v24, s[36:37] offset:1664
	s_waitcnt vmcnt(8)
	ds_write_b128 v19, v[164:167]
	ds_read_b128 v[164:167], v20 offset:32768
	ds_read_b128 v[172:175], v21 offset:49152
	s_waitcnt lgkmcnt(8)
	v_mfma_f32_16x16x32_bf16 v[42:45], v[136:139], v[112:115], v[42:45]
	s_waitcnt lgkmcnt(3)
	v_mfma_f32_16x16x32_bf16 v[26:29], v[160:163], v[112:115], v[26:29]
	v_mfma_f32_16x16x32_bf16 v[96:99], v[140:143], v[112:115], v[96:99]
	v_mfma_f32_16x16x32_bf16 v[104:107], v[156:159], v[112:115], v[104:107]
	global_load_dwordx4 v[112:115], v245, s[36:37] offset:1664
	s_waitcnt vmcnt(8)
	ds_write_b128 v19, v[78:81] offset:4096
	ds_read_b128 v[78:81], v20 offset:34816
	ds_read_b128 v[176:179], v21 offset:51200
	v_mfma_f32_16x16x32_bf16 v[46:49], v[136:139], v[120:123], v[46:49]
	v_mfma_f32_16x16x32_bf16 v[58:61], v[140:143], v[120:123], v[58:61]
	v_mfma_f32_16x16x32_bf16 v[30:33], v[160:163], v[120:123], v[30:33]
	v_mfma_f32_16x16x32_bf16 v[100:103], v[156:159], v[120:123], v[100:103]
	global_load_dwordx4 v[120:123], v246, s[36:37] offset:1664
	s_waitcnt vmcnt(8)
	ds_write_b128 v19, v[116:119] offset:8192
	ds_read_b128 v[116:119], v20 offset:36864
	ds_read_b128 v[180:183], v21 offset:53248
	v_mfma_f32_16x16x32_bf16 v[50:53], v[136:139], v[148:151], v[50:53]
	v_mfma_f32_16x16x32_bf16 v[62:65], v[140:143], v[148:151], v[62:65]
	v_mfma_f32_16x16x32_bf16 v[74:77], v[156:159], v[148:151], v[74:77]
	v_mfma_f32_16x16x32_bf16 v[34:37], v[160:163], v[148:151], v[34:37]
	global_load_dwordx4 v[148:151], v247, s[36:37] offset:1664
	s_waitcnt vmcnt(8)
	ds_write_b128 v19, v[144:147] offset:12288
	ds_read_b128 v[144:147], v20 offset:38912
	ds_read_b128 v[184:187], v21 offset:55296
	v_mfma_f32_16x16x32_bf16 v[54:57], v[136:139], v[152:155], v[54:57]
	v_mfma_f32_16x16x32_bf16 v[66:69], v[140:143], v[152:155], v[66:69]
	v_mfma_f32_16x16x32_bf16 v[70:73], v[156:159], v[152:155], v[70:73]
	v_mfma_f32_16x16x32_bf16 v[38:41], v[160:163], v[152:155], v[38:41]
	global_load_dwordx4 v[136:139], v18, s[6:7] offset:1664
	s_waitcnt vmcnt(8)
	ds_write_b128 v19, v[132:135] offset:16384
	s_waitcnt lgkmcnt(10)
	v_mfma_f32_16x16x32_bf16 v[42:45], v[172:175], v[164:167], v[42:45]
	s_waitcnt lgkmcnt(1)
	v_mfma_f32_16x16x32_bf16 v[26:29], v[184:187], v[164:167], v[26:29]
	v_mfma_f32_16x16x32_bf16 v[96:99], v[176:179], v[164:167], v[96:99]
	v_mfma_f32_16x16x32_bf16 v[104:107], v[180:183], v[164:167], v[104:107]
	global_load_dwordx4 v[132:135], v248, s[6:7] offset:1664
	s_waitcnt vmcnt(8)
	ds_write_b128 v19, v[124:127] offset:20480
	v_mfma_f32_16x16x32_bf16 v[46:49], v[172:175], v[78:81], v[46:49]
	v_mfma_f32_16x16x32_bf16 v[58:61], v[176:179], v[78:81], v[58:61]
	v_mfma_f32_16x16x32_bf16 v[30:33], v[184:187], v[78:81], v[30:33]
	v_mfma_f32_16x16x32_bf16 v[100:103], v[180:183], v[78:81], v[100:103]
	global_load_dwordx4 v[78:81], v249, s[6:7] offset:1664
	s_waitcnt vmcnt(8)
	ds_write_b128 v19, v[108:111] offset:24576
	v_mfma_f32_16x16x32_bf16 v[50:53], v[172:175], v[116:119], v[50:53]
	v_mfma_f32_16x16x32_bf16 v[62:65], v[176:179], v[116:119], v[62:65]
	v_mfma_f32_16x16x32_bf16 v[74:77], v[180:183], v[116:119], v[74:77]
	v_mfma_f32_16x16x32_bf16 v[34:37], v[184:187], v[116:119], v[34:37]
	global_load_dwordx4 v[108:111], v250, s[6:7] offset:1664
	s_waitcnt vmcnt(8)
	ds_write_b128 v19, v[92:95] offset:28672
	v_mfma_f32_16x16x32_bf16 v[54:57], v[172:175], v[144:147], v[54:57]
	v_mfma_f32_16x16x32_bf16 v[66:69], v[176:179], v[144:147], v[66:69]
	v_mfma_f32_16x16x32_bf16 v[70:73], v[180:183], v[144:147], v[70:73]
	v_mfma_f32_16x16x32_bf16 v[38:41], v[184:187], v[144:147], v[38:41]
	s_setprio 0
	s_waitcnt lgkmcnt(0)
	s_barrier
	ds_read_b128 v[92:95], v22
	ds_read_b128 v[116:119], v22 offset:2048
	ds_read_b128 v[124:127], v23 offset:16384
	ds_read_b128 v[140:143], v23 offset:18432
	ds_read_b128 v[144:147], v22 offset:4096
	ds_read_b128 v[152:155], v22 offset:6144
	ds_read_b128 v[156:159], v23 offset:20480
	ds_read_b128 v[160:163], v23 offset:22528
	s_setprio 2
	global_load_dwordx4 v[164:167], v24, s[36:37] offset:1792
	s_waitcnt vmcnt(8)
	ds_write_b128 v19, v[168:171] offset:32768
	ds_read_b128 v[168:171], v20
	ds_read_b128 v[172:175], v21 offset:16384
	s_waitcnt lgkmcnt(8)
	v_mfma_f32_16x16x32_bf16 v[42:45], v[124:127], v[92:95], v[42:45]
	s_waitcnt lgkmcnt(3)
	v_mfma_f32_16x16x32_bf16 v[26:29], v[160:163], v[92:95], v[26:29]
	v_mfma_f32_16x16x32_bf16 v[96:99], v[140:143], v[92:95], v[96:99]
	v_mfma_f32_16x16x32_bf16 v[104:107], v[156:159], v[92:95], v[104:107]
	global_load_dwordx4 v[92:95], v245, s[36:37] offset:1792
	s_waitcnt vmcnt(8)
	ds_write_b128 v19, v[112:115] offset:36864
	ds_read_b128 v[112:115], v20 offset:2048
	ds_read_b128 v[176:179], v21 offset:18432
	v_mfma_f32_16x16x32_bf16 v[46:49], v[124:127], v[116:119], v[46:49]
	v_mfma_f32_16x16x32_bf16 v[58:61], v[140:143], v[116:119], v[58:61]
	v_mfma_f32_16x16x32_bf16 v[30:33], v[160:163], v[116:119], v[30:33]
	v_mfma_f32_16x16x32_bf16 v[100:103], v[156:159], v[116:119], v[100:103]
	global_load_dwordx4 v[116:119], v246, s[36:37] offset:1792
	s_waitcnt vmcnt(8)
; template <int MODE>
; __device__ __forceinline__ void gemm_tile(const Params& P, int tm, int tn, unsigned char* smem) {
;     ...
;     for (int kt = 0; kt < 16; ++kt) {
;         unsigned char* sA = (kt & 1) ? sA1 : sA0; unsigned char* sB = (kt & 1) ? sB1 : sB0;
;         unsigned char* nA = (kt & 1) ? sA0 : sA1; unsigned char* nB = (kt & 1) ? sB0 : sB1;
;         bf16x8 fa[4], fb[4], ga[4], gb[4];
;         const int ch0 = ((g ^ sw) << 4), ch1 = (((4 + g) ^ sw) << 4);
;         const unsigned ko = (unsigned)(kt + 2) * 128u;
;         const unsigned koa = ko + ((MODE == 2 && kt + 2 >= 8) ? (unsigned)(ZC_FQ - 512) * 2u : 0u);
;         const bool wr_ok = kt < 15, ld_ok = kt < 14;
; #pragma unroll
;         for (int i = 0; i < 4; ++i) { fa[i] = *(const bf16x8*)(sA + arow_off + i * 2048 + ch0); fb[i] = *(const bf16x8*)(sB + brow_off + i * 2048 + ch0); }
;         __builtin_amdgcn_sched_barrier(0);
;         __builtin_amdgcn_s_setprio(2);
;         if (wr_ok) *(uint4*)(nA + soff0) = ra0;
;         if (ld_ok) ra0 = *(const uint4*)(Ab + (aoff + 0u * LDA + koa));
;         ga[0] = *(const bf16x8*)(sA + arow_off + 0 * 2048 + ch1); gb[0] = *(const bf16x8*)(sB + brow_off + 0 * 2048 + ch1);
;         __builtin_amdgcn_sched_barrier(0);
; #pragma unroll
;         for (int j = 0; j < 4; ++j) acc[0][j] = __builtin_amdgcn_mfma_f32_16x16x32_bf16(fb[j], fa[0], acc[0][j], 0, 0, 0);
;         __builtin_amdgcn_sched_barrier(0);
;         if (wr_ok) *(uint4*)(nA + soff0 + 4096) = ra1;
;         if (ld_ok) ra1 = *(const uint4*)(Ab + (aoff + 32u * LDA + koa));
;         ga[1] = *(const bf16x8*)(sA + arow_off + 1 * 2048 + ch1); gb[1] = *(const bf16x8*)(sB + brow_off + 1 * 2048 + ch1);
;         __builtin_amdgcn_sched_barrier(0);
; #pragma unroll
;         for (int j = 0; j < 4; ++j) acc[1][j] = __builtin_amdgcn_mfma_f32_16x16x32_bf16(fb[j], fa[1], acc[1][j], 0, 0, 0);
;         __builtin_amdgcn_sched_barrier(0);
;         if (wr_ok) *(uint4*)(nA + soff0 + 8192) = ra2;
;         if (ld_ok) ra2 = *(const uint4*)(Ab + (aoff + 64u * LDA + koa));
;         ga[2] = *(const bf16x8*)(sA + arow_off + 2 * 2048 + ch1); gb[2] = *(const bf16x8*)(sB + brow_off + 2 * 2048 + ch1);
;         __builtin_amdgcn_sched_barrier(0);
; #pragma unroll
;         for (int j = 0; j < 4; ++j) acc[2][j] = __builtin_amdgcn_mfma_f32_16x16x32_bf16(fb[j], fa[2], acc[2][j], 0, 0, 0);
	ds_write_b128 v19, v[120:123] offset:40960
	ds_read_b128 v[120:123], v20 offset:4096
	ds_read_b128 v[180:183], v21 offset:20480
	v_mfma_f32_16x16x32_bf16 v[50:53], v[124:127], v[144:147], v[50:53]
	v_mfma_f32_16x16x32_bf16 v[62:65], v[140:143], v[144:147], v[62:65]
	v_mfma_f32_16x16x32_bf16 v[74:77], v[156:159], v[144:147], v[74:77]
	v_mfma_f32_16x16x32_bf16 v[34:37], v[160:163], v[144:147], v[34:37]
	global_load_dwordx4 v[144:147], v247, s[36:37] offset:1792
	s_waitcnt vmcnt(8)
	ds_write_b128 v19, v[148:151] offset:45056
	ds_read_b128 v[148:151], v20 offset:6144
	ds_read_b128 v[184:187], v21 offset:22528
	v_mfma_f32_16x16x32_bf16 v[54:57], v[124:127], v[152:155], v[54:57]
	v_mfma_f32_16x16x32_bf16 v[66:69], v[140:143], v[152:155], v[66:69]
	v_mfma_f32_16x16x32_bf16 v[70:73], v[156:159], v[152:155], v[70:73]
	v_mfma_f32_16x16x32_bf16 v[38:41], v[160:163], v[152:155], v[38:41]
	global_load_dwordx4 v[124:127], v18, s[6:7] offset:1792
	s_waitcnt vmcnt(8)
	ds_write_b128 v19, v[136:139] offset:49152
	s_waitcnt lgkmcnt(10)
	v_mfma_f32_16x16x32_bf16 v[42:45], v[172:175], v[168:171], v[42:45]
	s_waitcnt lgkmcnt(1)
	v_mfma_f32_16x16x32_bf16 v[26:29], v[184:187], v[168:171], v[26:29]
	v_mfma_f32_16x16x32_bf16 v[96:99], v[176:179], v[168:171], v[96:99]
	v_mfma_f32_16x16x32_bf16 v[104:107], v[180:183], v[168:171], v[104:107]
	global_load_dwordx4 v[136:139], v248, s[6:7] offset:1792
	s_waitcnt vmcnt(8)
	ds_write_b128 v19, v[132:135] offset:53248
	v_mfma_f32_16x16x32_bf16 v[46:49], v[172:175], v[112:115], v[46:49]
	v_mfma_f32_16x16x32_bf16 v[58:61], v[176:179], v[112:115], v[58:61]
	v_mfma_f32_16x16x32_bf16 v[30:33], v[184:187], v[112:115], v[30:33]
	v_mfma_f32_16x16x32_bf16 v[100:103], v[180:183], v[112:115], v[100:103]
	global_load_dwordx4 v[112:115], v249, s[6:7] offset:1792
	s_waitcnt vmcnt(8)
	ds_write_b128 v19, v[78:81] offset:57344
	v_mfma_f32_16x16x32_bf16 v[50:53], v[172:175], v[120:123], v[50:53]
	v_mfma_f32_16x16x32_bf16 v[62:65], v[176:179], v[120:123], v[62:65]
	v_mfma_f32_16x16x32_bf16 v[74:77], v[180:183], v[120:123], v[74:77]
	v_mfma_f32_16x16x32_bf16 v[34:37], v[184:187], v[120:123], v[34:37]
	global_load_dwordx4 v[78:81], v250, s[6:7] offset:1792
	s_waitcnt vmcnt(8)
	ds_write_b128 v19, v[108:111] offset:61440
	v_mfma_f32_16x16x32_bf16 v[54:57], v[172:175], v[148:151], v[54:57]
	v_mfma_f32_16x16x32_bf16 v[66:69], v[176:179], v[148:151], v[66:69]
	v_mfma_f32_16x16x32_bf16 v[70:73], v[180:183], v[148:151], v[70:73]
	v_mfma_f32_16x16x32_bf16 v[38:41], v[184:187], v[148:151], v[38:41]
	s_setprio 0
	s_waitcnt lgkmcnt(0)
	s_barrier
	ds_read_b128 v[108:111], v22 offset:32768
	ds_read_b128 v[120:123], v22 offset:34816
	ds_read_b128 v[132:135], v23 offset:49152
	ds_read_b128 v[140:143], v23 offset:51200
	ds_read_b128 v[148:151], v22 offset:36864
	ds_read_b128 v[152:155], v22 offset:38912
	ds_read_b128 v[156:159], v23 offset:53248
	ds_read_b128 v[160:163], v23 offset:55296
	s_setprio 2
	global_load_dwordx4 v[168:171], v24, s[36:37] offset:1920
	s_waitcnt vmcnt(8)
	ds_write_b128 v19, v[164:167]
	ds_read_b128 v[164:167], v20 offset:32768
	ds_read_b128 v[172:175], v21 offset:49152
	s_waitcnt lgkmcnt(8)
	v_mfma_f32_16x16x32_bf16 v[42:45], v[132:135], v[108:111], v[42:45]
	s_waitcnt lgkmcnt(3)
	v_mfma_f32_16x16x32_bf16 v[26:29], v[160:163], v[108:111], v[26:29]
	v_mfma_f32_16x16x32_bf16 v[96:99], v[140:143], v[108:111], v[96:99]
	v_mfma_f32_16x16x32_bf16 v[104:107], v[156:159], v[108:111], v[104:107]
	global_load_dwordx4 v[108:111], v245, s[36:37] offset:1920
	s_waitcnt vmcnt(8)
	ds_write_b128 v19, v[92:95] offset:4096
	ds_read_b128 v[92:95], v20 offset:34816
	ds_read_b128 v[176:179], v21 offset:51200
	v_mfma_f32_16x16x32_bf16 v[46:49], v[132:135], v[120:123], v[46:49]
	v_mfma_f32_16x16x32_bf16 v[58:61], v[140:143], v[120:123], v[58:61]
	v_mfma_f32_16x16x32_bf16 v[30:33], v[160:163], v[120:123], v[30:33]
	v_mfma_f32_16x16x32_bf16 v[100:103], v[156:159], v[120:123], v[100:103]
	global_load_dwordx4 v[120:123], v246, s[36:37] offset:1920
	s_waitcnt vmcnt(8)
	ds_write_b128 v19, v[116:119] offset:8192
	ds_read_b128 v[116:119], v20 offset:36864
	ds_read_b128 v[180:183], v21 offset:53248
	v_mfma_f32_16x16x32_bf16 v[50:53], v[132:135], v[148:151], v[50:53]
	v_mfma_f32_16x16x32_bf16 v[62:65], v[140:143], v[148:151], v[62:65]
	v_mfma_f32_16x16x32_bf16 v[74:77], v[156:159], v[148:151], v[74:77]
	v_mfma_f32_16x16x32_bf16 v[34:37], v[160:163], v[148:151], v[34:37]
	v_add_u32_e32 v24, 0x30780, v24
	global_load_dwordx4 v[148:151], v24, s[36:37]
	s_waitcnt vmcnt(8)
	ds_write_b128 v19, v[144:147] offset:12288
	ds_read_b128 v[144:147], v20 offset:38912
	ds_read_b128 v[184:187], v21 offset:55296
	v_mfma_f32_16x16x32_bf16 v[54:57], v[132:135], v[152:155], v[54:57]
	v_mfma_f32_16x16x32_bf16 v[66:69], v[140:143], v[152:155], v[66:69]
	v_mfma_f32_16x16x32_bf16 v[70:73], v[156:159], v[152:155], v[70:73]
	v_mfma_f32_16x16x32_bf16 v[38:41], v[160:163], v[152:155], v[38:41]
	global_load_dwordx4 v[132:135], v18, s[6:7] offset:1920
	s_waitcnt vmcnt(8)
	ds_write_b128 v19, v[124:127] offset:16384
	s_waitcnt lgkmcnt(10)
	v_mfma_f32_16x16x32_bf16 v[42:45], v[172:175], v[164:167], v[42:45]
	s_waitcnt lgkmcnt(1)
	v_mfma_f32_16x16x32_bf16 v[24:27], v[184:187], v[164:167], v[26:29]
	v_mfma_f32_16x16x32_bf16 v[96:99], v[176:179], v[164:167], v[96:99]
	v_mfma_f32_16x16x32_bf16 v[104:107], v[180:183], v[164:167], v[104:107]
	s_nop 0
	global_load_dwordx4 v[124:127], v248, s[6:7] offset:1920
	s_waitcnt vmcnt(8)
	ds_write_b128 v19, v[136:139] offset:20480
	v_mfma_f32_16x16x32_bf16 v[46:49], v[172:175], v[92:95], v[46:49]
	v_mfma_f32_16x16x32_bf16 v[58:61], v[176:179], v[92:95], v[58:61]
	v_mfma_f32_16x16x32_bf16 v[28:31], v[184:187], v[92:95], v[30:33]
	v_mfma_f32_16x16x32_bf16 v[100:103], v[180:183], v[92:95], v[100:103]
	s_nop 1
	global_load_dwordx4 v[92:95], v249, s[6:7] offset:1920
	s_waitcnt vmcnt(8)
	ds_write_b128 v19, v[112:115] offset:24576
	v_mfma_f32_16x16x32_bf16 v[50:53], v[172:175], v[116:119], v[50:53]
	v_mfma_f32_16x16x32_bf16 v[62:65], v[176:179], v[116:119], v[62:65]
	v_mfma_f32_16x16x32_bf16 v[74:77], v[180:183], v[116:119], v[74:77]
	v_mfma_f32_16x16x32_bf16 v[32:35], v[184:187], v[116:119], v[34:37]
	v_add_u32_e32 v18, 0x30780, v18
	global_load_dwordx4 v[112:115], v18, s[6:7]
	s_waitcnt vmcnt(8)
	ds_write_b128 v19, v[78:81] offset:28672
	v_mfma_f32_16x16x32_bf16 v[54:57], v[172:175], v[144:147], v[54:57]
	v_mfma_f32_16x16x32_bf16 v[66:69], v[176:179], v[144:147], v[66:69]
	v_mfma_f32_16x16x32_bf16 v[70:73], v[180:183], v[144:147], v[70:73]
	v_mfma_f32_16x16x32_bf16 v[36:39], v[184:187], v[144:147], v[38:41]
	s_setprio 0
	s_waitcnt lgkmcnt(0)
	s_barrier
; template <int MODE>
; __device__ __forceinline__ void gemm_tile(const Params& P, int tm, int tn, unsigned char* smem) {
;     ...
; #pragma unroll
;         for (int i = 0; i < 4; ++i) { fa[i] = *(const bf16x8*)(sA + arow_off + i * 2048 + ch0); fb[i] = *(const bf16x8*)(sB + brow_off + i * 2048 + ch0); }
;         __builtin_amdgcn_sched_barrier(0);
;         __builtin_amdgcn_s_setprio(2);
;         if (wr_ok) *(uint4*)(nA + soff0) = ra0;
;         if (ld_ok) ra0 = *(const uint4*)(Ab + (aoff + 0u * LDA + koa));
;         ga[0] = *(const bf16x8*)(sA + arow_off + 0 * 2048 + ch1); gb[0] = *(const bf16x8*)(sB + brow_off + 0 * 2048 + ch1);
;         __builtin_amdgcn_sched_barrier(0);
; #pragma unroll
;         for (int j = 0; j < 4; ++j) acc[0][j] = __builtin_amdgcn_mfma_f32_16x16x32_bf16(fb[j], fa[0], acc[0][j], 0, 0, 0);
;         __builtin_amdgcn_sched_barrier(0);
;         if (wr_ok) *(uint4*)(nA + soff0 + 4096) = ra1;
;         if (ld_ok) ra1 = *(const uint4*)(Ab + (aoff + 32u * LDA + koa));
;         ga[1] = *(const bf16x8*)(sA + arow_off + 1 * 2048 + ch1); gb[1] = *(const bf16x8*)(sB + brow_off + 1 * 2048 + ch1);
;         __builtin_amdgcn_sched_barrier(0);
; #pragma unroll
;         for (int j = 0; j < 4; ++j) acc[1][j] = __builtin_amdgcn_mfma_f32_16x16x32_bf16(fb[j], fa[1], acc[1][j], 0, 0, 0);
;         __builtin_amdgcn_sched_barrier(0);
;         if (wr_ok) *(uint4*)(nA + soff0 + 8192) = ra2;
;         if (ld_ok) ra2 = *(const uint4*)(Ab + (aoff + 64u * LDA + koa));
;         ga[2] = *(const bf16x8*)(sA + arow_off + 2 * 2048 + ch1); gb[2] = *(const bf16x8*)(sB + brow_off + 2 * 2048 + ch1);
;         __builtin_amdgcn_sched_barrier(0);
; #pragma unroll
;         for (int j = 0; j < 4; ++j) acc[2][j] = __builtin_amdgcn_mfma_f32_16x16x32_bf16(fb[j], fa[2], acc[2][j], 0, 0, 0);
;         __builtin_amdgcn_sched_barrier(0);
;         if (wr_ok) *(uint4*)(nA + soff0 + 12288) = ra3;
;         if (ld_ok) ra3 = *(const uint4*)(Ab + (aoff + 96u * LDA + koa));
;         ga[3] = *(const bf16x8*)(sA + arow_off + 3 * 2048 + ch1); gb[3] = *(const bf16x8*)(sB + brow_off + 3 * 2048 + ch1);
;         __builtin_amdgcn_sched_barrier(0);
; #pragma unroll
;         for (int j = 0; j < 4; ++j) acc[3][j] = __builtin_amdgcn_mfma_f32_16x16x32_bf16(fb[j], fa[3], acc[3][j], 0, 0, 0);
;         __builtin_amdgcn_sched_barrier(0);
;         if (wr_ok) *(uint4*)(nB + soff0) = rb0;
	ds_read_b128 v[78:81], v22
	ds_read_b128 v[116:119], v22 offset:2048
	ds_read_b128 v[136:139], v23 offset:16384
	ds_read_b128 v[140:143], v23 offset:18432
	ds_read_b128 v[144:147], v22 offset:4096
	ds_read_b128 v[152:155], v22 offset:6144
	ds_read_b128 v[156:159], v23 offset:20480
	ds_read_b128 v[160:163], v23 offset:22528
	s_setprio 2
	s_waitcnt vmcnt(7)
	ds_write_b128 v19, v[168:171] offset:32768
	ds_read_b128 v[164:167], v20
	ds_read_b128 v[168:171], v21 offset:16384
	s_waitcnt lgkmcnt(8)
	v_mfma_f32_16x16x32_bf16 v[40:43], v[136:139], v[78:81], v[42:45]
	s_waitcnt lgkmcnt(3)
	v_mfma_f32_16x16x32_bf16 v[24:27], v[160:163], v[78:81], v[24:27]
	v_mfma_f32_16x16x32_bf16 v[96:99], v[140:143], v[78:81], v[96:99]
	v_mfma_f32_16x16x32_bf16 v[104:107], v[156:159], v[78:81], v[104:107]
	s_waitcnt vmcnt(6)
	ds_write_b128 v19, v[108:111] offset:36864
	ds_read_b128 v[78:81], v20 offset:2048
	ds_read_b128 v[108:111], v21 offset:18432
	v_mfma_f32_16x16x32_bf16 v[44:47], v[136:139], v[116:119], v[46:49]
	v_mfma_f32_16x16x32_bf16 v[58:61], v[140:143], v[116:119], v[58:61]
	v_mfma_f32_16x16x32_bf16 v[28:31], v[160:163], v[116:119], v[28:31]
	v_mfma_f32_16x16x32_bf16 v[100:103], v[156:159], v[116:119], v[100:103]
	s_waitcnt vmcnt(5)
	ds_write_b128 v19, v[120:123] offset:40960
	ds_read_b128 v[116:119], v20 offset:4096
	ds_read_b128 v[120:123], v21 offset:20480
	v_mfma_f32_16x16x32_bf16 v[48:51], v[136:139], v[144:147], v[50:53]
	v_mfma_f32_16x16x32_bf16 v[62:65], v[140:143], v[144:147], v[62:65]
	v_mfma_f32_16x16x32_bf16 v[74:77], v[156:159], v[144:147], v[74:77]
	v_mfma_f32_16x16x32_bf16 v[32:35], v[160:163], v[144:147], v[32:35]
	s_waitcnt vmcnt(4)
	ds_write_b128 v19, v[148:151] offset:45056
	ds_read_b128 v[144:147], v20 offset:6144
	ds_read_b128 v[148:151], v21 offset:22528
	v_mfma_f32_16x16x32_bf16 v[52:55], v[136:139], v[152:155], v[54:57]
	v_mfma_f32_16x16x32_bf16 v[66:69], v[140:143], v[152:155], v[66:69]
	v_mfma_f32_16x16x32_bf16 v[70:73], v[156:159], v[152:155], v[70:73]
	v_mfma_f32_16x16x32_bf16 v[36:39], v[160:163], v[152:155], v[36:39]
	s_waitcnt vmcnt(3)
	ds_write_b128 v19, v[132:135] offset:49152
	s_waitcnt lgkmcnt(10)
	v_mfma_f32_16x16x32_bf16 v[40:43], v[168:171], v[164:167], v[40:43]
	s_waitcnt lgkmcnt(1)
	v_mfma_f32_16x16x32_bf16 v[24:27], v[148:151], v[164:167], v[24:27]
	v_mfma_f32_16x16x32_bf16 v[96:99], v[108:111], v[164:167], v[96:99]
	v_mfma_f32_16x16x32_bf16 v[104:107], v[120:123], v[164:167], v[104:107]
	s_waitcnt vmcnt(2)
	ds_write_b128 v19, v[124:127] offset:53248
	v_mfma_f32_16x16x32_bf16 v[44:47], v[168:171], v[78:81], v[44:47]
	v_mfma_f32_16x16x32_bf16 v[56:59], v[108:111], v[78:81], v[58:61]
	v_mfma_f32_16x16x32_bf16 v[28:31], v[148:151], v[78:81], v[28:31]
	v_mfma_f32_16x16x32_bf16 v[100:103], v[120:123], v[78:81], v[100:103]
	s_waitcnt vmcnt(1)
	ds_write_b128 v19, v[92:95] offset:57344
	v_mfma_f32_16x16x32_bf16 v[48:51], v[168:171], v[116:119], v[48:51]
	v_mfma_f32_16x16x32_bf16 v[60:63], v[108:111], v[116:119], v[62:65]
	v_mfma_f32_16x16x32_bf16 v[74:77], v[120:123], v[116:119], v[74:77]
	v_mfma_f32_16x16x32_bf16 v[32:35], v[148:151], v[116:119], v[32:35]
	s_waitcnt vmcnt(0)
	ds_write_b128 v19, v[112:115] offset:61440
	v_mfma_f32_16x16x32_bf16 v[52:55], v[168:171], v[144:147], v[52:55]
	v_mfma_f32_16x16x32_bf16 v[64:67], v[108:111], v[144:147], v[66:69]
	v_mfma_f32_16x16x32_bf16 v[68:71], v[120:123], v[144:147], v[70:73]
	v_mfma_f32_16x16x32_bf16 v[36:39], v[148:151], v[144:147], v[36:39]
	s_setprio 0
	s_waitcnt lgkmcnt(0)
	s_barrier
; template <int MODE>
; __device__ __forceinline__ void gemm_tile(const Params& P, int tm, int tn, unsigned char* smem) {
;     ...
;     for (int kt = 0; kt < 16; ++kt) {
;         unsigned char* sA = (kt & 1) ? sA1 : sA0; unsigned char* sB = (kt & 1) ? sB1 : sB0;
;         unsigned char* nA = (kt & 1) ? sA0 : sA1; unsigned char* nB = (kt & 1) ? sB0 : sB1;
;         bf16x8 fa[4], fb[4], ga[4], gb[4];
;         const int ch0 = ((g ^ sw) << 4), ch1 = (((4 + g) ^ sw) << 4);
;         const unsigned ko = (unsigned)(kt + 2) * 128u;
;         const unsigned koa = ko + ((MODE == 2 && kt + 2 >= 8) ? (unsigned)(ZC_FQ - 512) * 2u : 0u);
;         const bool wr_ok = kt < 15, ld_ok = kt < 14;
; #pragma unroll
;         for (int i = 0; i < 4; ++i) { fa[i] = *(const bf16x8*)(sA + arow_off + i * 2048 + ch0); fb[i] = *(const bf16x8*)(sB + brow_off + i * 2048 + ch0); }
;         __builtin_amdgcn_sched_barrier(0);
;         __builtin_amdgcn_s_setprio(2);
;         if (wr_ok) *(uint4*)(nA + soff0) = ra0;
;         if (ld_ok) ra0 = *(const uint4*)(Ab + (aoff + 0u * LDA + koa));
;         ga[0] = *(const bf16x8*)(sA + arow_off + 0 * 2048 + ch1); gb[0] = *(const bf16x8*)(sB + brow_off + 0 * 2048 + ch1);
;         __builtin_amdgcn_sched_barrier(0);
; #pragma unroll
;         for (int j = 0; j < 4; ++j) acc[0][j] = __builtin_amdgcn_mfma_f32_16x16x32_bf16(fb[j], fa[0], acc[0][j], 0, 0, 0);
;         __builtin_amdgcn_sched_barrier(0);
;         if (wr_ok) *(uint4*)(nA + soff0 + 4096) = ra1;
;         if (ld_ok) ra1 = *(const uint4*)(Ab + (aoff + 32u * LDA + koa));
;         ga[1] = *(const bf16x8*)(sA + arow_off + 1 * 2048 + ch1); gb[1] = *(const bf16x8*)(sB + brow_off + 1 * 2048 + ch1);
;         __builtin_amdgcn_sched_barrier(0);
; #pragma unroll
;         for (int j = 0; j < 4; ++j) acc[1][j] = __builtin_amdgcn_mfma_f32_16x16x32_bf16(fb[j], fa[1], acc[1][j], 0, 0, 0);
;         __builtin_amdgcn_sched_barrier(0);
;         if (wr_ok) *(uint4*)(nA + soff0 + 8192) = ra2;
;         if (ld_ok) ra2 = *(const uint4*)(Ab + (aoff + 64u * LDA + koa));
;         ga[2] = *(const bf16x8*)(sA + arow_off + 2 * 2048 + ch1); gb[2] = *(const bf16x8*)(sB + brow_off + 2 * 2048 + ch1);
;         __builtin_amdgcn_sched_barrier(0);
; #pragma unroll
;         for (int j = 0; j < 4; ++j) acc[2][j] = __builtin_amdgcn_mfma_f32_16x16x32_bf16(fb[j], fa[2], acc[2][j], 0, 0, 0);
	ds_read_b128 v[78:81], v22 offset:32768
	ds_read_b128 v[92:95], v22 offset:34816
	ds_read_b128 v[108:111], v23 offset:49152
	ds_read_b128 v[112:115], v23 offset:51200
	ds_read_b128 v[116:119], v22 offset:36864
	ds_read_b128 v[120:123], v22 offset:38912
	ds_read_b128 v[124:127], v23 offset:53248
	ds_read_b128 v[132:135], v23 offset:55296
	s_setprio 2
	ds_read_b128 v[136:139], v20 offset:32768
	ds_read_b128 v[140:143], v21 offset:49152
	s_waitcnt lgkmcnt(7)
	v_mfma_f32_16x16x32_bf16 v[40:43], v[108:111], v[78:81], v[40:43]
	s_waitcnt lgkmcnt(2)
	v_mfma_f32_16x16x32_bf16 v[22:25], v[132:135], v[78:81], v[24:27]
	v_mfma_f32_16x16x32_bf16 v[96:99], v[112:115], v[78:81], v[96:99]
	v_mfma_f32_16x16x32_bf16 v[104:107], v[124:127], v[78:81], v[104:107]
	ds_read_b128 v[144:147], v20 offset:34816
	ds_read_b128 v[148:151], v21 offset:51200
	v_mfma_f32_16x16x32_bf16 v[44:47], v[108:111], v[92:95], v[44:47]
	v_mfma_f32_16x16x32_bf16 v[56:59], v[112:115], v[92:95], v[56:59]
	v_mfma_f32_16x16x32_bf16 v[26:29], v[132:135], v[92:95], v[28:31]
	v_mfma_f32_16x16x32_bf16 v[100:103], v[124:127], v[92:95], v[100:103]
	ds_read_b128 v[92:95], v20 offset:36864
	ds_read_b128 v[152:155], v21 offset:53248
	v_mfma_f32_16x16x32_bf16 v[30:33], v[132:135], v[116:119], v[32:35]
	v_mfma_f32_16x16x32_bf16 v[156:159], v[108:111], v[116:119], v[48:51]
	v_mfma_f32_16x16x32_bf16 v[160:163], v[112:115], v[116:119], v[60:63]
	v_mfma_f32_16x16x32_bf16 v[164:167], v[124:127], v[116:119], v[74:77]
	ds_read_b128 v[116:119], v20 offset:38912
	ds_read_b128 v[18:21], v21 offset:55296
	v_mfma_f32_16x16x32_bf16 v[108:111], v[108:111], v[120:123], v[52:55]
	v_mfma_f32_16x16x32_bf16 v[112:115], v[112:115], v[120:123], v[64:67]
	v_mfma_f32_16x16x32_bf16 v[124:127], v[124:127], v[120:123], v[68:71]
	v_mfma_f32_16x16x32_bf16 v[120:123], v[132:135], v[120:123], v[36:39]
	s_waitcnt lgkmcnt(6)
	v_mfma_f32_16x16x32_bf16 v[78:81], v[140:143], v[136:139], v[40:43]
	s_waitcnt lgkmcnt(4)
	v_mfma_f32_16x16x32_bf16 v[74:77], v[148:151], v[136:139], v[96:99]
	s_waitcnt lgkmcnt(2)
	v_mfma_f32_16x16x32_bf16 v[70:73], v[152:155], v[136:139], v[104:107]
	s_waitcnt lgkmcnt(0)
	v_mfma_f32_16x16x32_bf16 v[66:69], v[18:21], v[136:139], v[22:25]
	v_mfma_f32_16x16x32_bf16 v[62:65], v[140:143], v[144:147], v[44:47]
	v_mfma_f32_16x16x32_bf16 v[58:61], v[148:151], v[144:147], v[56:59]
	v_mfma_f32_16x16x32_bf16 v[54:57], v[152:155], v[144:147], v[100:103]
	v_mfma_f32_16x16x32_bf16 v[50:53], v[18:21], v[144:147], v[26:29]
	v_mfma_f32_16x16x32_bf16 v[46:49], v[140:143], v[92:95], v[156:159]
	v_mfma_f32_16x16x32_bf16 v[42:45], v[148:151], v[92:95], v[160:163]
	v_mfma_f32_16x16x32_bf16 v[38:41], v[152:155], v[92:95], v[164:167]
	v_mfma_f32_16x16x32_bf16 v[34:37], v[18:21], v[92:95], v[30:33]
	v_mfma_f32_16x16x32_bf16 v[30:33], v[140:143], v[116:119], v[108:111]
	v_mfma_f32_16x16x32_bf16 v[26:29], v[148:151], v[116:119], v[112:115]
	v_mfma_f32_16x16x32_bf16 v[22:25], v[152:155], v[116:119], v[124:127]
	v_mfma_f32_16x16x32_bf16 v[18:21], v[18:21], v[116:119], v[120:123]
	s_setprio 0
	v_add_f32_e32 v10, v10, v11
	v_add_f32_e32 v11, v12, v13
	v_add_f32_e32 v10, v10, v11
	v_mov_b32_e32 v11, v10
	s_nop 1
	v_permlane32_swap_b32_e32 v10, v11
	v_add_f32_e32 v10, v10, v11
	v_mov_b32_e32 v11, v10
	s_nop 1
	v_permlane16_swap_b32_e32 v10, v11
	v_add_f32_e32 v10, v10, v11
	v_fmamk_f32 v10, v10, 0x3a800000, v86
	v_mul_f32_e32 v11, 0x4b800000, v10
	v_cmp_gt_f32_e64 s[0:1], s19, v10
	v_lshl_add_u64 v[84:85], v[84:85], 2, s[8:9]
	s_nop 0
	v_cndmask_b32_e64 v10, v10, v11, s[0:1]
	v_rsq_f32_e32 v10, v10
	v_or3_b32 v11, v91, s2, v89
	v_cmp_eq_u32_e32 vcc, 0, v11
	s_barrier
	v_mul_f32_e32 v11, 0x45800000, v10
	v_cndmask_b32_e64 v12, v10, v11, s[0:1]
	s_and_saveexec_b64 s[0:1], vcc
	s_cbranch_execz .LBB0_1265
	global_store_dword v[84:85], v12, off
